# GEMM k-tile prefetch loads issued before the end-of-segment barrier (unrolled K=1024 phases)
# speedup vs baseline: 1.1506x; 1.0103x over previous
.LBB0_73:
	s_bfe_u32 s4, s44, 0x80003
	s_mul_i32 s4, s4, 19
	s_lshr_b32 s4, s4, 9
	s_lshr_b32 s51, s44, 3
	s_mul_i32 s4, s4, 27
	s_sub_i32 s4, s51, s4
	s_and_b32 s76, s4, 0xff
	s_bfe_u32 s4, s44, 0xd0003
	s_mulk_i32 s4, 0x12f7
	s_lshr_b32 s4, s4, 11
	s_lshl_b32 s5, s44, 3
	s_and_b32 s4, s4, 0x7fc0
	s_and_b32 s5, s5, 56
	s_or_b32 s4, s5, s4
	s_or_b32 s4, s4, s3
	s_lshl_b32 s26, s4, 7
	s_lshl_b64 s[4:5], s[26:27], 11
	v_lshl_add_u64 v[160:161], v[144:145], 0, s[4:5]
	v_add_co_u32_e32 v162, vcc, s47, v160
	s_lshl_b32 s4, s76, 18
	s_nop 0
	v_addc_co_u32_e32 v163, vcc, 0, v161, vcc
	s_mov_b32 s5, s27
	v_add_co_u32_e32 v164, vcc, s87, v160
	v_lshl_add_u64 v[158:159], v[146:147], 0, s[4:5]
	s_nop 0
	v_addc_co_u32_e32 v165, vcc, 0, v161, vcc
	v_add_co_u32_e32 v166, vcc, s47, v158
	global_load_dwordx4 v[2:5], v[160:161], off
	global_load_dwordx4 v[6:9], v[162:163], off
	v_addc_co_u32_e32 v167, vcc, 0, v159, vcc
	global_load_dwordx4 v[10:13], v[164:165], off
	global_load_dwordx4 v[14:17], v[158:159], off
	v_add_co_u32_e32 v168, vcc, s87, v158
	global_load_dwordx4 v[18:21], v[166:167], off
	s_nop 0
	v_addc_co_u32_e32 v169, vcc, 0, v159, vcc
	v_add_co_u32_e32 v170, vcc, s10, v158
	global_load_dwordx4 v[22:25], v[168:169], off
	s_nop 0
	v_addc_co_u32_e32 v171, vcc, 0, v159, vcc
	global_load_dwordx4 v[26:29], v[170:171], off
	v_add_co_u32_e32 v172, vcc, s10, v160
	s_nop 1
	v_addc_co_u32_e32 v173, vcc, 0, v161, vcc
	global_load_dwordx4 v[30:33], v[172:173], off
	global_load_dwordx4 v[70:73], v[158:159], off offset:128
	global_load_dwordx4 v[102:105], v[160:161], off offset:128
	global_load_dwordx4 v[106:109], v[166:167], off offset:128
	global_load_dwordx4 v[110:113], v[168:169], off offset:128
	global_load_dwordx4 v[114:117], v[170:171], off offset:128
	global_load_dwordx4 v[118:121], v[162:163], off offset:128
	global_load_dwordx4 v[122:125], v[164:165], off offset:128
	global_load_dwordx4 v[126:129], v[172:173], off offset:128
	s_waitcnt vmcnt(12)
	ds_write_b128 v174, v[14:17] offset:36864
	ds_write_b128 v174, v[2:5]
	s_waitcnt vmcnt(11)
	ds_write_b128 v174, v[18:21] offset:41472
	s_waitcnt vmcnt(10)
	ds_write_b128 v174, v[22:25] offset:46080
	s_waitcnt vmcnt(9)
	ds_write_b128 v174, v[26:29] offset:50688
	ds_write_b128 v174, v[6:9] offset:4608
	ds_write_b128 v174, v[10:13] offset:9216
	s_waitcnt vmcnt(8)
	ds_write_b128 v174, v[30:33] offset:13824
	s_waitcnt lgkmcnt(0)
	s_barrier
	global_load_dwordx4 v[74:77], v[162:163], off offset:256
	global_load_dwordx4 v[78:81], v[164:165], off offset:256
	global_load_dwordx4 v[94:97], v[160:161], off offset:256
	global_load_dwordx4 v[66:69], v[158:159], off offset:256
	global_load_dwordx4 v[98:101], v[172:173], off offset:256
	global_load_dwordx4 v[82:85], v[166:167], off offset:256
	global_load_dwordx4 v[86:89], v[168:169], off offset:256
	global_load_dwordx4 v[90:93], v[170:171], off offset:256
	ds_read_b128 v[50:53], v148 offset:4608
	ds_read_b128 v[54:57], v149 offset:41472
	ds_read_b128 v[18:21], v148
	ds_read_b128 v[130:133], v148 offset:32
	ds_read_b128 v[34:37], v149 offset:36864
	ds_read_b128 v[134:137], v149 offset:36896
	ds_read_b128 v[138:141], v148 offset:4640
	ds_read_b128 v[208:211], v149 offset:41504
	s_waitcnt lgkmcnt(3)
	v_mfma_f32_32x32x16_bf16 v[2:17], v[18:21], v[34:37], 0
	v_mfma_f32_32x32x16_bf16 v[18:33], v[18:21], v[54:57], 0
	v_mfma_f32_32x32x16_bf16 v[34:49], v[50:53], v[34:37], 0
	v_mfma_f32_32x32x16_bf16 v[50:65], v[50:53], v[54:57], 0
	s_waitcnt lgkmcnt(2)
	v_mfma_f32_32x32x16_bf16 v[2:17], v[130:133], v[134:137], v[2:17]
	s_waitcnt lgkmcnt(0)
	v_mfma_f32_32x32x16_bf16 v[18:33], v[130:133], v[208:211], v[18:33]
	v_mfma_f32_32x32x16_bf16 v[34:49], v[138:141], v[134:137], v[34:49]
	v_mfma_f32_32x32x16_bf16 v[50:65], v[138:141], v[208:211], v[50:65]
	ds_read_b128 v[130:133], v148 offset:64
	ds_read_b128 v[134:137], v148 offset:4672
	ds_read_b128 v[138:141], v149 offset:36928
	ds_read_b128 v[208:211], v149 offset:41536
	s_waitcnt lgkmcnt(1)
	v_mfma_f32_32x32x16_bf16 v[2:17], v[130:133], v[138:141], v[2:17]
	s_waitcnt lgkmcnt(0)
	v_mfma_f32_32x32x16_bf16 v[18:33], v[130:133], v[208:211], v[18:33]
	v_mfma_f32_32x32x16_bf16 v[34:49], v[134:137], v[138:141], v[34:49]
	v_mfma_f32_32x32x16_bf16 v[50:65], v[134:137], v[208:211], v[50:65]
	ds_read_b128 v[130:133], v148 offset:96
	ds_read_b128 v[134:137], v148 offset:4704
	ds_read_b128 v[138:141], v149 offset:36960
	ds_read_b128 v[208:211], v149 offset:41568
	s_waitcnt vmcnt(14)
	ds_write_b128 v174, v[102:105] offset:18432
	s_waitcnt vmcnt(10)
	ds_write_b128 v174, v[118:121] offset:23040
	s_waitcnt vmcnt(9)
	ds_write_b128 v174, v[122:125] offset:27648
	s_waitcnt vmcnt(8)
	ds_write_b128 v174, v[126:129] offset:32256
	ds_write_b128 v174, v[70:73] offset:55296
	ds_write_b128 v174, v[106:109] offset:59904
	ds_write_b128 v174, v[110:113] offset:64512
	ds_write_b128 v175, v[114:117] offset:32256
	global_load_dwordx4 v[70:73], v[160:161], off offset:384
	global_load_dwordx4 v[102:105], v[162:163], off offset:384
	global_load_dwordx4 v[106:109], v[164:165], off offset:384
	global_load_dwordx4 v[110:113], v[172:173], off offset:384
	global_load_dwordx4 v[114:117], v[158:159], off offset:384
	global_load_dwordx4 v[118:121], v[166:167], off offset:384
	global_load_dwordx4 v[122:125], v[168:169], off offset:384
	global_load_dwordx4 v[126:129], v[170:171], off offset:384
	s_waitcnt lgkmcnt(0)
	s_barrier
	v_mfma_f32_32x32x16_bf16 v[2:17], v[130:133], v[138:141], v[2:17]
	v_mfma_f32_32x32x16_bf16 v[18:33], v[130:133], v[208:211], v[18:33]
	v_mfma_f32_32x32x16_bf16 v[34:49], v[134:137], v[138:141], v[34:49]
	v_mfma_f32_32x32x16_bf16 v[50:65], v[134:137], v[208:211], v[50:65]
	ds_read_b128 v[130:133], v148 offset:18432
	ds_read_b128 v[134:137], v149 offset:55296
	ds_read_b128 v[138:141], v149 offset:59904
	s_waitcnt lgkmcnt(1)
	v_mfma_f32_32x32x16_bf16 v[2:17], v[130:133], v[134:137], v[2:17]
	s_waitcnt lgkmcnt(0)
	v_mfma_f32_32x32x16_bf16 v[18:33], v[130:133], v[138:141], v[18:33]
	ds_read_b128 v[130:133], v148 offset:23040
	s_waitcnt lgkmcnt(0)
	v_mfma_f32_32x32x16_bf16 v[34:49], v[130:133], v[134:137], v[34:49]
	v_mfma_f32_32x32x16_bf16 v[50:65], v[130:133], v[138:141], v[50:65]
	ds_read_b128 v[130:133], v148 offset:18464
	ds_read_b128 v[134:137], v149 offset:55328
	ds_read_b128 v[138:141], v149 offset:59936
	s_waitcnt lgkmcnt(1)
	v_mfma_f32_32x32x16_bf16 v[2:17], v[130:133], v[134:137], v[2:17]
	s_waitcnt lgkmcnt(0)
	v_mfma_f32_32x32x16_bf16 v[18:33], v[130:133], v[138:141], v[18:33]
	ds_read_b128 v[130:133], v148 offset:23072
	s_waitcnt lgkmcnt(0)
	v_mfma_f32_32x32x16_bf16 v[34:49], v[130:133], v[134:137], v[34:49]
	v_mfma_f32_32x32x16_bf16 v[50:65], v[130:133], v[138:141], v[50:65]
	ds_read_b128 v[130:133], v148 offset:18496
	ds_read_b128 v[134:137], v149 offset:55360
	ds_read_b128 v[138:141], v149 offset:59968
	s_waitcnt lgkmcnt(1)
	v_mfma_f32_32x32x16_bf16 v[2:17], v[130:133], v[134:137], v[2:17]
	s_waitcnt lgkmcnt(0)
	v_mfma_f32_32x32x16_bf16 v[18:33], v[130:133], v[138:141], v[18:33]
	ds_read_b128 v[130:133], v148 offset:23104
	s_waitcnt lgkmcnt(0)
	v_mfma_f32_32x32x16_bf16 v[34:49], v[130:133], v[134:137], v[34:49]
	v_mfma_f32_32x32x16_bf16 v[50:65], v[130:133], v[138:141], v[50:65]
	ds_read_b128 v[130:133], v148 offset:18528
	ds_read_b128 v[134:137], v149 offset:55392
	ds_read_b128 v[208:211], v148 offset:23136
	ds_read_b128 v[212:215], v149 offset:60000
	s_waitcnt vmcnt(13)
	ds_write_b128 v174, v[94:97]
	ds_write_b128 v174, v[74:77] offset:4608
	ds_write_b128 v174, v[78:81] offset:9216
	s_waitcnt vmcnt(11)
	ds_write_b128 v174, v[98:101] offset:13824
	ds_write_b128 v174, v[66:69] offset:36864
	s_waitcnt vmcnt(10)
	ds_write_b128 v174, v[82:85] offset:41472
	s_waitcnt vmcnt(9)
	ds_write_b128 v174, v[86:89] offset:46080
	s_waitcnt vmcnt(8)
	ds_write_b128 v174, v[90:93] offset:50688
	s_waitcnt lgkmcnt(0)
	s_barrier
	v_mfma_f32_32x32x16_bf16 v[2:17], v[130:133], v[134:137], v[2:17]
	v_mfma_f32_32x32x16_bf16 v[18:33], v[130:133], v[212:215], v[18:33]
	v_mfma_f32_32x32x16_bf16 v[34:49], v[208:211], v[134:137], v[34:49]
	global_load_dwordx4 v[66:69], v[160:161], off offset:512
	global_load_dwordx4 v[74:77], v[162:163], off offset:512
	global_load_dwordx4 v[78:81], v[164:165], off offset:512
	global_load_dwordx4 v[82:85], v[172:173], off offset:512
	global_load_dwordx4 v[98:101], v[158:159], off offset:512
	global_load_dwordx4 v[130:133], v[166:167], off offset:512
	global_load_dwordx4 v[134:137], v[168:169], off offset:512
	global_load_dwordx4 v[138:141], v[170:171], off offset:512
	v_mfma_f32_32x32x16_bf16 v[50:65], v[208:211], v[212:215], v[50:65]
	ds_read_b128 v[86:89], v148
	ds_read_b128 v[90:93], v149 offset:36864
	ds_read_b128 v[94:97], v149 offset:41472
	s_waitcnt lgkmcnt(1)
	v_mfma_f32_32x32x16_bf16 v[2:17], v[86:89], v[90:93], v[2:17]
	s_waitcnt lgkmcnt(0)
	v_mfma_f32_32x32x16_bf16 v[18:33], v[86:89], v[94:97], v[18:33]
	ds_read_b128 v[86:89], v148 offset:4608
	s_waitcnt lgkmcnt(0)
	v_mfma_f32_32x32x16_bf16 v[34:49], v[86:89], v[90:93], v[34:49]
	v_mfma_f32_32x32x16_bf16 v[50:65], v[86:89], v[94:97], v[50:65]
	ds_read_b128 v[86:89], v148 offset:32
	ds_read_b128 v[90:93], v149 offset:36896
	ds_read_b128 v[94:97], v149 offset:41504
	s_waitcnt lgkmcnt(1)
	v_mfma_f32_32x32x16_bf16 v[2:17], v[86:89], v[90:93], v[2:17]
	s_waitcnt lgkmcnt(0)
	v_mfma_f32_32x32x16_bf16 v[18:33], v[86:89], v[94:97], v[18:33]
	ds_read_b128 v[86:89], v148 offset:4640
	s_waitcnt lgkmcnt(0)
	v_mfma_f32_32x32x16_bf16 v[34:49], v[86:89], v[90:93], v[34:49]
	v_mfma_f32_32x32x16_bf16 v[50:65], v[86:89], v[94:97], v[50:65]
	ds_read_b128 v[86:89], v148 offset:64
	ds_read_b128 v[90:93], v149 offset:36928
	ds_read_b128 v[94:97], v149 offset:41536
	s_waitcnt lgkmcnt(1)
	v_mfma_f32_32x32x16_bf16 v[2:17], v[86:89], v[90:93], v[2:17]
	s_waitcnt lgkmcnt(0)
	v_mfma_f32_32x32x16_bf16 v[18:33], v[86:89], v[94:97], v[18:33]
	ds_read_b128 v[86:89], v148 offset:4672
	s_waitcnt lgkmcnt(0)
	v_mfma_f32_32x32x16_bf16 v[34:49], v[86:89], v[90:93], v[34:49]
	v_mfma_f32_32x32x16_bf16 v[50:65], v[86:89], v[94:97], v[50:65]
	ds_read_b128 v[86:89], v148 offset:96
	ds_read_b128 v[90:93], v149 offset:36960
	ds_read_b128 v[208:211], v148 offset:4704
	ds_read_b128 v[212:215], v149 offset:41568
	s_waitcnt vmcnt(15)
	ds_write_b128 v174, v[70:73] offset:18432
	s_waitcnt vmcnt(14)
	ds_write_b128 v174, v[102:105] offset:23040
	s_waitcnt vmcnt(13)
	ds_write_b128 v174, v[106:109] offset:27648
	s_waitcnt vmcnt(12)
	ds_write_b128 v174, v[110:113] offset:32256
	s_waitcnt vmcnt(11)
	ds_write_b128 v174, v[114:117] offset:55296
	s_waitcnt vmcnt(10)
	ds_write_b128 v174, v[118:121] offset:59904
	s_waitcnt vmcnt(9)
	ds_write_b128 v174, v[122:125] offset:64512
	s_waitcnt vmcnt(8)
	ds_write_b128 v175, v[126:129] offset:32256
	s_waitcnt lgkmcnt(0)
	s_barrier
	v_mfma_f32_32x32x16_bf16 v[2:17], v[86:89], v[90:93], v[2:17]
	v_mfma_f32_32x32x16_bf16 v[18:33], v[86:89], v[212:215], v[18:33]
	v_mfma_f32_32x32x16_bf16 v[34:49], v[208:211], v[90:93], v[34:49]
	global_load_dwordx4 v[70:73], v[160:161], off offset:640
	global_load_dwordx4 v[86:89], v[162:163], off offset:640
	global_load_dwordx4 v[90:93], v[164:165], off offset:640
	global_load_dwordx4 v[94:97], v[172:173], off offset:640
	global_load_dwordx4 v[102:105], v[158:159], off offset:640
	global_load_dwordx4 v[106:109], v[166:167], off offset:640
	global_load_dwordx4 v[110:113], v[168:169], off offset:640
	global_load_dwordx4 v[114:117], v[170:171], off offset:640
	v_mfma_f32_32x32x16_bf16 v[50:65], v[208:211], v[212:215], v[50:65]
	ds_read_b128 v[118:121], v148 offset:18432
	ds_read_b128 v[122:125], v149 offset:55296
	ds_read_b128 v[126:129], v149 offset:59904
	s_waitcnt lgkmcnt(1)
	v_mfma_f32_32x32x16_bf16 v[2:17], v[118:121], v[122:125], v[2:17]
	s_waitcnt lgkmcnt(0)
	v_mfma_f32_32x32x16_bf16 v[18:33], v[118:121], v[126:129], v[18:33]
	ds_read_b128 v[118:121], v148 offset:23040
	s_waitcnt lgkmcnt(0)
	v_mfma_f32_32x32x16_bf16 v[34:49], v[118:121], v[122:125], v[34:49]
	v_mfma_f32_32x32x16_bf16 v[50:65], v[118:121], v[126:129], v[50:65]
	ds_read_b128 v[118:121], v148 offset:18464
	ds_read_b128 v[122:125], v149 offset:55328
	ds_read_b128 v[126:129], v149 offset:59936
	s_waitcnt lgkmcnt(1)
	v_mfma_f32_32x32x16_bf16 v[2:17], v[118:121], v[122:125], v[2:17]
	s_waitcnt lgkmcnt(0)
	v_mfma_f32_32x32x16_bf16 v[18:33], v[118:121], v[126:129], v[18:33]
	ds_read_b128 v[118:121], v148 offset:23072
	s_waitcnt lgkmcnt(0)
	v_mfma_f32_32x32x16_bf16 v[34:49], v[118:121], v[122:125], v[34:49]
	v_mfma_f32_32x32x16_bf16 v[50:65], v[118:121], v[126:129], v[50:65]
	ds_read_b128 v[118:121], v148 offset:18496
	ds_read_b128 v[122:125], v149 offset:55360
	ds_read_b128 v[126:129], v149 offset:59968
	s_waitcnt lgkmcnt(1)
	v_mfma_f32_32x32x16_bf16 v[2:17], v[118:121], v[122:125], v[2:17]
	s_waitcnt lgkmcnt(0)
	v_mfma_f32_32x32x16_bf16 v[18:33], v[118:121], v[126:129], v[18:33]
	ds_read_b128 v[118:121], v148 offset:23104
	s_waitcnt lgkmcnt(0)
	v_mfma_f32_32x32x16_bf16 v[34:49], v[118:121], v[122:125], v[34:49]
	v_mfma_f32_32x32x16_bf16 v[50:65], v[118:121], v[126:129], v[50:65]
	ds_read_b128 v[118:121], v148 offset:18528
	ds_read_b128 v[122:125], v149 offset:55392
	ds_read_b128 v[208:211], v148 offset:23136
	ds_read_b128 v[212:215], v149 offset:60000
	s_waitcnt vmcnt(15)
	ds_write_b128 v174, v[66:69]
	s_waitcnt vmcnt(14)
	ds_write_b128 v174, v[74:77] offset:4608
	s_waitcnt vmcnt(13)
	ds_write_b128 v174, v[78:81] offset:9216
	s_waitcnt vmcnt(12)
	ds_write_b128 v174, v[82:85] offset:13824
	s_waitcnt vmcnt(11)
	ds_write_b128 v174, v[98:101] offset:36864
	s_waitcnt vmcnt(10)
	ds_write_b128 v174, v[130:133] offset:41472
	s_waitcnt vmcnt(9)
	ds_write_b128 v174, v[134:137] offset:46080
	s_waitcnt vmcnt(8)
	ds_write_b128 v174, v[138:141] offset:50688
	s_waitcnt lgkmcnt(0)
	s_barrier
	v_mfma_f32_32x32x16_bf16 v[2:17], v[118:121], v[122:125], v[2:17]
	v_mfma_f32_32x32x16_bf16 v[18:33], v[118:121], v[212:215], v[18:33]
	v_mfma_f32_32x32x16_bf16 v[34:49], v[208:211], v[122:125], v[34:49]
	global_load_dwordx4 v[66:69], v[160:161], off offset:768
	global_load_dwordx4 v[74:77], v[162:163], off offset:768
	global_load_dwordx4 v[78:81], v[164:165], off offset:768
	global_load_dwordx4 v[82:85], v[172:173], off offset:768
	global_load_dwordx4 v[98:101], v[158:159], off offset:768
	global_load_dwordx4 v[118:121], v[166:167], off offset:768
	global_load_dwordx4 v[122:125], v[168:169], off offset:768
	global_load_dwordx4 v[126:129], v[170:171], off offset:768
	v_mfma_f32_32x32x16_bf16 v[50:65], v[208:211], v[212:215], v[50:65]
	ds_read_b128 v[130:133], v148
	ds_read_b128 v[134:137], v149 offset:36864
	ds_read_b128 v[138:141], v149 offset:41472
	s_waitcnt lgkmcnt(1)
	v_mfma_f32_32x32x16_bf16 v[2:17], v[130:133], v[134:137], v[2:17]
	s_waitcnt lgkmcnt(0)
	v_mfma_f32_32x32x16_bf16 v[18:33], v[130:133], v[138:141], v[18:33]
	ds_read_b128 v[130:133], v148 offset:4608
	s_waitcnt lgkmcnt(0)
	v_mfma_f32_32x32x16_bf16 v[34:49], v[130:133], v[134:137], v[34:49]
	v_mfma_f32_32x32x16_bf16 v[50:65], v[130:133], v[138:141], v[50:65]
	ds_read_b128 v[130:133], v148 offset:32
	ds_read_b128 v[134:137], v149 offset:36896
	ds_read_b128 v[138:141], v149 offset:41504
	s_waitcnt lgkmcnt(1)
	v_mfma_f32_32x32x16_bf16 v[2:17], v[130:133], v[134:137], v[2:17]
	s_waitcnt lgkmcnt(0)
	v_mfma_f32_32x32x16_bf16 v[18:33], v[130:133], v[138:141], v[18:33]
	ds_read_b128 v[130:133], v148 offset:4640
	s_waitcnt lgkmcnt(0)
	v_mfma_f32_32x32x16_bf16 v[34:49], v[130:133], v[134:137], v[34:49]
	v_mfma_f32_32x32x16_bf16 v[50:65], v[130:133], v[138:141], v[50:65]
	ds_read_b128 v[130:133], v148 offset:64
	ds_read_b128 v[134:137], v149 offset:36928
	ds_read_b128 v[138:141], v149 offset:41536
	s_waitcnt lgkmcnt(1)
	v_mfma_f32_32x32x16_bf16 v[2:17], v[130:133], v[134:137], v[2:17]
	s_waitcnt lgkmcnt(0)
	v_mfma_f32_32x32x16_bf16 v[18:33], v[130:133], v[138:141], v[18:33]
	ds_read_b128 v[130:133], v148 offset:4672
	s_waitcnt lgkmcnt(0)
	v_mfma_f32_32x32x16_bf16 v[34:49], v[130:133], v[134:137], v[34:49]
	v_mfma_f32_32x32x16_bf16 v[50:65], v[130:133], v[138:141], v[50:65]
	ds_read_b128 v[130:133], v148 offset:96
	ds_read_b128 v[134:137], v149 offset:36960
	ds_read_b128 v[138:141], v148 offset:4704
	ds_read_b128 v[208:211], v149 offset:41568
	s_waitcnt vmcnt(15)
	ds_write_b128 v174, v[70:73] offset:18432
	s_waitcnt vmcnt(14)
	ds_write_b128 v174, v[86:89] offset:23040
	s_waitcnt vmcnt(13)
	ds_write_b128 v174, v[90:93] offset:27648
	s_waitcnt vmcnt(12)
	ds_write_b128 v174, v[94:97] offset:32256
	s_waitcnt vmcnt(11)
	ds_write_b128 v174, v[102:105] offset:55296
	s_waitcnt vmcnt(10)
	ds_write_b128 v174, v[106:109] offset:59904
	s_waitcnt vmcnt(9)
	ds_write_b128 v174, v[110:113] offset:64512
	s_waitcnt vmcnt(8)
	ds_write_b128 v175, v[114:117] offset:32256
	global_load_dwordx4 v[70:73], v[160:161], off offset:896
	global_load_dwordx4 v[86:89], v[162:163], off offset:896
	global_load_dwordx4 v[90:93], v[164:165], off offset:896
	global_load_dwordx4 v[94:97], v[172:173], off offset:896
	global_load_dwordx4 v[102:105], v[158:159], off offset:896
	global_load_dwordx4 v[106:109], v[166:167], off offset:896
	global_load_dwordx4 v[110:113], v[168:169], off offset:896
	global_load_dwordx4 v[114:117], v[170:171], off offset:896
	s_waitcnt lgkmcnt(0)
	s_barrier
	v_mfma_f32_32x32x16_bf16 v[2:17], v[130:133], v[134:137], v[2:17]
	v_mfma_f32_32x32x16_bf16 v[18:33], v[130:133], v[208:211], v[18:33]
	v_mfma_f32_32x32x16_bf16 v[34:49], v[138:141], v[134:137], v[34:49]
	v_mfma_f32_32x32x16_bf16 v[50:65], v[138:141], v[208:211], v[50:65]
	ds_read_b128 v[130:133], v148 offset:18432
	ds_read_b128 v[134:137], v149 offset:55296
	ds_read_b128 v[138:141], v149 offset:59904
	s_waitcnt lgkmcnt(1)
	v_mfma_f32_32x32x16_bf16 v[2:17], v[130:133], v[134:137], v[2:17]
	s_waitcnt lgkmcnt(0)
	v_mfma_f32_32x32x16_bf16 v[18:33], v[130:133], v[138:141], v[18:33]
	ds_read_b128 v[130:133], v148 offset:23040
	s_waitcnt lgkmcnt(0)
	v_mfma_f32_32x32x16_bf16 v[34:49], v[130:133], v[134:137], v[34:49]
	v_mfma_f32_32x32x16_bf16 v[50:65], v[130:133], v[138:141], v[50:65]
	ds_read_b128 v[130:133], v148 offset:18464
	ds_read_b128 v[134:137], v149 offset:55328
	ds_read_b128 v[138:141], v149 offset:59936
	s_waitcnt lgkmcnt(1)
	v_mfma_f32_32x32x16_bf16 v[2:17], v[130:133], v[134:137], v[2:17]
	s_waitcnt lgkmcnt(0)
	v_mfma_f32_32x32x16_bf16 v[18:33], v[130:133], v[138:141], v[18:33]
	ds_read_b128 v[130:133], v148 offset:23072
	s_waitcnt lgkmcnt(0)
	v_mfma_f32_32x32x16_bf16 v[34:49], v[130:133], v[134:137], v[34:49]
	v_mfma_f32_32x32x16_bf16 v[50:65], v[130:133], v[138:141], v[50:65]
	ds_read_b128 v[130:133], v148 offset:18496
	ds_read_b128 v[134:137], v149 offset:55360
	ds_read_b128 v[138:141], v149 offset:59968
	s_waitcnt lgkmcnt(1)
	v_mfma_f32_32x32x16_bf16 v[2:17], v[130:133], v[134:137], v[2:17]
	s_waitcnt lgkmcnt(0)
	v_mfma_f32_32x32x16_bf16 v[18:33], v[130:133], v[138:141], v[18:33]
	ds_read_b128 v[130:133], v148 offset:23104
	s_waitcnt lgkmcnt(0)
	v_mfma_f32_32x32x16_bf16 v[34:49], v[130:133], v[134:137], v[34:49]
	v_mfma_f32_32x32x16_bf16 v[50:65], v[130:133], v[138:141], v[50:65]
	ds_read_b128 v[130:133], v148 offset:18528
	ds_read_b128 v[134:137], v149 offset:55392
	ds_read_b128 v[138:141], v148 offset:23136
	ds_read_b128 v[208:211], v149 offset:60000
	s_waitcnt vmcnt(15)
	ds_write_b128 v174, v[66:69]
	s_waitcnt vmcnt(14)
	ds_write_b128 v174, v[74:77] offset:4608
	s_waitcnt vmcnt(13)
	ds_write_b128 v174, v[78:81] offset:9216
	s_waitcnt vmcnt(12)
	ds_write_b128 v174, v[82:85] offset:13824
	s_waitcnt vmcnt(11)
	ds_write_b128 v174, v[98:101] offset:36864
	s_waitcnt vmcnt(10)
	ds_write_b128 v174, v[118:121] offset:41472
	s_waitcnt vmcnt(9)
	ds_write_b128 v174, v[122:125] offset:46080
	s_waitcnt vmcnt(8)
	ds_write_b128 v174, v[126:129] offset:50688
	global_load_dwordx4 v[66:69], v[160:161], off offset:1024
	global_load_dwordx4 v[74:77], v[162:163], off offset:1024
	global_load_dwordx4 v[78:81], v[164:165], off offset:1024
	global_load_dwordx4 v[82:85], v[172:173], off offset:1024
	global_load_dwordx4 v[98:101], v[158:159], off offset:1024
	global_load_dwordx4 v[118:121], v[166:167], off offset:1024
	global_load_dwordx4 v[122:125], v[168:169], off offset:1024
	global_load_dwordx4 v[126:129], v[170:171], off offset:1024
	s_waitcnt lgkmcnt(0)
	s_barrier
	v_mfma_f32_32x32x16_bf16 v[2:17], v[130:133], v[134:137], v[2:17]
	v_mfma_f32_32x32x16_bf16 v[18:33], v[130:133], v[208:211], v[18:33]
	v_mfma_f32_32x32x16_bf16 v[34:49], v[138:141], v[134:137], v[34:49]
	v_mfma_f32_32x32x16_bf16 v[50:65], v[138:141], v[208:211], v[50:65]
	ds_read_b128 v[130:133], v148
	ds_read_b128 v[134:137], v149 offset:36864
	ds_read_b128 v[138:141], v149 offset:41472
	s_waitcnt lgkmcnt(1)
	v_mfma_f32_32x32x16_bf16 v[2:17], v[130:133], v[134:137], v[2:17]
	s_waitcnt lgkmcnt(0)
	v_mfma_f32_32x32x16_bf16 v[18:33], v[130:133], v[138:141], v[18:33]
	ds_read_b128 v[130:133], v148 offset:4608
	s_waitcnt lgkmcnt(0)
	v_mfma_f32_32x32x16_bf16 v[34:49], v[130:133], v[134:137], v[34:49]
	v_mfma_f32_32x32x16_bf16 v[50:65], v[130:133], v[138:141], v[50:65]
	ds_read_b128 v[130:133], v148 offset:32
	ds_read_b128 v[134:137], v149 offset:36896
	ds_read_b128 v[138:141], v149 offset:41504
	s_waitcnt lgkmcnt(1)
	v_mfma_f32_32x32x16_bf16 v[2:17], v[130:133], v[134:137], v[2:17]
	s_waitcnt lgkmcnt(0)
	v_mfma_f32_32x32x16_bf16 v[18:33], v[130:133], v[138:141], v[18:33]
	ds_read_b128 v[130:133], v148 offset:4640
	s_waitcnt lgkmcnt(0)
	v_mfma_f32_32x32x16_bf16 v[34:49], v[130:133], v[134:137], v[34:49]
	v_mfma_f32_32x32x16_bf16 v[50:65], v[130:133], v[138:141], v[50:65]
	ds_read_b128 v[130:133], v148 offset:64
	ds_read_b128 v[134:137], v149 offset:36928
	ds_read_b128 v[138:141], v149 offset:41536
	s_waitcnt lgkmcnt(1)
	v_mfma_f32_32x32x16_bf16 v[2:17], v[130:133], v[134:137], v[2:17]
	s_waitcnt lgkmcnt(0)
	v_mfma_f32_32x32x16_bf16 v[18:33], v[130:133], v[138:141], v[18:33]
	ds_read_b128 v[130:133], v148 offset:4672
	s_waitcnt lgkmcnt(0)
	v_mfma_f32_32x32x16_bf16 v[34:49], v[130:133], v[134:137], v[34:49]
	v_mfma_f32_32x32x16_bf16 v[50:65], v[130:133], v[138:141], v[50:65]
	ds_read_b128 v[130:133], v148 offset:96
	ds_read_b128 v[134:137], v149 offset:36960
	ds_read_b128 v[138:141], v148 offset:4704
	ds_read_b128 v[208:211], v149 offset:41568
	s_waitcnt vmcnt(15)
	ds_write_b128 v174, v[70:73] offset:18432
	s_waitcnt vmcnt(14)
	ds_write_b128 v174, v[86:89] offset:23040
	s_waitcnt vmcnt(13)
	ds_write_b128 v174, v[90:93] offset:27648
	s_waitcnt vmcnt(12)
	ds_write_b128 v174, v[94:97] offset:32256
	s_waitcnt vmcnt(11)
	ds_write_b128 v174, v[102:105] offset:55296
	s_waitcnt vmcnt(10)
	ds_write_b128 v174, v[106:109] offset:59904
	s_waitcnt vmcnt(9)
	ds_write_b128 v174, v[110:113] offset:64512
	s_waitcnt vmcnt(8)
	ds_write_b128 v175, v[114:117] offset:32256
	global_load_dwordx4 v[70:73], v[160:161], off offset:1152
	global_load_dwordx4 v[86:89], v[162:163], off offset:1152
	global_load_dwordx4 v[90:93], v[164:165], off offset:1152
	global_load_dwordx4 v[94:97], v[172:173], off offset:1152
	global_load_dwordx4 v[102:105], v[158:159], off offset:1152
	global_load_dwordx4 v[106:109], v[166:167], off offset:1152
	global_load_dwordx4 v[110:113], v[168:169], off offset:1152
	global_load_dwordx4 v[114:117], v[170:171], off offset:1152
	s_waitcnt lgkmcnt(0)
	s_barrier
	v_mfma_f32_32x32x16_bf16 v[2:17], v[130:133], v[134:137], v[2:17]
	v_mfma_f32_32x32x16_bf16 v[18:33], v[130:133], v[208:211], v[18:33]
	v_mfma_f32_32x32x16_bf16 v[34:49], v[138:141], v[134:137], v[34:49]
	v_mfma_f32_32x32x16_bf16 v[50:65], v[138:141], v[208:211], v[50:65]
	ds_read_b128 v[130:133], v148 offset:18432
	ds_read_b128 v[134:137], v149 offset:55296
	ds_read_b128 v[138:141], v149 offset:59904
	s_waitcnt lgkmcnt(1)
	v_mfma_f32_32x32x16_bf16 v[2:17], v[130:133], v[134:137], v[2:17]
	s_waitcnt lgkmcnt(0)
	v_mfma_f32_32x32x16_bf16 v[18:33], v[130:133], v[138:141], v[18:33]
	ds_read_b128 v[130:133], v148 offset:23040
	s_waitcnt lgkmcnt(0)
	v_mfma_f32_32x32x16_bf16 v[34:49], v[130:133], v[134:137], v[34:49]
	v_mfma_f32_32x32x16_bf16 v[50:65], v[130:133], v[138:141], v[50:65]
	ds_read_b128 v[130:133], v148 offset:18464
	ds_read_b128 v[134:137], v149 offset:55328
	ds_read_b128 v[138:141], v149 offset:59936
	s_waitcnt lgkmcnt(1)
	v_mfma_f32_32x32x16_bf16 v[2:17], v[130:133], v[134:137], v[2:17]
	s_waitcnt lgkmcnt(0)
	v_mfma_f32_32x32x16_bf16 v[18:33], v[130:133], v[138:141], v[18:33]
	ds_read_b128 v[130:133], v148 offset:23072
	s_waitcnt lgkmcnt(0)
	v_mfma_f32_32x32x16_bf16 v[34:49], v[130:133], v[134:137], v[34:49]
	v_mfma_f32_32x32x16_bf16 v[50:65], v[130:133], v[138:141], v[50:65]
	ds_read_b128 v[130:133], v148 offset:18496
	ds_read_b128 v[134:137], v149 offset:55360
	ds_read_b128 v[138:141], v149 offset:59968
	s_waitcnt lgkmcnt(1)
	v_mfma_f32_32x32x16_bf16 v[2:17], v[130:133], v[134:137], v[2:17]
	s_waitcnt lgkmcnt(0)
	v_mfma_f32_32x32x16_bf16 v[18:33], v[130:133], v[138:141], v[18:33]
	ds_read_b128 v[130:133], v148 offset:23104
	s_waitcnt lgkmcnt(0)
	v_mfma_f32_32x32x16_bf16 v[34:49], v[130:133], v[134:137], v[34:49]
	v_mfma_f32_32x32x16_bf16 v[50:65], v[130:133], v[138:141], v[50:65]
	ds_read_b128 v[130:133], v148 offset:18528
	ds_read_b128 v[134:137], v149 offset:55392
	ds_read_b128 v[138:141], v148 offset:23136
	ds_read_b128 v[208:211], v149 offset:60000
	s_waitcnt vmcnt(15)
	ds_write_b128 v174, v[66:69]
	s_waitcnt vmcnt(14)
	ds_write_b128 v174, v[74:77] offset:4608
	s_waitcnt vmcnt(13)
	ds_write_b128 v174, v[78:81] offset:9216
	s_waitcnt vmcnt(12)
	ds_write_b128 v174, v[82:85] offset:13824
	s_waitcnt vmcnt(11)
	ds_write_b128 v174, v[98:101] offset:36864
	s_waitcnt vmcnt(10)
	ds_write_b128 v174, v[118:121] offset:41472
	s_waitcnt vmcnt(9)
	ds_write_b128 v174, v[122:125] offset:46080
	s_waitcnt vmcnt(8)
	ds_write_b128 v174, v[126:129] offset:50688
	global_load_dwordx4 v[66:69], v[160:161], off offset:1280
	global_load_dwordx4 v[74:77], v[162:163], off offset:1280
	global_load_dwordx4 v[78:81], v[164:165], off offset:1280
	global_load_dwordx4 v[82:85], v[172:173], off offset:1280
	global_load_dwordx4 v[98:101], v[158:159], off offset:1280
	global_load_dwordx4 v[118:121], v[166:167], off offset:1280
	global_load_dwordx4 v[122:125], v[168:169], off offset:1280
	global_load_dwordx4 v[126:129], v[170:171], off offset:1280
	s_waitcnt lgkmcnt(0)
	s_barrier
	v_mfma_f32_32x32x16_bf16 v[2:17], v[130:133], v[134:137], v[2:17]
	v_mfma_f32_32x32x16_bf16 v[18:33], v[130:133], v[208:211], v[18:33]
	v_mfma_f32_32x32x16_bf16 v[34:49], v[138:141], v[134:137], v[34:49]
	v_mfma_f32_32x32x16_bf16 v[50:65], v[138:141], v[208:211], v[50:65]
	ds_read_b128 v[130:133], v148
	ds_read_b128 v[134:137], v149 offset:36864
	ds_read_b128 v[138:141], v149 offset:41472
	s_waitcnt lgkmcnt(1)
	v_mfma_f32_32x32x16_bf16 v[2:17], v[130:133], v[134:137], v[2:17]
	s_waitcnt lgkmcnt(0)
	v_mfma_f32_32x32x16_bf16 v[18:33], v[130:133], v[138:141], v[18:33]
	ds_read_b128 v[130:133], v148 offset:4608
	s_waitcnt lgkmcnt(0)
	v_mfma_f32_32x32x16_bf16 v[34:49], v[130:133], v[134:137], v[34:49]
	v_mfma_f32_32x32x16_bf16 v[50:65], v[130:133], v[138:141], v[50:65]
	ds_read_b128 v[130:133], v148 offset:32
	ds_read_b128 v[134:137], v149 offset:36896
	ds_read_b128 v[138:141], v149 offset:41504
	s_waitcnt lgkmcnt(1)
	v_mfma_f32_32x32x16_bf16 v[2:17], v[130:133], v[134:137], v[2:17]
	s_waitcnt lgkmcnt(0)
	v_mfma_f32_32x32x16_bf16 v[18:33], v[130:133], v[138:141], v[18:33]
	ds_read_b128 v[130:133], v148 offset:4640
	s_waitcnt lgkmcnt(0)
	v_mfma_f32_32x32x16_bf16 v[34:49], v[130:133], v[134:137], v[34:49]
	v_mfma_f32_32x32x16_bf16 v[50:65], v[130:133], v[138:141], v[50:65]
	ds_read_b128 v[130:133], v148 offset:64
	ds_read_b128 v[134:137], v149 offset:36928
	ds_read_b128 v[138:141], v149 offset:41536
	s_waitcnt lgkmcnt(1)
	v_mfma_f32_32x32x16_bf16 v[2:17], v[130:133], v[134:137], v[2:17]
	s_waitcnt lgkmcnt(0)
	v_mfma_f32_32x32x16_bf16 v[18:33], v[130:133], v[138:141], v[18:33]
	ds_read_b128 v[130:133], v148 offset:4672
	s_waitcnt lgkmcnt(0)
	v_mfma_f32_32x32x16_bf16 v[34:49], v[130:133], v[134:137], v[34:49]
	v_mfma_f32_32x32x16_bf16 v[50:65], v[130:133], v[138:141], v[50:65]
	ds_read_b128 v[130:133], v148 offset:96
	ds_read_b128 v[134:137], v149 offset:36960
	ds_read_b128 v[138:141], v148 offset:4704
	ds_read_b128 v[208:211], v149 offset:41568
	s_waitcnt vmcnt(15)
	ds_write_b128 v174, v[70:73] offset:18432
	s_waitcnt vmcnt(14)
	ds_write_b128 v174, v[86:89] offset:23040
	s_waitcnt vmcnt(13)
	ds_write_b128 v174, v[90:93] offset:27648
	s_waitcnt vmcnt(12)
	ds_write_b128 v174, v[94:97] offset:32256
	s_waitcnt vmcnt(11)
	ds_write_b128 v174, v[102:105] offset:55296
	s_waitcnt vmcnt(10)
	ds_write_b128 v174, v[106:109] offset:59904
	s_waitcnt vmcnt(9)
	ds_write_b128 v174, v[110:113] offset:64512
	s_waitcnt vmcnt(8)
	ds_write_b128 v175, v[114:117] offset:32256
	global_load_dwordx4 v[70:73], v[160:161], off offset:1408
	global_load_dwordx4 v[86:89], v[162:163], off offset:1408
	global_load_dwordx4 v[90:93], v[164:165], off offset:1408
	global_load_dwordx4 v[94:97], v[172:173], off offset:1408
	global_load_dwordx4 v[102:105], v[158:159], off offset:1408
	global_load_dwordx4 v[106:109], v[166:167], off offset:1408
	global_load_dwordx4 v[110:113], v[168:169], off offset:1408
	global_load_dwordx4 v[114:117], v[170:171], off offset:1408
	s_waitcnt lgkmcnt(0)
	s_barrier
	v_mfma_f32_32x32x16_bf16 v[2:17], v[130:133], v[134:137], v[2:17]
	v_mfma_f32_32x32x16_bf16 v[18:33], v[130:133], v[208:211], v[18:33]
	v_mfma_f32_32x32x16_bf16 v[34:49], v[138:141], v[134:137], v[34:49]
	v_mfma_f32_32x32x16_bf16 v[50:65], v[138:141], v[208:211], v[50:65]
	ds_read_b128 v[130:133], v148 offset:18432
	ds_read_b128 v[134:137], v149 offset:55296
	ds_read_b128 v[138:141], v149 offset:59904
	s_waitcnt lgkmcnt(1)
	v_mfma_f32_32x32x16_bf16 v[2:17], v[130:133], v[134:137], v[2:17]
	s_waitcnt lgkmcnt(0)
	v_mfma_f32_32x32x16_bf16 v[18:33], v[130:133], v[138:141], v[18:33]
	ds_read_b128 v[130:133], v148 offset:23040
	s_waitcnt lgkmcnt(0)
	v_mfma_f32_32x32x16_bf16 v[34:49], v[130:133], v[134:137], v[34:49]
	v_mfma_f32_32x32x16_bf16 v[50:65], v[130:133], v[138:141], v[50:65]
	ds_read_b128 v[130:133], v148 offset:18464
	ds_read_b128 v[134:137], v149 offset:55328
	ds_read_b128 v[138:141], v149 offset:59936
	s_waitcnt lgkmcnt(1)
	v_mfma_f32_32x32x16_bf16 v[2:17], v[130:133], v[134:137], v[2:17]
	s_waitcnt lgkmcnt(0)
	v_mfma_f32_32x32x16_bf16 v[18:33], v[130:133], v[138:141], v[18:33]
	ds_read_b128 v[130:133], v148 offset:23072
	s_waitcnt lgkmcnt(0)
	v_mfma_f32_32x32x16_bf16 v[34:49], v[130:133], v[134:137], v[34:49]
	v_mfma_f32_32x32x16_bf16 v[50:65], v[130:133], v[138:141], v[50:65]
	ds_read_b128 v[130:133], v148 offset:18496
	ds_read_b128 v[134:137], v149 offset:55360
	ds_read_b128 v[138:141], v149 offset:59968
	s_waitcnt lgkmcnt(1)
	v_mfma_f32_32x32x16_bf16 v[2:17], v[130:133], v[134:137], v[2:17]
	s_waitcnt lgkmcnt(0)
	v_mfma_f32_32x32x16_bf16 v[18:33], v[130:133], v[138:141], v[18:33]
	ds_read_b128 v[130:133], v148 offset:23104
	s_waitcnt lgkmcnt(0)
	v_mfma_f32_32x32x16_bf16 v[34:49], v[130:133], v[134:137], v[34:49]
	v_mfma_f32_32x32x16_bf16 v[50:65], v[130:133], v[138:141], v[50:65]
	ds_read_b128 v[130:133], v148 offset:18528
	ds_read_b128 v[134:137], v149 offset:55392
	ds_read_b128 v[138:141], v148 offset:23136
	ds_read_b128 v[208:211], v149 offset:60000
	s_waitcnt vmcnt(15)
	ds_write_b128 v174, v[66:69]
	s_waitcnt vmcnt(14)
	ds_write_b128 v174, v[74:77] offset:4608
	s_waitcnt vmcnt(13)
	ds_write_b128 v174, v[78:81] offset:9216
	s_waitcnt vmcnt(12)
	ds_write_b128 v174, v[82:85] offset:13824
	s_waitcnt vmcnt(11)
	ds_write_b128 v174, v[98:101] offset:36864
	s_waitcnt vmcnt(10)
	ds_write_b128 v174, v[118:121] offset:41472
	s_waitcnt vmcnt(9)
	ds_write_b128 v174, v[122:125] offset:46080
	s_waitcnt vmcnt(8)
	ds_write_b128 v174, v[126:129] offset:50688
	global_load_dwordx4 v[66:69], v[160:161], off offset:1536
	global_load_dwordx4 v[74:77], v[162:163], off offset:1536
	global_load_dwordx4 v[78:81], v[164:165], off offset:1536
	global_load_dwordx4 v[82:85], v[172:173], off offset:1536
	global_load_dwordx4 v[98:101], v[158:159], off offset:1536
	global_load_dwordx4 v[118:121], v[166:167], off offset:1536
	global_load_dwordx4 v[122:125], v[168:169], off offset:1536
	global_load_dwordx4 v[126:129], v[170:171], off offset:1536
	s_waitcnt lgkmcnt(0)
	s_barrier
	v_mfma_f32_32x32x16_bf16 v[2:17], v[130:133], v[134:137], v[2:17]
	v_mfma_f32_32x32x16_bf16 v[18:33], v[130:133], v[208:211], v[18:33]
	v_mfma_f32_32x32x16_bf16 v[34:49], v[138:141], v[134:137], v[34:49]
	v_mfma_f32_32x32x16_bf16 v[50:65], v[138:141], v[208:211], v[50:65]
	ds_read_b128 v[130:133], v148
	ds_read_b128 v[134:137], v149 offset:36864
	ds_read_b128 v[138:141], v149 offset:41472
	s_waitcnt lgkmcnt(1)
	v_mfma_f32_32x32x16_bf16 v[2:17], v[130:133], v[134:137], v[2:17]
	s_waitcnt lgkmcnt(0)
	v_mfma_f32_32x32x16_bf16 v[18:33], v[130:133], v[138:141], v[18:33]
	ds_read_b128 v[130:133], v148 offset:4608
	s_waitcnt lgkmcnt(0)
	v_mfma_f32_32x32x16_bf16 v[34:49], v[130:133], v[134:137], v[34:49]
	v_mfma_f32_32x32x16_bf16 v[50:65], v[130:133], v[138:141], v[50:65]
	ds_read_b128 v[130:133], v148 offset:32
	ds_read_b128 v[134:137], v149 offset:36896
	ds_read_b128 v[138:141], v149 offset:41504
	s_waitcnt lgkmcnt(1)
	v_mfma_f32_32x32x16_bf16 v[2:17], v[130:133], v[134:137], v[2:17]
	s_waitcnt lgkmcnt(0)
	v_mfma_f32_32x32x16_bf16 v[18:33], v[130:133], v[138:141], v[18:33]
	ds_read_b128 v[130:133], v148 offset:4640
	s_waitcnt lgkmcnt(0)
	v_mfma_f32_32x32x16_bf16 v[34:49], v[130:133], v[134:137], v[34:49]
	v_mfma_f32_32x32x16_bf16 v[50:65], v[130:133], v[138:141], v[50:65]
	ds_read_b128 v[130:133], v148 offset:64
	ds_read_b128 v[134:137], v149 offset:36928
	ds_read_b128 v[138:141], v149 offset:41536
	s_waitcnt lgkmcnt(1)
	v_mfma_f32_32x32x16_bf16 v[2:17], v[130:133], v[134:137], v[2:17]
	s_waitcnt lgkmcnt(0)
	v_mfma_f32_32x32x16_bf16 v[18:33], v[130:133], v[138:141], v[18:33]
	ds_read_b128 v[130:133], v148 offset:4672
	s_waitcnt lgkmcnt(0)
	v_mfma_f32_32x32x16_bf16 v[34:49], v[130:133], v[134:137], v[34:49]
	v_mfma_f32_32x32x16_bf16 v[50:65], v[130:133], v[138:141], v[50:65]
	ds_read_b128 v[130:133], v148 offset:96
	ds_read_b128 v[134:137], v149 offset:36960
	ds_read_b128 v[138:141], v148 offset:4704
	ds_read_b128 v[208:211], v149 offset:41568
	s_waitcnt vmcnt(15)
	ds_write_b128 v174, v[70:73] offset:18432
	s_waitcnt vmcnt(14)
	ds_write_b128 v174, v[86:89] offset:23040
	s_waitcnt vmcnt(13)
	ds_write_b128 v174, v[90:93] offset:27648
	s_waitcnt vmcnt(12)
	ds_write_b128 v174, v[94:97] offset:32256
	s_waitcnt vmcnt(11)
	ds_write_b128 v174, v[102:105] offset:55296
	s_waitcnt vmcnt(10)
	ds_write_b128 v174, v[106:109] offset:59904
	s_waitcnt vmcnt(9)
	ds_write_b128 v174, v[110:113] offset:64512
	s_waitcnt vmcnt(8)
	ds_write_b128 v175, v[114:117] offset:32256
	global_load_dwordx4 v[70:73], v[160:161], off offset:1664
	global_load_dwordx4 v[86:89], v[162:163], off offset:1664
	global_load_dwordx4 v[90:93], v[164:165], off offset:1664
	global_load_dwordx4 v[94:97], v[172:173], off offset:1664
	global_load_dwordx4 v[102:105], v[158:159], off offset:1664
	global_load_dwordx4 v[106:109], v[166:167], off offset:1664
	global_load_dwordx4 v[110:113], v[168:169], off offset:1664
	global_load_dwordx4 v[114:117], v[170:171], off offset:1664
	s_waitcnt lgkmcnt(0)
	s_barrier
	v_mfma_f32_32x32x16_bf16 v[2:17], v[130:133], v[134:137], v[2:17]
	v_mfma_f32_32x32x16_bf16 v[18:33], v[130:133], v[208:211], v[18:33]
	v_mfma_f32_32x32x16_bf16 v[34:49], v[138:141], v[134:137], v[34:49]
	v_mfma_f32_32x32x16_bf16 v[50:65], v[138:141], v[208:211], v[50:65]
	ds_read_b128 v[130:133], v148 offset:18432
	ds_read_b128 v[134:137], v149 offset:55296
	ds_read_b128 v[138:141], v149 offset:59904
	s_waitcnt lgkmcnt(1)
	v_mfma_f32_32x32x16_bf16 v[2:17], v[130:133], v[134:137], v[2:17]
	s_waitcnt lgkmcnt(0)
	v_mfma_f32_32x32x16_bf16 v[18:33], v[130:133], v[138:141], v[18:33]
	ds_read_b128 v[130:133], v148 offset:23040
	s_waitcnt lgkmcnt(0)
	v_mfma_f32_32x32x16_bf16 v[34:49], v[130:133], v[134:137], v[34:49]
	v_mfma_f32_32x32x16_bf16 v[50:65], v[130:133], v[138:141], v[50:65]
	ds_read_b128 v[130:133], v148 offset:18464
	ds_read_b128 v[134:137], v149 offset:55328
	ds_read_b128 v[138:141], v149 offset:59936
	s_waitcnt lgkmcnt(1)
	v_mfma_f32_32x32x16_bf16 v[2:17], v[130:133], v[134:137], v[2:17]
	s_waitcnt lgkmcnt(0)
	v_mfma_f32_32x32x16_bf16 v[18:33], v[130:133], v[138:141], v[18:33]
	ds_read_b128 v[130:133], v148 offset:23072
	s_waitcnt lgkmcnt(0)
	v_mfma_f32_32x32x16_bf16 v[34:49], v[130:133], v[134:137], v[34:49]
	v_mfma_f32_32x32x16_bf16 v[50:65], v[130:133], v[138:141], v[50:65]
	ds_read_b128 v[130:133], v148 offset:18496
	ds_read_b128 v[134:137], v149 offset:55360
	ds_read_b128 v[138:141], v149 offset:59968
	s_waitcnt lgkmcnt(1)
	v_mfma_f32_32x32x16_bf16 v[2:17], v[130:133], v[134:137], v[2:17]
	s_waitcnt lgkmcnt(0)
	v_mfma_f32_32x32x16_bf16 v[18:33], v[130:133], v[138:141], v[18:33]
	ds_read_b128 v[130:133], v148 offset:23104
	s_waitcnt lgkmcnt(0)
	v_mfma_f32_32x32x16_bf16 v[34:49], v[130:133], v[134:137], v[34:49]
	v_mfma_f32_32x32x16_bf16 v[50:65], v[130:133], v[138:141], v[50:65]
	ds_read_b128 v[130:133], v148 offset:18528
	ds_read_b128 v[134:137], v149 offset:55392
	ds_read_b128 v[138:141], v148 offset:23136
	ds_read_b128 v[208:211], v149 offset:60000
	s_waitcnt vmcnt(15)
	ds_write_b128 v174, v[66:69]
	s_waitcnt vmcnt(14)
	ds_write_b128 v174, v[74:77] offset:4608
	s_waitcnt vmcnt(13)
	ds_write_b128 v174, v[78:81] offset:9216
	s_waitcnt vmcnt(12)
	ds_write_b128 v174, v[82:85] offset:13824
	s_waitcnt vmcnt(11)
	ds_write_b128 v174, v[98:101] offset:36864
	s_waitcnt vmcnt(10)
	ds_write_b128 v174, v[118:121] offset:41472
	s_waitcnt vmcnt(9)
	ds_write_b128 v174, v[122:125] offset:46080
	s_waitcnt vmcnt(8)
	ds_write_b128 v174, v[126:129] offset:50688
	global_load_dwordx4 v[66:69], v[160:161], off offset:1792
	global_load_dwordx4 v[78:81], v[162:163], off offset:1792
	global_load_dwordx4 v[82:85], v[164:165], off offset:1792
	global_load_dwordx4 v[74:77], v[172:173], off offset:1792
	global_load_dwordx4 v[98:101], v[158:159], off offset:1792
	global_load_dwordx4 v[118:121], v[166:167], off offset:1792
	global_load_dwordx4 v[122:125], v[168:169], off offset:1792
	global_load_dwordx4 v[126:129], v[170:171], off offset:1792
	s_waitcnt lgkmcnt(0)
	s_barrier
	v_mfma_f32_32x32x16_bf16 v[2:17], v[130:133], v[134:137], v[2:17]
	v_mfma_f32_32x32x16_bf16 v[18:33], v[130:133], v[208:211], v[18:33]
	v_mfma_f32_32x32x16_bf16 v[34:49], v[138:141], v[134:137], v[34:49]
	v_mfma_f32_32x32x16_bf16 v[50:65], v[138:141], v[208:211], v[50:65]
	ds_read_b128 v[130:133], v148
	ds_read_b128 v[134:137], v149 offset:36864
	ds_read_b128 v[138:141], v149 offset:41472
	s_waitcnt lgkmcnt(1)
	v_mfma_f32_32x32x16_bf16 v[2:17], v[130:133], v[134:137], v[2:17]
	s_waitcnt lgkmcnt(0)
	v_mfma_f32_32x32x16_bf16 v[18:33], v[130:133], v[138:141], v[18:33]
	ds_read_b128 v[130:133], v148 offset:4608
	s_waitcnt lgkmcnt(0)
	v_mfma_f32_32x32x16_bf16 v[34:49], v[130:133], v[134:137], v[34:49]
	v_mfma_f32_32x32x16_bf16 v[50:65], v[130:133], v[138:141], v[50:65]
	ds_read_b128 v[130:133], v148 offset:32
	ds_read_b128 v[134:137], v149 offset:36896
	ds_read_b128 v[138:141], v149 offset:41504
	s_waitcnt lgkmcnt(1)
	v_mfma_f32_32x32x16_bf16 v[2:17], v[130:133], v[134:137], v[2:17]
	s_waitcnt lgkmcnt(0)
	v_mfma_f32_32x32x16_bf16 v[18:33], v[130:133], v[138:141], v[18:33]
	ds_read_b128 v[130:133], v148 offset:4640
	s_waitcnt lgkmcnt(0)
	v_mfma_f32_32x32x16_bf16 v[34:49], v[130:133], v[134:137], v[34:49]
	v_mfma_f32_32x32x16_bf16 v[50:65], v[130:133], v[138:141], v[50:65]
	ds_read_b128 v[130:133], v148 offset:64
	ds_read_b128 v[134:137], v149 offset:36928
	ds_read_b128 v[138:141], v149 offset:41536
	s_waitcnt lgkmcnt(1)
	v_mfma_f32_32x32x16_bf16 v[2:17], v[130:133], v[134:137], v[2:17]
	s_waitcnt lgkmcnt(0)
	v_mfma_f32_32x32x16_bf16 v[18:33], v[130:133], v[138:141], v[18:33]
	ds_read_b128 v[130:133], v148 offset:4672
	s_waitcnt lgkmcnt(0)
	v_mfma_f32_32x32x16_bf16 v[34:49], v[130:133], v[134:137], v[34:49]
	v_mfma_f32_32x32x16_bf16 v[50:65], v[130:133], v[138:141], v[50:65]
	ds_read_b128 v[130:133], v148 offset:96
	ds_read_b128 v[134:137], v149 offset:36960
	ds_read_b128 v[138:141], v148 offset:4704
	ds_read_b128 v[208:211], v149 offset:41568
	s_waitcnt vmcnt(15)
	ds_write_b128 v174, v[70:73] offset:18432
	s_waitcnt vmcnt(14)
	ds_write_b128 v174, v[86:89] offset:23040
	s_waitcnt vmcnt(13)
	ds_write_b128 v174, v[90:93] offset:27648
	s_waitcnt vmcnt(12)
	ds_write_b128 v174, v[94:97] offset:32256
	s_waitcnt vmcnt(11)
	ds_write_b128 v174, v[102:105] offset:55296
	s_waitcnt vmcnt(10)
	ds_write_b128 v174, v[106:109] offset:59904
	s_waitcnt vmcnt(9)
	ds_write_b128 v174, v[110:113] offset:64512
	s_waitcnt vmcnt(8)
	ds_write_b128 v175, v[114:117] offset:32256
	global_load_dwordx4 v[70:73], v[160:161], off offset:1920
	global_load_dwordx4 v[90:93], v[162:163], off offset:1920
	global_load_dwordx4 v[94:97], v[164:165], off offset:1920
	global_load_dwordx4 v[86:89], v[172:173], off offset:1920
	global_load_dwordx4 v[102:105], v[158:159], off offset:1920
	global_load_dwordx4 v[106:109], v[166:167], off offset:1920
	global_load_dwordx4 v[110:113], v[168:169], off offset:1920
	global_load_dwordx4 v[114:117], v[170:171], off offset:1920
	s_waitcnt lgkmcnt(0)
	s_barrier
	v_mfma_f32_32x32x16_bf16 v[2:17], v[130:133], v[134:137], v[2:17]
	v_mfma_f32_32x32x16_bf16 v[18:33], v[130:133], v[208:211], v[18:33]
	v_mfma_f32_32x32x16_bf16 v[34:49], v[138:141], v[134:137], v[34:49]
	v_mfma_f32_32x32x16_bf16 v[50:65], v[138:141], v[208:211], v[50:65]
	ds_read_b128 v[130:133], v148 offset:18432
	ds_read_b128 v[134:137], v149 offset:55296
	ds_read_b128 v[138:141], v149 offset:59904
	s_waitcnt lgkmcnt(1)
	v_mfma_f32_32x32x16_bf16 v[2:17], v[130:133], v[134:137], v[2:17]
	s_waitcnt lgkmcnt(0)
	v_mfma_f32_32x32x16_bf16 v[18:33], v[130:133], v[138:141], v[18:33]
	ds_read_b128 v[130:133], v148 offset:23040
	s_waitcnt lgkmcnt(0)
	v_mfma_f32_32x32x16_bf16 v[34:49], v[130:133], v[134:137], v[34:49]
	v_mfma_f32_32x32x16_bf16 v[50:65], v[130:133], v[138:141], v[50:65]
	ds_read_b128 v[130:133], v148 offset:18464
	ds_read_b128 v[134:137], v149 offset:55328
	ds_read_b128 v[138:141], v149 offset:59936
	s_waitcnt lgkmcnt(1)
	v_mfma_f32_32x32x16_bf16 v[2:17], v[130:133], v[134:137], v[2:17]
	s_waitcnt lgkmcnt(0)
	v_mfma_f32_32x32x16_bf16 v[18:33], v[130:133], v[138:141], v[18:33]
	ds_read_b128 v[130:133], v148 offset:23072
	s_waitcnt lgkmcnt(0)
	v_mfma_f32_32x32x16_bf16 v[34:49], v[130:133], v[134:137], v[34:49]
	v_mfma_f32_32x32x16_bf16 v[50:65], v[130:133], v[138:141], v[50:65]
	ds_read_b128 v[130:133], v148 offset:18496
	ds_read_b128 v[134:137], v149 offset:55360
	ds_read_b128 v[138:141], v149 offset:59968
	s_waitcnt lgkmcnt(1)
	v_mfma_f32_32x32x16_bf16 v[2:17], v[130:133], v[134:137], v[2:17]
	s_waitcnt lgkmcnt(0)
	v_mfma_f32_32x32x16_bf16 v[18:33], v[130:133], v[138:141], v[18:33]
	ds_read_b128 v[130:133], v148 offset:23104
	s_waitcnt lgkmcnt(0)
	v_mfma_f32_32x32x16_bf16 v[34:49], v[130:133], v[134:137], v[34:49]
	v_mfma_f32_32x32x16_bf16 v[50:65], v[130:133], v[138:141], v[50:65]
	ds_read_b128 v[130:133], v148 offset:18528
	ds_read_b128 v[134:137], v149 offset:55392
	ds_read_b128 v[138:141], v149 offset:60000
	s_waitcnt lgkmcnt(1)
	v_mfma_f32_32x32x16_bf16 v[2:17], v[130:133], v[134:137], v[2:17]
	s_waitcnt lgkmcnt(0)
	v_mfma_f32_32x32x16_bf16 v[18:33], v[130:133], v[138:141], v[18:33]
	ds_read_b128 v[130:133], v148 offset:23136
	s_waitcnt vmcnt(15)
	ds_write_b128 v174, v[66:69]
	s_waitcnt vmcnt(14)
	ds_write_b128 v174, v[78:81] offset:4608
	s_waitcnt vmcnt(13)
	ds_write_b128 v174, v[82:85] offset:9216
	s_waitcnt vmcnt(12)
	ds_write_b128 v174, v[74:77] offset:13824
	s_waitcnt vmcnt(11)
	ds_write_b128 v174, v[98:101] offset:36864
	s_waitcnt vmcnt(10)
	ds_write_b128 v174, v[118:121] offset:41472
	s_waitcnt vmcnt(9)
	ds_write_b128 v174, v[122:125] offset:46080
	s_waitcnt vmcnt(8)
	ds_write_b128 v174, v[126:129] offset:50688
	s_waitcnt lgkmcnt(0)
	s_barrier
	v_mfma_f32_32x32x16_bf16 v[34:49], v[130:133], v[134:137], v[34:49]
	v_mfma_f32_32x32x16_bf16 v[50:65], v[130:133], v[138:141], v[50:65]
	ds_read_b128 v[66:69], v148
	ds_read_b128 v[74:77], v149 offset:36864
	ds_read_b128 v[78:81], v149 offset:41472
	s_waitcnt lgkmcnt(1)
	v_mfma_f32_32x32x16_bf16 v[2:17], v[66:69], v[74:77], v[2:17]
	s_waitcnt lgkmcnt(0)
	v_mfma_f32_32x32x16_bf16 v[18:33], v[66:69], v[78:81], v[18:33]
	ds_read_b128 v[66:69], v148 offset:4608
	s_waitcnt lgkmcnt(0)
	v_mfma_f32_32x32x16_bf16 v[34:49], v[66:69], v[74:77], v[34:49]
	v_mfma_f32_32x32x16_bf16 v[50:65], v[66:69], v[78:81], v[50:65]
	ds_read_b128 v[66:69], v148 offset:32
	ds_read_b128 v[74:77], v149 offset:36896
	ds_read_b128 v[78:81], v149 offset:41504
	s_waitcnt lgkmcnt(1)
	v_mfma_f32_32x32x16_bf16 v[2:17], v[66:69], v[74:77], v[2:17]
	s_waitcnt lgkmcnt(0)
	v_mfma_f32_32x32x16_bf16 v[18:33], v[66:69], v[78:81], v[18:33]
	ds_read_b128 v[66:69], v148 offset:4640
	s_waitcnt lgkmcnt(0)
	v_mfma_f32_32x32x16_bf16 v[34:49], v[66:69], v[74:77], v[34:49]
	v_mfma_f32_32x32x16_bf16 v[50:65], v[66:69], v[78:81], v[50:65]
	ds_read_b128 v[66:69], v148 offset:64
	ds_read_b128 v[74:77], v149 offset:36928
	ds_read_b128 v[78:81], v149 offset:41536
	s_waitcnt lgkmcnt(1)
	v_mfma_f32_32x32x16_bf16 v[2:17], v[66:69], v[74:77], v[2:17]
	s_waitcnt lgkmcnt(0)
	v_mfma_f32_32x32x16_bf16 v[18:33], v[66:69], v[78:81], v[18:33]
	ds_read_b128 v[66:69], v148 offset:4672
	s_waitcnt lgkmcnt(0)
	v_mfma_f32_32x32x16_bf16 v[34:49], v[66:69], v[74:77], v[34:49]
	v_mfma_f32_32x32x16_bf16 v[50:65], v[66:69], v[78:81], v[50:65]
	ds_read_b128 v[66:69], v148 offset:96
	ds_read_b128 v[74:77], v149 offset:36960
	ds_read_b128 v[78:81], v149 offset:41568
	s_waitcnt lgkmcnt(1)
	v_mfma_f32_32x32x16_bf16 v[2:17], v[66:69], v[74:77], v[2:17]
	s_waitcnt lgkmcnt(0)
	v_mfma_f32_32x32x16_bf16 v[18:33], v[66:69], v[78:81], v[18:33]
	ds_read_b128 v[66:69], v148 offset:4704
	s_waitcnt vmcnt(7)
	ds_write_b128 v174, v[70:73] offset:18432
	s_waitcnt vmcnt(6)
	ds_write_b128 v174, v[90:93] offset:23040
	s_waitcnt vmcnt(5)
	ds_write_b128 v174, v[94:97] offset:27648
	s_waitcnt vmcnt(4)
	ds_write_b128 v174, v[86:89] offset:32256
	s_waitcnt vmcnt(3)
	ds_write_b128 v174, v[102:105] offset:55296
	s_waitcnt vmcnt(2)
	ds_write_b128 v174, v[106:109] offset:59904
	s_waitcnt vmcnt(1)
	ds_write_b128 v174, v[110:113] offset:64512
	s_waitcnt vmcnt(0)
	ds_write_b128 v175, v[114:117] offset:32256
	s_waitcnt lgkmcnt(0)
	s_barrier
	v_mfma_f32_32x32x16_bf16 v[34:49], v[66:69], v[74:77], v[34:49]
	v_mfma_f32_32x32x16_bf16 v[50:65], v[66:69], v[78:81], v[50:65]
	ds_read_b128 v[66:69], v148 offset:18432
	ds_read_b128 v[70:73], v149 offset:55296
	ds_read_b128 v[74:77], v149 offset:59904
	s_lshl_b32 s77, s76, 7
	s_cmp_eq_u32 s76, 5
	s_waitcnt lgkmcnt(1)
	v_mfma_f32_32x32x16_bf16 v[2:17], v[66:69], v[70:73], v[2:17]
	s_waitcnt lgkmcnt(0)
	v_mfma_f32_32x32x16_bf16 v[18:33], v[66:69], v[74:77], v[18:33]
	ds_read_b128 v[66:69], v148 offset:23040
	s_waitcnt lgkmcnt(0)
	v_mfma_f32_32x32x16_bf16 v[34:49], v[66:69], v[70:73], v[34:49]
	v_mfma_f32_32x32x16_bf16 v[50:65], v[66:69], v[74:77], v[50:65]
	ds_read_b128 v[66:69], v148 offset:18464
	ds_read_b128 v[70:73], v149 offset:55328
	ds_read_b128 v[74:77], v149 offset:59936
	s_waitcnt lgkmcnt(1)
	v_mfma_f32_32x32x16_bf16 v[2:17], v[66:69], v[70:73], v[2:17]
	s_waitcnt lgkmcnt(0)
	v_mfma_f32_32x32x16_bf16 v[18:33], v[66:69], v[74:77], v[18:33]
	ds_read_b128 v[66:69], v148 offset:23072
	s_waitcnt lgkmcnt(0)
	v_mfma_f32_32x32x16_bf16 v[34:49], v[66:69], v[70:73], v[34:49]
	v_mfma_f32_32x32x16_bf16 v[50:65], v[66:69], v[74:77], v[50:65]
	ds_read_b128 v[66:69], v148 offset:18496
	ds_read_b128 v[70:73], v149 offset:55360
	ds_read_b128 v[74:77], v149 offset:59968
	s_waitcnt lgkmcnt(1)
	v_mfma_f32_32x32x16_bf16 v[2:17], v[66:69], v[70:73], v[2:17]
	s_waitcnt lgkmcnt(0)
	v_mfma_f32_32x32x16_bf16 v[18:33], v[66:69], v[74:77], v[18:33]
	ds_read_b128 v[66:69], v148 offset:23104
	s_waitcnt lgkmcnt(0)
	v_mfma_f32_32x32x16_bf16 v[34:49], v[66:69], v[70:73], v[34:49]
	v_mfma_f32_32x32x16_bf16 v[50:65], v[66:69], v[74:77], v[50:65]
	ds_read_b128 v[66:69], v148 offset:18528
	ds_read_b128 v[70:73], v149 offset:55392
	ds_read_b128 v[74:77], v149 offset:60000
	s_waitcnt lgkmcnt(1)
	v_mfma_f32_32x32x16_bf16 v[2:17], v[66:69], v[70:73], v[2:17]
	s_waitcnt lgkmcnt(0)
	v_mfma_f32_32x32x16_bf16 v[18:33], v[66:69], v[74:77], v[18:33]
	ds_read_b128 v[66:69], v148 offset:23136
	s_waitcnt lgkmcnt(0)
	s_barrier
	v_mfma_f32_32x32x16_bf16 v[34:49], v[66:69], v[70:73], v[34:49]
	s_nop 7
	ds_write2_b32 v181, v2, v18 offset1:32
	v_mfma_f32_32x32x16_bf16 v[50:65], v[66:69], v[74:77], v[50:65]
	s_nop 11
	ds_write2_b32 v189, v34, v50 offset0:32 offset1:64
	ds_write2_b32 v181, v3, v19 offset0:129 offset1:161
	ds_write2_b32 v189, v35, v51 offset0:161 offset1:193
	ds_write2_b32 v190, v4, v20 offset0:2 offset1:34
	ds_write2_b32 v191, v36, v52 offset0:34 offset1:66
	ds_write2_b32 v190, v5, v21 offset0:131 offset1:163
	ds_write2_b32 v191, v37, v53 offset0:163 offset1:195
	ds_write2_b32 v192, v6, v22 offset0:8 offset1:40
	ds_write2_b32 v193, v38, v54 offset0:40 offset1:72
	ds_write2_b32 v192, v7, v23 offset0:137 offset1:169
	ds_write2_b32 v193, v39, v55 offset0:169 offset1:201
	ds_write2_b32 v194, v8, v24 offset0:10 offset1:42
	ds_write2_b32 v195, v40, v56 offset0:42 offset1:74
	ds_write2_b32 v194, v9, v25 offset0:139 offset1:171
	ds_write2_b32 v195, v41, v57 offset0:171 offset1:203
	ds_write2_b32 v196, v10, v26 offset0:16 offset1:48
	ds_write2_b32 v197, v42, v58 offset0:48 offset1:80
	ds_write2_b32 v196, v11, v27 offset0:145 offset1:177
	ds_write2_b32 v197, v43, v59 offset0:177 offset1:209
	ds_write2_b32 v198, v12, v28 offset0:18 offset1:50
	ds_write2_b32 v199, v44, v60 offset0:50 offset1:82
	ds_write2_b32 v198, v13, v29 offset0:147 offset1:179
	ds_write2_b32 v199, v45, v61 offset0:179 offset1:211
	ds_write2_b32 v200, v14, v30 offset0:24 offset1:56
	ds_write2_b32 v201, v46, v62 offset0:56 offset1:88
	ds_write2_b32 v200, v15, v31 offset0:153 offset1:185
	ds_write2_b32 v201, v47, v63 offset0:185 offset1:217
	ds_write2_b32 v202, v16, v32 offset0:26 offset1:58
	ds_write2_b32 v203, v48, v64 offset0:58 offset1:90
	ds_write2_b32 v202, v17, v33 offset0:155 offset1:187
	ds_write2_b32 v203, v49, v65 offset0:187 offset1:219
	s_waitcnt lgkmcnt(0)
	s_barrier
	s_cbranch_scc1 .LBB0_79
	s_add_i32 s4, s77, 0xfffffa80
	s_cmpk_lt_u32 s4, 0x200
	s_cbranch_scc1 .LBB0_80
	s_add_i32 s4, s77, 0xfffff880
	s_cmpk_lt_u32 s4, 0x200
	s_cbranch_scc1 .LBB0_81
	s_add_i32 s4, s77, 0xfffff680
	s_mov_b64 s[24:25], -1
	s_cmpk_lt_u32 s4, 0x200
	s_mov_b64 s[22:23], 0
	s_cbranch_scc1 .LBB0_82
	s_cmp_lt_u32 s76, 23
	s_cbranch_scc1 .LBB0_83
	v_readlane_b32 s12, v252, 28
	s_movk_i32 s50, 0xb80
	s_mov_b64 s[90:91], 0x200
	s_mov_b64 s[42:43], -1
	v_readlane_b32 s13, v252, 29
	s_branch .LBB0_84

.LBB0_300:
	s_and_b32 s12, s17, 0x1ffffc0
	s_lshl_b32 s14, s17, 3
	s_and_b32 s14, s14, 56
	s_or_b32 s12, s12, s3
	s_or_b32 s12, s12, s14
	s_lshl_b32 s12, s12, 7
	s_lshl_b64 s[26:27], s[12:13], 11
	v_lshl_add_u64 v[74:75], v[70:71], 0, s[26:27]
	v_add_co_u32_e32 v78, vcc, s20, v74
	s_lshl_b32 s14, s17, 4
	s_nop 0
	v_addc_co_u32_e32 v79, vcc, 0, v75, vcc
	v_add_co_u32_e32 v80, vcc, s21, v74
	s_and_b32 s14, s14, 0x380
	s_nop 0
	v_addc_co_u32_e32 v81, vcc, 0, v75, vcc
	v_add_co_u32_e32 v82, vcc, s22, v74
	s_lshl_b32 s12, s14, 11
	s_nop 0
	v_addc_co_u32_e32 v83, vcc, 0, v75, vcc
	v_lshl_add_u64 v[76:77], v[72:73], 0, s[12:13]
	global_load_dwordx4 v[2:5], v[74:75], off
	global_load_dwordx4 v[6:9], v[78:79], off
	global_load_dwordx4 v[10:13], v[80:81], off
	global_load_dwordx4 v[14:17], v[82:83], off
	global_load_dwordx4 v[18:21], v[76:77], off
	v_add_co_u32_e32 v84, vcc, s20, v76
	s_nop 1
	v_addc_co_u32_e32 v85, vcc, 0, v77, vcc
	v_add_co_u32_e32 v86, vcc, s21, v76
	global_load_dwordx4 v[22:25], v[84:85], off
	s_nop 0
	v_addc_co_u32_e32 v87, vcc, 0, v77, vcc
	global_load_dwordx4 v[26:29], v[86:87], off
	v_add_co_u32_e32 v88, vcc, s22, v76
	s_nop 1
	v_addc_co_u32_e32 v89, vcc, 0, v77, vcc
	global_load_dwordx4 v[30:33], v[88:89], off
	global_load_dwordx4 v[112:115], v[74:75], off offset:128
	global_load_dwordx4 v[116:119], v[76:77], off offset:128
	global_load_dwordx4 v[120:123], v[78:79], off offset:128
	global_load_dwordx4 v[124:127], v[80:81], off offset:128
	global_load_dwordx4 v[128:131], v[82:83], off offset:128
	global_load_dwordx4 v[132:135], v[84:85], off offset:128
	global_load_dwordx4 v[136:139], v[86:87], off offset:128
	global_load_dwordx4 v[140:143], v[88:89], off offset:128
	s_waitcnt vmcnt(15)
	ds_write_b128 v90, v[2:5]
	s_waitcnt vmcnt(11)
	ds_write_b128 v90, v[18:21] offset:36864
	ds_write_b128 v90, v[6:9] offset:4608
	ds_write_b128 v90, v[10:13] offset:9216
	ds_write_b128 v90, v[14:17] offset:13824
	s_waitcnt vmcnt(10)
	ds_write_b128 v90, v[22:25] offset:41472
	s_waitcnt vmcnt(9)
	ds_write_b128 v90, v[26:29] offset:46080
	s_waitcnt vmcnt(8)
	ds_write_b128 v90, v[30:33] offset:50688
	s_waitcnt lgkmcnt(0)
	s_barrier
	global_load_dwordx4 v[144:147], v[78:79], off offset:256
	global_load_dwordx4 v[148:151], v[80:81], off offset:256
	global_load_dwordx4 v[152:155], v[74:75], off offset:256
	global_load_dwordx4 v[156:159], v[76:77], off offset:256
	global_load_dwordx4 v[160:163], v[82:83], off offset:256
	global_load_dwordx4 v[164:167], v[84:85], off offset:256
	global_load_dwordx4 v[168:171], v[86:87], off offset:256
	global_load_dwordx4 v[172:175], v[88:89], off offset:256
	ds_read_b128 v[18:21], v66
	ds_read_b128 v[34:37], v67 offset:36864
	ds_read_b128 v[176:179], v66 offset:32
	ds_read_b128 v[180:183], v67 offset:36896
	ds_read_b128 v[50:53], v67 offset:41472
	ds_read_b128 v[184:187], v67 offset:41504
	ds_read_b128 v[54:57], v66 offset:4608
	ds_read_b128 v[188:191], v66 offset:4640
	s_waitcnt lgkmcnt(6)
	v_mfma_f32_32x32x16_bf16 v[2:17], v[18:21], v[34:37], 0
	s_waitcnt lgkmcnt(3)
	v_mfma_f32_32x32x16_bf16 v[18:33], v[18:21], v[50:53], 0
	s_waitcnt lgkmcnt(1)
	v_mfma_f32_32x32x16_bf16 v[34:49], v[54:57], v[34:37], 0
	v_mfma_f32_32x32x16_bf16 v[50:65], v[54:57], v[50:53], 0
	v_mfma_f32_32x32x16_bf16 v[2:17], v[176:179], v[180:183], v[2:17]
	v_mfma_f32_32x32x16_bf16 v[18:33], v[176:179], v[184:187], v[18:33]
	s_waitcnt lgkmcnt(0)
	v_mfma_f32_32x32x16_bf16 v[34:49], v[188:191], v[180:183], v[34:49]
	v_mfma_f32_32x32x16_bf16 v[50:65], v[188:191], v[184:187], v[50:65]
	ds_read_b128 v[176:179], v66 offset:64
	ds_read_b128 v[180:183], v67 offset:36928
	ds_read_b128 v[184:187], v66 offset:96
	ds_read_b128 v[188:191], v67 offset:36960
	ds_read_b128 v[192:195], v67 offset:41536
	ds_read_b128 v[196:199], v67 offset:41568
	s_waitcnt lgkmcnt(4)
	v_mfma_f32_32x32x16_bf16 v[2:17], v[176:179], v[180:183], v[2:17]
	s_waitcnt lgkmcnt(1)
	v_mfma_f32_32x32x16_bf16 v[18:33], v[176:179], v[192:195], v[18:33]
	ds_read_b128 v[176:179], v66 offset:4672
	ds_read_b128 v[200:203], v66 offset:4704
	s_waitcnt vmcnt(15)
	ds_write_b128 v90, v[112:115] offset:18432
	s_waitcnt vmcnt(13)
	ds_write_b128 v90, v[120:123] offset:23040
	s_waitcnt vmcnt(12)
	ds_write_b128 v90, v[124:127] offset:27648
	s_waitcnt vmcnt(11)
	ds_write_b128 v90, v[128:131] offset:32256
	ds_write_b128 v90, v[116:119] offset:55296
	s_waitcnt vmcnt(10)
	ds_write_b128 v90, v[132:135] offset:59904
	s_waitcnt vmcnt(9)
	ds_write_b128 v90, v[136:139] offset:64512
	s_waitcnt vmcnt(8)
	ds_write_b128 v91, v[140:143] offset:32256
	global_load_dwordx4 v[112:115], v[78:79], off offset:384
	global_load_dwordx4 v[116:119], v[80:81], off offset:384
	global_load_dwordx4 v[120:123], v[74:75], off offset:384
	global_load_dwordx4 v[124:127], v[76:77], off offset:384
	global_load_dwordx4 v[128:131], v[82:83], off offset:384
	global_load_dwordx4 v[132:135], v[84:85], off offset:384
	global_load_dwordx4 v[136:139], v[86:87], off offset:384
	global_load_dwordx4 v[140:143], v[88:89], off offset:384
	s_waitcnt lgkmcnt(0)
	s_barrier
	v_mfma_f32_32x32x16_bf16 v[34:49], v[176:179], v[180:183], v[34:49]
	v_mfma_f32_32x32x16_bf16 v[50:65], v[176:179], v[192:195], v[50:65]
	v_mfma_f32_32x32x16_bf16 v[2:17], v[184:187], v[188:191], v[2:17]
	v_mfma_f32_32x32x16_bf16 v[18:33], v[184:187], v[196:199], v[18:33]
	v_mfma_f32_32x32x16_bf16 v[34:49], v[200:203], v[188:191], v[34:49]
	v_mfma_f32_32x32x16_bf16 v[50:65], v[200:203], v[196:199], v[50:65]
	ds_read_b128 v[176:179], v66 offset:18432
	ds_read_b128 v[180:183], v67 offset:55296
	ds_read_b128 v[184:187], v66 offset:18464
	ds_read_b128 v[188:191], v67 offset:55328
	ds_read_b128 v[192:195], v67 offset:59904
	ds_read_b128 v[196:199], v67 offset:59936
	s_waitcnt lgkmcnt(4)
	v_mfma_f32_32x32x16_bf16 v[2:17], v[176:179], v[180:183], v[2:17]
	s_waitcnt lgkmcnt(1)
	v_mfma_f32_32x32x16_bf16 v[18:33], v[176:179], v[192:195], v[18:33]
	ds_read_b128 v[176:179], v66 offset:23040
	ds_read_b128 v[200:203], v66 offset:23072
	s_waitcnt lgkmcnt(1)
	v_mfma_f32_32x32x16_bf16 v[34:49], v[176:179], v[180:183], v[34:49]
	v_mfma_f32_32x32x16_bf16 v[50:65], v[176:179], v[192:195], v[50:65]
	v_mfma_f32_32x32x16_bf16 v[2:17], v[184:187], v[188:191], v[2:17]
	v_mfma_f32_32x32x16_bf16 v[18:33], v[184:187], v[196:199], v[18:33]
	s_waitcnt lgkmcnt(0)
	v_mfma_f32_32x32x16_bf16 v[34:49], v[200:203], v[188:191], v[34:49]
	ds_read_b128 v[176:179], v66 offset:18496
	ds_read_b128 v[180:183], v67 offset:55360
	ds_read_b128 v[184:187], v66 offset:18528
	ds_read_b128 v[188:191], v67 offset:55392
	v_mfma_f32_32x32x16_bf16 v[50:65], v[200:203], v[196:199], v[50:65]
	ds_read_b128 v[192:195], v67 offset:59968
	ds_read_b128 v[196:199], v67 offset:60000
	s_waitcnt lgkmcnt(4)
	v_mfma_f32_32x32x16_bf16 v[2:17], v[176:179], v[180:183], v[2:17]
	s_waitcnt lgkmcnt(1)
	v_mfma_f32_32x32x16_bf16 v[18:33], v[176:179], v[192:195], v[18:33]
	ds_read_b128 v[176:179], v66 offset:23104
	ds_read_b128 v[200:203], v66 offset:23136
	s_waitcnt vmcnt(13)
	ds_write_b128 v90, v[152:155]
	ds_write_b128 v90, v[144:147] offset:4608
	ds_write_b128 v90, v[148:151] offset:9216
	s_waitcnt vmcnt(11)
	ds_write_b128 v90, v[160:163] offset:13824
	ds_write_b128 v90, v[156:159] offset:36864
	s_waitcnt vmcnt(10)
	ds_write_b128 v90, v[164:167] offset:41472
	s_waitcnt vmcnt(9)
	ds_write_b128 v90, v[168:171] offset:46080
	s_waitcnt vmcnt(8)
	ds_write_b128 v90, v[172:175] offset:50688
	global_load_dwordx4 v[144:147], v[78:79], off offset:512
	global_load_dwordx4 v[148:151], v[80:81], off offset:512
	global_load_dwordx4 v[152:155], v[74:75], off offset:512
	global_load_dwordx4 v[156:159], v[76:77], off offset:512
	global_load_dwordx4 v[160:163], v[82:83], off offset:512
	global_load_dwordx4 v[164:167], v[84:85], off offset:512
	global_load_dwordx4 v[168:171], v[86:87], off offset:512
	global_load_dwordx4 v[172:175], v[88:89], off offset:512
	s_waitcnt lgkmcnt(0)
	s_barrier
	v_mfma_f32_32x32x16_bf16 v[34:49], v[176:179], v[180:183], v[34:49]
	v_mfma_f32_32x32x16_bf16 v[50:65], v[176:179], v[192:195], v[50:65]
	v_mfma_f32_32x32x16_bf16 v[2:17], v[184:187], v[188:191], v[2:17]
	v_mfma_f32_32x32x16_bf16 v[18:33], v[184:187], v[196:199], v[18:33]
	v_mfma_f32_32x32x16_bf16 v[34:49], v[200:203], v[188:191], v[34:49]
	v_mfma_f32_32x32x16_bf16 v[50:65], v[200:203], v[196:199], v[50:65]
	ds_read_b128 v[176:179], v66
	ds_read_b128 v[180:183], v67 offset:36864
	ds_read_b128 v[184:187], v66 offset:32
	ds_read_b128 v[188:191], v67 offset:36896
	ds_read_b128 v[192:195], v67 offset:41472
	ds_read_b128 v[196:199], v67 offset:41504
	s_waitcnt lgkmcnt(4)
	v_mfma_f32_32x32x16_bf16 v[2:17], v[176:179], v[180:183], v[2:17]
	s_waitcnt lgkmcnt(1)
	v_mfma_f32_32x32x16_bf16 v[18:33], v[176:179], v[192:195], v[18:33]
	ds_read_b128 v[176:179], v66 offset:4608
	ds_read_b128 v[200:203], v66 offset:4640
	s_waitcnt lgkmcnt(1)
	v_mfma_f32_32x32x16_bf16 v[34:49], v[176:179], v[180:183], v[34:49]
	v_mfma_f32_32x32x16_bf16 v[50:65], v[176:179], v[192:195], v[50:65]
	v_mfma_f32_32x32x16_bf16 v[2:17], v[184:187], v[188:191], v[2:17]
	v_mfma_f32_32x32x16_bf16 v[18:33], v[184:187], v[196:199], v[18:33]
	s_waitcnt lgkmcnt(0)
	v_mfma_f32_32x32x16_bf16 v[34:49], v[200:203], v[188:191], v[34:49]
	ds_read_b128 v[176:179], v66 offset:64
	ds_read_b128 v[180:183], v67 offset:36928
	ds_read_b128 v[184:187], v66 offset:96
	ds_read_b128 v[188:191], v67 offset:36960
	v_mfma_f32_32x32x16_bf16 v[50:65], v[200:203], v[196:199], v[50:65]
	ds_read_b128 v[192:195], v67 offset:41536
	ds_read_b128 v[196:199], v67 offset:41568
	s_waitcnt lgkmcnt(4)
	v_mfma_f32_32x32x16_bf16 v[2:17], v[176:179], v[180:183], v[2:17]
	s_waitcnt lgkmcnt(1)
	v_mfma_f32_32x32x16_bf16 v[18:33], v[176:179], v[192:195], v[18:33]
	ds_read_b128 v[176:179], v66 offset:4672
	ds_read_b128 v[200:203], v66 offset:4704
	s_waitcnt vmcnt(13)
	ds_write_b128 v90, v[120:123] offset:18432
	ds_write_b128 v90, v[112:115] offset:23040
	ds_write_b128 v90, v[116:119] offset:27648
	s_waitcnt vmcnt(11)
	ds_write_b128 v90, v[128:131] offset:32256
	ds_write_b128 v90, v[124:127] offset:55296
	s_waitcnt vmcnt(10)
	ds_write_b128 v90, v[132:135] offset:59904
	s_waitcnt vmcnt(9)
	ds_write_b128 v90, v[136:139] offset:64512
	s_waitcnt vmcnt(8)
	ds_write_b128 v91, v[140:143] offset:32256
	global_load_dwordx4 v[112:115], v[78:79], off offset:640
	global_load_dwordx4 v[116:119], v[80:81], off offset:640
	global_load_dwordx4 v[120:123], v[74:75], off offset:640
	global_load_dwordx4 v[124:127], v[76:77], off offset:640
	global_load_dwordx4 v[128:131], v[82:83], off offset:640
	global_load_dwordx4 v[132:135], v[84:85], off offset:640
	global_load_dwordx4 v[136:139], v[86:87], off offset:640
	global_load_dwordx4 v[140:143], v[88:89], off offset:640
	s_waitcnt lgkmcnt(0)
	s_barrier
	v_mfma_f32_32x32x16_bf16 v[34:49], v[176:179], v[180:183], v[34:49]
	v_mfma_f32_32x32x16_bf16 v[50:65], v[176:179], v[192:195], v[50:65]
	v_mfma_f32_32x32x16_bf16 v[2:17], v[184:187], v[188:191], v[2:17]
	v_mfma_f32_32x32x16_bf16 v[18:33], v[184:187], v[196:199], v[18:33]
	v_mfma_f32_32x32x16_bf16 v[34:49], v[200:203], v[188:191], v[34:49]
	v_mfma_f32_32x32x16_bf16 v[50:65], v[200:203], v[196:199], v[50:65]
	ds_read_b128 v[176:179], v66 offset:18432
	ds_read_b128 v[180:183], v67 offset:55296
	ds_read_b128 v[184:187], v66 offset:18464
	ds_read_b128 v[188:191], v67 offset:55328
	ds_read_b128 v[192:195], v67 offset:59904
	ds_read_b128 v[196:199], v67 offset:59936
	s_waitcnt lgkmcnt(4)
	v_mfma_f32_32x32x16_bf16 v[2:17], v[176:179], v[180:183], v[2:17]
	s_waitcnt lgkmcnt(1)
	v_mfma_f32_32x32x16_bf16 v[18:33], v[176:179], v[192:195], v[18:33]
	ds_read_b128 v[176:179], v66 offset:23040
	ds_read_b128 v[200:203], v66 offset:23072
	s_waitcnt lgkmcnt(1)
	v_mfma_f32_32x32x16_bf16 v[34:49], v[176:179], v[180:183], v[34:49]
	v_mfma_f32_32x32x16_bf16 v[50:65], v[176:179], v[192:195], v[50:65]
	v_mfma_f32_32x32x16_bf16 v[2:17], v[184:187], v[188:191], v[2:17]
	v_mfma_f32_32x32x16_bf16 v[18:33], v[184:187], v[196:199], v[18:33]
	s_waitcnt lgkmcnt(0)
	v_mfma_f32_32x32x16_bf16 v[34:49], v[200:203], v[188:191], v[34:49]
	ds_read_b128 v[176:179], v66 offset:18496
	ds_read_b128 v[180:183], v67 offset:55360
	ds_read_b128 v[184:187], v66 offset:18528
	ds_read_b128 v[188:191], v67 offset:55392
	v_mfma_f32_32x32x16_bf16 v[50:65], v[200:203], v[196:199], v[50:65]
	ds_read_b128 v[192:195], v67 offset:59968
	ds_read_b128 v[196:199], v67 offset:60000
	s_waitcnt lgkmcnt(4)
	v_mfma_f32_32x32x16_bf16 v[2:17], v[176:179], v[180:183], v[2:17]
	s_waitcnt lgkmcnt(1)
	v_mfma_f32_32x32x16_bf16 v[18:33], v[176:179], v[192:195], v[18:33]
	ds_read_b128 v[176:179], v66 offset:23104
	ds_read_b128 v[200:203], v66 offset:23136
	s_waitcnt vmcnt(13)
	ds_write_b128 v90, v[152:155]
	ds_write_b128 v90, v[144:147] offset:4608
	ds_write_b128 v90, v[148:151] offset:9216
	s_waitcnt vmcnt(11)
	ds_write_b128 v90, v[160:163] offset:13824
	ds_write_b128 v90, v[156:159] offset:36864
	s_waitcnt vmcnt(10)
	ds_write_b128 v90, v[164:167] offset:41472
	s_waitcnt vmcnt(9)
	ds_write_b128 v90, v[168:171] offset:46080
	s_waitcnt vmcnt(8)
	ds_write_b128 v90, v[172:175] offset:50688
	global_load_dwordx4 v[144:147], v[78:79], off offset:768
	global_load_dwordx4 v[148:151], v[80:81], off offset:768
	global_load_dwordx4 v[152:155], v[74:75], off offset:768
	global_load_dwordx4 v[156:159], v[76:77], off offset:768
	global_load_dwordx4 v[160:163], v[82:83], off offset:768
	global_load_dwordx4 v[164:167], v[84:85], off offset:768
	global_load_dwordx4 v[168:171], v[86:87], off offset:768
	global_load_dwordx4 v[172:175], v[88:89], off offset:768
	s_waitcnt lgkmcnt(0)
	s_barrier
	v_mfma_f32_32x32x16_bf16 v[34:49], v[176:179], v[180:183], v[34:49]
	v_mfma_f32_32x32x16_bf16 v[50:65], v[176:179], v[192:195], v[50:65]
	v_mfma_f32_32x32x16_bf16 v[2:17], v[184:187], v[188:191], v[2:17]
	v_mfma_f32_32x32x16_bf16 v[18:33], v[184:187], v[196:199], v[18:33]
	v_mfma_f32_32x32x16_bf16 v[34:49], v[200:203], v[188:191], v[34:49]
	v_mfma_f32_32x32x16_bf16 v[50:65], v[200:203], v[196:199], v[50:65]
	ds_read_b128 v[176:179], v66
	ds_read_b128 v[180:183], v67 offset:36864
	ds_read_b128 v[184:187], v66 offset:32
	ds_read_b128 v[188:191], v67 offset:36896
	ds_read_b128 v[192:195], v67 offset:41472
	ds_read_b128 v[196:199], v67 offset:41504
	s_waitcnt lgkmcnt(4)
	v_mfma_f32_32x32x16_bf16 v[2:17], v[176:179], v[180:183], v[2:17]
	s_waitcnt lgkmcnt(1)
	v_mfma_f32_32x32x16_bf16 v[18:33], v[176:179], v[192:195], v[18:33]
	ds_read_b128 v[176:179], v66 offset:4608
	ds_read_b128 v[200:203], v66 offset:4640
	s_waitcnt lgkmcnt(1)
	v_mfma_f32_32x32x16_bf16 v[34:49], v[176:179], v[180:183], v[34:49]
	v_mfma_f32_32x32x16_bf16 v[50:65], v[176:179], v[192:195], v[50:65]
	v_mfma_f32_32x32x16_bf16 v[2:17], v[184:187], v[188:191], v[2:17]
	v_mfma_f32_32x32x16_bf16 v[18:33], v[184:187], v[196:199], v[18:33]
	s_waitcnt lgkmcnt(0)
	v_mfma_f32_32x32x16_bf16 v[34:49], v[200:203], v[188:191], v[34:49]
	ds_read_b128 v[176:179], v66 offset:64
	ds_read_b128 v[180:183], v67 offset:36928
	ds_read_b128 v[184:187], v66 offset:96
	ds_read_b128 v[188:191], v67 offset:36960
	v_mfma_f32_32x32x16_bf16 v[50:65], v[200:203], v[196:199], v[50:65]
	ds_read_b128 v[192:195], v67 offset:41536
	ds_read_b128 v[196:199], v67 offset:41568
	s_waitcnt lgkmcnt(4)
	v_mfma_f32_32x32x16_bf16 v[2:17], v[176:179], v[180:183], v[2:17]
	s_waitcnt lgkmcnt(1)
	v_mfma_f32_32x32x16_bf16 v[18:33], v[176:179], v[192:195], v[18:33]
	ds_read_b128 v[176:179], v66 offset:4672
	ds_read_b128 v[200:203], v66 offset:4704
	s_waitcnt vmcnt(13)
	ds_write_b128 v90, v[120:123] offset:18432
	ds_write_b128 v90, v[112:115] offset:23040
	ds_write_b128 v90, v[116:119] offset:27648
	s_waitcnt vmcnt(11)
	ds_write_b128 v90, v[128:131] offset:32256
	ds_write_b128 v90, v[124:127] offset:55296
	s_waitcnt vmcnt(10)
	ds_write_b128 v90, v[132:135] offset:59904
	s_waitcnt vmcnt(9)
	ds_write_b128 v90, v[136:139] offset:64512
	s_waitcnt vmcnt(8)
	ds_write_b128 v91, v[140:143] offset:32256
	global_load_dwordx4 v[112:115], v[78:79], off offset:896
	global_load_dwordx4 v[116:119], v[80:81], off offset:896
	global_load_dwordx4 v[120:123], v[74:75], off offset:896
	global_load_dwordx4 v[124:127], v[76:77], off offset:896
	global_load_dwordx4 v[128:131], v[82:83], off offset:896
	global_load_dwordx4 v[132:135], v[84:85], off offset:896
	global_load_dwordx4 v[136:139], v[86:87], off offset:896
	global_load_dwordx4 v[140:143], v[88:89], off offset:896
	s_waitcnt lgkmcnt(0)
	s_barrier
	v_mfma_f32_32x32x16_bf16 v[34:49], v[176:179], v[180:183], v[34:49]
	v_mfma_f32_32x32x16_bf16 v[50:65], v[176:179], v[192:195], v[50:65]
	v_mfma_f32_32x32x16_bf16 v[2:17], v[184:187], v[188:191], v[2:17]
	v_mfma_f32_32x32x16_bf16 v[18:33], v[184:187], v[196:199], v[18:33]
	v_mfma_f32_32x32x16_bf16 v[34:49], v[200:203], v[188:191], v[34:49]
	v_mfma_f32_32x32x16_bf16 v[50:65], v[200:203], v[196:199], v[50:65]
	ds_read_b128 v[176:179], v66 offset:18432
	ds_read_b128 v[180:183], v67 offset:55296
	ds_read_b128 v[184:187], v66 offset:18464
	ds_read_b128 v[188:191], v67 offset:55328
	ds_read_b128 v[192:195], v67 offset:59904
	ds_read_b128 v[196:199], v67 offset:59936
	s_waitcnt lgkmcnt(4)
	v_mfma_f32_32x32x16_bf16 v[2:17], v[176:179], v[180:183], v[2:17]
	s_waitcnt lgkmcnt(1)
	v_mfma_f32_32x32x16_bf16 v[18:33], v[176:179], v[192:195], v[18:33]
	ds_read_b128 v[176:179], v66 offset:23040
	ds_read_b128 v[200:203], v66 offset:23072
	s_waitcnt lgkmcnt(1)
	v_mfma_f32_32x32x16_bf16 v[34:49], v[176:179], v[180:183], v[34:49]
	v_mfma_f32_32x32x16_bf16 v[50:65], v[176:179], v[192:195], v[50:65]
	v_mfma_f32_32x32x16_bf16 v[2:17], v[184:187], v[188:191], v[2:17]
	v_mfma_f32_32x32x16_bf16 v[18:33], v[184:187], v[196:199], v[18:33]
	s_waitcnt lgkmcnt(0)
	v_mfma_f32_32x32x16_bf16 v[34:49], v[200:203], v[188:191], v[34:49]
	ds_read_b128 v[176:179], v66 offset:18496
	ds_read_b128 v[180:183], v67 offset:55360
	ds_read_b128 v[184:187], v66 offset:18528
	ds_read_b128 v[188:191], v67 offset:55392
	v_mfma_f32_32x32x16_bf16 v[50:65], v[200:203], v[196:199], v[50:65]
	ds_read_b128 v[192:195], v67 offset:59968
	ds_read_b128 v[196:199], v67 offset:60000
	s_waitcnt lgkmcnt(4)
	v_mfma_f32_32x32x16_bf16 v[2:17], v[176:179], v[180:183], v[2:17]
	s_waitcnt lgkmcnt(1)
	v_mfma_f32_32x32x16_bf16 v[18:33], v[176:179], v[192:195], v[18:33]
	ds_read_b128 v[176:179], v66 offset:23104
	ds_read_b128 v[200:203], v66 offset:23136
	s_waitcnt vmcnt(13)
	ds_write_b128 v90, v[152:155]
	ds_write_b128 v90, v[144:147] offset:4608
	ds_write_b128 v90, v[148:151] offset:9216
	s_waitcnt vmcnt(11)
	ds_write_b128 v90, v[160:163] offset:13824
	ds_write_b128 v90, v[156:159] offset:36864
	s_waitcnt vmcnt(10)
	ds_write_b128 v90, v[164:167] offset:41472
	s_waitcnt vmcnt(9)
	ds_write_b128 v90, v[168:171] offset:46080
	s_waitcnt vmcnt(8)
	ds_write_b128 v90, v[172:175] offset:50688
	global_load_dwordx4 v[144:147], v[78:79], off offset:1024
	global_load_dwordx4 v[148:151], v[80:81], off offset:1024
	global_load_dwordx4 v[152:155], v[74:75], off offset:1024
	global_load_dwordx4 v[156:159], v[76:77], off offset:1024
	global_load_dwordx4 v[160:163], v[82:83], off offset:1024
	global_load_dwordx4 v[164:167], v[84:85], off offset:1024
	global_load_dwordx4 v[168:171], v[86:87], off offset:1024
	global_load_dwordx4 v[172:175], v[88:89], off offset:1024
	s_waitcnt lgkmcnt(0)
	s_barrier
	v_mfma_f32_32x32x16_bf16 v[34:49], v[176:179], v[180:183], v[34:49]
	v_mfma_f32_32x32x16_bf16 v[50:65], v[176:179], v[192:195], v[50:65]
	v_mfma_f32_32x32x16_bf16 v[2:17], v[184:187], v[188:191], v[2:17]
	v_mfma_f32_32x32x16_bf16 v[18:33], v[184:187], v[196:199], v[18:33]
	v_mfma_f32_32x32x16_bf16 v[34:49], v[200:203], v[188:191], v[34:49]
	v_mfma_f32_32x32x16_bf16 v[50:65], v[200:203], v[196:199], v[50:65]
	ds_read_b128 v[176:179], v66
	ds_read_b128 v[180:183], v67 offset:36864
	ds_read_b128 v[184:187], v66 offset:32
	ds_read_b128 v[188:191], v67 offset:36896
	ds_read_b128 v[192:195], v67 offset:41472
	ds_read_b128 v[196:199], v67 offset:41504
	s_waitcnt lgkmcnt(4)
	v_mfma_f32_32x32x16_bf16 v[2:17], v[176:179], v[180:183], v[2:17]
	s_waitcnt lgkmcnt(1)
	v_mfma_f32_32x32x16_bf16 v[18:33], v[176:179], v[192:195], v[18:33]
	ds_read_b128 v[176:179], v66 offset:4608
	ds_read_b128 v[200:203], v66 offset:4640
	s_waitcnt lgkmcnt(1)
	v_mfma_f32_32x32x16_bf16 v[34:49], v[176:179], v[180:183], v[34:49]
	v_mfma_f32_32x32x16_bf16 v[50:65], v[176:179], v[192:195], v[50:65]
	v_mfma_f32_32x32x16_bf16 v[2:17], v[184:187], v[188:191], v[2:17]
	v_mfma_f32_32x32x16_bf16 v[18:33], v[184:187], v[196:199], v[18:33]
	s_waitcnt lgkmcnt(0)
	v_mfma_f32_32x32x16_bf16 v[34:49], v[200:203], v[188:191], v[34:49]
	ds_read_b128 v[176:179], v66 offset:64
	ds_read_b128 v[180:183], v67 offset:36928
	ds_read_b128 v[184:187], v66 offset:96
	ds_read_b128 v[188:191], v67 offset:36960
	v_mfma_f32_32x32x16_bf16 v[50:65], v[200:203], v[196:199], v[50:65]
	ds_read_b128 v[192:195], v67 offset:41536
	ds_read_b128 v[196:199], v67 offset:41568
	s_waitcnt lgkmcnt(4)
	v_mfma_f32_32x32x16_bf16 v[2:17], v[176:179], v[180:183], v[2:17]
	s_waitcnt lgkmcnt(1)
	v_mfma_f32_32x32x16_bf16 v[18:33], v[176:179], v[192:195], v[18:33]
	ds_read_b128 v[176:179], v66 offset:4672
	ds_read_b128 v[200:203], v66 offset:4704
	s_waitcnt vmcnt(13)
	ds_write_b128 v90, v[120:123] offset:18432
	ds_write_b128 v90, v[112:115] offset:23040
	ds_write_b128 v90, v[116:119] offset:27648
	s_waitcnt vmcnt(11)
	ds_write_b128 v90, v[128:131] offset:32256
	ds_write_b128 v90, v[124:127] offset:55296
	s_waitcnt vmcnt(10)
	ds_write_b128 v90, v[132:135] offset:59904
	s_waitcnt vmcnt(9)
	ds_write_b128 v90, v[136:139] offset:64512
	s_waitcnt vmcnt(8)
	ds_write_b128 v91, v[140:143] offset:32256
	global_load_dwordx4 v[112:115], v[78:79], off offset:1152
	global_load_dwordx4 v[116:119], v[80:81], off offset:1152
	global_load_dwordx4 v[120:123], v[74:75], off offset:1152
	global_load_dwordx4 v[124:127], v[76:77], off offset:1152
	global_load_dwordx4 v[128:131], v[82:83], off offset:1152
	global_load_dwordx4 v[132:135], v[84:85], off offset:1152
	global_load_dwordx4 v[136:139], v[86:87], off offset:1152
	global_load_dwordx4 v[140:143], v[88:89], off offset:1152
	s_waitcnt lgkmcnt(0)
	s_barrier
	v_mfma_f32_32x32x16_bf16 v[34:49], v[176:179], v[180:183], v[34:49]
	v_mfma_f32_32x32x16_bf16 v[50:65], v[176:179], v[192:195], v[50:65]
	v_mfma_f32_32x32x16_bf16 v[2:17], v[184:187], v[188:191], v[2:17]
	v_mfma_f32_32x32x16_bf16 v[18:33], v[184:187], v[196:199], v[18:33]
	v_mfma_f32_32x32x16_bf16 v[34:49], v[200:203], v[188:191], v[34:49]
	v_mfma_f32_32x32x16_bf16 v[50:65], v[200:203], v[196:199], v[50:65]
	ds_read_b128 v[176:179], v66 offset:18432
	ds_read_b128 v[180:183], v67 offset:55296
	ds_read_b128 v[184:187], v66 offset:18464
	ds_read_b128 v[188:191], v67 offset:55328
	ds_read_b128 v[192:195], v67 offset:59904
	ds_read_b128 v[196:199], v67 offset:59936
	s_waitcnt lgkmcnt(4)
	v_mfma_f32_32x32x16_bf16 v[2:17], v[176:179], v[180:183], v[2:17]
	s_waitcnt lgkmcnt(1)
	v_mfma_f32_32x32x16_bf16 v[18:33], v[176:179], v[192:195], v[18:33]
	ds_read_b128 v[176:179], v66 offset:23040
	ds_read_b128 v[200:203], v66 offset:23072
	s_waitcnt lgkmcnt(1)
	v_mfma_f32_32x32x16_bf16 v[34:49], v[176:179], v[180:183], v[34:49]
	v_mfma_f32_32x32x16_bf16 v[50:65], v[176:179], v[192:195], v[50:65]
	v_mfma_f32_32x32x16_bf16 v[2:17], v[184:187], v[188:191], v[2:17]
	v_mfma_f32_32x32x16_bf16 v[18:33], v[184:187], v[196:199], v[18:33]
	s_waitcnt lgkmcnt(0)
	v_mfma_f32_32x32x16_bf16 v[34:49], v[200:203], v[188:191], v[34:49]
	ds_read_b128 v[176:179], v66 offset:18496
	ds_read_b128 v[180:183], v67 offset:55360
	ds_read_b128 v[184:187], v66 offset:18528
	ds_read_b128 v[188:191], v67 offset:55392
	v_mfma_f32_32x32x16_bf16 v[50:65], v[200:203], v[196:199], v[50:65]
	ds_read_b128 v[192:195], v67 offset:59968
	ds_read_b128 v[196:199], v67 offset:60000
	s_waitcnt lgkmcnt(4)
	v_mfma_f32_32x32x16_bf16 v[2:17], v[176:179], v[180:183], v[2:17]
	s_waitcnt lgkmcnt(1)
	v_mfma_f32_32x32x16_bf16 v[18:33], v[176:179], v[192:195], v[18:33]
	ds_read_b128 v[176:179], v66 offset:23104
	ds_read_b128 v[200:203], v66 offset:23136
	s_waitcnt vmcnt(13)
	ds_write_b128 v90, v[152:155]
	ds_write_b128 v90, v[144:147] offset:4608
	ds_write_b128 v90, v[148:151] offset:9216
	s_waitcnt vmcnt(11)
	ds_write_b128 v90, v[160:163] offset:13824
	ds_write_b128 v90, v[156:159] offset:36864
	s_waitcnt vmcnt(10)
	ds_write_b128 v90, v[164:167] offset:41472
	s_waitcnt vmcnt(9)
	ds_write_b128 v90, v[168:171] offset:46080
	s_waitcnt vmcnt(8)
	ds_write_b128 v90, v[172:175] offset:50688
	global_load_dwordx4 v[144:147], v[78:79], off offset:1280
	global_load_dwordx4 v[148:151], v[80:81], off offset:1280
	global_load_dwordx4 v[152:155], v[74:75], off offset:1280
	global_load_dwordx4 v[156:159], v[76:77], off offset:1280
	global_load_dwordx4 v[160:163], v[82:83], off offset:1280
	global_load_dwordx4 v[164:167], v[84:85], off offset:1280
	global_load_dwordx4 v[168:171], v[86:87], off offset:1280
	global_load_dwordx4 v[172:175], v[88:89], off offset:1280
	s_waitcnt lgkmcnt(0)
	s_barrier
	v_mfma_f32_32x32x16_bf16 v[34:49], v[176:179], v[180:183], v[34:49]
	v_mfma_f32_32x32x16_bf16 v[50:65], v[176:179], v[192:195], v[50:65]
	v_mfma_f32_32x32x16_bf16 v[2:17], v[184:187], v[188:191], v[2:17]
	v_mfma_f32_32x32x16_bf16 v[18:33], v[184:187], v[196:199], v[18:33]
	v_mfma_f32_32x32x16_bf16 v[34:49], v[200:203], v[188:191], v[34:49]
	v_mfma_f32_32x32x16_bf16 v[50:65], v[200:203], v[196:199], v[50:65]
	ds_read_b128 v[176:179], v66
	ds_read_b128 v[180:183], v67 offset:36864
	ds_read_b128 v[184:187], v66 offset:32
	ds_read_b128 v[188:191], v67 offset:36896
	ds_read_b128 v[192:195], v67 offset:41472
	ds_read_b128 v[196:199], v67 offset:41504
	s_waitcnt lgkmcnt(4)
	v_mfma_f32_32x32x16_bf16 v[2:17], v[176:179], v[180:183], v[2:17]
	s_waitcnt lgkmcnt(1)
	v_mfma_f32_32x32x16_bf16 v[18:33], v[176:179], v[192:195], v[18:33]
	ds_read_b128 v[176:179], v66 offset:4608
	ds_read_b128 v[200:203], v66 offset:4640
	s_waitcnt lgkmcnt(1)
	v_mfma_f32_32x32x16_bf16 v[34:49], v[176:179], v[180:183], v[34:49]
	v_mfma_f32_32x32x16_bf16 v[50:65], v[176:179], v[192:195], v[50:65]
	v_mfma_f32_32x32x16_bf16 v[2:17], v[184:187], v[188:191], v[2:17]
	v_mfma_f32_32x32x16_bf16 v[18:33], v[184:187], v[196:199], v[18:33]
	s_waitcnt lgkmcnt(0)
	v_mfma_f32_32x32x16_bf16 v[34:49], v[200:203], v[188:191], v[34:49]
	ds_read_b128 v[176:179], v66 offset:64
	ds_read_b128 v[180:183], v67 offset:36928
	ds_read_b128 v[184:187], v66 offset:96
	ds_read_b128 v[188:191], v67 offset:36960
	v_mfma_f32_32x32x16_bf16 v[50:65], v[200:203], v[196:199], v[50:65]
	ds_read_b128 v[192:195], v67 offset:41536
	ds_read_b128 v[196:199], v67 offset:41568
	s_waitcnt lgkmcnt(4)
	v_mfma_f32_32x32x16_bf16 v[2:17], v[176:179], v[180:183], v[2:17]
	s_waitcnt lgkmcnt(1)
	v_mfma_f32_32x32x16_bf16 v[18:33], v[176:179], v[192:195], v[18:33]
	ds_read_b128 v[176:179], v66 offset:4672
	ds_read_b128 v[200:203], v66 offset:4704
	s_waitcnt vmcnt(13)
	ds_write_b128 v90, v[120:123] offset:18432
	ds_write_b128 v90, v[112:115] offset:23040
	ds_write_b128 v90, v[116:119] offset:27648
	s_waitcnt vmcnt(11)
	ds_write_b128 v90, v[128:131] offset:32256
	ds_write_b128 v90, v[124:127] offset:55296
	s_waitcnt vmcnt(10)
	ds_write_b128 v90, v[132:135] offset:59904
	s_waitcnt vmcnt(9)
	ds_write_b128 v90, v[136:139] offset:64512
	s_waitcnt vmcnt(8)
	ds_write_b128 v91, v[140:143] offset:32256
	global_load_dwordx4 v[112:115], v[78:79], off offset:1408
	global_load_dwordx4 v[116:119], v[80:81], off offset:1408
	global_load_dwordx4 v[120:123], v[74:75], off offset:1408
	global_load_dwordx4 v[124:127], v[76:77], off offset:1408
	global_load_dwordx4 v[128:131], v[82:83], off offset:1408
	global_load_dwordx4 v[132:135], v[84:85], off offset:1408
	global_load_dwordx4 v[136:139], v[86:87], off offset:1408
	global_load_dwordx4 v[140:143], v[88:89], off offset:1408
	s_waitcnt lgkmcnt(0)
	s_barrier
	v_mfma_f32_32x32x16_bf16 v[34:49], v[176:179], v[180:183], v[34:49]
	v_mfma_f32_32x32x16_bf16 v[50:65], v[176:179], v[192:195], v[50:65]
	v_mfma_f32_32x32x16_bf16 v[2:17], v[184:187], v[188:191], v[2:17]
	v_mfma_f32_32x32x16_bf16 v[18:33], v[184:187], v[196:199], v[18:33]
	v_mfma_f32_32x32x16_bf16 v[34:49], v[200:203], v[188:191], v[34:49]
	v_mfma_f32_32x32x16_bf16 v[50:65], v[200:203], v[196:199], v[50:65]
	ds_read_b128 v[176:179], v66 offset:18432
	ds_read_b128 v[180:183], v67 offset:55296
	ds_read_b128 v[184:187], v66 offset:18464
	ds_read_b128 v[188:191], v67 offset:55328
	ds_read_b128 v[192:195], v67 offset:59904
	ds_read_b128 v[196:199], v67 offset:59936
	s_waitcnt lgkmcnt(4)
	v_mfma_f32_32x32x16_bf16 v[2:17], v[176:179], v[180:183], v[2:17]
	s_waitcnt lgkmcnt(1)
	v_mfma_f32_32x32x16_bf16 v[18:33], v[176:179], v[192:195], v[18:33]
	ds_read_b128 v[176:179], v66 offset:23040
	ds_read_b128 v[200:203], v66 offset:23072
	s_waitcnt lgkmcnt(1)
	v_mfma_f32_32x32x16_bf16 v[34:49], v[176:179], v[180:183], v[34:49]
	v_mfma_f32_32x32x16_bf16 v[50:65], v[176:179], v[192:195], v[50:65]
	v_mfma_f32_32x32x16_bf16 v[2:17], v[184:187], v[188:191], v[2:17]
	v_mfma_f32_32x32x16_bf16 v[18:33], v[184:187], v[196:199], v[18:33]
	s_waitcnt lgkmcnt(0)
	v_mfma_f32_32x32x16_bf16 v[34:49], v[200:203], v[188:191], v[34:49]
	ds_read_b128 v[176:179], v66 offset:18496
	ds_read_b128 v[180:183], v67 offset:55360
	ds_read_b128 v[184:187], v66 offset:18528
	ds_read_b128 v[188:191], v67 offset:55392
	v_mfma_f32_32x32x16_bf16 v[50:65], v[200:203], v[196:199], v[50:65]
	ds_read_b128 v[192:195], v67 offset:59968
	ds_read_b128 v[196:199], v67 offset:60000
	s_waitcnt lgkmcnt(4)
	v_mfma_f32_32x32x16_bf16 v[2:17], v[176:179], v[180:183], v[2:17]
	s_waitcnt lgkmcnt(1)
	v_mfma_f32_32x32x16_bf16 v[18:33], v[176:179], v[192:195], v[18:33]
	ds_read_b128 v[176:179], v66 offset:23104
	ds_read_b128 v[200:203], v66 offset:23136
	s_waitcnt vmcnt(13)
	ds_write_b128 v90, v[152:155]
	ds_write_b128 v90, v[144:147] offset:4608
	ds_write_b128 v90, v[148:151] offset:9216
	s_waitcnt vmcnt(11)
	ds_write_b128 v90, v[160:163] offset:13824
	ds_write_b128 v90, v[156:159] offset:36864
	s_waitcnt vmcnt(10)
	ds_write_b128 v90, v[164:167] offset:41472
	s_waitcnt vmcnt(9)
	ds_write_b128 v90, v[168:171] offset:46080
	s_waitcnt vmcnt(8)
	ds_write_b128 v90, v[172:175] offset:50688
	global_load_dwordx4 v[144:147], v[78:79], off offset:1536
	global_load_dwordx4 v[148:151], v[80:81], off offset:1536
	global_load_dwordx4 v[152:155], v[74:75], off offset:1536
	global_load_dwordx4 v[156:159], v[76:77], off offset:1536
	global_load_dwordx4 v[160:163], v[82:83], off offset:1536
	global_load_dwordx4 v[164:167], v[84:85], off offset:1536
	global_load_dwordx4 v[168:171], v[86:87], off offset:1536
	global_load_dwordx4 v[172:175], v[88:89], off offset:1536
	s_waitcnt lgkmcnt(0)
	s_barrier
	v_mfma_f32_32x32x16_bf16 v[34:49], v[176:179], v[180:183], v[34:49]
	v_mfma_f32_32x32x16_bf16 v[50:65], v[176:179], v[192:195], v[50:65]
	v_mfma_f32_32x32x16_bf16 v[2:17], v[184:187], v[188:191], v[2:17]
	v_mfma_f32_32x32x16_bf16 v[18:33], v[184:187], v[196:199], v[18:33]
	v_mfma_f32_32x32x16_bf16 v[34:49], v[200:203], v[188:191], v[34:49]
	v_mfma_f32_32x32x16_bf16 v[50:65], v[200:203], v[196:199], v[50:65]
	ds_read_b128 v[176:179], v66
	ds_read_b128 v[180:183], v67 offset:36864
	ds_read_b128 v[184:187], v66 offset:32
	ds_read_b128 v[188:191], v67 offset:36896
	ds_read_b128 v[192:195], v67 offset:41472
	ds_read_b128 v[196:199], v67 offset:41504
	s_waitcnt lgkmcnt(4)
	v_mfma_f32_32x32x16_bf16 v[2:17], v[176:179], v[180:183], v[2:17]
	s_waitcnt lgkmcnt(1)
	v_mfma_f32_32x32x16_bf16 v[18:33], v[176:179], v[192:195], v[18:33]
	ds_read_b128 v[176:179], v66 offset:4608
	ds_read_b128 v[200:203], v66 offset:4640
	s_waitcnt lgkmcnt(1)
	v_mfma_f32_32x32x16_bf16 v[34:49], v[176:179], v[180:183], v[34:49]
	v_mfma_f32_32x32x16_bf16 v[50:65], v[176:179], v[192:195], v[50:65]
	v_mfma_f32_32x32x16_bf16 v[2:17], v[184:187], v[188:191], v[2:17]
	v_mfma_f32_32x32x16_bf16 v[18:33], v[184:187], v[196:199], v[18:33]
	s_waitcnt lgkmcnt(0)
	v_mfma_f32_32x32x16_bf16 v[34:49], v[200:203], v[188:191], v[34:49]
	ds_read_b128 v[176:179], v66 offset:64
	ds_read_b128 v[180:183], v67 offset:36928
	ds_read_b128 v[184:187], v66 offset:96
	ds_read_b128 v[188:191], v67 offset:36960
	v_mfma_f32_32x32x16_bf16 v[50:65], v[200:203], v[196:199], v[50:65]
	ds_read_b128 v[192:195], v67 offset:41536
	ds_read_b128 v[196:199], v67 offset:41568
	s_waitcnt lgkmcnt(4)
	v_mfma_f32_32x32x16_bf16 v[2:17], v[176:179], v[180:183], v[2:17]
	s_waitcnt lgkmcnt(1)
	v_mfma_f32_32x32x16_bf16 v[18:33], v[176:179], v[192:195], v[18:33]
	ds_read_b128 v[176:179], v66 offset:4672
	ds_read_b128 v[200:203], v66 offset:4704
	s_waitcnt vmcnt(13)
	ds_write_b128 v90, v[120:123] offset:18432
	ds_write_b128 v90, v[112:115] offset:23040
	ds_write_b128 v90, v[116:119] offset:27648
	s_waitcnt vmcnt(11)
	ds_write_b128 v90, v[128:131] offset:32256
	ds_write_b128 v90, v[124:127] offset:55296
	s_waitcnt vmcnt(10)
	ds_write_b128 v90, v[132:135] offset:59904
	s_waitcnt vmcnt(9)
	ds_write_b128 v90, v[136:139] offset:64512
	s_waitcnt vmcnt(8)
	ds_write_b128 v91, v[140:143] offset:32256
	global_load_dwordx4 v[112:115], v[78:79], off offset:1664
	global_load_dwordx4 v[116:119], v[80:81], off offset:1664
	global_load_dwordx4 v[120:123], v[74:75], off offset:1664
	global_load_dwordx4 v[124:127], v[76:77], off offset:1664
	global_load_dwordx4 v[128:131], v[82:83], off offset:1664
	global_load_dwordx4 v[132:135], v[84:85], off offset:1664
	global_load_dwordx4 v[136:139], v[86:87], off offset:1664
	global_load_dwordx4 v[140:143], v[88:89], off offset:1664
	s_waitcnt lgkmcnt(0)
	s_barrier
	v_mfma_f32_32x32x16_bf16 v[34:49], v[176:179], v[180:183], v[34:49]
	v_mfma_f32_32x32x16_bf16 v[50:65], v[176:179], v[192:195], v[50:65]
	v_mfma_f32_32x32x16_bf16 v[2:17], v[184:187], v[188:191], v[2:17]
	v_mfma_f32_32x32x16_bf16 v[18:33], v[184:187], v[196:199], v[18:33]
	v_mfma_f32_32x32x16_bf16 v[34:49], v[200:203], v[188:191], v[34:49]
	v_mfma_f32_32x32x16_bf16 v[50:65], v[200:203], v[196:199], v[50:65]
	ds_read_b128 v[176:179], v66 offset:18432
	ds_read_b128 v[180:183], v67 offset:55296
	ds_read_b128 v[184:187], v66 offset:18464
	ds_read_b128 v[188:191], v67 offset:55328
	ds_read_b128 v[192:195], v67 offset:59904
	ds_read_b128 v[196:199], v67 offset:59936
	s_waitcnt lgkmcnt(4)
	v_mfma_f32_32x32x16_bf16 v[2:17], v[176:179], v[180:183], v[2:17]
	s_waitcnt lgkmcnt(1)
	v_mfma_f32_32x32x16_bf16 v[18:33], v[176:179], v[192:195], v[18:33]
	ds_read_b128 v[176:179], v66 offset:23040
	ds_read_b128 v[200:203], v66 offset:23072
	s_waitcnt lgkmcnt(1)
	v_mfma_f32_32x32x16_bf16 v[34:49], v[176:179], v[180:183], v[34:49]
	v_mfma_f32_32x32x16_bf16 v[50:65], v[176:179], v[192:195], v[50:65]
	v_mfma_f32_32x32x16_bf16 v[2:17], v[184:187], v[188:191], v[2:17]
	v_mfma_f32_32x32x16_bf16 v[18:33], v[184:187], v[196:199], v[18:33]
	s_waitcnt lgkmcnt(0)
	v_mfma_f32_32x32x16_bf16 v[34:49], v[200:203], v[188:191], v[34:49]
	ds_read_b128 v[176:179], v66 offset:18496
	ds_read_b128 v[180:183], v67 offset:55360
	ds_read_b128 v[184:187], v66 offset:18528
	ds_read_b128 v[188:191], v67 offset:55392
	v_mfma_f32_32x32x16_bf16 v[50:65], v[200:203], v[196:199], v[50:65]
	ds_read_b128 v[192:195], v67 offset:59968
	ds_read_b128 v[196:199], v67 offset:60000
	s_waitcnt lgkmcnt(4)
	v_mfma_f32_32x32x16_bf16 v[2:17], v[176:179], v[180:183], v[2:17]
	s_waitcnt lgkmcnt(1)
	v_mfma_f32_32x32x16_bf16 v[18:33], v[176:179], v[192:195], v[18:33]
	ds_read_b128 v[176:179], v66 offset:23104
	ds_read_b128 v[200:203], v66 offset:23136
	s_waitcnt vmcnt(13)
	ds_write_b128 v90, v[152:155]
	ds_write_b128 v90, v[144:147] offset:4608
	ds_write_b128 v90, v[148:151] offset:9216
	s_waitcnt vmcnt(11)
	ds_write_b128 v90, v[160:163] offset:13824
	ds_write_b128 v90, v[156:159] offset:36864
	s_waitcnt vmcnt(10)
	ds_write_b128 v90, v[164:167] offset:41472
	s_waitcnt vmcnt(9)
	ds_write_b128 v90, v[168:171] offset:46080
	s_waitcnt vmcnt(8)
	ds_write_b128 v90, v[172:175] offset:50688
	global_load_dwordx4 v[144:147], v[78:79], off offset:1792
	global_load_dwordx4 v[148:151], v[80:81], off offset:1792
	global_load_dwordx4 v[152:155], v[74:75], off offset:1792
	global_load_dwordx4 v[156:159], v[76:77], off offset:1792
	global_load_dwordx4 v[160:163], v[82:83], off offset:1792
	global_load_dwordx4 v[164:167], v[84:85], off offset:1792
	global_load_dwordx4 v[168:171], v[86:87], off offset:1792
	global_load_dwordx4 v[172:175], v[88:89], off offset:1792
	s_waitcnt lgkmcnt(0)
	s_barrier
	v_mfma_f32_32x32x16_bf16 v[34:49], v[176:179], v[180:183], v[34:49]
	v_mfma_f32_32x32x16_bf16 v[50:65], v[176:179], v[192:195], v[50:65]
	v_mfma_f32_32x32x16_bf16 v[2:17], v[184:187], v[188:191], v[2:17]
	v_mfma_f32_32x32x16_bf16 v[18:33], v[184:187], v[196:199], v[18:33]
	v_mfma_f32_32x32x16_bf16 v[34:49], v[200:203], v[188:191], v[34:49]
	v_mfma_f32_32x32x16_bf16 v[50:65], v[200:203], v[196:199], v[50:65]
	ds_read_b128 v[176:179], v66
	ds_read_b128 v[180:183], v67 offset:36864
	ds_read_b128 v[184:187], v66 offset:32
	ds_read_b128 v[188:191], v67 offset:36896
	ds_read_b128 v[192:195], v67 offset:41472
	ds_read_b128 v[196:199], v67 offset:41504
	s_waitcnt lgkmcnt(4)
	v_mfma_f32_32x32x16_bf16 v[2:17], v[176:179], v[180:183], v[2:17]
	s_waitcnt lgkmcnt(1)
	v_mfma_f32_32x32x16_bf16 v[18:33], v[176:179], v[192:195], v[18:33]
	ds_read_b128 v[176:179], v66 offset:4608
	ds_read_b128 v[200:203], v66 offset:4640
	s_waitcnt lgkmcnt(1)
	v_mfma_f32_32x32x16_bf16 v[34:49], v[176:179], v[180:183], v[34:49]
	v_mfma_f32_32x32x16_bf16 v[50:65], v[176:179], v[192:195], v[50:65]
	v_mfma_f32_32x32x16_bf16 v[2:17], v[184:187], v[188:191], v[2:17]
	v_mfma_f32_32x32x16_bf16 v[18:33], v[184:187], v[196:199], v[18:33]
	s_waitcnt lgkmcnt(0)
	v_mfma_f32_32x32x16_bf16 v[34:49], v[200:203], v[188:191], v[34:49]
	ds_read_b128 v[176:179], v66 offset:64
	ds_read_b128 v[180:183], v67 offset:36928
	ds_read_b128 v[184:187], v66 offset:96
	ds_read_b128 v[188:191], v67 offset:36960
	v_mfma_f32_32x32x16_bf16 v[50:65], v[200:203], v[196:199], v[50:65]
	ds_read_b128 v[192:195], v67 offset:41536
	ds_read_b128 v[196:199], v67 offset:41568
	s_waitcnt lgkmcnt(4)
	v_mfma_f32_32x32x16_bf16 v[2:17], v[176:179], v[180:183], v[2:17]
	s_waitcnt lgkmcnt(1)
	v_mfma_f32_32x32x16_bf16 v[18:33], v[176:179], v[192:195], v[18:33]
	ds_read_b128 v[176:179], v66 offset:4672
	ds_read_b128 v[200:203], v66 offset:4704
	s_waitcnt vmcnt(13)
	ds_write_b128 v90, v[120:123] offset:18432
	ds_write_b128 v90, v[112:115] offset:23040
	ds_write_b128 v90, v[116:119] offset:27648
	s_waitcnt vmcnt(11)
	ds_write_b128 v90, v[128:131] offset:32256
	ds_write_b128 v90, v[124:127] offset:55296
	s_waitcnt vmcnt(10)
	ds_write_b128 v90, v[132:135] offset:59904
	s_waitcnt vmcnt(9)
	ds_write_b128 v90, v[136:139] offset:64512
	s_waitcnt vmcnt(8)
	ds_write_b128 v91, v[140:143] offset:32256
	s_waitcnt lgkmcnt(0)
	s_barrier
	global_load_dwordx4 v[112:115], v[78:79], off offset:1920
	s_nop 0
	global_load_dwordx4 v[78:81], v[80:81], off offset:1920
	s_nop 0
	global_load_dwordx4 v[116:119], v[74:75], off offset:1920
	s_nop 0
	global_load_dwordx4 v[74:77], v[76:77], off offset:1920
	s_nop 0
	global_load_dwordx4 v[120:123], v[82:83], off offset:1920
	s_nop 0
	global_load_dwordx4 v[82:85], v[84:85], off offset:1920
	s_nop 0
	global_load_dwordx4 v[124:127], v[86:87], off offset:1920
	s_nop 0
	global_load_dwordx4 v[86:89], v[88:89], off offset:1920
	v_mfma_f32_32x32x16_bf16 v[34:49], v[176:179], v[180:183], v[34:49]
	v_mfma_f32_32x32x16_bf16 v[50:65], v[176:179], v[192:195], v[50:65]
	v_mfma_f32_32x32x16_bf16 v[2:17], v[184:187], v[188:191], v[2:17]
	v_mfma_f32_32x32x16_bf16 v[18:33], v[184:187], v[196:199], v[18:33]
	v_mfma_f32_32x32x16_bf16 v[34:49], v[200:203], v[188:191], v[34:49]
	v_mfma_f32_32x32x16_bf16 v[50:65], v[200:203], v[196:199], v[50:65]
	ds_read_b128 v[128:131], v66 offset:18432
	ds_read_b128 v[132:135], v67 offset:55296
	ds_read_b128 v[136:139], v66 offset:18464
	ds_read_b128 v[140:143], v67 offset:55328
	ds_read_b128 v[176:179], v67 offset:59904
	ds_read_b128 v[180:183], v67 offset:59936
	s_waitcnt lgkmcnt(4)
	v_mfma_f32_32x32x16_bf16 v[2:17], v[128:131], v[132:135], v[2:17]
	s_waitcnt lgkmcnt(1)
	v_mfma_f32_32x32x16_bf16 v[18:33], v[128:131], v[176:179], v[18:33]
	ds_read_b128 v[128:131], v66 offset:23040
	ds_read_b128 v[184:187], v66 offset:23072
	s_waitcnt lgkmcnt(1)
	v_mfma_f32_32x32x16_bf16 v[34:49], v[128:131], v[132:135], v[34:49]
	v_mfma_f32_32x32x16_bf16 v[50:65], v[128:131], v[176:179], v[50:65]
	v_mfma_f32_32x32x16_bf16 v[2:17], v[136:139], v[140:143], v[2:17]
	v_mfma_f32_32x32x16_bf16 v[18:33], v[136:139], v[180:183], v[18:33]
	s_waitcnt lgkmcnt(0)
	v_mfma_f32_32x32x16_bf16 v[34:49], v[184:187], v[140:143], v[34:49]
	ds_read_b128 v[128:131], v66 offset:18496
	ds_read_b128 v[132:135], v67 offset:55360
	ds_read_b128 v[136:139], v66 offset:18528
	ds_read_b128 v[140:143], v67 offset:55392
	v_mfma_f32_32x32x16_bf16 v[50:65], v[184:187], v[180:183], v[50:65]
	ds_read_b128 v[176:179], v67 offset:59968
	ds_read_b128 v[180:183], v67 offset:60000
	s_waitcnt lgkmcnt(4)
	v_mfma_f32_32x32x16_bf16 v[2:17], v[128:131], v[132:135], v[2:17]
	s_waitcnt lgkmcnt(1)
	v_mfma_f32_32x32x16_bf16 v[18:33], v[128:131], v[176:179], v[18:33]
	ds_read_b128 v[128:131], v66 offset:23104
	ds_read_b128 v[184:187], v66 offset:23136
	s_waitcnt vmcnt(13)
	ds_write_b128 v90, v[152:155]
	ds_write_b128 v90, v[144:147] offset:4608
	ds_write_b128 v90, v[148:151] offset:9216
	s_waitcnt vmcnt(11)
	ds_write_b128 v90, v[160:163] offset:13824
	ds_write_b128 v90, v[156:159] offset:36864
	s_waitcnt vmcnt(10)
	ds_write_b128 v90, v[164:167] offset:41472
	s_waitcnt vmcnt(9)
	ds_write_b128 v90, v[168:171] offset:46080
	s_waitcnt vmcnt(8)
	ds_write_b128 v90, v[172:175] offset:50688
	s_waitcnt lgkmcnt(0)
	s_barrier
	v_mfma_f32_32x32x16_bf16 v[34:49], v[128:131], v[132:135], v[34:49]
	v_mfma_f32_32x32x16_bf16 v[50:65], v[128:131], v[176:179], v[50:65]
	v_mfma_f32_32x32x16_bf16 v[2:17], v[136:139], v[140:143], v[2:17]
	v_mfma_f32_32x32x16_bf16 v[18:33], v[136:139], v[180:183], v[18:33]
	v_mfma_f32_32x32x16_bf16 v[34:49], v[184:187], v[140:143], v[34:49]
	v_mfma_f32_32x32x16_bf16 v[50:65], v[184:187], v[180:183], v[50:65]
	ds_read_b128 v[128:131], v66
	ds_read_b128 v[132:135], v67 offset:36864
	ds_read_b128 v[136:139], v66 offset:32
	ds_read_b128 v[140:143], v67 offset:36896
	ds_read_b128 v[144:147], v67 offset:41472
	ds_read_b128 v[148:151], v67 offset:41504
	s_waitcnt lgkmcnt(4)
	v_mfma_f32_32x32x16_bf16 v[2:17], v[128:131], v[132:135], v[2:17]
	s_waitcnt lgkmcnt(1)
	v_mfma_f32_32x32x16_bf16 v[18:33], v[128:131], v[144:147], v[18:33]
	ds_read_b128 v[128:131], v66 offset:4608
	ds_read_b128 v[152:155], v66 offset:4640
	s_waitcnt lgkmcnt(1)
	v_mfma_f32_32x32x16_bf16 v[34:49], v[128:131], v[132:135], v[34:49]
	v_mfma_f32_32x32x16_bf16 v[50:65], v[128:131], v[144:147], v[50:65]
	v_mfma_f32_32x32x16_bf16 v[2:17], v[136:139], v[140:143], v[2:17]
	v_mfma_f32_32x32x16_bf16 v[18:33], v[136:139], v[148:151], v[18:33]
	s_waitcnt lgkmcnt(0)
	v_mfma_f32_32x32x16_bf16 v[34:49], v[152:155], v[140:143], v[34:49]
	ds_read_b128 v[128:131], v66 offset:64
	ds_read_b128 v[132:135], v67 offset:36928
	ds_read_b128 v[136:139], v66 offset:96
	ds_read_b128 v[140:143], v67 offset:36960
	v_mfma_f32_32x32x16_bf16 v[50:65], v[152:155], v[148:151], v[50:65]
	ds_read_b128 v[144:147], v67 offset:41536
	ds_read_b128 v[148:151], v67 offset:41568
	s_waitcnt lgkmcnt(4)
	v_mfma_f32_32x32x16_bf16 v[2:17], v[128:131], v[132:135], v[2:17]
	s_waitcnt lgkmcnt(1)
	v_mfma_f32_32x32x16_bf16 v[18:33], v[128:131], v[144:147], v[18:33]
	ds_read_b128 v[128:131], v66 offset:4672
	ds_read_b128 v[152:155], v66 offset:4704
	s_waitcnt vmcnt(5)
	ds_write_b128 v90, v[116:119] offset:18432
	ds_write_b128 v90, v[112:115] offset:23040
	ds_write_b128 v90, v[78:81] offset:27648
	s_waitcnt vmcnt(3)
	ds_write_b128 v90, v[120:123] offset:32256
	ds_write_b128 v90, v[74:77] offset:55296
	s_waitcnt vmcnt(2)
	ds_write_b128 v90, v[82:85] offset:59904
	s_waitcnt vmcnt(1)
	ds_write_b128 v90, v[124:127] offset:64512
	s_waitcnt vmcnt(0)
	ds_write_b128 v91, v[86:89] offset:32256
	s_waitcnt lgkmcnt(0)
	s_barrier
	v_mfma_f32_32x32x16_bf16 v[34:49], v[128:131], v[132:135], v[34:49]
	v_mfma_f32_32x32x16_bf16 v[50:65], v[128:131], v[144:147], v[50:65]
	v_mfma_f32_32x32x16_bf16 v[2:17], v[136:139], v[140:143], v[2:17]
	v_mfma_f32_32x32x16_bf16 v[18:33], v[136:139], v[148:151], v[18:33]
	v_mfma_f32_32x32x16_bf16 v[34:49], v[152:155], v[140:143], v[34:49]
	v_mfma_f32_32x32x16_bf16 v[50:65], v[152:155], v[148:151], v[50:65]
	ds_read_b128 v[74:77], v66 offset:18432
	ds_read_b128 v[78:81], v67 offset:55296
	ds_read_b128 v[82:85], v66 offset:18464
	ds_read_b128 v[86:89], v67 offset:55328
	ds_read_b128 v[112:115], v67 offset:59904
	ds_read_b128 v[116:119], v67 offset:59936
	s_and_b64 vcc, exec, s[4:5]
	s_waitcnt lgkmcnt(4)
	v_mfma_f32_32x32x16_bf16 v[2:17], v[74:77], v[78:81], v[2:17]
	s_waitcnt lgkmcnt(1)
	v_mfma_f32_32x32x16_bf16 v[18:33], v[74:77], v[112:115], v[18:33]
	ds_read_b128 v[74:77], v66 offset:23040
	ds_read_b128 v[120:123], v66 offset:23072
	s_waitcnt lgkmcnt(1)
	v_mfma_f32_32x32x16_bf16 v[34:49], v[74:77], v[78:81], v[34:49]
	v_mfma_f32_32x32x16_bf16 v[50:65], v[74:77], v[112:115], v[50:65]
	v_mfma_f32_32x32x16_bf16 v[2:17], v[82:85], v[86:89], v[2:17]
	v_mfma_f32_32x32x16_bf16 v[18:33], v[82:85], v[116:119], v[18:33]
	s_waitcnt lgkmcnt(0)
	v_mfma_f32_32x32x16_bf16 v[34:49], v[120:123], v[86:89], v[34:49]
	ds_read_b128 v[74:77], v66 offset:18496
	ds_read_b128 v[78:81], v67 offset:55360
	ds_read_b128 v[82:85], v66 offset:18528
	ds_read_b128 v[86:89], v67 offset:55392
	v_mfma_f32_32x32x16_bf16 v[50:65], v[120:123], v[116:119], v[50:65]
	ds_read_b128 v[112:115], v67 offset:59968
	ds_read_b128 v[116:119], v67 offset:60000
	s_waitcnt lgkmcnt(4)
	v_mfma_f32_32x32x16_bf16 v[2:17], v[74:77], v[78:81], v[2:17]
	s_waitcnt lgkmcnt(1)
	v_mfma_f32_32x32x16_bf16 v[18:33], v[74:77], v[112:115], v[18:33]
	ds_read_b128 v[74:77], v66 offset:23104
	ds_read_b128 v[120:123], v66 offset:23136
	s_waitcnt lgkmcnt(0)
	s_barrier
	v_mfma_f32_32x32x16_bf16 v[34:49], v[74:77], v[78:81], v[34:49]
	v_mfma_f32_32x32x16_bf16 v[50:65], v[74:77], v[112:115], v[50:65]
	v_mfma_f32_32x32x16_bf16 v[2:17], v[82:85], v[86:89], v[2:17]
	v_mfma_f32_32x32x16_bf16 v[18:33], v[82:85], v[116:119], v[18:33]
	v_mfma_f32_32x32x16_bf16 v[34:49], v[120:123], v[86:89], v[34:49]
	s_nop 10
	ds_write2_b32 v93, v2, v18 offset1:32
	v_mfma_f32_32x32x16_bf16 v[50:65], v[120:123], v[116:119], v[50:65]
	s_nop 11
	ds_write2_b32 v95, v34, v50 offset0:32 offset1:64
	ds_write2_b32 v93, v3, v19 offset0:129 offset1:161
	ds_write2_b32 v95, v35, v51 offset0:161 offset1:193
	ds_write2_b32 v96, v4, v20 offset0:2 offset1:34
	ds_write2_b32 v97, v36, v52 offset0:34 offset1:66
	ds_write2_b32 v96, v5, v21 offset0:131 offset1:163
	ds_write2_b32 v97, v37, v53 offset0:163 offset1:195
	ds_write2_b32 v98, v6, v22 offset0:8 offset1:40
	ds_write2_b32 v99, v38, v54 offset0:40 offset1:72
	ds_write2_b32 v98, v7, v23 offset0:137 offset1:169
	ds_write2_b32 v99, v39, v55 offset0:169 offset1:201
	ds_write2_b32 v100, v8, v24 offset0:10 offset1:42
	ds_write2_b32 v101, v40, v56 offset0:42 offset1:74
	ds_write2_b32 v100, v9, v25 offset0:139 offset1:171
	ds_write2_b32 v101, v41, v57 offset0:171 offset1:203
	ds_write2_b32 v102, v10, v26 offset0:16 offset1:48
	ds_write2_b32 v103, v42, v58 offset0:48 offset1:80
	ds_write2_b32 v102, v11, v27 offset0:145 offset1:177
	ds_write2_b32 v103, v43, v59 offset0:177 offset1:209
	ds_write2_b32 v104, v12, v28 offset0:18 offset1:50
	ds_write2_b32 v105, v44, v60 offset0:50 offset1:82
	ds_write2_b32 v104, v13, v29 offset0:147 offset1:179
	ds_write2_b32 v105, v45, v61 offset0:179 offset1:211
	ds_write2_b32 v106, v14, v30 offset0:24 offset1:56
	ds_write2_b32 v107, v46, v62 offset0:56 offset1:88
	ds_write2_b32 v106, v15, v31 offset0:153 offset1:185
	ds_write2_b32 v107, v47, v63 offset0:185 offset1:217
	ds_write2_b32 v108, v16, v32 offset0:26 offset1:58
	ds_write2_b32 v109, v48, v64 offset0:58 offset1:90
	ds_write2_b32 v108, v17, v33 offset0:155 offset1:187
	ds_write2_b32 v109, v49, v65 offset0:187 offset1:219
	v_or_b32_e32 v6, s14, v92
	v_lshlrev_b32_e32 v68, 2, v6
	s_waitcnt lgkmcnt(0)
	s_barrier
	s_lshl_b32 s12, s17, 7
	s_and_b32 s12, s12, 0xffffe000
	s_lshl_b32 s14, s18, 7
	s_or_b32 s12, s12, s23
	s_and_b32 s14, s14, 0x1c00
	s_or_b32 s12, s14, s12
	v_mov_b32_e32 v2, v6
	v_add_u32_e32 v3, s12, v1
	v_lshlrev_b32_e32 v64, 12, v3
	v_lshl_add_u32 v64, v2, 2, v64
	v_lshlrev_b32_e32 v74, 2, v2
	global_load_dwordx4 v[120:123], v74, s[50:51]
	global_load_dwordx4 v[4:7], v64, s[44:45]
	v_add_u32_e32 v74, 0x8000, v64
	global_load_dwordx4 v[8:11], v74, s[44:45]
	v_add_u32_e32 v65, 0x10000, v64
	global_load_dwordx4 v[12:15], v65, s[44:45]
	v_add_u32_e32 v74, 0x18000, v64
	global_load_dwordx4 v[16:19], v74, s[44:45]
	v_add_u32_e32 v65, 0x20000, v64
	global_load_dwordx4 v[20:23], v65, s[44:45]
	v_add_u32_e32 v74, 0x28000, v64
	global_load_dwordx4 v[24:27], v74, s[44:45]
	v_add_u32_e32 v65, 0x30000, v64
	global_load_dwordx4 v[28:31], v65, s[44:45]
	v_add_u32_e32 v74, 0x38000, v64
	global_load_dwordx4 v[32:35], v74, s[44:45]
	v_add_u32_e32 v65, 0x40000, v64
	global_load_dwordx4 v[36:39], v65, s[44:45]
	v_add_u32_e32 v74, 0x48000, v64
	global_load_dwordx4 v[40:43], v74, s[44:45]
	v_add_u32_e32 v65, 0x50000, v64
	global_load_dwordx4 v[44:47], v65, s[44:45]
	v_add_u32_e32 v74, 0x58000, v64
	global_load_dwordx4 v[48:51], v74, s[44:45]
	v_add_u32_e32 v65, 0x60000, v64
	global_load_dwordx4 v[52:55], v65, s[44:45]
	v_add_u32_e32 v74, 0x68000, v64
	global_load_dwordx4 v[56:59], v74, s[44:45]
	v_add_u32_e32 v65, 0x70000, v64
	global_load_dwordx4 v[60:63], v65, s[44:45]
	v_add_u32_e32 v74, 0x78000, v64
	global_load_dwordx4 v[76:79], v74, s[44:45]
	v_and_b32_e32 v75, 7, v3
	v_mul_u32_u24_e32 v75, 0x204, v75
	v_and_b32_e32 v88, 0x7f, v2
	v_lshl_add_u32 v75, v88, 2, v75
	v_lshlrev_b32_e32 v156, 2, v3
	s_movk_i32 s14, 0x7fff
	v_mov_b32_e32 v157, 1
	ds_read2_b32 v[80:81], v75 offset1:1
	ds_read2_b32 v[82:83], v75 offset0:2 offset1:3
	v_add_u32_e32 v89, 0x1020, v75
	ds_read2_b32 v[84:85], v89 offset1:1
	ds_read2_b32 v[86:87], v89 offset0:2 offset1:3
	v_add_u32_e32 v88, 0x2040, v75
	ds_read2_b32 v[112:113], v88 offset1:1
	ds_read2_b32 v[114:115], v88 offset0:2 offset1:3
	v_add_u32_e32 v89, 0x3060, v75
	ds_read2_b32 v[116:117], v89 offset1:1
	ds_read2_b32 v[118:119], v89 offset0:2 offset1:3
	s_waitcnt vmcnt(15) lgkmcnt(6)
	v_pk_add_f32 v[4:5], v[4:5], v[80:81]
	v_pk_add_f32 v[6:7], v[6:7], v[82:83]
	s_waitcnt vmcnt(14) lgkmcnt(4)
	v_pk_add_f32 v[8:9], v[8:9], v[84:85]
	v_pk_add_f32 v[10:11], v[10:11], v[86:87]
	s_waitcnt vmcnt(13) lgkmcnt(2)
	v_pk_add_f32 v[12:13], v[12:13], v[112:113]
	v_pk_add_f32 v[14:15], v[14:15], v[114:115]
	s_waitcnt vmcnt(12) lgkmcnt(0)
	v_pk_add_f32 v[16:17], v[16:17], v[116:117]
	v_pk_add_f32 v[18:19], v[18:19], v[118:119]
	v_add_u32_e32 v88, 0x4080, v75
	ds_read2_b32 v[80:81], v88 offset1:1
	ds_read2_b32 v[82:83], v88 offset0:2 offset1:3
	v_add_u32_e32 v89, 0x50a0, v75
	ds_read2_b32 v[84:85], v89 offset1:1
	ds_read2_b32 v[86:87], v89 offset0:2 offset1:3
	v_add_u32_e32 v88, 0x60c0, v75
	ds_read2_b32 v[112:113], v88 offset1:1
	ds_read2_b32 v[114:115], v88 offset0:2 offset1:3
	v_add_u32_e32 v89, 0x70e0, v75
	ds_read2_b32 v[116:117], v89 offset1:1
	ds_read2_b32 v[118:119], v89 offset0:2 offset1:3
	global_store_dwordx4 v64, v[4:7], s[80:81]
	v_pk_mul_f32 v[140:141], v[4:5], v[4:5]
	v_pk_mul_f32 v[142:143], v[6:7], v[6:7]
	v_pk_mul_f32 v[144:145], v[4:5], v[120:121]
	v_pk_mul_f32 v[146:147], v[6:7], v[122:123]
	v_lshrrev_b32_e32 v158, 1, v64
	v_add_f32_e32 v124, v140, v141
	v_and_b32_sdwa v148, v144, v157 dst_sel:DWORD dst_unused:UNUSED_PAD src0_sel:WORD_1 src1_sel:DWORD
	v_and_b32_sdwa v149, v145, v157 dst_sel:DWORD dst_unused:UNUSED_PAD src0_sel:WORD_1 src1_sel:DWORD
	v_and_b32_sdwa v150, v146, v157 dst_sel:DWORD dst_unused:UNUSED_PAD src0_sel:WORD_1 src1_sel:DWORD
	v_and_b32_sdwa v151, v147, v157 dst_sel:DWORD dst_unused:UNUSED_PAD src0_sel:WORD_1 src1_sel:DWORD
	v_add_f32_e32 v124, v124, v142
	v_add3_u32 v144, v144, v148, s14
	v_add3_u32 v145, v145, v149, s14
	v_add3_u32 v146, v146, v150, s14
	v_add3_u32 v147, v147, v151, s14
	v_add_f32_e32 v124, v124, v143
	v_and_b32_e32 v145, 0xffff0000, v145
	v_and_b32_e32 v147, 0xffff0000, v147
	s_nop 0
	v_or_b32_sdwa v152, v145, v144 dst_sel:DWORD dst_unused:UNUSED_PAD src0_sel:DWORD src1_sel:WORD_1
	v_or_b32_sdwa v153, v147, v146 dst_sel:DWORD dst_unused:UNUSED_PAD src0_sel:DWORD src1_sel:WORD_1
	global_store_dwordx2 v158, v[152:153], s[92:93]
	v_add_u32_e32 v74, 0x8000, v64
	global_store_dwordx4 v74, v[8:11], s[80:81]
	v_pk_mul_f32 v[140:141], v[8:9], v[8:9]
	v_pk_mul_f32 v[142:143], v[10:11], v[10:11]
	v_pk_mul_f32 v[144:145], v[8:9], v[120:121]
	v_pk_mul_f32 v[146:147], v[10:11], v[122:123]
	v_lshrrev_b32_e32 v159, 1, v74
	v_add_f32_e32 v125, v140, v141
	v_and_b32_sdwa v148, v144, v157 dst_sel:DWORD dst_unused:UNUSED_PAD src0_sel:WORD_1 src1_sel:DWORD
	v_and_b32_sdwa v149, v145, v157 dst_sel:DWORD dst_unused:UNUSED_PAD src0_sel:WORD_1 src1_sel:DWORD
	v_and_b32_sdwa v150, v146, v157 dst_sel:DWORD dst_unused:UNUSED_PAD src0_sel:WORD_1 src1_sel:DWORD
	v_and_b32_sdwa v151, v147, v157 dst_sel:DWORD dst_unused:UNUSED_PAD src0_sel:WORD_1 src1_sel:DWORD
	v_add_f32_e32 v125, v125, v142
	v_add3_u32 v144, v144, v148, s14
	v_add3_u32 v145, v145, v149, s14
	v_add3_u32 v146, v146, v150, s14
	v_add3_u32 v147, v147, v151, s14
	v_add_f32_e32 v125, v125, v143
	v_and_b32_e32 v145, 0xffff0000, v145
	v_and_b32_e32 v147, 0xffff0000, v147
	s_nop 0
	v_or_b32_sdwa v154, v145, v144 dst_sel:DWORD dst_unused:UNUSED_PAD src0_sel:DWORD src1_sel:WORD_1
	v_or_b32_sdwa v155, v147, v146 dst_sel:DWORD dst_unused:UNUSED_PAD src0_sel:DWORD src1_sel:WORD_1
	global_store_dwordx2 v159, v[154:155], s[92:93]
	v_add_u32_e32 v65, 0x10000, v64
	global_store_dwordx4 v65, v[12:15], s[80:81]
	v_pk_mul_f32 v[140:141], v[12:13], v[12:13]
	v_pk_mul_f32 v[142:143], v[14:15], v[14:15]
	v_pk_mul_f32 v[144:145], v[12:13], v[120:121]
	v_pk_mul_f32 v[146:147], v[14:15], v[122:123]
	v_lshrrev_b32_e32 v158, 1, v65
	v_add_f32_e32 v126, v140, v141
	v_and_b32_sdwa v148, v144, v157 dst_sel:DWORD dst_unused:UNUSED_PAD src0_sel:WORD_1 src1_sel:DWORD
	v_and_b32_sdwa v149, v145, v157 dst_sel:DWORD dst_unused:UNUSED_PAD src0_sel:WORD_1 src1_sel:DWORD
	v_and_b32_sdwa v150, v146, v157 dst_sel:DWORD dst_unused:UNUSED_PAD src0_sel:WORD_1 src1_sel:DWORD
	v_and_b32_sdwa v151, v147, v157 dst_sel:DWORD dst_unused:UNUSED_PAD src0_sel:WORD_1 src1_sel:DWORD
	v_add_f32_e32 v126, v126, v142
	v_add3_u32 v144, v144, v148, s14
	v_add3_u32 v145, v145, v149, s14
	v_add3_u32 v146, v146, v150, s14
	v_add3_u32 v147, v147, v151, s14
	v_add_f32_e32 v126, v126, v143
	v_and_b32_e32 v145, 0xffff0000, v145
	v_and_b32_e32 v147, 0xffff0000, v147
	s_nop 0
	v_or_b32_sdwa v152, v145, v144 dst_sel:DWORD dst_unused:UNUSED_PAD src0_sel:DWORD src1_sel:WORD_1
	v_or_b32_sdwa v153, v147, v146 dst_sel:DWORD dst_unused:UNUSED_PAD src0_sel:DWORD src1_sel:WORD_1
	global_store_dwordx2 v158, v[152:153], s[92:93]
	v_add_u32_e32 v74, 0x18000, v64
	global_store_dwordx4 v74, v[16:19], s[80:81]
	v_pk_mul_f32 v[140:141], v[16:17], v[16:17]
	v_pk_mul_f32 v[142:143], v[18:19], v[18:19]
	v_pk_mul_f32 v[144:145], v[16:17], v[120:121]
	v_pk_mul_f32 v[146:147], v[18:19], v[122:123]
	v_lshrrev_b32_e32 v159, 1, v74
	v_add_f32_e32 v127, v140, v141
	v_and_b32_sdwa v148, v144, v157 dst_sel:DWORD dst_unused:UNUSED_PAD src0_sel:WORD_1 src1_sel:DWORD
	v_and_b32_sdwa v149, v145, v157 dst_sel:DWORD dst_unused:UNUSED_PAD src0_sel:WORD_1 src1_sel:DWORD
	v_and_b32_sdwa v150, v146, v157 dst_sel:DWORD dst_unused:UNUSED_PAD src0_sel:WORD_1 src1_sel:DWORD
	v_and_b32_sdwa v151, v147, v157 dst_sel:DWORD dst_unused:UNUSED_PAD src0_sel:WORD_1 src1_sel:DWORD
	v_add_f32_e32 v127, v127, v142
	v_add3_u32 v144, v144, v148, s14
	v_add3_u32 v145, v145, v149, s14
	v_add3_u32 v146, v146, v150, s14
	v_add3_u32 v147, v147, v151, s14
	v_add_f32_e32 v127, v127, v143
	v_and_b32_e32 v145, 0xffff0000, v145
	v_and_b32_e32 v147, 0xffff0000, v147
	s_nop 0
	v_or_b32_sdwa v154, v145, v144 dst_sel:DWORD dst_unused:UNUSED_PAD src0_sel:DWORD src1_sel:WORD_1
	v_or_b32_sdwa v155, v147, v146 dst_sel:DWORD dst_unused:UNUSED_PAD src0_sel:DWORD src1_sel:WORD_1
	global_store_dwordx2 v159, v[154:155], s[92:93]
	s_nop 1
	v_add_f32_dpp v124, v124, v124 quad_perm:[1,0,3,2] row_mask:0xf bank_mask:0xf
	v_add_f32_dpp v125, v125, v125 quad_perm:[1,0,3,2] row_mask:0xf bank_mask:0xf
	v_add_f32_dpp v126, v126, v126 quad_perm:[1,0,3,2] row_mask:0xf bank_mask:0xf
	v_add_f32_dpp v127, v127, v127 quad_perm:[1,0,3,2] row_mask:0xf bank_mask:0xf
	v_add_f32_dpp v124, v124, v124 quad_perm:[2,3,0,1] row_mask:0xf bank_mask:0xf
	v_add_f32_dpp v125, v125, v125 quad_perm:[2,3,0,1] row_mask:0xf bank_mask:0xf
	v_add_f32_dpp v126, v126, v126 quad_perm:[2,3,0,1] row_mask:0xf bank_mask:0xf
	v_add_f32_dpp v127, v127, v127 quad_perm:[2,3,0,1] row_mask:0xf bank_mask:0xf
	v_add_f32_dpp v124, v124, v124 row_half_mirror row_mask:0xf bank_mask:0xf
	v_add_f32_dpp v125, v125, v125 row_half_mirror row_mask:0xf bank_mask:0xf
	v_add_f32_dpp v126, v126, v126 row_half_mirror row_mask:0xf bank_mask:0xf
	v_add_f32_dpp v127, v127, v127 row_half_mirror row_mask:0xf bank_mask:0xf
	v_add_f32_dpp v124, v124, v124 row_mirror row_mask:0xf bank_mask:0xf
	v_add_f32_dpp v125, v125, v125 row_mirror row_mask:0xf bank_mask:0xf
	v_add_f32_dpp v126, v126, v126 row_mirror row_mask:0xf bank_mask:0xf
	v_add_f32_dpp v127, v127, v127 row_mirror row_mask:0xf bank_mask:0xf
	v_add_f32_dpp v124, v124, v124 row_bcast:15 row_mask:0xa bank_mask:0xf
	v_add_f32_dpp v125, v125, v125 row_bcast:15 row_mask:0xa bank_mask:0xf
	v_add_f32_dpp v126, v126, v126 row_bcast:15 row_mask:0xa bank_mask:0xf
	v_add_f32_dpp v127, v127, v127 row_bcast:15 row_mask:0xa bank_mask:0xf
	s_waitcnt vmcnt(19) lgkmcnt(6)
	v_pk_add_f32 v[20:21], v[20:21], v[80:81]
	v_pk_add_f32 v[22:23], v[22:23], v[82:83]
	s_waitcnt vmcnt(18) lgkmcnt(4)
	v_pk_add_f32 v[24:25], v[24:25], v[84:85]
	v_pk_add_f32 v[26:27], v[26:27], v[86:87]
	s_waitcnt vmcnt(17) lgkmcnt(2)
	v_pk_add_f32 v[28:29], v[28:29], v[112:113]
	v_pk_add_f32 v[30:31], v[30:31], v[114:115]
	s_waitcnt vmcnt(16) lgkmcnt(0)
	v_pk_add_f32 v[32:33], v[32:33], v[116:117]
	v_pk_add_f32 v[34:35], v[34:35], v[118:119]
	v_add_u32_e32 v88, 0x8100, v75
	ds_read2_b32 v[80:81], v88 offset1:1
	ds_read2_b32 v[82:83], v88 offset0:2 offset1:3
	v_add_u32_e32 v89, 0x9120, v75
	ds_read2_b32 v[84:85], v89 offset1:1
	ds_read2_b32 v[86:87], v89 offset0:2 offset1:3
	v_add_u32_e32 v88, 0xa140, v75
	ds_read2_b32 v[112:113], v88 offset1:1
	ds_read2_b32 v[114:115], v88 offset0:2 offset1:3
	v_add_u32_e32 v89, 0xb160, v75
	ds_read2_b32 v[116:117], v89 offset1:1
	ds_read2_b32 v[118:119], v89 offset0:2 offset1:3
	v_add_u32_e32 v65, 0x20000, v64
	global_store_dwordx4 v65, v[20:23], s[80:81]
	v_pk_mul_f32 v[140:141], v[20:21], v[20:21]
	v_pk_mul_f32 v[142:143], v[22:23], v[22:23]
	v_pk_mul_f32 v[144:145], v[20:21], v[120:121]
	v_pk_mul_f32 v[146:147], v[22:23], v[122:123]
	v_lshrrev_b32_e32 v158, 1, v65
	v_add_f32_e32 v128, v140, v141
	v_and_b32_sdwa v148, v144, v157 dst_sel:DWORD dst_unused:UNUSED_PAD src0_sel:WORD_1 src1_sel:DWORD
	v_and_b32_sdwa v149, v145, v157 dst_sel:DWORD dst_unused:UNUSED_PAD src0_sel:WORD_1 src1_sel:DWORD
	v_and_b32_sdwa v150, v146, v157 dst_sel:DWORD dst_unused:UNUSED_PAD src0_sel:WORD_1 src1_sel:DWORD
	v_and_b32_sdwa v151, v147, v157 dst_sel:DWORD dst_unused:UNUSED_PAD src0_sel:WORD_1 src1_sel:DWORD
	v_add_f32_e32 v128, v128, v142
	v_add3_u32 v144, v144, v148, s14
	v_add3_u32 v145, v145, v149, s14
	v_add3_u32 v146, v146, v150, s14
	v_add3_u32 v147, v147, v151, s14
	v_add_f32_e32 v128, v128, v143
	v_and_b32_e32 v145, 0xffff0000, v145
	v_and_b32_e32 v147, 0xffff0000, v147
	s_nop 0
	v_or_b32_sdwa v152, v145, v144 dst_sel:DWORD dst_unused:UNUSED_PAD src0_sel:DWORD src1_sel:WORD_1
	v_or_b32_sdwa v153, v147, v146 dst_sel:DWORD dst_unused:UNUSED_PAD src0_sel:DWORD src1_sel:WORD_1
	global_store_dwordx2 v158, v[152:153], s[92:93]
	v_add_u32_e32 v74, 0x28000, v64
	global_store_dwordx4 v74, v[24:27], s[80:81]
	v_pk_mul_f32 v[140:141], v[24:25], v[24:25]
	v_pk_mul_f32 v[142:143], v[26:27], v[26:27]
	v_pk_mul_f32 v[144:145], v[24:25], v[120:121]
	v_pk_mul_f32 v[146:147], v[26:27], v[122:123]
	v_lshrrev_b32_e32 v159, 1, v74
	v_add_f32_e32 v129, v140, v141
	v_and_b32_sdwa v148, v144, v157 dst_sel:DWORD dst_unused:UNUSED_PAD src0_sel:WORD_1 src1_sel:DWORD
	v_and_b32_sdwa v149, v145, v157 dst_sel:DWORD dst_unused:UNUSED_PAD src0_sel:WORD_1 src1_sel:DWORD
	v_and_b32_sdwa v150, v146, v157 dst_sel:DWORD dst_unused:UNUSED_PAD src0_sel:WORD_1 src1_sel:DWORD
	v_and_b32_sdwa v151, v147, v157 dst_sel:DWORD dst_unused:UNUSED_PAD src0_sel:WORD_1 src1_sel:DWORD
	v_add_f32_e32 v129, v129, v142
	v_add3_u32 v144, v144, v148, s14
	v_add3_u32 v145, v145, v149, s14
	v_add3_u32 v146, v146, v150, s14
	v_add3_u32 v147, v147, v151, s14
	v_add_f32_e32 v129, v129, v143
	v_and_b32_e32 v145, 0xffff0000, v145
	v_and_b32_e32 v147, 0xffff0000, v147
	s_nop 0
	v_or_b32_sdwa v154, v145, v144 dst_sel:DWORD dst_unused:UNUSED_PAD src0_sel:DWORD src1_sel:WORD_1
	v_or_b32_sdwa v155, v147, v146 dst_sel:DWORD dst_unused:UNUSED_PAD src0_sel:DWORD src1_sel:WORD_1
	global_store_dwordx2 v159, v[154:155], s[92:93]
	v_add_u32_e32 v65, 0x30000, v64
	global_store_dwordx4 v65, v[28:31], s[80:81]
	v_pk_mul_f32 v[140:141], v[28:29], v[28:29]
	v_pk_mul_f32 v[142:143], v[30:31], v[30:31]
	v_pk_mul_f32 v[144:145], v[28:29], v[120:121]
	v_pk_mul_f32 v[146:147], v[30:31], v[122:123]
	v_lshrrev_b32_e32 v158, 1, v65
	v_add_f32_e32 v130, v140, v141
	v_and_b32_sdwa v148, v144, v157 dst_sel:DWORD dst_unused:UNUSED_PAD src0_sel:WORD_1 src1_sel:DWORD
	v_and_b32_sdwa v149, v145, v157 dst_sel:DWORD dst_unused:UNUSED_PAD src0_sel:WORD_1 src1_sel:DWORD
	v_and_b32_sdwa v150, v146, v157 dst_sel:DWORD dst_unused:UNUSED_PAD src0_sel:WORD_1 src1_sel:DWORD
	v_and_b32_sdwa v151, v147, v157 dst_sel:DWORD dst_unused:UNUSED_PAD src0_sel:WORD_1 src1_sel:DWORD
	v_add_f32_e32 v130, v130, v142
	v_add3_u32 v144, v144, v148, s14
	v_add3_u32 v145, v145, v149, s14
	v_add3_u32 v146, v146, v150, s14
	v_add3_u32 v147, v147, v151, s14
	v_add_f32_e32 v130, v130, v143
	v_and_b32_e32 v145, 0xffff0000, v145
	v_and_b32_e32 v147, 0xffff0000, v147
	s_nop 0
	v_or_b32_sdwa v152, v145, v144 dst_sel:DWORD dst_unused:UNUSED_PAD src0_sel:DWORD src1_sel:WORD_1
	v_or_b32_sdwa v153, v147, v146 dst_sel:DWORD dst_unused:UNUSED_PAD src0_sel:DWORD src1_sel:WORD_1
	global_store_dwordx2 v158, v[152:153], s[92:93]
	v_add_u32_e32 v74, 0x38000, v64
	global_store_dwordx4 v74, v[32:35], s[80:81]
	v_pk_mul_f32 v[140:141], v[32:33], v[32:33]
	v_pk_mul_f32 v[142:143], v[34:35], v[34:35]
	v_pk_mul_f32 v[144:145], v[32:33], v[120:121]
	v_pk_mul_f32 v[146:147], v[34:35], v[122:123]
	v_lshrrev_b32_e32 v159, 1, v74
	v_add_f32_e32 v131, v140, v141
	v_and_b32_sdwa v148, v144, v157 dst_sel:DWORD dst_unused:UNUSED_PAD src0_sel:WORD_1 src1_sel:DWORD
	v_and_b32_sdwa v149, v145, v157 dst_sel:DWORD dst_unused:UNUSED_PAD src0_sel:WORD_1 src1_sel:DWORD
	v_and_b32_sdwa v150, v146, v157 dst_sel:DWORD dst_unused:UNUSED_PAD src0_sel:WORD_1 src1_sel:DWORD
	v_and_b32_sdwa v151, v147, v157 dst_sel:DWORD dst_unused:UNUSED_PAD src0_sel:WORD_1 src1_sel:DWORD
	v_add_f32_e32 v131, v131, v142
	v_add3_u32 v144, v144, v148, s14
	v_add3_u32 v145, v145, v149, s14
	v_add3_u32 v146, v146, v150, s14
	v_add3_u32 v147, v147, v151, s14
	v_add_f32_e32 v131, v131, v143
	v_and_b32_e32 v145, 0xffff0000, v145
	v_and_b32_e32 v147, 0xffff0000, v147
	s_nop 0
	v_or_b32_sdwa v154, v145, v144 dst_sel:DWORD dst_unused:UNUSED_PAD src0_sel:DWORD src1_sel:WORD_1
	v_or_b32_sdwa v155, v147, v146 dst_sel:DWORD dst_unused:UNUSED_PAD src0_sel:DWORD src1_sel:WORD_1
	global_store_dwordx2 v159, v[154:155], s[92:93]
	s_nop 1
	v_add_f32_dpp v128, v128, v128 quad_perm:[1,0,3,2] row_mask:0xf bank_mask:0xf
	v_add_f32_dpp v129, v129, v129 quad_perm:[1,0,3,2] row_mask:0xf bank_mask:0xf
	v_add_f32_dpp v130, v130, v130 quad_perm:[1,0,3,2] row_mask:0xf bank_mask:0xf
	v_add_f32_dpp v131, v131, v131 quad_perm:[1,0,3,2] row_mask:0xf bank_mask:0xf
	v_add_f32_dpp v128, v128, v128 quad_perm:[2,3,0,1] row_mask:0xf bank_mask:0xf
	v_add_f32_dpp v129, v129, v129 quad_perm:[2,3,0,1] row_mask:0xf bank_mask:0xf
	v_add_f32_dpp v130, v130, v130 quad_perm:[2,3,0,1] row_mask:0xf bank_mask:0xf
	v_add_f32_dpp v131, v131, v131 quad_perm:[2,3,0,1] row_mask:0xf bank_mask:0xf
	v_add_f32_dpp v128, v128, v128 row_half_mirror row_mask:0xf bank_mask:0xf
	v_add_f32_dpp v129, v129, v129 row_half_mirror row_mask:0xf bank_mask:0xf
	v_add_f32_dpp v130, v130, v130 row_half_mirror row_mask:0xf bank_mask:0xf
	v_add_f32_dpp v131, v131, v131 row_half_mirror row_mask:0xf bank_mask:0xf
	v_add_f32_dpp v128, v128, v128 row_mirror row_mask:0xf bank_mask:0xf
	v_add_f32_dpp v129, v129, v129 row_mirror row_mask:0xf bank_mask:0xf
	v_add_f32_dpp v130, v130, v130 row_mirror row_mask:0xf bank_mask:0xf
	v_add_f32_dpp v131, v131, v131 row_mirror row_mask:0xf bank_mask:0xf
	v_add_f32_dpp v128, v128, v128 row_bcast:15 row_mask:0xa bank_mask:0xf
	v_add_f32_dpp v129, v129, v129 row_bcast:15 row_mask:0xa bank_mask:0xf
	v_add_f32_dpp v130, v130, v130 row_bcast:15 row_mask:0xa bank_mask:0xf
	v_add_f32_dpp v131, v131, v131 row_bcast:15 row_mask:0xa bank_mask:0xf
	s_waitcnt vmcnt(23) lgkmcnt(6)
	v_pk_add_f32 v[36:37], v[36:37], v[80:81]
	v_pk_add_f32 v[38:39], v[38:39], v[82:83]
	s_waitcnt vmcnt(22) lgkmcnt(4)
	v_pk_add_f32 v[40:41], v[40:41], v[84:85]
	v_pk_add_f32 v[42:43], v[42:43], v[86:87]
	s_waitcnt vmcnt(21) lgkmcnt(2)
	v_pk_add_f32 v[44:45], v[44:45], v[112:113]
	v_pk_add_f32 v[46:47], v[46:47], v[114:115]
	s_waitcnt vmcnt(20) lgkmcnt(0)
	v_pk_add_f32 v[48:49], v[48:49], v[116:117]
	v_pk_add_f32 v[50:51], v[50:51], v[118:119]
	v_add_u32_e32 v88, 0xc180, v75
	ds_read2_b32 v[80:81], v88 offset1:1
	ds_read2_b32 v[82:83], v88 offset0:2 offset1:3
	v_add_u32_e32 v89, 0xd1a0, v75
	ds_read2_b32 v[84:85], v89 offset1:1
	ds_read2_b32 v[86:87], v89 offset0:2 offset1:3
	v_add_u32_e32 v88, 0xe1c0, v75
	ds_read2_b32 v[112:113], v88 offset1:1
	ds_read2_b32 v[114:115], v88 offset0:2 offset1:3
	v_add_u32_e32 v89, 0xf1e0, v75
	ds_read2_b32 v[116:117], v89 offset1:1
	ds_read2_b32 v[118:119], v89 offset0:2 offset1:3
	v_add_u32_e32 v65, 0x40000, v64
	global_store_dwordx4 v65, v[36:39], s[80:81]
	v_pk_mul_f32 v[140:141], v[36:37], v[36:37]
	v_pk_mul_f32 v[142:143], v[38:39], v[38:39]
	v_pk_mul_f32 v[144:145], v[36:37], v[120:121]
	v_pk_mul_f32 v[146:147], v[38:39], v[122:123]
	v_lshrrev_b32_e32 v158, 1, v65
	v_add_f32_e32 v132, v140, v141
	v_and_b32_sdwa v148, v144, v157 dst_sel:DWORD dst_unused:UNUSED_PAD src0_sel:WORD_1 src1_sel:DWORD
	v_and_b32_sdwa v149, v145, v157 dst_sel:DWORD dst_unused:UNUSED_PAD src0_sel:WORD_1 src1_sel:DWORD
	v_and_b32_sdwa v150, v146, v157 dst_sel:DWORD dst_unused:UNUSED_PAD src0_sel:WORD_1 src1_sel:DWORD
	v_and_b32_sdwa v151, v147, v157 dst_sel:DWORD dst_unused:UNUSED_PAD src0_sel:WORD_1 src1_sel:DWORD
	v_add_f32_e32 v132, v132, v142
	v_add3_u32 v144, v144, v148, s14
	v_add3_u32 v145, v145, v149, s14
	v_add3_u32 v146, v146, v150, s14
	v_add3_u32 v147, v147, v151, s14
	v_add_f32_e32 v132, v132, v143
	v_and_b32_e32 v145, 0xffff0000, v145
	v_and_b32_e32 v147, 0xffff0000, v147
	s_nop 0
	v_or_b32_sdwa v152, v145, v144 dst_sel:DWORD dst_unused:UNUSED_PAD src0_sel:DWORD src1_sel:WORD_1
	v_or_b32_sdwa v153, v147, v146 dst_sel:DWORD dst_unused:UNUSED_PAD src0_sel:DWORD src1_sel:WORD_1
	global_store_dwordx2 v158, v[152:153], s[92:93]
	v_add_u32_e32 v74, 0x48000, v64
	global_store_dwordx4 v74, v[40:43], s[80:81]
	v_pk_mul_f32 v[140:141], v[40:41], v[40:41]
	v_pk_mul_f32 v[142:143], v[42:43], v[42:43]
	v_pk_mul_f32 v[144:145], v[40:41], v[120:121]
	v_pk_mul_f32 v[146:147], v[42:43], v[122:123]
	v_lshrrev_b32_e32 v159, 1, v74
	v_add_f32_e32 v133, v140, v141
	v_and_b32_sdwa v148, v144, v157 dst_sel:DWORD dst_unused:UNUSED_PAD src0_sel:WORD_1 src1_sel:DWORD
	v_and_b32_sdwa v149, v145, v157 dst_sel:DWORD dst_unused:UNUSED_PAD src0_sel:WORD_1 src1_sel:DWORD
	v_and_b32_sdwa v150, v146, v157 dst_sel:DWORD dst_unused:UNUSED_PAD src0_sel:WORD_1 src1_sel:DWORD
	v_and_b32_sdwa v151, v147, v157 dst_sel:DWORD dst_unused:UNUSED_PAD src0_sel:WORD_1 src1_sel:DWORD
	v_add_f32_e32 v133, v133, v142
	v_add3_u32 v144, v144, v148, s14
	v_add3_u32 v145, v145, v149, s14
	v_add3_u32 v146, v146, v150, s14
	v_add3_u32 v147, v147, v151, s14
	v_add_f32_e32 v133, v133, v143
	v_and_b32_e32 v145, 0xffff0000, v145
	v_and_b32_e32 v147, 0xffff0000, v147
	s_nop 0
	v_or_b32_sdwa v154, v145, v144 dst_sel:DWORD dst_unused:UNUSED_PAD src0_sel:DWORD src1_sel:WORD_1
	v_or_b32_sdwa v155, v147, v146 dst_sel:DWORD dst_unused:UNUSED_PAD src0_sel:DWORD src1_sel:WORD_1
	global_store_dwordx2 v159, v[154:155], s[92:93]
	v_add_u32_e32 v65, 0x50000, v64
	global_store_dwordx4 v65, v[44:47], s[80:81]
	v_pk_mul_f32 v[140:141], v[44:45], v[44:45]
	v_pk_mul_f32 v[142:143], v[46:47], v[46:47]
	v_pk_mul_f32 v[144:145], v[44:45], v[120:121]
	v_pk_mul_f32 v[146:147], v[46:47], v[122:123]
	v_lshrrev_b32_e32 v158, 1, v65
	v_add_f32_e32 v134, v140, v141
	v_and_b32_sdwa v148, v144, v157 dst_sel:DWORD dst_unused:UNUSED_PAD src0_sel:WORD_1 src1_sel:DWORD
	v_and_b32_sdwa v149, v145, v157 dst_sel:DWORD dst_unused:UNUSED_PAD src0_sel:WORD_1 src1_sel:DWORD
	v_and_b32_sdwa v150, v146, v157 dst_sel:DWORD dst_unused:UNUSED_PAD src0_sel:WORD_1 src1_sel:DWORD
	v_and_b32_sdwa v151, v147, v157 dst_sel:DWORD dst_unused:UNUSED_PAD src0_sel:WORD_1 src1_sel:DWORD
	v_add_f32_e32 v134, v134, v142
	v_add3_u32 v144, v144, v148, s14
	v_add3_u32 v145, v145, v149, s14
	v_add3_u32 v146, v146, v150, s14
	v_add3_u32 v147, v147, v151, s14
	v_add_f32_e32 v134, v134, v143
	v_and_b32_e32 v145, 0xffff0000, v145
	v_and_b32_e32 v147, 0xffff0000, v147
	s_nop 0
	v_or_b32_sdwa v152, v145, v144 dst_sel:DWORD dst_unused:UNUSED_PAD src0_sel:DWORD src1_sel:WORD_1
	v_or_b32_sdwa v153, v147, v146 dst_sel:DWORD dst_unused:UNUSED_PAD src0_sel:DWORD src1_sel:WORD_1
	global_store_dwordx2 v158, v[152:153], s[92:93]
	v_add_u32_e32 v74, 0x58000, v64
	global_store_dwordx4 v74, v[48:51], s[80:81]
	v_pk_mul_f32 v[140:141], v[48:49], v[48:49]
	v_pk_mul_f32 v[142:143], v[50:51], v[50:51]
	v_pk_mul_f32 v[144:145], v[48:49], v[120:121]
	v_pk_mul_f32 v[146:147], v[50:51], v[122:123]
	v_lshrrev_b32_e32 v159, 1, v74
	v_add_f32_e32 v135, v140, v141
	v_and_b32_sdwa v148, v144, v157 dst_sel:DWORD dst_unused:UNUSED_PAD src0_sel:WORD_1 src1_sel:DWORD
	v_and_b32_sdwa v149, v145, v157 dst_sel:DWORD dst_unused:UNUSED_PAD src0_sel:WORD_1 src1_sel:DWORD
	v_and_b32_sdwa v150, v146, v157 dst_sel:DWORD dst_unused:UNUSED_PAD src0_sel:WORD_1 src1_sel:DWORD
	v_and_b32_sdwa v151, v147, v157 dst_sel:DWORD dst_unused:UNUSED_PAD src0_sel:WORD_1 src1_sel:DWORD
	v_add_f32_e32 v135, v135, v142
	v_add3_u32 v144, v144, v148, s14
	v_add3_u32 v145, v145, v149, s14
	v_add3_u32 v146, v146, v150, s14
	v_add3_u32 v147, v147, v151, s14
	v_add_f32_e32 v135, v135, v143
	v_and_b32_e32 v145, 0xffff0000, v145
	v_and_b32_e32 v147, 0xffff0000, v147
	s_nop 0
	v_or_b32_sdwa v154, v145, v144 dst_sel:DWORD dst_unused:UNUSED_PAD src0_sel:DWORD src1_sel:WORD_1
	v_or_b32_sdwa v155, v147, v146 dst_sel:DWORD dst_unused:UNUSED_PAD src0_sel:DWORD src1_sel:WORD_1
	global_store_dwordx2 v159, v[154:155], s[92:93]
	s_nop 1
	v_add_f32_dpp v132, v132, v132 quad_perm:[1,0,3,2] row_mask:0xf bank_mask:0xf
	v_add_f32_dpp v133, v133, v133 quad_perm:[1,0,3,2] row_mask:0xf bank_mask:0xf
	v_add_f32_dpp v134, v134, v134 quad_perm:[1,0,3,2] row_mask:0xf bank_mask:0xf
	v_add_f32_dpp v135, v135, v135 quad_perm:[1,0,3,2] row_mask:0xf bank_mask:0xf
	v_add_f32_dpp v132, v132, v132 quad_perm:[2,3,0,1] row_mask:0xf bank_mask:0xf
	v_add_f32_dpp v133, v133, v133 quad_perm:[2,3,0,1] row_mask:0xf bank_mask:0xf
	v_add_f32_dpp v134, v134, v134 quad_perm:[2,3,0,1] row_mask:0xf bank_mask:0xf
	v_add_f32_dpp v135, v135, v135 quad_perm:[2,3,0,1] row_mask:0xf bank_mask:0xf
	v_add_f32_dpp v132, v132, v132 row_half_mirror row_mask:0xf bank_mask:0xf
	v_add_f32_dpp v133, v133, v133 row_half_mirror row_mask:0xf bank_mask:0xf
	v_add_f32_dpp v134, v134, v134 row_half_mirror row_mask:0xf bank_mask:0xf
	v_add_f32_dpp v135, v135, v135 row_half_mirror row_mask:0xf bank_mask:0xf
	v_add_f32_dpp v132, v132, v132 row_mirror row_mask:0xf bank_mask:0xf
	v_add_f32_dpp v133, v133, v133 row_mirror row_mask:0xf bank_mask:0xf
	v_add_f32_dpp v134, v134, v134 row_mirror row_mask:0xf bank_mask:0xf
	v_add_f32_dpp v135, v135, v135 row_mirror row_mask:0xf bank_mask:0xf
	v_add_f32_dpp v132, v132, v132 row_bcast:15 row_mask:0xa bank_mask:0xf
	v_add_f32_dpp v133, v133, v133 row_bcast:15 row_mask:0xa bank_mask:0xf
	v_add_f32_dpp v134, v134, v134 row_bcast:15 row_mask:0xa bank_mask:0xf
	v_add_f32_dpp v135, v135, v135 row_bcast:15 row_mask:0xa bank_mask:0xf
	s_waitcnt vmcnt(27) lgkmcnt(6)
	v_pk_add_f32 v[52:53], v[52:53], v[80:81]
	v_pk_add_f32 v[54:55], v[54:55], v[82:83]
	s_waitcnt vmcnt(26) lgkmcnt(4)
	v_pk_add_f32 v[56:57], v[56:57], v[84:85]
	v_pk_add_f32 v[58:59], v[58:59], v[86:87]
	s_waitcnt vmcnt(25) lgkmcnt(2)
	v_pk_add_f32 v[60:61], v[60:61], v[112:113]
	v_pk_add_f32 v[62:63], v[62:63], v[114:115]
	s_waitcnt vmcnt(24) lgkmcnt(0)
	v_pk_add_f32 v[76:77], v[76:77], v[116:117]
	v_pk_add_f32 v[78:79], v[78:79], v[118:119]
	v_add_u32_e32 v65, 0x60000, v64
	global_store_dwordx4 v65, v[52:55], s[80:81]
	v_pk_mul_f32 v[140:141], v[52:53], v[52:53]
	v_pk_mul_f32 v[142:143], v[54:55], v[54:55]
	v_pk_mul_f32 v[144:145], v[52:53], v[120:121]
	v_pk_mul_f32 v[146:147], v[54:55], v[122:123]
	v_lshrrev_b32_e32 v158, 1, v65
	v_add_f32_e32 v136, v140, v141
	v_and_b32_sdwa v148, v144, v157 dst_sel:DWORD dst_unused:UNUSED_PAD src0_sel:WORD_1 src1_sel:DWORD
	v_and_b32_sdwa v149, v145, v157 dst_sel:DWORD dst_unused:UNUSED_PAD src0_sel:WORD_1 src1_sel:DWORD
	v_and_b32_sdwa v150, v146, v157 dst_sel:DWORD dst_unused:UNUSED_PAD src0_sel:WORD_1 src1_sel:DWORD
	v_and_b32_sdwa v151, v147, v157 dst_sel:DWORD dst_unused:UNUSED_PAD src0_sel:WORD_1 src1_sel:DWORD
	v_add_f32_e32 v136, v136, v142
	v_add3_u32 v144, v144, v148, s14
	v_add3_u32 v145, v145, v149, s14
	v_add3_u32 v146, v146, v150, s14
	v_add3_u32 v147, v147, v151, s14
	v_add_f32_e32 v136, v136, v143
	v_and_b32_e32 v145, 0xffff0000, v145
	v_and_b32_e32 v147, 0xffff0000, v147
	s_nop 0
	v_or_b32_sdwa v152, v145, v144 dst_sel:DWORD dst_unused:UNUSED_PAD src0_sel:DWORD src1_sel:WORD_1
	v_or_b32_sdwa v153, v147, v146 dst_sel:DWORD dst_unused:UNUSED_PAD src0_sel:DWORD src1_sel:WORD_1
	global_store_dwordx2 v158, v[152:153], s[92:93]
	v_add_u32_e32 v74, 0x68000, v64
	global_store_dwordx4 v74, v[56:59], s[80:81]
	v_pk_mul_f32 v[140:141], v[56:57], v[56:57]
	v_pk_mul_f32 v[142:143], v[58:59], v[58:59]
	v_pk_mul_f32 v[144:145], v[56:57], v[120:121]
	v_pk_mul_f32 v[146:147], v[58:59], v[122:123]
	v_lshrrev_b32_e32 v159, 1, v74
	v_add_f32_e32 v137, v140, v141
	v_and_b32_sdwa v148, v144, v157 dst_sel:DWORD dst_unused:UNUSED_PAD src0_sel:WORD_1 src1_sel:DWORD
	v_and_b32_sdwa v149, v145, v157 dst_sel:DWORD dst_unused:UNUSED_PAD src0_sel:WORD_1 src1_sel:DWORD
	v_and_b32_sdwa v150, v146, v157 dst_sel:DWORD dst_unused:UNUSED_PAD src0_sel:WORD_1 src1_sel:DWORD
	v_and_b32_sdwa v151, v147, v157 dst_sel:DWORD dst_unused:UNUSED_PAD src0_sel:WORD_1 src1_sel:DWORD
	v_add_f32_e32 v137, v137, v142
	v_add3_u32 v144, v144, v148, s14
	v_add3_u32 v145, v145, v149, s14
	v_add3_u32 v146, v146, v150, s14
	v_add3_u32 v147, v147, v151, s14
	v_add_f32_e32 v137, v137, v143
	v_and_b32_e32 v145, 0xffff0000, v145
	v_and_b32_e32 v147, 0xffff0000, v147
	s_nop 0
	v_or_b32_sdwa v154, v145, v144 dst_sel:DWORD dst_unused:UNUSED_PAD src0_sel:DWORD src1_sel:WORD_1
	v_or_b32_sdwa v155, v147, v146 dst_sel:DWORD dst_unused:UNUSED_PAD src0_sel:DWORD src1_sel:WORD_1
	global_store_dwordx2 v159, v[154:155], s[92:93]
	v_add_u32_e32 v65, 0x70000, v64
	global_store_dwordx4 v65, v[60:63], s[80:81]
	v_pk_mul_f32 v[140:141], v[60:61], v[60:61]
	v_pk_mul_f32 v[142:143], v[62:63], v[62:63]
	v_pk_mul_f32 v[144:145], v[60:61], v[120:121]
	v_pk_mul_f32 v[146:147], v[62:63], v[122:123]
	v_lshrrev_b32_e32 v158, 1, v65
	v_add_f32_e32 v138, v140, v141
	v_and_b32_sdwa v148, v144, v157 dst_sel:DWORD dst_unused:UNUSED_PAD src0_sel:WORD_1 src1_sel:DWORD
	v_and_b32_sdwa v149, v145, v157 dst_sel:DWORD dst_unused:UNUSED_PAD src0_sel:WORD_1 src1_sel:DWORD
	v_and_b32_sdwa v150, v146, v157 dst_sel:DWORD dst_unused:UNUSED_PAD src0_sel:WORD_1 src1_sel:DWORD
	v_and_b32_sdwa v151, v147, v157 dst_sel:DWORD dst_unused:UNUSED_PAD src0_sel:WORD_1 src1_sel:DWORD
	v_add_f32_e32 v138, v138, v142
	v_add3_u32 v144, v144, v148, s14
	v_add3_u32 v145, v145, v149, s14
	v_add3_u32 v146, v146, v150, s14
	v_add3_u32 v147, v147, v151, s14
	v_add_f32_e32 v138, v138, v143
	v_and_b32_e32 v145, 0xffff0000, v145
	v_and_b32_e32 v147, 0xffff0000, v147
	s_nop 0
	v_or_b32_sdwa v152, v145, v144 dst_sel:DWORD dst_unused:UNUSED_PAD src0_sel:DWORD src1_sel:WORD_1
	v_or_b32_sdwa v153, v147, v146 dst_sel:DWORD dst_unused:UNUSED_PAD src0_sel:DWORD src1_sel:WORD_1
	global_store_dwordx2 v158, v[152:153], s[92:93]
	v_add_u32_e32 v74, 0x78000, v64
	global_store_dwordx4 v74, v[76:79], s[80:81]
	v_pk_mul_f32 v[140:141], v[76:77], v[76:77]
	v_pk_mul_f32 v[142:143], v[78:79], v[78:79]
	v_pk_mul_f32 v[144:145], v[76:77], v[120:121]
	v_pk_mul_f32 v[146:147], v[78:79], v[122:123]
	v_lshrrev_b32_e32 v159, 1, v74
	v_add_f32_e32 v139, v140, v141
	v_and_b32_sdwa v148, v144, v157 dst_sel:DWORD dst_unused:UNUSED_PAD src0_sel:WORD_1 src1_sel:DWORD
	v_and_b32_sdwa v149, v145, v157 dst_sel:DWORD dst_unused:UNUSED_PAD src0_sel:WORD_1 src1_sel:DWORD
	v_and_b32_sdwa v150, v146, v157 dst_sel:DWORD dst_unused:UNUSED_PAD src0_sel:WORD_1 src1_sel:DWORD
	v_and_b32_sdwa v151, v147, v157 dst_sel:DWORD dst_unused:UNUSED_PAD src0_sel:WORD_1 src1_sel:DWORD
	v_add_f32_e32 v139, v139, v142
	v_add3_u32 v144, v144, v148, s14
	v_add3_u32 v145, v145, v149, s14
	v_add3_u32 v146, v146, v150, s14
	v_add3_u32 v147, v147, v151, s14
	v_add_f32_e32 v139, v139, v143
	v_and_b32_e32 v145, 0xffff0000, v145
	v_and_b32_e32 v147, 0xffff0000, v147
	s_nop 0
	v_or_b32_sdwa v154, v145, v144 dst_sel:DWORD dst_unused:UNUSED_PAD src0_sel:DWORD src1_sel:WORD_1
	v_or_b32_sdwa v155, v147, v146 dst_sel:DWORD dst_unused:UNUSED_PAD src0_sel:DWORD src1_sel:WORD_1
	global_store_dwordx2 v159, v[154:155], s[92:93]
	s_nop 1
	v_add_f32_dpp v136, v136, v136 quad_perm:[1,0,3,2] row_mask:0xf bank_mask:0xf
	v_add_f32_dpp v137, v137, v137 quad_perm:[1,0,3,2] row_mask:0xf bank_mask:0xf
	v_add_f32_dpp v138, v138, v138 quad_perm:[1,0,3,2] row_mask:0xf bank_mask:0xf
	v_add_f32_dpp v139, v139, v139 quad_perm:[1,0,3,2] row_mask:0xf bank_mask:0xf
	v_add_f32_dpp v136, v136, v136 quad_perm:[2,3,0,1] row_mask:0xf bank_mask:0xf
	v_add_f32_dpp v137, v137, v137 quad_perm:[2,3,0,1] row_mask:0xf bank_mask:0xf
	v_add_f32_dpp v138, v138, v138 quad_perm:[2,3,0,1] row_mask:0xf bank_mask:0xf
	v_add_f32_dpp v139, v139, v139 quad_perm:[2,3,0,1] row_mask:0xf bank_mask:0xf
	v_add_f32_dpp v136, v136, v136 row_half_mirror row_mask:0xf bank_mask:0xf
	v_add_f32_dpp v137, v137, v137 row_half_mirror row_mask:0xf bank_mask:0xf
	v_add_f32_dpp v138, v138, v138 row_half_mirror row_mask:0xf bank_mask:0xf
	v_add_f32_dpp v139, v139, v139 row_half_mirror row_mask:0xf bank_mask:0xf
	v_add_f32_dpp v136, v136, v136 row_mirror row_mask:0xf bank_mask:0xf
	v_add_f32_dpp v137, v137, v137 row_mirror row_mask:0xf bank_mask:0xf
	v_add_f32_dpp v138, v138, v138 row_mirror row_mask:0xf bank_mask:0xf
	v_add_f32_dpp v139, v139, v139 row_mirror row_mask:0xf bank_mask:0xf
	v_add_f32_dpp v136, v136, v136 row_bcast:15 row_mask:0xa bank_mask:0xf
	v_add_f32_dpp v137, v137, v137 row_bcast:15 row_mask:0xa bank_mask:0xf
	v_add_f32_dpp v138, v138, v138 row_bcast:15 row_mask:0xa bank_mask:0xf
	v_add_f32_dpp v139, v139, v139 row_bcast:15 row_mask:0xa bank_mask:0xf
	s_nop 1
	s_mov_b32 exec_lo, 0x80000000
	s_mov_b32 exec_hi, 0x80000000
	global_atomic_add_f32 v156, v124, s[10:11]
	global_atomic_add_f32 v156, v125, s[10:11] offset:32
	global_atomic_add_f32 v156, v126, s[10:11] offset:64
	global_atomic_add_f32 v156, v127, s[10:11] offset:96
	global_atomic_add_f32 v156, v128, s[10:11] offset:128
	global_atomic_add_f32 v156, v129, s[10:11] offset:160
	global_atomic_add_f32 v156, v130, s[10:11] offset:192
	global_atomic_add_f32 v156, v131, s[10:11] offset:224
	global_atomic_add_f32 v156, v132, s[10:11] offset:256
	global_atomic_add_f32 v156, v133, s[10:11] offset:288
	global_atomic_add_f32 v156, v134, s[10:11] offset:320
	global_atomic_add_f32 v156, v135, s[10:11] offset:352
	global_atomic_add_f32 v156, v136, s[10:11] offset:384
	global_atomic_add_f32 v156, v137, s[10:11] offset:416
	global_atomic_add_f32 v156, v138, s[10:11] offset:448
	global_atomic_add_f32 v156, v139, s[10:11] offset:480
	s_mov_b64 exec, -1
	s_branch .LBB0_299

.LBB0_338:
	s_lshr_b32 s8, s13, 2
	s_and_b32 s10, s16, 56
	s_and_b32 s8, s8, 0x1ffffc0
	s_or_b32 s10, s10, s3
	s_or_b32 s8, s10, s8
	s_lshl_b32 s8, s8, 7
	s_lshl_b64 s[24:25], s[8:9], 11
	v_lshl_add_u64 v[78:79], v[68:69], 0, s[24:25]
	v_add_co_u32_e32 v80, vcc, s18, v78
	s_and_b32 s10, s14, 0xf80
	s_nop 0
	v_addc_co_u32_e32 v81, vcc, 0, v79, vcc
	s_lshl_b32 s26, s10, 11
	s_mov_b32 s27, s9
	v_add_co_u32_e32 v82, vcc, s19, v78
	v_lshl_add_u64 v[76:77], v[70:71], 0, s[26:27]
	s_nop 0
	v_addc_co_u32_e32 v83, vcc, 0, v79, vcc
	v_add_co_u32_e32 v84, vcc, s18, v76
	global_load_dwordx4 v[2:5], v[78:79], off
	global_load_dwordx4 v[6:9], v[80:81], off
	v_addc_co_u32_e32 v85, vcc, 0, v77, vcc
	v_add_co_u32_e32 v86, vcc, s19, v76
	global_load_dwordx4 v[10:13], v[82:83], off
	global_load_dwordx4 v[14:17], v[76:77], off
	v_addc_co_u32_e32 v87, vcc, 0, v77, vcc
	global_load_dwordx4 v[18:21], v[84:85], off
	global_load_dwordx4 v[22:25], v[86:87], off
	v_add_co_u32_e32 v88, vcc, s20, v76
	s_nop 1
	v_addc_co_u32_e32 v89, vcc, 0, v77, vcc
	global_load_dwordx4 v[26:29], v[88:89], off
	v_add_co_u32_e32 v90, vcc, s20, v78
	s_nop 1
	v_addc_co_u32_e32 v91, vcc, 0, v79, vcc
	global_load_dwordx4 v[30:33], v[90:91], off
	global_load_dwordx4 v[148:151], v[76:77], off offset:128
	global_load_dwordx4 v[152:155], v[84:85], off offset:128
	global_load_dwordx4 v[156:159], v[86:87], off offset:128
	global_load_dwordx4 v[160:163], v[88:89], off offset:128
	global_load_dwordx4 v[164:167], v[78:79], off offset:128
	global_load_dwordx4 v[168:171], v[80:81], off offset:128
	global_load_dwordx4 v[172:175], v[82:83], off offset:128
	global_load_dwordx4 v[176:179], v[90:91], off offset:128
	s_waitcnt vmcnt(12)
	ds_write_b128 v1, v[14:17] offset:36864
	s_waitcnt vmcnt(11)
	ds_write_b128 v1, v[18:21] offset:41472
	s_waitcnt vmcnt(10)
	ds_write_b128 v1, v[22:25] offset:46080
	s_waitcnt vmcnt(9)
	ds_write_b128 v1, v[26:29] offset:50688
	ds_write_b128 v1, v[2:5]
	ds_write_b128 v1, v[6:9] offset:4608
	ds_write_b128 v1, v[10:13] offset:9216
	s_waitcnt vmcnt(8)
	ds_write_b128 v1, v[30:33] offset:13824
	s_waitcnt lgkmcnt(0)
	s_barrier
	global_load_dwordx4 v[180:183], v[80:81], off offset:256
	global_load_dwordx4 v[184:187], v[82:83], off offset:256
	global_load_dwordx4 v[188:191], v[78:79], off offset:256
	global_load_dwordx4 v[192:195], v[76:77], off offset:256
	global_load_dwordx4 v[196:199], v[90:91], off offset:256
	global_load_dwordx4 v[200:203], v[84:85], off offset:256
	global_load_dwordx4 v[204:207], v[86:87], off offset:256
	global_load_dwordx4 v[208:211], v[88:89], off offset:256
	ds_read_b128 v[18:21], v72
	ds_read_b128 v[34:37], v73 offset:36864
	ds_read_b128 v[212:215], v72 offset:32
	ds_read_b128 v[216:219], v73 offset:36896
	ds_read_b128 v[50:53], v73 offset:41472
	ds_read_b128 v[220:223], v73 offset:41504
	ds_read_b128 v[54:57], v72 offset:4608
	ds_read_b128 v[224:227], v72 offset:4640
	s_waitcnt lgkmcnt(6)
	v_mfma_f32_32x32x16_bf16 v[2:17], v[18:21], v[34:37], 0
	s_waitcnt lgkmcnt(3)
	v_mfma_f32_32x32x16_bf16 v[18:33], v[18:21], v[50:53], 0
	s_waitcnt lgkmcnt(1)
	v_mfma_f32_32x32x16_bf16 v[34:49], v[54:57], v[34:37], 0
	v_mfma_f32_32x32x16_bf16 v[50:65], v[54:57], v[50:53], 0
	v_mfma_f32_32x32x16_bf16 v[2:17], v[212:215], v[216:219], v[2:17]
	v_mfma_f32_32x32x16_bf16 v[18:33], v[212:215], v[220:223], v[18:33]
	s_waitcnt lgkmcnt(0)
	v_mfma_f32_32x32x16_bf16 v[34:49], v[224:227], v[216:219], v[34:49]
	v_mfma_f32_32x32x16_bf16 v[50:65], v[224:227], v[220:223], v[50:65]
	ds_read_b128 v[212:215], v72 offset:64
	ds_read_b128 v[216:219], v73 offset:36928
	ds_read_b128 v[220:223], v72 offset:96
	ds_read_b128 v[224:227], v73 offset:36960
	ds_read_b128 v[228:231], v73 offset:41536
	ds_read_b128 v[232:235], v73 offset:41568
	s_waitcnt lgkmcnt(4)
	v_mfma_f32_32x32x16_bf16 v[2:17], v[212:215], v[216:219], v[2:17]
	s_waitcnt lgkmcnt(1)
	v_mfma_f32_32x32x16_bf16 v[18:33], v[212:215], v[228:231], v[18:33]
	ds_read_b128 v[212:215], v72 offset:4672
	ds_read_b128 v[236:239], v72 offset:4704
	s_waitcnt vmcnt(11)
	ds_write_b128 v1, v[164:167] offset:18432
	s_waitcnt vmcnt(10)
	ds_write_b128 v1, v[168:171] offset:23040
	s_waitcnt vmcnt(9)
	ds_write_b128 v1, v[172:175] offset:27648
	s_waitcnt vmcnt(8)
	ds_write_b128 v1, v[176:179] offset:32256
	ds_write_b128 v1, v[148:151] offset:55296
	ds_write_b128 v1, v[152:155] offset:59904
	ds_write_b128 v1, v[156:159] offset:64512
	ds_write_b128 v92, v[160:163] offset:32256
	global_load_dwordx4 v[148:151], v[80:81], off offset:384
	global_load_dwordx4 v[152:155], v[82:83], off offset:384
	global_load_dwordx4 v[156:159], v[78:79], off offset:384
	global_load_dwordx4 v[160:163], v[76:77], off offset:384
	global_load_dwordx4 v[164:167], v[90:91], off offset:384
	global_load_dwordx4 v[168:171], v[84:85], off offset:384
	global_load_dwordx4 v[172:175], v[86:87], off offset:384
	global_load_dwordx4 v[176:179], v[88:89], off offset:384
	s_waitcnt lgkmcnt(0)
	s_barrier
	v_mfma_f32_32x32x16_bf16 v[34:49], v[212:215], v[216:219], v[34:49]
	v_mfma_f32_32x32x16_bf16 v[50:65], v[212:215], v[228:231], v[50:65]
	v_mfma_f32_32x32x16_bf16 v[2:17], v[220:223], v[224:227], v[2:17]
	v_mfma_f32_32x32x16_bf16 v[18:33], v[220:223], v[232:235], v[18:33]
	v_mfma_f32_32x32x16_bf16 v[34:49], v[236:239], v[224:227], v[34:49]
	v_mfma_f32_32x32x16_bf16 v[50:65], v[236:239], v[232:235], v[50:65]
	ds_read_b128 v[212:215], v72 offset:18432
	ds_read_b128 v[216:219], v73 offset:55296
	ds_read_b128 v[220:223], v72 offset:18464
	ds_read_b128 v[224:227], v73 offset:55328
	ds_read_b128 v[228:231], v73 offset:59904
	ds_read_b128 v[232:235], v73 offset:59936
	s_waitcnt lgkmcnt(4)
	v_mfma_f32_32x32x16_bf16 v[2:17], v[212:215], v[216:219], v[2:17]
	s_waitcnt lgkmcnt(1)
	v_mfma_f32_32x32x16_bf16 v[18:33], v[212:215], v[228:231], v[18:33]
	ds_read_b128 v[212:215], v72 offset:23040
	ds_read_b128 v[236:239], v72 offset:23072
	s_waitcnt lgkmcnt(1)
	v_mfma_f32_32x32x16_bf16 v[34:49], v[212:215], v[216:219], v[34:49]
	v_mfma_f32_32x32x16_bf16 v[50:65], v[212:215], v[228:231], v[50:65]
	v_mfma_f32_32x32x16_bf16 v[2:17], v[220:223], v[224:227], v[2:17]
	v_mfma_f32_32x32x16_bf16 v[18:33], v[220:223], v[232:235], v[18:33]
	s_waitcnt lgkmcnt(0)
	v_mfma_f32_32x32x16_bf16 v[34:49], v[236:239], v[224:227], v[34:49]
	ds_read_b128 v[212:215], v72 offset:18496
	ds_read_b128 v[216:219], v73 offset:55360
	ds_read_b128 v[220:223], v72 offset:18528
	ds_read_b128 v[224:227], v73 offset:55392
	v_mfma_f32_32x32x16_bf16 v[50:65], v[236:239], v[232:235], v[50:65]
	ds_read_b128 v[228:231], v73 offset:59968
	ds_read_b128 v[232:235], v73 offset:60000
	s_waitcnt lgkmcnt(4)
	v_mfma_f32_32x32x16_bf16 v[2:17], v[212:215], v[216:219], v[2:17]
	s_waitcnt lgkmcnt(1)
	v_mfma_f32_32x32x16_bf16 v[18:33], v[212:215], v[228:231], v[18:33]
	ds_read_b128 v[212:215], v72 offset:23104
	ds_read_b128 v[236:239], v72 offset:23136
	s_waitcnt vmcnt(13)
	ds_write_b128 v1, v[188:191]
	ds_write_b128 v1, v[180:183] offset:4608
	ds_write_b128 v1, v[184:187] offset:9216
	s_waitcnt vmcnt(11)
	ds_write_b128 v1, v[196:199] offset:13824
	ds_write_b128 v1, v[192:195] offset:36864
	s_waitcnt vmcnt(10)
	ds_write_b128 v1, v[200:203] offset:41472
	s_waitcnt vmcnt(9)
	ds_write_b128 v1, v[204:207] offset:46080
	s_waitcnt vmcnt(8)
	ds_write_b128 v1, v[208:211] offset:50688
	global_load_dwordx4 v[180:183], v[80:81], off offset:512
	global_load_dwordx4 v[184:187], v[82:83], off offset:512
	global_load_dwordx4 v[188:191], v[78:79], off offset:512
	global_load_dwordx4 v[192:195], v[76:77], off offset:512
	global_load_dwordx4 v[196:199], v[90:91], off offset:512
	global_load_dwordx4 v[200:203], v[84:85], off offset:512
	global_load_dwordx4 v[204:207], v[86:87], off offset:512
	global_load_dwordx4 v[208:211], v[88:89], off offset:512
	s_waitcnt lgkmcnt(0)
	s_barrier
	v_mfma_f32_32x32x16_bf16 v[34:49], v[212:215], v[216:219], v[34:49]
	v_mfma_f32_32x32x16_bf16 v[50:65], v[212:215], v[228:231], v[50:65]
	v_mfma_f32_32x32x16_bf16 v[2:17], v[220:223], v[224:227], v[2:17]
	v_mfma_f32_32x32x16_bf16 v[18:33], v[220:223], v[232:235], v[18:33]
	v_mfma_f32_32x32x16_bf16 v[34:49], v[236:239], v[224:227], v[34:49]
	v_mfma_f32_32x32x16_bf16 v[50:65], v[236:239], v[232:235], v[50:65]
	ds_read_b128 v[212:215], v72
	ds_read_b128 v[216:219], v73 offset:36864
	ds_read_b128 v[220:223], v72 offset:32
	ds_read_b128 v[224:227], v73 offset:36896
	ds_read_b128 v[228:231], v73 offset:41472
	ds_read_b128 v[232:235], v73 offset:41504
	s_waitcnt lgkmcnt(4)
	v_mfma_f32_32x32x16_bf16 v[2:17], v[212:215], v[216:219], v[2:17]
	s_waitcnt lgkmcnt(1)
	v_mfma_f32_32x32x16_bf16 v[18:33], v[212:215], v[228:231], v[18:33]
	ds_read_b128 v[212:215], v72 offset:4608
	ds_read_b128 v[236:239], v72 offset:4640
	s_waitcnt lgkmcnt(1)
	v_mfma_f32_32x32x16_bf16 v[34:49], v[212:215], v[216:219], v[34:49]
	v_mfma_f32_32x32x16_bf16 v[50:65], v[212:215], v[228:231], v[50:65]
	v_mfma_f32_32x32x16_bf16 v[2:17], v[220:223], v[224:227], v[2:17]
	v_mfma_f32_32x32x16_bf16 v[18:33], v[220:223], v[232:235], v[18:33]
	s_waitcnt lgkmcnt(0)
	v_mfma_f32_32x32x16_bf16 v[34:49], v[236:239], v[224:227], v[34:49]
	ds_read_b128 v[212:215], v72 offset:64
	ds_read_b128 v[216:219], v73 offset:36928
	ds_read_b128 v[220:223], v72 offset:96
	ds_read_b128 v[224:227], v73 offset:36960
	v_mfma_f32_32x32x16_bf16 v[50:65], v[236:239], v[232:235], v[50:65]
	ds_read_b128 v[228:231], v73 offset:41536
	ds_read_b128 v[232:235], v73 offset:41568
	s_waitcnt lgkmcnt(4)
	v_mfma_f32_32x32x16_bf16 v[2:17], v[212:215], v[216:219], v[2:17]
	s_waitcnt lgkmcnt(1)
	v_mfma_f32_32x32x16_bf16 v[18:33], v[212:215], v[228:231], v[18:33]
	ds_read_b128 v[212:215], v72 offset:4672
	ds_read_b128 v[236:239], v72 offset:4704
	s_waitcnt vmcnt(13)
	ds_write_b128 v1, v[156:159] offset:18432
	ds_write_b128 v1, v[148:151] offset:23040
	ds_write_b128 v1, v[152:155] offset:27648
	s_waitcnt vmcnt(11)
	ds_write_b128 v1, v[164:167] offset:32256
	ds_write_b128 v1, v[160:163] offset:55296
	s_waitcnt vmcnt(10)
	ds_write_b128 v1, v[168:171] offset:59904
	s_waitcnt vmcnt(9)
	ds_write_b128 v1, v[172:175] offset:64512
	s_waitcnt vmcnt(8)
	ds_write_b128 v92, v[176:179] offset:32256
	global_load_dwordx4 v[148:151], v[80:81], off offset:640
	global_load_dwordx4 v[152:155], v[82:83], off offset:640
	global_load_dwordx4 v[156:159], v[78:79], off offset:640
	global_load_dwordx4 v[160:163], v[76:77], off offset:640
	global_load_dwordx4 v[164:167], v[90:91], off offset:640
	global_load_dwordx4 v[168:171], v[84:85], off offset:640
	global_load_dwordx4 v[172:175], v[86:87], off offset:640
	global_load_dwordx4 v[176:179], v[88:89], off offset:640
	s_waitcnt lgkmcnt(0)
	s_barrier
	v_mfma_f32_32x32x16_bf16 v[34:49], v[212:215], v[216:219], v[34:49]
	v_mfma_f32_32x32x16_bf16 v[50:65], v[212:215], v[228:231], v[50:65]
	v_mfma_f32_32x32x16_bf16 v[2:17], v[220:223], v[224:227], v[2:17]
	v_mfma_f32_32x32x16_bf16 v[18:33], v[220:223], v[232:235], v[18:33]
	v_mfma_f32_32x32x16_bf16 v[34:49], v[236:239], v[224:227], v[34:49]
	v_mfma_f32_32x32x16_bf16 v[50:65], v[236:239], v[232:235], v[50:65]
	ds_read_b128 v[212:215], v72 offset:18432
	ds_read_b128 v[216:219], v73 offset:55296
	ds_read_b128 v[220:223], v72 offset:18464
	ds_read_b128 v[224:227], v73 offset:55328
	ds_read_b128 v[228:231], v73 offset:59904
	ds_read_b128 v[232:235], v73 offset:59936
	s_waitcnt lgkmcnt(4)
	v_mfma_f32_32x32x16_bf16 v[2:17], v[212:215], v[216:219], v[2:17]
	s_waitcnt lgkmcnt(1)
	v_mfma_f32_32x32x16_bf16 v[18:33], v[212:215], v[228:231], v[18:33]
	ds_read_b128 v[212:215], v72 offset:23040
	ds_read_b128 v[236:239], v72 offset:23072
	s_waitcnt lgkmcnt(1)
	v_mfma_f32_32x32x16_bf16 v[34:49], v[212:215], v[216:219], v[34:49]
	v_mfma_f32_32x32x16_bf16 v[50:65], v[212:215], v[228:231], v[50:65]
	v_mfma_f32_32x32x16_bf16 v[2:17], v[220:223], v[224:227], v[2:17]
	v_mfma_f32_32x32x16_bf16 v[18:33], v[220:223], v[232:235], v[18:33]
	s_waitcnt lgkmcnt(0)
	v_mfma_f32_32x32x16_bf16 v[34:49], v[236:239], v[224:227], v[34:49]
	ds_read_b128 v[212:215], v72 offset:18496
	ds_read_b128 v[216:219], v73 offset:55360
	ds_read_b128 v[220:223], v72 offset:18528
	ds_read_b128 v[224:227], v73 offset:55392
	v_mfma_f32_32x32x16_bf16 v[50:65], v[236:239], v[232:235], v[50:65]
	ds_read_b128 v[228:231], v73 offset:59968
	ds_read_b128 v[232:235], v73 offset:60000
	s_waitcnt lgkmcnt(4)
	v_mfma_f32_32x32x16_bf16 v[2:17], v[212:215], v[216:219], v[2:17]
	s_waitcnt lgkmcnt(1)
	v_mfma_f32_32x32x16_bf16 v[18:33], v[212:215], v[228:231], v[18:33]
	ds_read_b128 v[212:215], v72 offset:23104
	ds_read_b128 v[236:239], v72 offset:23136
	s_waitcnt vmcnt(13)
	ds_write_b128 v1, v[188:191]
	ds_write_b128 v1, v[180:183] offset:4608
	ds_write_b128 v1, v[184:187] offset:9216
	s_waitcnt vmcnt(11)
	ds_write_b128 v1, v[196:199] offset:13824
	ds_write_b128 v1, v[192:195] offset:36864
	s_waitcnt vmcnt(10)
	ds_write_b128 v1, v[200:203] offset:41472
	s_waitcnt vmcnt(9)
	ds_write_b128 v1, v[204:207] offset:46080
	s_waitcnt vmcnt(8)
	ds_write_b128 v1, v[208:211] offset:50688
	global_load_dwordx4 v[180:183], v[80:81], off offset:768
	global_load_dwordx4 v[184:187], v[82:83], off offset:768
	global_load_dwordx4 v[188:191], v[78:79], off offset:768
	global_load_dwordx4 v[192:195], v[76:77], off offset:768
	global_load_dwordx4 v[196:199], v[90:91], off offset:768
	global_load_dwordx4 v[200:203], v[84:85], off offset:768
	global_load_dwordx4 v[204:207], v[86:87], off offset:768
	global_load_dwordx4 v[208:211], v[88:89], off offset:768
	s_waitcnt lgkmcnt(0)
	s_barrier
	v_mfma_f32_32x32x16_bf16 v[34:49], v[212:215], v[216:219], v[34:49]
	v_mfma_f32_32x32x16_bf16 v[50:65], v[212:215], v[228:231], v[50:65]
	v_mfma_f32_32x32x16_bf16 v[2:17], v[220:223], v[224:227], v[2:17]
	v_mfma_f32_32x32x16_bf16 v[18:33], v[220:223], v[232:235], v[18:33]
	v_mfma_f32_32x32x16_bf16 v[34:49], v[236:239], v[224:227], v[34:49]
	v_mfma_f32_32x32x16_bf16 v[50:65], v[236:239], v[232:235], v[50:65]
	ds_read_b128 v[212:215], v72
	ds_read_b128 v[216:219], v73 offset:36864
	ds_read_b128 v[220:223], v72 offset:32
	ds_read_b128 v[224:227], v73 offset:36896
	ds_read_b128 v[228:231], v73 offset:41472
	ds_read_b128 v[232:235], v73 offset:41504
	s_waitcnt lgkmcnt(4)
	v_mfma_f32_32x32x16_bf16 v[2:17], v[212:215], v[216:219], v[2:17]
	s_waitcnt lgkmcnt(1)
	v_mfma_f32_32x32x16_bf16 v[18:33], v[212:215], v[228:231], v[18:33]
	ds_read_b128 v[212:215], v72 offset:4608
	ds_read_b128 v[236:239], v72 offset:4640
	s_waitcnt lgkmcnt(1)
	v_mfma_f32_32x32x16_bf16 v[34:49], v[212:215], v[216:219], v[34:49]
	v_mfma_f32_32x32x16_bf16 v[50:65], v[212:215], v[228:231], v[50:65]
	v_mfma_f32_32x32x16_bf16 v[2:17], v[220:223], v[224:227], v[2:17]
	v_mfma_f32_32x32x16_bf16 v[18:33], v[220:223], v[232:235], v[18:33]
	s_waitcnt lgkmcnt(0)
	v_mfma_f32_32x32x16_bf16 v[34:49], v[236:239], v[224:227], v[34:49]
	ds_read_b128 v[212:215], v72 offset:64
	ds_read_b128 v[216:219], v73 offset:36928
	ds_read_b128 v[220:223], v72 offset:96
	ds_read_b128 v[224:227], v73 offset:36960
	v_mfma_f32_32x32x16_bf16 v[50:65], v[236:239], v[232:235], v[50:65]
	ds_read_b128 v[228:231], v73 offset:41536
	ds_read_b128 v[232:235], v73 offset:41568
	s_waitcnt lgkmcnt(4)
	v_mfma_f32_32x32x16_bf16 v[2:17], v[212:215], v[216:219], v[2:17]
	s_waitcnt lgkmcnt(1)
	v_mfma_f32_32x32x16_bf16 v[18:33], v[212:215], v[228:231], v[18:33]
	ds_read_b128 v[212:215], v72 offset:4672
	ds_read_b128 v[236:239], v72 offset:4704
	s_waitcnt vmcnt(13)
	ds_write_b128 v1, v[156:159] offset:18432
	ds_write_b128 v1, v[148:151] offset:23040
	ds_write_b128 v1, v[152:155] offset:27648
	s_waitcnt vmcnt(11)
	ds_write_b128 v1, v[164:167] offset:32256
	ds_write_b128 v1, v[160:163] offset:55296
	s_waitcnt vmcnt(10)
	ds_write_b128 v1, v[168:171] offset:59904
	s_waitcnt vmcnt(9)
	ds_write_b128 v1, v[172:175] offset:64512
	s_waitcnt vmcnt(8)
	ds_write_b128 v92, v[176:179] offset:32256
	global_load_dwordx4 v[148:151], v[80:81], off offset:896
	global_load_dwordx4 v[152:155], v[82:83], off offset:896
	global_load_dwordx4 v[156:159], v[78:79], off offset:896
	global_load_dwordx4 v[160:163], v[76:77], off offset:896
	global_load_dwordx4 v[164:167], v[90:91], off offset:896
	global_load_dwordx4 v[168:171], v[84:85], off offset:896
	global_load_dwordx4 v[172:175], v[86:87], off offset:896
	global_load_dwordx4 v[176:179], v[88:89], off offset:896
	s_waitcnt lgkmcnt(0)
	s_barrier
	v_mfma_f32_32x32x16_bf16 v[34:49], v[212:215], v[216:219], v[34:49]
	v_mfma_f32_32x32x16_bf16 v[50:65], v[212:215], v[228:231], v[50:65]
	v_mfma_f32_32x32x16_bf16 v[2:17], v[220:223], v[224:227], v[2:17]
	v_mfma_f32_32x32x16_bf16 v[18:33], v[220:223], v[232:235], v[18:33]
	v_mfma_f32_32x32x16_bf16 v[34:49], v[236:239], v[224:227], v[34:49]
	v_mfma_f32_32x32x16_bf16 v[50:65], v[236:239], v[232:235], v[50:65]
	ds_read_b128 v[212:215], v72 offset:18432
	ds_read_b128 v[216:219], v73 offset:55296
	ds_read_b128 v[220:223], v72 offset:18464
	ds_read_b128 v[224:227], v73 offset:55328
	ds_read_b128 v[228:231], v73 offset:59904
	ds_read_b128 v[232:235], v73 offset:59936
	s_waitcnt lgkmcnt(4)
	v_mfma_f32_32x32x16_bf16 v[2:17], v[212:215], v[216:219], v[2:17]
	s_waitcnt lgkmcnt(1)
	v_mfma_f32_32x32x16_bf16 v[18:33], v[212:215], v[228:231], v[18:33]
	ds_read_b128 v[212:215], v72 offset:23040
	ds_read_b128 v[236:239], v72 offset:23072
	s_waitcnt lgkmcnt(1)
	v_mfma_f32_32x32x16_bf16 v[34:49], v[212:215], v[216:219], v[34:49]
	v_mfma_f32_32x32x16_bf16 v[50:65], v[212:215], v[228:231], v[50:65]
	v_mfma_f32_32x32x16_bf16 v[2:17], v[220:223], v[224:227], v[2:17]
	v_mfma_f32_32x32x16_bf16 v[18:33], v[220:223], v[232:235], v[18:33]
	s_waitcnt lgkmcnt(0)
	v_mfma_f32_32x32x16_bf16 v[34:49], v[236:239], v[224:227], v[34:49]
	ds_read_b128 v[212:215], v72 offset:18496
	ds_read_b128 v[216:219], v73 offset:55360
	ds_read_b128 v[220:223], v72 offset:18528
	ds_read_b128 v[224:227], v73 offset:55392
	v_mfma_f32_32x32x16_bf16 v[50:65], v[236:239], v[232:235], v[50:65]
	ds_read_b128 v[228:231], v73 offset:59968
	ds_read_b128 v[232:235], v73 offset:60000
	s_waitcnt lgkmcnt(4)
	v_mfma_f32_32x32x16_bf16 v[2:17], v[212:215], v[216:219], v[2:17]
	s_waitcnt lgkmcnt(1)
	v_mfma_f32_32x32x16_bf16 v[18:33], v[212:215], v[228:231], v[18:33]
	ds_read_b128 v[212:215], v72 offset:23104
	ds_read_b128 v[236:239], v72 offset:23136
	s_waitcnt vmcnt(13)
	ds_write_b128 v1, v[188:191]
	ds_write_b128 v1, v[180:183] offset:4608
	ds_write_b128 v1, v[184:187] offset:9216
	s_waitcnt vmcnt(11)
	ds_write_b128 v1, v[196:199] offset:13824
	ds_write_b128 v1, v[192:195] offset:36864
	s_waitcnt vmcnt(10)
	ds_write_b128 v1, v[200:203] offset:41472
	s_waitcnt vmcnt(9)
	ds_write_b128 v1, v[204:207] offset:46080
	s_waitcnt vmcnt(8)
	ds_write_b128 v1, v[208:211] offset:50688
	global_load_dwordx4 v[180:183], v[80:81], off offset:1024
	global_load_dwordx4 v[184:187], v[82:83], off offset:1024
	global_load_dwordx4 v[188:191], v[78:79], off offset:1024
	global_load_dwordx4 v[192:195], v[76:77], off offset:1024
	global_load_dwordx4 v[196:199], v[90:91], off offset:1024
	global_load_dwordx4 v[200:203], v[84:85], off offset:1024
	global_load_dwordx4 v[204:207], v[86:87], off offset:1024
	global_load_dwordx4 v[208:211], v[88:89], off offset:1024
	s_waitcnt lgkmcnt(0)
	s_barrier
	v_mfma_f32_32x32x16_bf16 v[34:49], v[212:215], v[216:219], v[34:49]
	v_mfma_f32_32x32x16_bf16 v[50:65], v[212:215], v[228:231], v[50:65]
	v_mfma_f32_32x32x16_bf16 v[2:17], v[220:223], v[224:227], v[2:17]
	v_mfma_f32_32x32x16_bf16 v[18:33], v[220:223], v[232:235], v[18:33]
	v_mfma_f32_32x32x16_bf16 v[34:49], v[236:239], v[224:227], v[34:49]
	v_mfma_f32_32x32x16_bf16 v[50:65], v[236:239], v[232:235], v[50:65]
	ds_read_b128 v[212:215], v72
	ds_read_b128 v[216:219], v73 offset:36864
	ds_read_b128 v[220:223], v72 offset:32
	ds_read_b128 v[224:227], v73 offset:36896
	ds_read_b128 v[228:231], v73 offset:41472
	ds_read_b128 v[232:235], v73 offset:41504
	s_waitcnt lgkmcnt(4)
	v_mfma_f32_32x32x16_bf16 v[2:17], v[212:215], v[216:219], v[2:17]
	s_waitcnt lgkmcnt(1)
	v_mfma_f32_32x32x16_bf16 v[18:33], v[212:215], v[228:231], v[18:33]
	ds_read_b128 v[212:215], v72 offset:4608
	ds_read_b128 v[236:239], v72 offset:4640
	s_waitcnt lgkmcnt(1)
	v_mfma_f32_32x32x16_bf16 v[34:49], v[212:215], v[216:219], v[34:49]
	v_mfma_f32_32x32x16_bf16 v[50:65], v[212:215], v[228:231], v[50:65]
	v_mfma_f32_32x32x16_bf16 v[2:17], v[220:223], v[224:227], v[2:17]
	v_mfma_f32_32x32x16_bf16 v[18:33], v[220:223], v[232:235], v[18:33]
	s_waitcnt lgkmcnt(0)
	v_mfma_f32_32x32x16_bf16 v[34:49], v[236:239], v[224:227], v[34:49]
	ds_read_b128 v[212:215], v72 offset:64
	ds_read_b128 v[216:219], v73 offset:36928
	ds_read_b128 v[220:223], v72 offset:96
	ds_read_b128 v[224:227], v73 offset:36960
	v_mfma_f32_32x32x16_bf16 v[50:65], v[236:239], v[232:235], v[50:65]
	ds_read_b128 v[228:231], v73 offset:41536
	ds_read_b128 v[232:235], v73 offset:41568
	s_waitcnt lgkmcnt(4)
	v_mfma_f32_32x32x16_bf16 v[2:17], v[212:215], v[216:219], v[2:17]
	s_waitcnt lgkmcnt(1)
	v_mfma_f32_32x32x16_bf16 v[18:33], v[212:215], v[228:231], v[18:33]
	ds_read_b128 v[212:215], v72 offset:4672
	ds_read_b128 v[236:239], v72 offset:4704
	s_waitcnt vmcnt(13)
	ds_write_b128 v1, v[156:159] offset:18432
	ds_write_b128 v1, v[148:151] offset:23040
	ds_write_b128 v1, v[152:155] offset:27648
	s_waitcnt vmcnt(11)
	ds_write_b128 v1, v[164:167] offset:32256
	ds_write_b128 v1, v[160:163] offset:55296
	s_waitcnt vmcnt(10)
	ds_write_b128 v1, v[168:171] offset:59904
	s_waitcnt vmcnt(9)
	ds_write_b128 v1, v[172:175] offset:64512
	s_waitcnt vmcnt(8)
	ds_write_b128 v92, v[176:179] offset:32256
	global_load_dwordx4 v[148:151], v[80:81], off offset:1152
	global_load_dwordx4 v[152:155], v[82:83], off offset:1152
	global_load_dwordx4 v[156:159], v[78:79], off offset:1152
	global_load_dwordx4 v[160:163], v[76:77], off offset:1152
	global_load_dwordx4 v[164:167], v[90:91], off offset:1152
	global_load_dwordx4 v[168:171], v[84:85], off offset:1152
	global_load_dwordx4 v[172:175], v[86:87], off offset:1152
	global_load_dwordx4 v[176:179], v[88:89], off offset:1152
	s_waitcnt lgkmcnt(0)
	s_barrier
	v_mfma_f32_32x32x16_bf16 v[34:49], v[212:215], v[216:219], v[34:49]
	v_mfma_f32_32x32x16_bf16 v[50:65], v[212:215], v[228:231], v[50:65]
	v_mfma_f32_32x32x16_bf16 v[2:17], v[220:223], v[224:227], v[2:17]
	v_mfma_f32_32x32x16_bf16 v[18:33], v[220:223], v[232:235], v[18:33]
	v_mfma_f32_32x32x16_bf16 v[34:49], v[236:239], v[224:227], v[34:49]
	v_mfma_f32_32x32x16_bf16 v[50:65], v[236:239], v[232:235], v[50:65]
	ds_read_b128 v[212:215], v72 offset:18432
	ds_read_b128 v[216:219], v73 offset:55296
	ds_read_b128 v[220:223], v72 offset:18464
	ds_read_b128 v[224:227], v73 offset:55328
	ds_read_b128 v[228:231], v73 offset:59904
	ds_read_b128 v[232:235], v73 offset:59936
	s_waitcnt lgkmcnt(4)
	v_mfma_f32_32x32x16_bf16 v[2:17], v[212:215], v[216:219], v[2:17]
	s_waitcnt lgkmcnt(1)
	v_mfma_f32_32x32x16_bf16 v[18:33], v[212:215], v[228:231], v[18:33]
	ds_read_b128 v[212:215], v72 offset:23040
	ds_read_b128 v[236:239], v72 offset:23072
	s_waitcnt lgkmcnt(1)
	v_mfma_f32_32x32x16_bf16 v[34:49], v[212:215], v[216:219], v[34:49]
	v_mfma_f32_32x32x16_bf16 v[50:65], v[212:215], v[228:231], v[50:65]
	v_mfma_f32_32x32x16_bf16 v[2:17], v[220:223], v[224:227], v[2:17]
	v_mfma_f32_32x32x16_bf16 v[18:33], v[220:223], v[232:235], v[18:33]
	s_waitcnt lgkmcnt(0)
	v_mfma_f32_32x32x16_bf16 v[34:49], v[236:239], v[224:227], v[34:49]
	ds_read_b128 v[212:215], v72 offset:18496
	ds_read_b128 v[216:219], v73 offset:55360
	ds_read_b128 v[220:223], v72 offset:18528
	ds_read_b128 v[224:227], v73 offset:55392
	v_mfma_f32_32x32x16_bf16 v[50:65], v[236:239], v[232:235], v[50:65]
	ds_read_b128 v[228:231], v73 offset:59968
	ds_read_b128 v[232:235], v73 offset:60000
	s_waitcnt lgkmcnt(4)
	v_mfma_f32_32x32x16_bf16 v[2:17], v[212:215], v[216:219], v[2:17]
	s_waitcnt lgkmcnt(1)
	v_mfma_f32_32x32x16_bf16 v[18:33], v[212:215], v[228:231], v[18:33]
	ds_read_b128 v[212:215], v72 offset:23104
	ds_read_b128 v[236:239], v72 offset:23136
	s_waitcnt vmcnt(13)
	ds_write_b128 v1, v[188:191]
	ds_write_b128 v1, v[180:183] offset:4608
	ds_write_b128 v1, v[184:187] offset:9216
	s_waitcnt vmcnt(11)
	ds_write_b128 v1, v[196:199] offset:13824
	ds_write_b128 v1, v[192:195] offset:36864
	s_waitcnt vmcnt(10)
	ds_write_b128 v1, v[200:203] offset:41472
	s_waitcnt vmcnt(9)
	ds_write_b128 v1, v[204:207] offset:46080
	s_waitcnt vmcnt(8)
	ds_write_b128 v1, v[208:211] offset:50688
	global_load_dwordx4 v[180:183], v[80:81], off offset:1280
	global_load_dwordx4 v[184:187], v[82:83], off offset:1280
	global_load_dwordx4 v[188:191], v[78:79], off offset:1280
	global_load_dwordx4 v[192:195], v[76:77], off offset:1280
	global_load_dwordx4 v[196:199], v[90:91], off offset:1280
	global_load_dwordx4 v[200:203], v[84:85], off offset:1280
	global_load_dwordx4 v[204:207], v[86:87], off offset:1280
	global_load_dwordx4 v[208:211], v[88:89], off offset:1280
	s_waitcnt lgkmcnt(0)
	s_barrier
	v_mfma_f32_32x32x16_bf16 v[34:49], v[212:215], v[216:219], v[34:49]
	v_mfma_f32_32x32x16_bf16 v[50:65], v[212:215], v[228:231], v[50:65]
	v_mfma_f32_32x32x16_bf16 v[2:17], v[220:223], v[224:227], v[2:17]
	v_mfma_f32_32x32x16_bf16 v[18:33], v[220:223], v[232:235], v[18:33]
	v_mfma_f32_32x32x16_bf16 v[34:49], v[236:239], v[224:227], v[34:49]
	v_mfma_f32_32x32x16_bf16 v[50:65], v[236:239], v[232:235], v[50:65]
	ds_read_b128 v[212:215], v72
	ds_read_b128 v[216:219], v73 offset:36864
	ds_read_b128 v[220:223], v72 offset:32
	ds_read_b128 v[224:227], v73 offset:36896
	ds_read_b128 v[228:231], v73 offset:41472
	ds_read_b128 v[232:235], v73 offset:41504
	s_waitcnt lgkmcnt(4)
	v_mfma_f32_32x32x16_bf16 v[2:17], v[212:215], v[216:219], v[2:17]
	s_waitcnt lgkmcnt(1)
	v_mfma_f32_32x32x16_bf16 v[18:33], v[212:215], v[228:231], v[18:33]
	ds_read_b128 v[212:215], v72 offset:4608
	ds_read_b128 v[236:239], v72 offset:4640
	s_waitcnt lgkmcnt(1)
	v_mfma_f32_32x32x16_bf16 v[34:49], v[212:215], v[216:219], v[34:49]
	v_mfma_f32_32x32x16_bf16 v[50:65], v[212:215], v[228:231], v[50:65]
	v_mfma_f32_32x32x16_bf16 v[2:17], v[220:223], v[224:227], v[2:17]
	v_mfma_f32_32x32x16_bf16 v[18:33], v[220:223], v[232:235], v[18:33]
	s_waitcnt lgkmcnt(0)
	v_mfma_f32_32x32x16_bf16 v[34:49], v[236:239], v[224:227], v[34:49]
	ds_read_b128 v[212:215], v72 offset:64
	ds_read_b128 v[216:219], v73 offset:36928
	ds_read_b128 v[220:223], v72 offset:96
	ds_read_b128 v[224:227], v73 offset:36960
	v_mfma_f32_32x32x16_bf16 v[50:65], v[236:239], v[232:235], v[50:65]
	ds_read_b128 v[228:231], v73 offset:41536
	ds_read_b128 v[232:235], v73 offset:41568
	s_waitcnt lgkmcnt(4)
	v_mfma_f32_32x32x16_bf16 v[2:17], v[212:215], v[216:219], v[2:17]
	s_waitcnt lgkmcnt(1)
	v_mfma_f32_32x32x16_bf16 v[18:33], v[212:215], v[228:231], v[18:33]
	ds_read_b128 v[212:215], v72 offset:4672
	ds_read_b128 v[236:239], v72 offset:4704
	s_waitcnt vmcnt(13)
	ds_write_b128 v1, v[156:159] offset:18432
	ds_write_b128 v1, v[148:151] offset:23040
	ds_write_b128 v1, v[152:155] offset:27648
	s_waitcnt vmcnt(11)
	ds_write_b128 v1, v[164:167] offset:32256
	ds_write_b128 v1, v[160:163] offset:55296
	s_waitcnt vmcnt(10)
	ds_write_b128 v1, v[168:171] offset:59904
	s_waitcnt vmcnt(9)
	ds_write_b128 v1, v[172:175] offset:64512
	s_waitcnt vmcnt(8)
	ds_write_b128 v92, v[176:179] offset:32256
	global_load_dwordx4 v[148:151], v[80:81], off offset:1408
	global_load_dwordx4 v[152:155], v[82:83], off offset:1408
	global_load_dwordx4 v[156:159], v[78:79], off offset:1408
	global_load_dwordx4 v[160:163], v[76:77], off offset:1408
	global_load_dwordx4 v[164:167], v[90:91], off offset:1408
	global_load_dwordx4 v[168:171], v[84:85], off offset:1408
	global_load_dwordx4 v[172:175], v[86:87], off offset:1408
	global_load_dwordx4 v[176:179], v[88:89], off offset:1408
	s_waitcnt lgkmcnt(0)
	s_barrier
	v_mfma_f32_32x32x16_bf16 v[34:49], v[212:215], v[216:219], v[34:49]
	v_mfma_f32_32x32x16_bf16 v[50:65], v[212:215], v[228:231], v[50:65]
	v_mfma_f32_32x32x16_bf16 v[2:17], v[220:223], v[224:227], v[2:17]
	v_mfma_f32_32x32x16_bf16 v[18:33], v[220:223], v[232:235], v[18:33]
	v_mfma_f32_32x32x16_bf16 v[34:49], v[236:239], v[224:227], v[34:49]
	v_mfma_f32_32x32x16_bf16 v[50:65], v[236:239], v[232:235], v[50:65]
	ds_read_b128 v[212:215], v72 offset:18432
	ds_read_b128 v[216:219], v73 offset:55296
	ds_read_b128 v[220:223], v72 offset:18464
	ds_read_b128 v[224:227], v73 offset:55328
	ds_read_b128 v[228:231], v73 offset:59904
	ds_read_b128 v[232:235], v73 offset:59936
	s_waitcnt lgkmcnt(4)
	v_mfma_f32_32x32x16_bf16 v[2:17], v[212:215], v[216:219], v[2:17]
	s_waitcnt lgkmcnt(1)
	v_mfma_f32_32x32x16_bf16 v[18:33], v[212:215], v[228:231], v[18:33]
	ds_read_b128 v[212:215], v72 offset:23040
	ds_read_b128 v[236:239], v72 offset:23072
	s_waitcnt lgkmcnt(1)
	v_mfma_f32_32x32x16_bf16 v[34:49], v[212:215], v[216:219], v[34:49]
	v_mfma_f32_32x32x16_bf16 v[50:65], v[212:215], v[228:231], v[50:65]
	v_mfma_f32_32x32x16_bf16 v[2:17], v[220:223], v[224:227], v[2:17]
	v_mfma_f32_32x32x16_bf16 v[18:33], v[220:223], v[232:235], v[18:33]
	s_waitcnt lgkmcnt(0)
	v_mfma_f32_32x32x16_bf16 v[34:49], v[236:239], v[224:227], v[34:49]
	ds_read_b128 v[212:215], v72 offset:18496
	ds_read_b128 v[216:219], v73 offset:55360
	ds_read_b128 v[220:223], v72 offset:18528
	ds_read_b128 v[224:227], v73 offset:55392
	v_mfma_f32_32x32x16_bf16 v[50:65], v[236:239], v[232:235], v[50:65]
	ds_read_b128 v[228:231], v73 offset:59968
	ds_read_b128 v[232:235], v73 offset:60000
	s_waitcnt lgkmcnt(4)
	v_mfma_f32_32x32x16_bf16 v[2:17], v[212:215], v[216:219], v[2:17]
	s_waitcnt lgkmcnt(1)
	v_mfma_f32_32x32x16_bf16 v[18:33], v[212:215], v[228:231], v[18:33]
	ds_read_b128 v[212:215], v72 offset:23104
	ds_read_b128 v[236:239], v72 offset:23136
	s_waitcnt vmcnt(13)
	ds_write_b128 v1, v[188:191]
	ds_write_b128 v1, v[180:183] offset:4608
	ds_write_b128 v1, v[184:187] offset:9216
	s_waitcnt vmcnt(11)
	ds_write_b128 v1, v[196:199] offset:13824
	ds_write_b128 v1, v[192:195] offset:36864
	s_waitcnt vmcnt(10)
	ds_write_b128 v1, v[200:203] offset:41472
	s_waitcnt vmcnt(9)
	ds_write_b128 v1, v[204:207] offset:46080
	s_waitcnt vmcnt(8)
	ds_write_b128 v1, v[208:211] offset:50688
	global_load_dwordx4 v[180:183], v[80:81], off offset:1536
	global_load_dwordx4 v[184:187], v[82:83], off offset:1536
	global_load_dwordx4 v[188:191], v[78:79], off offset:1536
	global_load_dwordx4 v[192:195], v[76:77], off offset:1536
	global_load_dwordx4 v[196:199], v[90:91], off offset:1536
	global_load_dwordx4 v[200:203], v[84:85], off offset:1536
	global_load_dwordx4 v[204:207], v[86:87], off offset:1536
	global_load_dwordx4 v[208:211], v[88:89], off offset:1536
	s_waitcnt lgkmcnt(0)
	s_barrier
	v_mfma_f32_32x32x16_bf16 v[34:49], v[212:215], v[216:219], v[34:49]
	v_mfma_f32_32x32x16_bf16 v[50:65], v[212:215], v[228:231], v[50:65]
	v_mfma_f32_32x32x16_bf16 v[2:17], v[220:223], v[224:227], v[2:17]
	v_mfma_f32_32x32x16_bf16 v[18:33], v[220:223], v[232:235], v[18:33]
	v_mfma_f32_32x32x16_bf16 v[34:49], v[236:239], v[224:227], v[34:49]
	v_mfma_f32_32x32x16_bf16 v[50:65], v[236:239], v[232:235], v[50:65]
	ds_read_b128 v[212:215], v72
	ds_read_b128 v[216:219], v73 offset:36864
	ds_read_b128 v[220:223], v72 offset:32
	ds_read_b128 v[224:227], v73 offset:36896
	ds_read_b128 v[228:231], v73 offset:41472
	ds_read_b128 v[232:235], v73 offset:41504
	s_waitcnt lgkmcnt(4)
	v_mfma_f32_32x32x16_bf16 v[2:17], v[212:215], v[216:219], v[2:17]
	s_waitcnt lgkmcnt(1)
	v_mfma_f32_32x32x16_bf16 v[18:33], v[212:215], v[228:231], v[18:33]
	ds_read_b128 v[212:215], v72 offset:4608
	ds_read_b128 v[236:239], v72 offset:4640
	s_waitcnt lgkmcnt(1)
	v_mfma_f32_32x32x16_bf16 v[34:49], v[212:215], v[216:219], v[34:49]
	v_mfma_f32_32x32x16_bf16 v[50:65], v[212:215], v[228:231], v[50:65]
	v_mfma_f32_32x32x16_bf16 v[2:17], v[220:223], v[224:227], v[2:17]
	v_mfma_f32_32x32x16_bf16 v[18:33], v[220:223], v[232:235], v[18:33]
	s_waitcnt lgkmcnt(0)
	v_mfma_f32_32x32x16_bf16 v[34:49], v[236:239], v[224:227], v[34:49]
	ds_read_b128 v[212:215], v72 offset:64
	ds_read_b128 v[216:219], v73 offset:36928
	ds_read_b128 v[220:223], v72 offset:96
	ds_read_b128 v[224:227], v73 offset:36960
	v_mfma_f32_32x32x16_bf16 v[50:65], v[236:239], v[232:235], v[50:65]
	ds_read_b128 v[228:231], v73 offset:41536
	ds_read_b128 v[232:235], v73 offset:41568
	s_waitcnt lgkmcnt(4)
	v_mfma_f32_32x32x16_bf16 v[2:17], v[212:215], v[216:219], v[2:17]
	s_waitcnt lgkmcnt(1)
	v_mfma_f32_32x32x16_bf16 v[18:33], v[212:215], v[228:231], v[18:33]
	ds_read_b128 v[212:215], v72 offset:4672
	ds_read_b128 v[236:239], v72 offset:4704
	s_waitcnt vmcnt(13)
	ds_write_b128 v1, v[156:159] offset:18432
	ds_write_b128 v1, v[148:151] offset:23040
	ds_write_b128 v1, v[152:155] offset:27648
	s_waitcnt vmcnt(11)
	ds_write_b128 v1, v[164:167] offset:32256
	ds_write_b128 v1, v[160:163] offset:55296
	s_waitcnt vmcnt(10)
	ds_write_b128 v1, v[168:171] offset:59904
	s_waitcnt vmcnt(9)
	ds_write_b128 v1, v[172:175] offset:64512
	s_waitcnt vmcnt(8)
	ds_write_b128 v92, v[176:179] offset:32256
	global_load_dwordx4 v[148:151], v[80:81], off offset:1664
	global_load_dwordx4 v[152:155], v[82:83], off offset:1664
	global_load_dwordx4 v[156:159], v[78:79], off offset:1664
	global_load_dwordx4 v[160:163], v[76:77], off offset:1664
	global_load_dwordx4 v[164:167], v[90:91], off offset:1664
	global_load_dwordx4 v[168:171], v[84:85], off offset:1664
	global_load_dwordx4 v[172:175], v[86:87], off offset:1664
	global_load_dwordx4 v[176:179], v[88:89], off offset:1664
	s_waitcnt lgkmcnt(0)
	s_barrier
	v_mfma_f32_32x32x16_bf16 v[34:49], v[212:215], v[216:219], v[34:49]
	v_mfma_f32_32x32x16_bf16 v[50:65], v[212:215], v[228:231], v[50:65]
	v_mfma_f32_32x32x16_bf16 v[2:17], v[220:223], v[224:227], v[2:17]
	v_mfma_f32_32x32x16_bf16 v[18:33], v[220:223], v[232:235], v[18:33]
	v_mfma_f32_32x32x16_bf16 v[34:49], v[236:239], v[224:227], v[34:49]
	v_mfma_f32_32x32x16_bf16 v[50:65], v[236:239], v[232:235], v[50:65]
	ds_read_b128 v[212:215], v72 offset:18432
	ds_read_b128 v[216:219], v73 offset:55296
	ds_read_b128 v[220:223], v72 offset:18464
	ds_read_b128 v[224:227], v73 offset:55328
	ds_read_b128 v[228:231], v73 offset:59904
	ds_read_b128 v[232:235], v73 offset:59936
	s_waitcnt lgkmcnt(4)
	v_mfma_f32_32x32x16_bf16 v[2:17], v[212:215], v[216:219], v[2:17]
	s_waitcnt lgkmcnt(1)
	v_mfma_f32_32x32x16_bf16 v[18:33], v[212:215], v[228:231], v[18:33]
	ds_read_b128 v[212:215], v72 offset:23040
	ds_read_b128 v[236:239], v72 offset:23072
	s_waitcnt lgkmcnt(1)
	v_mfma_f32_32x32x16_bf16 v[34:49], v[212:215], v[216:219], v[34:49]
	v_mfma_f32_32x32x16_bf16 v[50:65], v[212:215], v[228:231], v[50:65]
	v_mfma_f32_32x32x16_bf16 v[2:17], v[220:223], v[224:227], v[2:17]
	v_mfma_f32_32x32x16_bf16 v[18:33], v[220:223], v[232:235], v[18:33]
	s_waitcnt lgkmcnt(0)
	v_mfma_f32_32x32x16_bf16 v[34:49], v[236:239], v[224:227], v[34:49]
	ds_read_b128 v[212:215], v72 offset:18496
	ds_read_b128 v[216:219], v73 offset:55360
	ds_read_b128 v[220:223], v72 offset:18528
	ds_read_b128 v[224:227], v73 offset:55392
	v_mfma_f32_32x32x16_bf16 v[50:65], v[236:239], v[232:235], v[50:65]
	ds_read_b128 v[228:231], v73 offset:59968
	ds_read_b128 v[232:235], v73 offset:60000
	s_waitcnt lgkmcnt(4)
	v_mfma_f32_32x32x16_bf16 v[2:17], v[212:215], v[216:219], v[2:17]
	s_waitcnt lgkmcnt(1)
	v_mfma_f32_32x32x16_bf16 v[18:33], v[212:215], v[228:231], v[18:33]
	ds_read_b128 v[212:215], v72 offset:23104
	ds_read_b128 v[236:239], v72 offset:23136
	s_waitcnt vmcnt(13)
	ds_write_b128 v1, v[188:191]
	ds_write_b128 v1, v[180:183] offset:4608
	ds_write_b128 v1, v[184:187] offset:9216
	s_waitcnt vmcnt(11)
	ds_write_b128 v1, v[196:199] offset:13824
	ds_write_b128 v1, v[192:195] offset:36864
	s_waitcnt vmcnt(10)
	ds_write_b128 v1, v[200:203] offset:41472
	s_waitcnt vmcnt(9)
	ds_write_b128 v1, v[204:207] offset:46080
	s_waitcnt vmcnt(8)
	ds_write_b128 v1, v[208:211] offset:50688
	global_load_dwordx4 v[180:183], v[80:81], off offset:1792
	global_load_dwordx4 v[184:187], v[82:83], off offset:1792
	global_load_dwordx4 v[188:191], v[78:79], off offset:1792
	global_load_dwordx4 v[192:195], v[76:77], off offset:1792
	global_load_dwordx4 v[196:199], v[90:91], off offset:1792
	global_load_dwordx4 v[200:203], v[84:85], off offset:1792
	global_load_dwordx4 v[204:207], v[86:87], off offset:1792
	global_load_dwordx4 v[208:211], v[88:89], off offset:1792
	s_waitcnt lgkmcnt(0)
	s_barrier
	v_mfma_f32_32x32x16_bf16 v[34:49], v[212:215], v[216:219], v[34:49]
	v_mfma_f32_32x32x16_bf16 v[50:65], v[212:215], v[228:231], v[50:65]
	v_mfma_f32_32x32x16_bf16 v[2:17], v[220:223], v[224:227], v[2:17]
	v_mfma_f32_32x32x16_bf16 v[18:33], v[220:223], v[232:235], v[18:33]
	v_mfma_f32_32x32x16_bf16 v[34:49], v[236:239], v[224:227], v[34:49]
	v_mfma_f32_32x32x16_bf16 v[50:65], v[236:239], v[232:235], v[50:65]
	ds_read_b128 v[212:215], v72
	ds_read_b128 v[216:219], v73 offset:36864
	ds_read_b128 v[220:223], v72 offset:32
	ds_read_b128 v[224:227], v73 offset:36896
	ds_read_b128 v[228:231], v73 offset:41472
	ds_read_b128 v[232:235], v73 offset:41504
	s_waitcnt lgkmcnt(4)
	v_mfma_f32_32x32x16_bf16 v[2:17], v[212:215], v[216:219], v[2:17]
	s_waitcnt lgkmcnt(1)
	v_mfma_f32_32x32x16_bf16 v[18:33], v[212:215], v[228:231], v[18:33]
	ds_read_b128 v[212:215], v72 offset:4608
	ds_read_b128 v[236:239], v72 offset:4640
	s_waitcnt lgkmcnt(1)
	v_mfma_f32_32x32x16_bf16 v[34:49], v[212:215], v[216:219], v[34:49]
	v_mfma_f32_32x32x16_bf16 v[50:65], v[212:215], v[228:231], v[50:65]
	v_mfma_f32_32x32x16_bf16 v[2:17], v[220:223], v[224:227], v[2:17]
	v_mfma_f32_32x32x16_bf16 v[18:33], v[220:223], v[232:235], v[18:33]
	s_waitcnt lgkmcnt(0)
	v_mfma_f32_32x32x16_bf16 v[34:49], v[236:239], v[224:227], v[34:49]
	ds_read_b128 v[212:215], v72 offset:64
	ds_read_b128 v[216:219], v73 offset:36928
	ds_read_b128 v[220:223], v72 offset:96
	ds_read_b128 v[224:227], v73 offset:36960
	v_mfma_f32_32x32x16_bf16 v[50:65], v[236:239], v[232:235], v[50:65]
	ds_read_b128 v[228:231], v73 offset:41536
	ds_read_b128 v[232:235], v73 offset:41568
	s_waitcnt lgkmcnt(4)
	v_mfma_f32_32x32x16_bf16 v[2:17], v[212:215], v[216:219], v[2:17]
	s_waitcnt lgkmcnt(1)
	v_mfma_f32_32x32x16_bf16 v[18:33], v[212:215], v[228:231], v[18:33]
	ds_read_b128 v[212:215], v72 offset:4672
	ds_read_b128 v[236:239], v72 offset:4704
	s_waitcnt vmcnt(13)
	ds_write_b128 v1, v[156:159] offset:18432
	ds_write_b128 v1, v[148:151] offset:23040
	ds_write_b128 v1, v[152:155] offset:27648
	s_waitcnt vmcnt(11)
	ds_write_b128 v1, v[164:167] offset:32256
	ds_write_b128 v1, v[160:163] offset:55296
	s_waitcnt vmcnt(10)
	ds_write_b128 v1, v[168:171] offset:59904
	s_waitcnt vmcnt(9)
	ds_write_b128 v1, v[172:175] offset:64512
	s_waitcnt vmcnt(8)
	ds_write_b128 v92, v[176:179] offset:32256
	s_waitcnt lgkmcnt(0)
	s_barrier
	global_load_dwordx4 v[148:151], v[80:81], off offset:1920
	s_nop 0
	global_load_dwordx4 v[80:83], v[82:83], off offset:1920
	s_nop 0
	global_load_dwordx4 v[152:155], v[78:79], off offset:1920
	s_nop 0
	global_load_dwordx4 v[76:79], v[76:77], off offset:1920
	s_nop 0
	global_load_dwordx4 v[156:159], v[90:91], off offset:1920
	global_load_dwordx4 v[160:163], v[84:85], off offset:1920
	s_nop 0
	global_load_dwordx4 v[84:87], v[86:87], off offset:1920
	s_nop 0
	global_load_dwordx4 v[88:91], v[88:89], off offset:1920
	v_mfma_f32_32x32x16_bf16 v[34:49], v[212:215], v[216:219], v[34:49]
	v_mfma_f32_32x32x16_bf16 v[50:65], v[212:215], v[228:231], v[50:65]
	v_mfma_f32_32x32x16_bf16 v[2:17], v[220:223], v[224:227], v[2:17]
	v_mfma_f32_32x32x16_bf16 v[18:33], v[220:223], v[232:235], v[18:33]
	v_mfma_f32_32x32x16_bf16 v[34:49], v[236:239], v[224:227], v[34:49]
	v_mfma_f32_32x32x16_bf16 v[50:65], v[236:239], v[232:235], v[50:65]
	ds_read_b128 v[164:167], v72 offset:18432
	ds_read_b128 v[168:171], v73 offset:55296
	ds_read_b128 v[172:175], v72 offset:18464
	ds_read_b128 v[176:179], v73 offset:55328
	ds_read_b128 v[212:215], v73 offset:59904
	ds_read_b128 v[216:219], v73 offset:59936
	s_waitcnt lgkmcnt(4)
	v_mfma_f32_32x32x16_bf16 v[2:17], v[164:167], v[168:171], v[2:17]
	s_waitcnt lgkmcnt(1)
	v_mfma_f32_32x32x16_bf16 v[18:33], v[164:167], v[212:215], v[18:33]
	ds_read_b128 v[164:167], v72 offset:23040
	ds_read_b128 v[220:223], v72 offset:23072
	s_waitcnt lgkmcnt(1)
	v_mfma_f32_32x32x16_bf16 v[34:49], v[164:167], v[168:171], v[34:49]
	v_mfma_f32_32x32x16_bf16 v[50:65], v[164:167], v[212:215], v[50:65]
	v_mfma_f32_32x32x16_bf16 v[2:17], v[172:175], v[176:179], v[2:17]
	v_mfma_f32_32x32x16_bf16 v[18:33], v[172:175], v[216:219], v[18:33]
	s_waitcnt lgkmcnt(0)
	v_mfma_f32_32x32x16_bf16 v[34:49], v[220:223], v[176:179], v[34:49]
	ds_read_b128 v[164:167], v72 offset:18496
	ds_read_b128 v[168:171], v73 offset:55360
	ds_read_b128 v[172:175], v72 offset:18528
	ds_read_b128 v[176:179], v73 offset:55392
	v_mfma_f32_32x32x16_bf16 v[50:65], v[220:223], v[216:219], v[50:65]
	ds_read_b128 v[212:215], v73 offset:59968
	ds_read_b128 v[216:219], v73 offset:60000
	s_waitcnt lgkmcnt(4)
	v_mfma_f32_32x32x16_bf16 v[2:17], v[164:167], v[168:171], v[2:17]
	s_waitcnt lgkmcnt(1)
	v_mfma_f32_32x32x16_bf16 v[18:33], v[164:167], v[212:215], v[18:33]
	ds_read_b128 v[164:167], v72 offset:23104
	ds_read_b128 v[220:223], v72 offset:23136
	s_waitcnt vmcnt(13)
	ds_write_b128 v1, v[188:191]
	ds_write_b128 v1, v[180:183] offset:4608
	ds_write_b128 v1, v[184:187] offset:9216
	s_waitcnt vmcnt(11)
	ds_write_b128 v1, v[196:199] offset:13824
	ds_write_b128 v1, v[192:195] offset:36864
	s_waitcnt vmcnt(10)
	ds_write_b128 v1, v[200:203] offset:41472
	s_waitcnt vmcnt(9)
	ds_write_b128 v1, v[204:207] offset:46080
	s_waitcnt vmcnt(8)
	ds_write_b128 v1, v[208:211] offset:50688
	s_waitcnt lgkmcnt(0)
	s_barrier
	v_mfma_f32_32x32x16_bf16 v[34:49], v[164:167], v[168:171], v[34:49]
	v_mfma_f32_32x32x16_bf16 v[50:65], v[164:167], v[212:215], v[50:65]
	v_mfma_f32_32x32x16_bf16 v[2:17], v[172:175], v[176:179], v[2:17]
	v_mfma_f32_32x32x16_bf16 v[18:33], v[172:175], v[216:219], v[18:33]
	v_mfma_f32_32x32x16_bf16 v[34:49], v[220:223], v[176:179], v[34:49]
	v_mfma_f32_32x32x16_bf16 v[50:65], v[220:223], v[216:219], v[50:65]
	ds_read_b128 v[164:167], v72
	ds_read_b128 v[168:171], v73 offset:36864
	ds_read_b128 v[172:175], v72 offset:32
	ds_read_b128 v[176:179], v73 offset:36896
	ds_read_b128 v[180:183], v73 offset:41472
	ds_read_b128 v[184:187], v73 offset:41504
	s_waitcnt lgkmcnt(4)
	v_mfma_f32_32x32x16_bf16 v[2:17], v[164:167], v[168:171], v[2:17]
	s_waitcnt lgkmcnt(1)
	v_mfma_f32_32x32x16_bf16 v[18:33], v[164:167], v[180:183], v[18:33]
	ds_read_b128 v[164:167], v72 offset:4608
	ds_read_b128 v[188:191], v72 offset:4640
	s_waitcnt lgkmcnt(1)
	v_mfma_f32_32x32x16_bf16 v[34:49], v[164:167], v[168:171], v[34:49]
	v_mfma_f32_32x32x16_bf16 v[50:65], v[164:167], v[180:183], v[50:65]
	v_mfma_f32_32x32x16_bf16 v[2:17], v[172:175], v[176:179], v[2:17]
	v_mfma_f32_32x32x16_bf16 v[18:33], v[172:175], v[184:187], v[18:33]
	s_waitcnt lgkmcnt(0)
	v_mfma_f32_32x32x16_bf16 v[34:49], v[188:191], v[176:179], v[34:49]
	ds_read_b128 v[164:167], v72 offset:64
	ds_read_b128 v[168:171], v73 offset:36928
	ds_read_b128 v[172:175], v72 offset:96
	ds_read_b128 v[176:179], v73 offset:36960
	v_mfma_f32_32x32x16_bf16 v[50:65], v[188:191], v[184:187], v[50:65]
	ds_read_b128 v[180:183], v73 offset:41536
	ds_read_b128 v[184:187], v73 offset:41568
	s_waitcnt lgkmcnt(4)
	v_mfma_f32_32x32x16_bf16 v[2:17], v[164:167], v[168:171], v[2:17]
	s_waitcnt lgkmcnt(1)
	v_mfma_f32_32x32x16_bf16 v[18:33], v[164:167], v[180:183], v[18:33]
	ds_read_b128 v[164:167], v72 offset:4672
	ds_read_b128 v[188:191], v72 offset:4704
	s_waitcnt vmcnt(5)
	ds_write_b128 v1, v[152:155] offset:18432
	ds_write_b128 v1, v[148:151] offset:23040
	ds_write_b128 v1, v[80:83] offset:27648
	s_waitcnt vmcnt(3)
	ds_write_b128 v1, v[156:159] offset:32256
	ds_write_b128 v1, v[76:79] offset:55296
	s_waitcnt vmcnt(2)
	ds_write_b128 v1, v[160:163] offset:59904
	s_waitcnt vmcnt(1)
	ds_write_b128 v1, v[84:87] offset:64512
	s_waitcnt vmcnt(0)
	ds_write_b128 v92, v[88:91] offset:32256
	s_waitcnt lgkmcnt(0)
	s_barrier
	v_mfma_f32_32x32x16_bf16 v[34:49], v[164:167], v[168:171], v[34:49]
	v_mfma_f32_32x32x16_bf16 v[50:65], v[164:167], v[180:183], v[50:65]
	v_mfma_f32_32x32x16_bf16 v[2:17], v[172:175], v[176:179], v[2:17]
	v_mfma_f32_32x32x16_bf16 v[18:33], v[172:175], v[184:187], v[18:33]
	v_mfma_f32_32x32x16_bf16 v[34:49], v[188:191], v[176:179], v[34:49]
	v_mfma_f32_32x32x16_bf16 v[50:65], v[188:191], v[184:187], v[50:65]
	ds_read_b128 v[76:79], v72 offset:18432
	ds_read_b128 v[80:83], v73 offset:55296
	ds_read_b128 v[84:87], v72 offset:18464
	ds_read_b128 v[88:91], v73 offset:55328
	ds_read_b128 v[148:151], v73 offset:59904
	ds_read_b128 v[152:155], v73 offset:59936
	v_or_b32_e32 v66, s8, v93
	s_waitcnt lgkmcnt(4)
	v_mfma_f32_32x32x16_bf16 v[2:17], v[76:79], v[80:83], v[2:17]
	s_lshl_b32 s10, s10, 1
	s_mov_b32 s11, s9
	s_add_i32 s13, s13, s12
	s_add_i32 s14, s14, s15
	s_add_i32 s16, s16, s17
	s_cmpk_lt_u32 s13, 0x400
	s_waitcnt lgkmcnt(1)
	v_mfma_f32_32x32x16_bf16 v[18:33], v[76:79], v[148:151], v[18:33]
	ds_read_b128 v[76:79], v72 offset:23040
	ds_read_b128 v[156:159], v72 offset:23072
	s_waitcnt lgkmcnt(1)
	v_mfma_f32_32x32x16_bf16 v[34:49], v[76:79], v[80:83], v[34:49]
	v_mfma_f32_32x32x16_bf16 v[50:65], v[76:79], v[148:151], v[50:65]
	v_mfma_f32_32x32x16_bf16 v[2:17], v[84:87], v[88:91], v[2:17]
	v_mfma_f32_32x32x16_bf16 v[18:33], v[84:87], v[152:155], v[18:33]
	s_waitcnt lgkmcnt(0)
	v_mfma_f32_32x32x16_bf16 v[34:49], v[156:159], v[88:91], v[34:49]
	ds_read_b128 v[76:79], v72 offset:18496
	ds_read_b128 v[80:83], v73 offset:55360
	ds_read_b128 v[84:87], v72 offset:18528
	ds_read_b128 v[88:91], v73 offset:55392
	v_mfma_f32_32x32x16_bf16 v[50:65], v[156:159], v[152:155], v[50:65]
	ds_read_b128 v[148:151], v73 offset:59968
	ds_read_b128 v[152:155], v73 offset:60000
	s_waitcnt lgkmcnt(4)
	v_mfma_f32_32x32x16_bf16 v[2:17], v[76:79], v[80:83], v[2:17]
	s_waitcnt lgkmcnt(1)
	v_mfma_f32_32x32x16_bf16 v[18:33], v[76:79], v[148:151], v[18:33]
	ds_read_b128 v[76:79], v72 offset:23104
	ds_read_b128 v[156:159], v72 offset:23136
	s_waitcnt lgkmcnt(0)
	s_barrier
	v_mfma_f32_32x32x16_bf16 v[34:49], v[76:79], v[80:83], v[34:49]
	v_mfma_f32_32x32x16_bf16 v[50:65], v[76:79], v[148:151], v[50:65]
	v_mfma_f32_32x32x16_bf16 v[2:17], v[84:87], v[88:91], v[2:17]
	v_mfma_f32_32x32x16_bf16 v[18:33], v[84:87], v[152:155], v[18:33]
	v_mfma_f32_32x32x16_bf16 v[34:49], v[156:159], v[88:91], v[34:49]
	s_nop 10
	ds_write2_b32 v101, v2, v18 offset1:32
	v_mfma_f32_32x32x16_bf16 v[50:65], v[156:159], v[152:155], v[50:65]
	s_nop 11
	ds_write2_b32 v132, v34, v50 offset0:32 offset1:64
	ds_write2_b32 v101, v3, v19 offset0:129 offset1:161
	ds_write2_b32 v132, v35, v51 offset0:161 offset1:193
	ds_write2_b32 v133, v4, v20 offset0:2 offset1:34
	ds_write2_b32 v134, v36, v52 offset0:34 offset1:66
	ds_write2_b32 v133, v5, v21 offset0:131 offset1:163
	ds_write2_b32 v134, v37, v53 offset0:163 offset1:195
	ds_write2_b32 v135, v6, v22 offset0:8 offset1:40
	ds_write2_b32 v136, v38, v54 offset0:40 offset1:72
	ds_write2_b32 v135, v7, v23 offset0:137 offset1:169
	ds_write2_b32 v136, v39, v55 offset0:169 offset1:201
	ds_write2_b32 v137, v8, v24 offset0:10 offset1:42
	ds_write2_b32 v138, v40, v56 offset0:42 offset1:74
	ds_write2_b32 v137, v9, v25 offset0:139 offset1:171
	ds_write2_b32 v138, v41, v57 offset0:171 offset1:203
	ds_write2_b32 v139, v10, v26 offset0:16 offset1:48
	ds_write2_b32 v140, v42, v58 offset0:48 offset1:80
	ds_write2_b32 v139, v11, v27 offset0:145 offset1:177
	ds_write2_b32 v140, v43, v59 offset0:177 offset1:209
	ds_write2_b32 v141, v12, v28 offset0:18 offset1:50
	ds_write2_b32 v142, v44, v60 offset0:50 offset1:82
	ds_write2_b32 v141, v13, v29 offset0:147 offset1:179
	ds_write2_b32 v142, v45, v61 offset0:179 offset1:211
	ds_write2_b32 v143, v14, v30 offset0:24 offset1:56
	ds_write2_b32 v144, v46, v62 offset0:56 offset1:88
	ds_write2_b32 v143, v15, v31 offset0:153 offset1:185
	ds_write2_b32 v144, v47, v63 offset0:185 offset1:217
	ds_write2_b32 v145, v16, v32 offset0:26 offset1:58
	ds_write2_b32 v146, v48, v64 offset0:58 offset1:90
	ds_write2_b32 v145, v17, v33 offset0:155 offset1:187
	ds_write2_b32 v146, v49, v65 offset0:187 offset1:219
	v_lshl_add_u64 v[2:3], v[66:67], 2, s[6:7]
	s_waitcnt lgkmcnt(0)
	s_barrier
	v_mov_b32_e32 v2, v66
	v_lshlrev_b32_e32 v3, 2, v2
	global_load_dword v5, v3, s[6:7]
	global_load_dword v6, v3, s[6:7] offset:64
	global_load_dword v7, v3, s[6:7] offset:128
	global_load_dword v8, v3, s[6:7] offset:192
	global_load_dword v9, v3, s[6:7] offset:256
	global_load_dword v10, v3, s[6:7] offset:320
	global_load_dword v11, v3, s[6:7] offset:384
	global_load_dword v12, v3, s[6:7] offset:448
	v_lshlrev_b32_e32 v4, 13, v2
	v_add3_u32 v4, v4, v74, s10
	s_movk_i32 s24, 0x7fff
	v_mov_b32_e32 v59, 1
	v_mov_b32_e32 v13, 0x358637bd
	ds_read2_b32 v[14:15], v103 offset0:0 offset1:1
	ds_read2_b32 v[16:17], v103 offset0:2 offset1:3
	ds_read2_b32 v[18:19], v103 offset0:4 offset1:5
	ds_read2_b32 v[20:21], v103 offset0:6 offset1:7
	v_add_u32_e32 v56, 0x2040, v103
	ds_read2_b32 v[22:23], v56 offset0:0 offset1:1
	ds_read2_b32 v[24:25], v56 offset0:2 offset1:3
	ds_read2_b32 v[26:27], v56 offset0:4 offset1:5
	ds_read2_b32 v[28:29], v56 offset0:6 offset1:7
	s_waitcnt vmcnt(7) lgkmcnt(4)
	v_fmamk_f32 v54, v5, 0x3a800000, v13
	v_rsq_f32_e32 v54, v54
	s_nop 0
	v_mul_f32_e32 v14, v14, v54
	v_mul_f32_e32 v15, v15, v54
	v_mul_f32_e32 v16, v16, v54
	v_mul_f32_e32 v17, v17, v54
	v_mul_f32_e32 v18, v18, v54
	v_mul_f32_e32 v19, v19, v54
	v_mul_f32_e32 v20, v20, v54
	v_mul_f32_e32 v21, v21, v54
	v_max_f32_e32 v14, 0, v14
	v_max_f32_e32 v15, 0, v15
	v_max_f32_e32 v16, 0, v16
	v_max_f32_e32 v17, 0, v17
	v_max_f32_e32 v18, 0, v18
	v_max_f32_e32 v19, 0, v19
	v_max_f32_e32 v20, 0, v20
	v_max_f32_e32 v21, 0, v21
	v_pk_mul_f32 v[14:15], v[14:15], v[14:15]
	v_pk_mul_f32 v[16:17], v[16:17], v[16:17]
	v_pk_mul_f32 v[18:19], v[18:19], v[18:19]
	v_pk_mul_f32 v[20:21], v[20:21], v[20:21]
	v_and_b32_sdwa v46, v14, v59 dst_sel:DWORD dst_unused:UNUSED_PAD src0_sel:WORD_1 src1_sel:DWORD
	v_and_b32_sdwa v47, v15, v59 dst_sel:DWORD dst_unused:UNUSED_PAD src0_sel:WORD_1 src1_sel:DWORD
	v_and_b32_sdwa v48, v16, v59 dst_sel:DWORD dst_unused:UNUSED_PAD src0_sel:WORD_1 src1_sel:DWORD
	v_and_b32_sdwa v49, v17, v59 dst_sel:DWORD dst_unused:UNUSED_PAD src0_sel:WORD_1 src1_sel:DWORD
	v_and_b32_sdwa v50, v18, v59 dst_sel:DWORD dst_unused:UNUSED_PAD src0_sel:WORD_1 src1_sel:DWORD
	v_and_b32_sdwa v51, v19, v59 dst_sel:DWORD dst_unused:UNUSED_PAD src0_sel:WORD_1 src1_sel:DWORD
	v_and_b32_sdwa v52, v20, v59 dst_sel:DWORD dst_unused:UNUSED_PAD src0_sel:WORD_1 src1_sel:DWORD
	v_and_b32_sdwa v53, v21, v59 dst_sel:DWORD dst_unused:UNUSED_PAD src0_sel:WORD_1 src1_sel:DWORD
	v_add3_u32 v14, v14, v46, s24
	v_add3_u32 v15, v15, v47, s24
	v_add3_u32 v16, v16, v48, s24
	v_add3_u32 v17, v17, v49, s24
	v_add3_u32 v18, v18, v50, s24
	v_add3_u32 v19, v19, v51, s24
	v_add3_u32 v20, v20, v52, s24
	v_add3_u32 v21, v21, v53, s24
	v_and_b32_e32 v15, 0xffff0000, v15
	v_and_b32_e32 v17, 0xffff0000, v17
	v_and_b32_e32 v19, 0xffff0000, v19
	v_and_b32_e32 v21, 0xffff0000, v21
	v_or_b32_sdwa v60, v15, v14 dst_sel:DWORD dst_unused:UNUSED_PAD src0_sel:DWORD src1_sel:WORD_1
	v_or_b32_sdwa v61, v17, v16 dst_sel:DWORD dst_unused:UNUSED_PAD src0_sel:DWORD src1_sel:WORD_1
	v_or_b32_sdwa v62, v19, v18 dst_sel:DWORD dst_unused:UNUSED_PAD src0_sel:DWORD src1_sel:WORD_1
	v_or_b32_sdwa v63, v21, v20 dst_sel:DWORD dst_unused:UNUSED_PAD src0_sel:DWORD src1_sel:WORD_1
	global_store_dwordx4 v4, v[60:63], s[56:57]
	v_add_u32_e32 v55, 0x4080, v103
	ds_read2_b32 v[30:31], v55 offset0:0 offset1:1
	ds_read2_b32 v[32:33], v55 offset0:2 offset1:3
	ds_read2_b32 v[34:35], v55 offset0:4 offset1:5
	ds_read2_b32 v[36:37], v55 offset0:6 offset1:7
	v_add_u32_e32 v56, 0x60c0, v103
	ds_read2_b32 v[38:39], v56 offset0:0 offset1:1
	ds_read2_b32 v[40:41], v56 offset0:2 offset1:3
	ds_read2_b32 v[42:43], v56 offset0:4 offset1:5
	ds_read2_b32 v[44:45], v56 offset0:6 offset1:7
	s_waitcnt vmcnt(7) lgkmcnt(8)
	v_fmamk_f32 v54, v6, 0x3a800000, v13
	v_rsq_f32_e32 v54, v54
	v_add_u32_e32 v58, 0x20000, v4
	v_mul_f32_e32 v22, v22, v54
	v_mul_f32_e32 v23, v23, v54
	v_mul_f32_e32 v24, v24, v54
	v_mul_f32_e32 v25, v25, v54
	v_mul_f32_e32 v26, v26, v54
	v_mul_f32_e32 v27, v27, v54
	v_mul_f32_e32 v28, v28, v54
	v_mul_f32_e32 v29, v29, v54
	v_max_f32_e32 v22, 0, v22
	v_max_f32_e32 v23, 0, v23
	v_max_f32_e32 v24, 0, v24
	v_max_f32_e32 v25, 0, v25
	v_max_f32_e32 v26, 0, v26
	v_max_f32_e32 v27, 0, v27
	v_max_f32_e32 v28, 0, v28
	v_max_f32_e32 v29, 0, v29
	v_pk_mul_f32 v[22:23], v[22:23], v[22:23]
	v_pk_mul_f32 v[24:25], v[24:25], v[24:25]
	v_pk_mul_f32 v[26:27], v[26:27], v[26:27]
	v_pk_mul_f32 v[28:29], v[28:29], v[28:29]
	v_and_b32_sdwa v46, v22, v59 dst_sel:DWORD dst_unused:UNUSED_PAD src0_sel:WORD_1 src1_sel:DWORD
	v_and_b32_sdwa v47, v23, v59 dst_sel:DWORD dst_unused:UNUSED_PAD src0_sel:WORD_1 src1_sel:DWORD
	v_and_b32_sdwa v48, v24, v59 dst_sel:DWORD dst_unused:UNUSED_PAD src0_sel:WORD_1 src1_sel:DWORD
	v_and_b32_sdwa v49, v25, v59 dst_sel:DWORD dst_unused:UNUSED_PAD src0_sel:WORD_1 src1_sel:DWORD
	v_and_b32_sdwa v50, v26, v59 dst_sel:DWORD dst_unused:UNUSED_PAD src0_sel:WORD_1 src1_sel:DWORD
	v_and_b32_sdwa v51, v27, v59 dst_sel:DWORD dst_unused:UNUSED_PAD src0_sel:WORD_1 src1_sel:DWORD
	v_and_b32_sdwa v52, v28, v59 dst_sel:DWORD dst_unused:UNUSED_PAD src0_sel:WORD_1 src1_sel:DWORD
	v_and_b32_sdwa v53, v29, v59 dst_sel:DWORD dst_unused:UNUSED_PAD src0_sel:WORD_1 src1_sel:DWORD
	v_add3_u32 v22, v22, v46, s24
	v_add3_u32 v23, v23, v47, s24
	v_add3_u32 v24, v24, v48, s24
	v_add3_u32 v25, v25, v49, s24
	v_add3_u32 v26, v26, v50, s24
	v_add3_u32 v27, v27, v51, s24
	v_add3_u32 v28, v28, v52, s24
	v_add3_u32 v29, v29, v53, s24
	v_and_b32_e32 v23, 0xffff0000, v23
	v_and_b32_e32 v25, 0xffff0000, v25
	v_and_b32_e32 v27, 0xffff0000, v27
	v_and_b32_e32 v29, 0xffff0000, v29
	v_or_b32_sdwa v76, v23, v22 dst_sel:DWORD dst_unused:UNUSED_PAD src0_sel:DWORD src1_sel:WORD_1
	v_or_b32_sdwa v77, v25, v24 dst_sel:DWORD dst_unused:UNUSED_PAD src0_sel:DWORD src1_sel:WORD_1
	v_or_b32_sdwa v78, v27, v26 dst_sel:DWORD dst_unused:UNUSED_PAD src0_sel:DWORD src1_sel:WORD_1
	v_or_b32_sdwa v79, v29, v28 dst_sel:DWORD dst_unused:UNUSED_PAD src0_sel:DWORD src1_sel:WORD_1
	global_store_dwordx4 v58, v[76:79], s[56:57]
	s_waitcnt vmcnt(7) lgkmcnt(4)
	v_fmamk_f32 v54, v7, 0x3a800000, v13
	v_rsq_f32_e32 v54, v54
	v_add_u32_e32 v57, 0x40000, v4
	v_mul_f32_e32 v30, v30, v54
	v_mul_f32_e32 v31, v31, v54
	v_mul_f32_e32 v32, v32, v54
	v_mul_f32_e32 v33, v33, v54
	v_mul_f32_e32 v34, v34, v54
	v_mul_f32_e32 v35, v35, v54
	v_mul_f32_e32 v36, v36, v54
	v_mul_f32_e32 v37, v37, v54
	v_max_f32_e32 v30, 0, v30
	v_max_f32_e32 v31, 0, v31
	v_max_f32_e32 v32, 0, v32
	v_max_f32_e32 v33, 0, v33
	v_max_f32_e32 v34, 0, v34
	v_max_f32_e32 v35, 0, v35
	v_max_f32_e32 v36, 0, v36
	v_max_f32_e32 v37, 0, v37
	v_pk_mul_f32 v[30:31], v[30:31], v[30:31]
	v_pk_mul_f32 v[32:33], v[32:33], v[32:33]
	v_pk_mul_f32 v[34:35], v[34:35], v[34:35]
	v_pk_mul_f32 v[36:37], v[36:37], v[36:37]
	v_and_b32_sdwa v46, v30, v59 dst_sel:DWORD dst_unused:UNUSED_PAD src0_sel:WORD_1 src1_sel:DWORD
	v_and_b32_sdwa v47, v31, v59 dst_sel:DWORD dst_unused:UNUSED_PAD src0_sel:WORD_1 src1_sel:DWORD
	v_and_b32_sdwa v48, v32, v59 dst_sel:DWORD dst_unused:UNUSED_PAD src0_sel:WORD_1 src1_sel:DWORD
	v_and_b32_sdwa v49, v33, v59 dst_sel:DWORD dst_unused:UNUSED_PAD src0_sel:WORD_1 src1_sel:DWORD
	v_and_b32_sdwa v50, v34, v59 dst_sel:DWORD dst_unused:UNUSED_PAD src0_sel:WORD_1 src1_sel:DWORD
	v_and_b32_sdwa v51, v35, v59 dst_sel:DWORD dst_unused:UNUSED_PAD src0_sel:WORD_1 src1_sel:DWORD
	v_and_b32_sdwa v52, v36, v59 dst_sel:DWORD dst_unused:UNUSED_PAD src0_sel:WORD_1 src1_sel:DWORD
	v_and_b32_sdwa v53, v37, v59 dst_sel:DWORD dst_unused:UNUSED_PAD src0_sel:WORD_1 src1_sel:DWORD
	v_add3_u32 v30, v30, v46, s24
	v_add3_u32 v31, v31, v47, s24
	v_add3_u32 v32, v32, v48, s24
	v_add3_u32 v33, v33, v49, s24
	v_add3_u32 v34, v34, v50, s24
	v_add3_u32 v35, v35, v51, s24
	v_add3_u32 v36, v36, v52, s24
	v_add3_u32 v37, v37, v53, s24
	v_and_b32_e32 v31, 0xffff0000, v31
	v_and_b32_e32 v33, 0xffff0000, v33
	v_and_b32_e32 v35, 0xffff0000, v35
	v_and_b32_e32 v37, 0xffff0000, v37
	v_or_b32_sdwa v60, v31, v30 dst_sel:DWORD dst_unused:UNUSED_PAD src0_sel:DWORD src1_sel:WORD_1
	v_or_b32_sdwa v61, v33, v32 dst_sel:DWORD dst_unused:UNUSED_PAD src0_sel:DWORD src1_sel:WORD_1
	v_or_b32_sdwa v62, v35, v34 dst_sel:DWORD dst_unused:UNUSED_PAD src0_sel:DWORD src1_sel:WORD_1
	v_or_b32_sdwa v63, v37, v36 dst_sel:DWORD dst_unused:UNUSED_PAD src0_sel:DWORD src1_sel:WORD_1
	global_store_dwordx4 v57, v[60:63], s[56:57]
	v_add_u32_e32 v55, 0x8100, v103
	ds_read2_b32 v[14:15], v55 offset0:0 offset1:1
	ds_read2_b32 v[16:17], v55 offset0:2 offset1:3
	ds_read2_b32 v[18:19], v55 offset0:4 offset1:5
	ds_read2_b32 v[20:21], v55 offset0:6 offset1:7
	v_add_u32_e32 v56, 0xa140, v103
	ds_read2_b32 v[22:23], v56 offset0:0 offset1:1
	ds_read2_b32 v[24:25], v56 offset0:2 offset1:3
	ds_read2_b32 v[26:27], v56 offset0:4 offset1:5
	ds_read2_b32 v[28:29], v56 offset0:6 offset1:7
	s_waitcnt vmcnt(7) lgkmcnt(8)
	v_fmamk_f32 v54, v8, 0x3a800000, v13
	v_rsq_f32_e32 v54, v54
	v_add_u32_e32 v58, 0x60000, v4
	v_mul_f32_e32 v38, v38, v54
	v_mul_f32_e32 v39, v39, v54
	v_mul_f32_e32 v40, v40, v54
	v_mul_f32_e32 v41, v41, v54
	v_mul_f32_e32 v42, v42, v54
	v_mul_f32_e32 v43, v43, v54
	v_mul_f32_e32 v44, v44, v54
	v_mul_f32_e32 v45, v45, v54
	v_max_f32_e32 v38, 0, v38
	v_max_f32_e32 v39, 0, v39
	v_max_f32_e32 v40, 0, v40
	v_max_f32_e32 v41, 0, v41
	v_max_f32_e32 v42, 0, v42
	v_max_f32_e32 v43, 0, v43
	v_max_f32_e32 v44, 0, v44
	v_max_f32_e32 v45, 0, v45
	v_pk_mul_f32 v[38:39], v[38:39], v[38:39]
	v_pk_mul_f32 v[40:41], v[40:41], v[40:41]
	v_pk_mul_f32 v[42:43], v[42:43], v[42:43]
	v_pk_mul_f32 v[44:45], v[44:45], v[44:45]
	v_and_b32_sdwa v46, v38, v59 dst_sel:DWORD dst_unused:UNUSED_PAD src0_sel:WORD_1 src1_sel:DWORD
	v_and_b32_sdwa v47, v39, v59 dst_sel:DWORD dst_unused:UNUSED_PAD src0_sel:WORD_1 src1_sel:DWORD
	v_and_b32_sdwa v48, v40, v59 dst_sel:DWORD dst_unused:UNUSED_PAD src0_sel:WORD_1 src1_sel:DWORD
	v_and_b32_sdwa v49, v41, v59 dst_sel:DWORD dst_unused:UNUSED_PAD src0_sel:WORD_1 src1_sel:DWORD
	v_and_b32_sdwa v50, v42, v59 dst_sel:DWORD dst_unused:UNUSED_PAD src0_sel:WORD_1 src1_sel:DWORD
	v_and_b32_sdwa v51, v43, v59 dst_sel:DWORD dst_unused:UNUSED_PAD src0_sel:WORD_1 src1_sel:DWORD
	v_and_b32_sdwa v52, v44, v59 dst_sel:DWORD dst_unused:UNUSED_PAD src0_sel:WORD_1 src1_sel:DWORD
	v_and_b32_sdwa v53, v45, v59 dst_sel:DWORD dst_unused:UNUSED_PAD src0_sel:WORD_1 src1_sel:DWORD
	v_add3_u32 v38, v38, v46, s24
	v_add3_u32 v39, v39, v47, s24
	v_add3_u32 v40, v40, v48, s24
	v_add3_u32 v41, v41, v49, s24
	v_add3_u32 v42, v42, v50, s24
	v_add3_u32 v43, v43, v51, s24
	v_add3_u32 v44, v44, v52, s24
	v_add3_u32 v45, v45, v53, s24
	v_and_b32_e32 v39, 0xffff0000, v39
	v_and_b32_e32 v41, 0xffff0000, v41
	v_and_b32_e32 v43, 0xffff0000, v43
	v_and_b32_e32 v45, 0xffff0000, v45
	v_or_b32_sdwa v76, v39, v38 dst_sel:DWORD dst_unused:UNUSED_PAD src0_sel:DWORD src1_sel:WORD_1
	v_or_b32_sdwa v77, v41, v40 dst_sel:DWORD dst_unused:UNUSED_PAD src0_sel:DWORD src1_sel:WORD_1
	v_or_b32_sdwa v78, v43, v42 dst_sel:DWORD dst_unused:UNUSED_PAD src0_sel:DWORD src1_sel:WORD_1
	v_or_b32_sdwa v79, v45, v44 dst_sel:DWORD dst_unused:UNUSED_PAD src0_sel:DWORD src1_sel:WORD_1
	global_store_dwordx4 v58, v[76:79], s[56:57]
	s_waitcnt vmcnt(7) lgkmcnt(4)
	v_fmamk_f32 v54, v9, 0x3a800000, v13
	v_rsq_f32_e32 v54, v54
	v_add_u32_e32 v57, 0x80000, v4
	v_mul_f32_e32 v14, v14, v54
	v_mul_f32_e32 v15, v15, v54
	v_mul_f32_e32 v16, v16, v54
	v_mul_f32_e32 v17, v17, v54
	v_mul_f32_e32 v18, v18, v54
	v_mul_f32_e32 v19, v19, v54
	v_mul_f32_e32 v20, v20, v54
	v_mul_f32_e32 v21, v21, v54
	v_max_f32_e32 v14, 0, v14
	v_max_f32_e32 v15, 0, v15
	v_max_f32_e32 v16, 0, v16
	v_max_f32_e32 v17, 0, v17
	v_max_f32_e32 v18, 0, v18
	v_max_f32_e32 v19, 0, v19
	v_max_f32_e32 v20, 0, v20
	v_max_f32_e32 v21, 0, v21
	v_pk_mul_f32 v[14:15], v[14:15], v[14:15]
	v_pk_mul_f32 v[16:17], v[16:17], v[16:17]
	v_pk_mul_f32 v[18:19], v[18:19], v[18:19]
	v_pk_mul_f32 v[20:21], v[20:21], v[20:21]
	v_and_b32_sdwa v46, v14, v59 dst_sel:DWORD dst_unused:UNUSED_PAD src0_sel:WORD_1 src1_sel:DWORD
	v_and_b32_sdwa v47, v15, v59 dst_sel:DWORD dst_unused:UNUSED_PAD src0_sel:WORD_1 src1_sel:DWORD
	v_and_b32_sdwa v48, v16, v59 dst_sel:DWORD dst_unused:UNUSED_PAD src0_sel:WORD_1 src1_sel:DWORD
	v_and_b32_sdwa v49, v17, v59 dst_sel:DWORD dst_unused:UNUSED_PAD src0_sel:WORD_1 src1_sel:DWORD
	v_and_b32_sdwa v50, v18, v59 dst_sel:DWORD dst_unused:UNUSED_PAD src0_sel:WORD_1 src1_sel:DWORD
	v_and_b32_sdwa v51, v19, v59 dst_sel:DWORD dst_unused:UNUSED_PAD src0_sel:WORD_1 src1_sel:DWORD
	v_and_b32_sdwa v52, v20, v59 dst_sel:DWORD dst_unused:UNUSED_PAD src0_sel:WORD_1 src1_sel:DWORD
	v_and_b32_sdwa v53, v21, v59 dst_sel:DWORD dst_unused:UNUSED_PAD src0_sel:WORD_1 src1_sel:DWORD
	v_add3_u32 v14, v14, v46, s24
	v_add3_u32 v15, v15, v47, s24
	v_add3_u32 v16, v16, v48, s24
	v_add3_u32 v17, v17, v49, s24
	v_add3_u32 v18, v18, v50, s24
	v_add3_u32 v19, v19, v51, s24
	v_add3_u32 v20, v20, v52, s24
	v_add3_u32 v21, v21, v53, s24
	v_and_b32_e32 v15, 0xffff0000, v15
	v_and_b32_e32 v17, 0xffff0000, v17
	v_and_b32_e32 v19, 0xffff0000, v19
	v_and_b32_e32 v21, 0xffff0000, v21
	v_or_b32_sdwa v60, v15, v14 dst_sel:DWORD dst_unused:UNUSED_PAD src0_sel:DWORD src1_sel:WORD_1
	v_or_b32_sdwa v61, v17, v16 dst_sel:DWORD dst_unused:UNUSED_PAD src0_sel:DWORD src1_sel:WORD_1
	v_or_b32_sdwa v62, v19, v18 dst_sel:DWORD dst_unused:UNUSED_PAD src0_sel:DWORD src1_sel:WORD_1
	v_or_b32_sdwa v63, v21, v20 dst_sel:DWORD dst_unused:UNUSED_PAD src0_sel:DWORD src1_sel:WORD_1
	global_store_dwordx4 v57, v[60:63], s[56:57]
	v_add_u32_e32 v55, 0xc180, v103
	ds_read2_b32 v[30:31], v55 offset0:0 offset1:1
	ds_read2_b32 v[32:33], v55 offset0:2 offset1:3
	ds_read2_b32 v[34:35], v55 offset0:4 offset1:5
	ds_read2_b32 v[36:37], v55 offset0:6 offset1:7
	v_add_u32_e32 v56, 0xe1c0, v103
	ds_read2_b32 v[38:39], v56 offset0:0 offset1:1
	ds_read2_b32 v[40:41], v56 offset0:2 offset1:3
	ds_read2_b32 v[42:43], v56 offset0:4 offset1:5
	ds_read2_b32 v[44:45], v56 offset0:6 offset1:7
	s_waitcnt vmcnt(7) lgkmcnt(8)
	v_fmamk_f32 v54, v10, 0x3a800000, v13
	v_rsq_f32_e32 v54, v54
	v_add_u32_e32 v58, 0xa0000, v4
	v_mul_f32_e32 v22, v22, v54
	v_mul_f32_e32 v23, v23, v54
	v_mul_f32_e32 v24, v24, v54
	v_mul_f32_e32 v25, v25, v54
	v_mul_f32_e32 v26, v26, v54
	v_mul_f32_e32 v27, v27, v54
	v_mul_f32_e32 v28, v28, v54
	v_mul_f32_e32 v29, v29, v54
	v_max_f32_e32 v22, 0, v22
	v_max_f32_e32 v23, 0, v23
	v_max_f32_e32 v24, 0, v24
	v_max_f32_e32 v25, 0, v25
	v_max_f32_e32 v26, 0, v26
	v_max_f32_e32 v27, 0, v27
	v_max_f32_e32 v28, 0, v28
	v_max_f32_e32 v29, 0, v29
	v_pk_mul_f32 v[22:23], v[22:23], v[22:23]
	v_pk_mul_f32 v[24:25], v[24:25], v[24:25]
	v_pk_mul_f32 v[26:27], v[26:27], v[26:27]
	v_pk_mul_f32 v[28:29], v[28:29], v[28:29]
	v_and_b32_sdwa v46, v22, v59 dst_sel:DWORD dst_unused:UNUSED_PAD src0_sel:WORD_1 src1_sel:DWORD
	v_and_b32_sdwa v47, v23, v59 dst_sel:DWORD dst_unused:UNUSED_PAD src0_sel:WORD_1 src1_sel:DWORD
	v_and_b32_sdwa v48, v24, v59 dst_sel:DWORD dst_unused:UNUSED_PAD src0_sel:WORD_1 src1_sel:DWORD
	v_and_b32_sdwa v49, v25, v59 dst_sel:DWORD dst_unused:UNUSED_PAD src0_sel:WORD_1 src1_sel:DWORD
	v_and_b32_sdwa v50, v26, v59 dst_sel:DWORD dst_unused:UNUSED_PAD src0_sel:WORD_1 src1_sel:DWORD
	v_and_b32_sdwa v51, v27, v59 dst_sel:DWORD dst_unused:UNUSED_PAD src0_sel:WORD_1 src1_sel:DWORD
	v_and_b32_sdwa v52, v28, v59 dst_sel:DWORD dst_unused:UNUSED_PAD src0_sel:WORD_1 src1_sel:DWORD
	v_and_b32_sdwa v53, v29, v59 dst_sel:DWORD dst_unused:UNUSED_PAD src0_sel:WORD_1 src1_sel:DWORD
	v_add3_u32 v22, v22, v46, s24
	v_add3_u32 v23, v23, v47, s24
	v_add3_u32 v24, v24, v48, s24
	v_add3_u32 v25, v25, v49, s24
	v_add3_u32 v26, v26, v50, s24
	v_add3_u32 v27, v27, v51, s24
	v_add3_u32 v28, v28, v52, s24
	v_add3_u32 v29, v29, v53, s24
	v_and_b32_e32 v23, 0xffff0000, v23
	v_and_b32_e32 v25, 0xffff0000, v25
	v_and_b32_e32 v27, 0xffff0000, v27
	v_and_b32_e32 v29, 0xffff0000, v29
	v_or_b32_sdwa v76, v23, v22 dst_sel:DWORD dst_unused:UNUSED_PAD src0_sel:DWORD src1_sel:WORD_1
	v_or_b32_sdwa v77, v25, v24 dst_sel:DWORD dst_unused:UNUSED_PAD src0_sel:DWORD src1_sel:WORD_1
	v_or_b32_sdwa v78, v27, v26 dst_sel:DWORD dst_unused:UNUSED_PAD src0_sel:DWORD src1_sel:WORD_1
	v_or_b32_sdwa v79, v29, v28 dst_sel:DWORD dst_unused:UNUSED_PAD src0_sel:DWORD src1_sel:WORD_1
	global_store_dwordx4 v58, v[76:79], s[56:57]
	s_waitcnt vmcnt(7) lgkmcnt(4)
	v_fmamk_f32 v54, v11, 0x3a800000, v13
	v_rsq_f32_e32 v54, v54
	v_add_u32_e32 v57, 0xc0000, v4
	v_mul_f32_e32 v30, v30, v54
	v_mul_f32_e32 v31, v31, v54
	v_mul_f32_e32 v32, v32, v54
	v_mul_f32_e32 v33, v33, v54
	v_mul_f32_e32 v34, v34, v54
	v_mul_f32_e32 v35, v35, v54
	v_mul_f32_e32 v36, v36, v54
	v_mul_f32_e32 v37, v37, v54
	v_max_f32_e32 v30, 0, v30
	v_max_f32_e32 v31, 0, v31
	v_max_f32_e32 v32, 0, v32
	v_max_f32_e32 v33, 0, v33
	v_max_f32_e32 v34, 0, v34
	v_max_f32_e32 v35, 0, v35
	v_max_f32_e32 v36, 0, v36
	v_max_f32_e32 v37, 0, v37
	v_pk_mul_f32 v[30:31], v[30:31], v[30:31]
	v_pk_mul_f32 v[32:33], v[32:33], v[32:33]
	v_pk_mul_f32 v[34:35], v[34:35], v[34:35]
	v_pk_mul_f32 v[36:37], v[36:37], v[36:37]
	v_and_b32_sdwa v46, v30, v59 dst_sel:DWORD dst_unused:UNUSED_PAD src0_sel:WORD_1 src1_sel:DWORD
	v_and_b32_sdwa v47, v31, v59 dst_sel:DWORD dst_unused:UNUSED_PAD src0_sel:WORD_1 src1_sel:DWORD
	v_and_b32_sdwa v48, v32, v59 dst_sel:DWORD dst_unused:UNUSED_PAD src0_sel:WORD_1 src1_sel:DWORD
	v_and_b32_sdwa v49, v33, v59 dst_sel:DWORD dst_unused:UNUSED_PAD src0_sel:WORD_1 src1_sel:DWORD
	v_and_b32_sdwa v50, v34, v59 dst_sel:DWORD dst_unused:UNUSED_PAD src0_sel:WORD_1 src1_sel:DWORD
	v_and_b32_sdwa v51, v35, v59 dst_sel:DWORD dst_unused:UNUSED_PAD src0_sel:WORD_1 src1_sel:DWORD
	v_and_b32_sdwa v52, v36, v59 dst_sel:DWORD dst_unused:UNUSED_PAD src0_sel:WORD_1 src1_sel:DWORD
	v_and_b32_sdwa v53, v37, v59 dst_sel:DWORD dst_unused:UNUSED_PAD src0_sel:WORD_1 src1_sel:DWORD
	v_add3_u32 v30, v30, v46, s24
	v_add3_u32 v31, v31, v47, s24
	v_add3_u32 v32, v32, v48, s24
	v_add3_u32 v33, v33, v49, s24
	v_add3_u32 v34, v34, v50, s24
	v_add3_u32 v35, v35, v51, s24
	v_add3_u32 v36, v36, v52, s24
	v_add3_u32 v37, v37, v53, s24
	v_and_b32_e32 v31, 0xffff0000, v31
	v_and_b32_e32 v33, 0xffff0000, v33
	v_and_b32_e32 v35, 0xffff0000, v35
	v_and_b32_e32 v37, 0xffff0000, v37
	v_or_b32_sdwa v60, v31, v30 dst_sel:DWORD dst_unused:UNUSED_PAD src0_sel:DWORD src1_sel:WORD_1
	v_or_b32_sdwa v61, v33, v32 dst_sel:DWORD dst_unused:UNUSED_PAD src0_sel:DWORD src1_sel:WORD_1
	v_or_b32_sdwa v62, v35, v34 dst_sel:DWORD dst_unused:UNUSED_PAD src0_sel:DWORD src1_sel:WORD_1
	v_or_b32_sdwa v63, v37, v36 dst_sel:DWORD dst_unused:UNUSED_PAD src0_sel:DWORD src1_sel:WORD_1
	global_store_dwordx4 v57, v[60:63], s[56:57]
	s_waitcnt vmcnt(7) lgkmcnt(0)
	v_fmamk_f32 v54, v12, 0x3a800000, v13
	v_rsq_f32_e32 v54, v54
	v_add_u32_e32 v58, 0xe0000, v4
	v_mul_f32_e32 v38, v38, v54
	v_mul_f32_e32 v39, v39, v54
	v_mul_f32_e32 v40, v40, v54
	v_mul_f32_e32 v41, v41, v54
	v_mul_f32_e32 v42, v42, v54
	v_mul_f32_e32 v43, v43, v54
	v_mul_f32_e32 v44, v44, v54
	v_mul_f32_e32 v45, v45, v54
	v_max_f32_e32 v38, 0, v38
	v_max_f32_e32 v39, 0, v39
	v_max_f32_e32 v40, 0, v40
	v_max_f32_e32 v41, 0, v41
	v_max_f32_e32 v42, 0, v42
	v_max_f32_e32 v43, 0, v43
	v_max_f32_e32 v44, 0, v44
	v_max_f32_e32 v45, 0, v45
	v_pk_mul_f32 v[38:39], v[38:39], v[38:39]
	v_pk_mul_f32 v[40:41], v[40:41], v[40:41]
	v_pk_mul_f32 v[42:43], v[42:43], v[42:43]
	v_pk_mul_f32 v[44:45], v[44:45], v[44:45]
	v_and_b32_sdwa v46, v38, v59 dst_sel:DWORD dst_unused:UNUSED_PAD src0_sel:WORD_1 src1_sel:DWORD
	v_and_b32_sdwa v47, v39, v59 dst_sel:DWORD dst_unused:UNUSED_PAD src0_sel:WORD_1 src1_sel:DWORD
	v_and_b32_sdwa v48, v40, v59 dst_sel:DWORD dst_unused:UNUSED_PAD src0_sel:WORD_1 src1_sel:DWORD
	v_and_b32_sdwa v49, v41, v59 dst_sel:DWORD dst_unused:UNUSED_PAD src0_sel:WORD_1 src1_sel:DWORD
	v_and_b32_sdwa v50, v42, v59 dst_sel:DWORD dst_unused:UNUSED_PAD src0_sel:WORD_1 src1_sel:DWORD
	v_and_b32_sdwa v51, v43, v59 dst_sel:DWORD dst_unused:UNUSED_PAD src0_sel:WORD_1 src1_sel:DWORD
	v_and_b32_sdwa v52, v44, v59 dst_sel:DWORD dst_unused:UNUSED_PAD src0_sel:WORD_1 src1_sel:DWORD
	v_and_b32_sdwa v53, v45, v59 dst_sel:DWORD dst_unused:UNUSED_PAD src0_sel:WORD_1 src1_sel:DWORD
	v_add3_u32 v38, v38, v46, s24
	v_add3_u32 v39, v39, v47, s24
	v_add3_u32 v40, v40, v48, s24
	v_add3_u32 v41, v41, v49, s24
	v_add3_u32 v42, v42, v50, s24
	v_add3_u32 v43, v43, v51, s24
	v_add3_u32 v44, v44, v52, s24
	v_add3_u32 v45, v45, v53, s24
	v_and_b32_e32 v39, 0xffff0000, v39
	v_and_b32_e32 v41, 0xffff0000, v41
	v_and_b32_e32 v43, 0xffff0000, v43
	v_and_b32_e32 v45, 0xffff0000, v45
	v_or_b32_sdwa v76, v39, v38 dst_sel:DWORD dst_unused:UNUSED_PAD src0_sel:DWORD src1_sel:WORD_1
	v_or_b32_sdwa v77, v41, v40 dst_sel:DWORD dst_unused:UNUSED_PAD src0_sel:DWORD src1_sel:WORD_1
	v_or_b32_sdwa v78, v43, v42 dst_sel:DWORD dst_unused:UNUSED_PAD src0_sel:DWORD src1_sel:WORD_1
	v_or_b32_sdwa v79, v45, v44 dst_sel:DWORD dst_unused:UNUSED_PAD src0_sel:DWORD src1_sel:WORD_1
	global_store_dwordx4 v58, v[76:79], s[56:57]
	s_cmpk_lt_u32 s13, 0x400
	s_barrier
	s_cbranch_scc1 .LBB0_338

.LBB0_393:
	s_bfe_u32 s4, s33, 0x70004
	s_mulk_i32 s4, 0x93
	s_bfe_u32 s4, s4, 0x6000a
	s_lshr_b32 s42, s33, 3
	s_mul_i32 s4, s4, 14
	s_sub_i32 s4, s42, s4
	s_and_b32 s53, s4, 0xff
	s_bfe_u32 s4, s33, 0xc0004
	s_mulk_i32 s4, 0x2493
	s_lshr_b32 s4, s4, 10
	s_lshl_b32 s5, s33, 3
	s_and_b32 s4, s4, 0xffc0
	s_and_b32 s5, s5, 56
	s_or_b32 s4, s5, s4
	s_or_b32 s4, s4, s3
	s_lshl_b32 s18, s4, 7
	s_lshl_b64 s[4:5], s[18:19], 11
	v_lshl_add_u64 v[84:85], v[70:71], 0, s[4:5]
	v_add_co_u32_e32 v88, vcc, s47, v84
	s_lshl_b32 s18, s53, 18
	s_nop 0
	v_addc_co_u32_e32 v89, vcc, 0, v85, vcc
	v_add_co_u32_e32 v90, vcc, s48, v84
	v_lshl_add_u64 v[86:87], v[72:73], 0, s[18:19]
	s_nop 0
	v_addc_co_u32_e32 v91, vcc, 0, v85, vcc
	v_add_co_u32_e32 v92, vcc, s49, v84
	global_load_dwordx4 v[2:5], v[84:85], off
	global_load_dwordx4 v[6:9], v[88:89], off
	v_addc_co_u32_e32 v93, vcc, 0, v85, vcc
	global_load_dwordx4 v[10:13], v[90:91], off
	global_load_dwordx4 v[14:17], v[92:93], off
	global_load_dwordx4 v[18:21], v[86:87], off
	v_add_co_u32_e32 v94, vcc, s47, v86
	s_nop 1
	v_addc_co_u32_e32 v95, vcc, 0, v87, vcc
	v_add_co_u32_e32 v96, vcc, s48, v86
	global_load_dwordx4 v[22:25], v[94:95], off
	s_nop 0
	v_addc_co_u32_e32 v97, vcc, 0, v87, vcc
	global_load_dwordx4 v[26:29], v[96:97], off
	v_add_co_u32_e32 v98, vcc, s49, v86
	s_nop 1
	v_addc_co_u32_e32 v99, vcc, 0, v87, vcc
	global_load_dwordx4 v[30:33], v[98:99], off
	global_load_dwordx4 v[130:133], v[84:85], off offset:128
	global_load_dwordx4 v[134:137], v[86:87], off offset:128
	global_load_dwordx4 v[138:141], v[88:89], off offset:128
	global_load_dwordx4 v[142:145], v[90:91], off offset:128
	global_load_dwordx4 v[146:149], v[92:93], off offset:128
	global_load_dwordx4 v[150:153], v[94:95], off offset:128
	global_load_dwordx4 v[154:157], v[96:97], off offset:128
	global_load_dwordx4 v[158:161], v[98:99], off offset:128
	s_waitcnt vmcnt(15)
	ds_write_b128 v100, v[2:5]
	s_waitcnt vmcnt(11)
	ds_write_b128 v100, v[18:21] offset:36864
	ds_write_b128 v100, v[6:9] offset:4608
	ds_write_b128 v100, v[10:13] offset:9216
	ds_write_b128 v100, v[14:17] offset:13824
	s_waitcnt vmcnt(10)
	ds_write_b128 v100, v[22:25] offset:41472
	s_waitcnt vmcnt(9)
	ds_write_b128 v100, v[26:29] offset:46080
	s_waitcnt vmcnt(8)
	ds_write_b128 v100, v[30:33] offset:50688
	s_waitcnt lgkmcnt(0)
	s_barrier
	global_load_dwordx4 v[162:165], v[88:89], off offset:256
	global_load_dwordx4 v[166:169], v[90:91], off offset:256
	global_load_dwordx4 v[170:173], v[84:85], off offset:256
	global_load_dwordx4 v[174:177], v[86:87], off offset:256
	global_load_dwordx4 v[178:181], v[92:93], off offset:256
	global_load_dwordx4 v[182:185], v[94:95], off offset:256
	global_load_dwordx4 v[186:189], v[96:97], off offset:256
	global_load_dwordx4 v[190:193], v[98:99], off offset:256
	ds_read_b128 v[18:21], v66
	ds_read_b128 v[34:37], v67 offset:36864
	ds_read_b128 v[194:197], v66 offset:32
	ds_read_b128 v[198:201], v67 offset:36896
	ds_read_b128 v[50:53], v67 offset:41472
	ds_read_b128 v[202:205], v67 offset:41504
	ds_read_b128 v[54:57], v66 offset:4608
	ds_read_b128 v[206:209], v66 offset:4640
	s_waitcnt lgkmcnt(6)
	v_mfma_f32_32x32x16_bf16 v[2:17], v[18:21], v[34:37], 0
	s_waitcnt lgkmcnt(3)
	v_mfma_f32_32x32x16_bf16 v[18:33], v[18:21], v[50:53], 0
	s_waitcnt lgkmcnt(1)
	v_mfma_f32_32x32x16_bf16 v[34:49], v[54:57], v[34:37], 0
	v_mfma_f32_32x32x16_bf16 v[50:65], v[54:57], v[50:53], 0
	v_mfma_f32_32x32x16_bf16 v[2:17], v[194:197], v[198:201], v[2:17]
	v_mfma_f32_32x32x16_bf16 v[18:33], v[194:197], v[202:205], v[18:33]
	s_waitcnt lgkmcnt(0)
	v_mfma_f32_32x32x16_bf16 v[34:49], v[206:209], v[198:201], v[34:49]
	v_mfma_f32_32x32x16_bf16 v[50:65], v[206:209], v[202:205], v[50:65]
	ds_read_b128 v[194:197], v66 offset:64
	ds_read_b128 v[198:201], v67 offset:36928
	ds_read_b128 v[202:205], v66 offset:96
	ds_read_b128 v[206:209], v67 offset:36960
	ds_read_b128 v[210:213], v67 offset:41536
	ds_read_b128 v[214:217], v67 offset:41568
	s_waitcnt lgkmcnt(4)
	v_mfma_f32_32x32x16_bf16 v[2:17], v[194:197], v[198:201], v[2:17]
	s_waitcnt lgkmcnt(1)
	v_mfma_f32_32x32x16_bf16 v[18:33], v[194:197], v[210:213], v[18:33]
	ds_read_b128 v[194:197], v66 offset:4672
	ds_read_b128 v[218:221], v66 offset:4704
	s_waitcnt vmcnt(15)
	ds_write_b128 v100, v[130:133] offset:18432
	s_waitcnt vmcnt(13)
	ds_write_b128 v100, v[138:141] offset:23040
	s_waitcnt vmcnt(12)
	ds_write_b128 v100, v[142:145] offset:27648
	s_waitcnt vmcnt(11)
	ds_write_b128 v100, v[146:149] offset:32256
	ds_write_b128 v100, v[134:137] offset:55296
	s_waitcnt vmcnt(10)
	ds_write_b128 v100, v[150:153] offset:59904
	s_waitcnt vmcnt(9)
	ds_write_b128 v100, v[154:157] offset:64512
	s_waitcnt vmcnt(8)
	ds_write_b128 v101, v[158:161] offset:32256
	global_load_dwordx4 v[130:133], v[88:89], off offset:384
	global_load_dwordx4 v[134:137], v[90:91], off offset:384
	global_load_dwordx4 v[138:141], v[84:85], off offset:384
	global_load_dwordx4 v[142:145], v[86:87], off offset:384
	global_load_dwordx4 v[146:149], v[92:93], off offset:384
	global_load_dwordx4 v[150:153], v[94:95], off offset:384
	global_load_dwordx4 v[154:157], v[96:97], off offset:384
	global_load_dwordx4 v[158:161], v[98:99], off offset:384
	s_waitcnt lgkmcnt(0)
	s_barrier
	v_mfma_f32_32x32x16_bf16 v[34:49], v[194:197], v[198:201], v[34:49]
	v_mfma_f32_32x32x16_bf16 v[50:65], v[194:197], v[210:213], v[50:65]
	v_mfma_f32_32x32x16_bf16 v[2:17], v[202:205], v[206:209], v[2:17]
	v_mfma_f32_32x32x16_bf16 v[18:33], v[202:205], v[214:217], v[18:33]
	v_mfma_f32_32x32x16_bf16 v[34:49], v[218:221], v[206:209], v[34:49]
	v_mfma_f32_32x32x16_bf16 v[50:65], v[218:221], v[214:217], v[50:65]
	ds_read_b128 v[194:197], v66 offset:18432
	ds_read_b128 v[198:201], v67 offset:55296
	ds_read_b128 v[202:205], v66 offset:18464
	ds_read_b128 v[206:209], v67 offset:55328
	ds_read_b128 v[210:213], v67 offset:59904
	ds_read_b128 v[214:217], v67 offset:59936
	s_waitcnt lgkmcnt(4)
	v_mfma_f32_32x32x16_bf16 v[2:17], v[194:197], v[198:201], v[2:17]
	s_waitcnt lgkmcnt(1)
	v_mfma_f32_32x32x16_bf16 v[18:33], v[194:197], v[210:213], v[18:33]
	ds_read_b128 v[194:197], v66 offset:23040
	ds_read_b128 v[218:221], v66 offset:23072
	s_waitcnt lgkmcnt(1)
	v_mfma_f32_32x32x16_bf16 v[34:49], v[194:197], v[198:201], v[34:49]
	v_mfma_f32_32x32x16_bf16 v[50:65], v[194:197], v[210:213], v[50:65]
	v_mfma_f32_32x32x16_bf16 v[2:17], v[202:205], v[206:209], v[2:17]
	v_mfma_f32_32x32x16_bf16 v[18:33], v[202:205], v[214:217], v[18:33]
	s_waitcnt lgkmcnt(0)
	v_mfma_f32_32x32x16_bf16 v[34:49], v[218:221], v[206:209], v[34:49]
	ds_read_b128 v[194:197], v66 offset:18496
	ds_read_b128 v[198:201], v67 offset:55360
	ds_read_b128 v[202:205], v66 offset:18528
	ds_read_b128 v[206:209], v67 offset:55392
	v_mfma_f32_32x32x16_bf16 v[50:65], v[218:221], v[214:217], v[50:65]
	ds_read_b128 v[210:213], v67 offset:59968
	ds_read_b128 v[214:217], v67 offset:60000
	s_waitcnt lgkmcnt(4)
	v_mfma_f32_32x32x16_bf16 v[2:17], v[194:197], v[198:201], v[2:17]
	s_waitcnt lgkmcnt(1)
	v_mfma_f32_32x32x16_bf16 v[18:33], v[194:197], v[210:213], v[18:33]
	ds_read_b128 v[194:197], v66 offset:23104
	ds_read_b128 v[218:221], v66 offset:23136
	s_waitcnt vmcnt(13)
	ds_write_b128 v100, v[170:173]
	ds_write_b128 v100, v[162:165] offset:4608
	ds_write_b128 v100, v[166:169] offset:9216
	s_waitcnt vmcnt(11)
	ds_write_b128 v100, v[178:181] offset:13824
	ds_write_b128 v100, v[174:177] offset:36864
	s_waitcnt vmcnt(10)
	ds_write_b128 v100, v[182:185] offset:41472
	s_waitcnt vmcnt(9)
	ds_write_b128 v100, v[186:189] offset:46080
	s_waitcnt vmcnt(8)
	ds_write_b128 v100, v[190:193] offset:50688
	global_load_dwordx4 v[162:165], v[88:89], off offset:512
	global_load_dwordx4 v[166:169], v[90:91], off offset:512
	global_load_dwordx4 v[170:173], v[84:85], off offset:512
	global_load_dwordx4 v[174:177], v[86:87], off offset:512
	global_load_dwordx4 v[178:181], v[92:93], off offset:512
	global_load_dwordx4 v[182:185], v[94:95], off offset:512
	global_load_dwordx4 v[186:189], v[96:97], off offset:512
	global_load_dwordx4 v[190:193], v[98:99], off offset:512
	s_waitcnt lgkmcnt(0)
	s_barrier
	v_mfma_f32_32x32x16_bf16 v[34:49], v[194:197], v[198:201], v[34:49]
	v_mfma_f32_32x32x16_bf16 v[50:65], v[194:197], v[210:213], v[50:65]
	v_mfma_f32_32x32x16_bf16 v[2:17], v[202:205], v[206:209], v[2:17]
	v_mfma_f32_32x32x16_bf16 v[18:33], v[202:205], v[214:217], v[18:33]
	v_mfma_f32_32x32x16_bf16 v[34:49], v[218:221], v[206:209], v[34:49]
	v_mfma_f32_32x32x16_bf16 v[50:65], v[218:221], v[214:217], v[50:65]
	ds_read_b128 v[194:197], v66
	ds_read_b128 v[198:201], v67 offset:36864
	ds_read_b128 v[202:205], v66 offset:32
	ds_read_b128 v[206:209], v67 offset:36896
	ds_read_b128 v[210:213], v67 offset:41472
	ds_read_b128 v[214:217], v67 offset:41504
	s_waitcnt lgkmcnt(4)
	v_mfma_f32_32x32x16_bf16 v[2:17], v[194:197], v[198:201], v[2:17]
	s_waitcnt lgkmcnt(1)
	v_mfma_f32_32x32x16_bf16 v[18:33], v[194:197], v[210:213], v[18:33]
	ds_read_b128 v[194:197], v66 offset:4608
	ds_read_b128 v[218:221], v66 offset:4640
	s_waitcnt lgkmcnt(1)
	v_mfma_f32_32x32x16_bf16 v[34:49], v[194:197], v[198:201], v[34:49]
	v_mfma_f32_32x32x16_bf16 v[50:65], v[194:197], v[210:213], v[50:65]
	v_mfma_f32_32x32x16_bf16 v[2:17], v[202:205], v[206:209], v[2:17]
	v_mfma_f32_32x32x16_bf16 v[18:33], v[202:205], v[214:217], v[18:33]
	s_waitcnt lgkmcnt(0)
	v_mfma_f32_32x32x16_bf16 v[34:49], v[218:221], v[206:209], v[34:49]
	ds_read_b128 v[194:197], v66 offset:64
	ds_read_b128 v[198:201], v67 offset:36928
	ds_read_b128 v[202:205], v66 offset:96
	ds_read_b128 v[206:209], v67 offset:36960
	v_mfma_f32_32x32x16_bf16 v[50:65], v[218:221], v[214:217], v[50:65]
	ds_read_b128 v[210:213], v67 offset:41536
	ds_read_b128 v[214:217], v67 offset:41568
	s_waitcnt lgkmcnt(4)
	v_mfma_f32_32x32x16_bf16 v[2:17], v[194:197], v[198:201], v[2:17]
	s_waitcnt lgkmcnt(1)
	v_mfma_f32_32x32x16_bf16 v[18:33], v[194:197], v[210:213], v[18:33]
	ds_read_b128 v[194:197], v66 offset:4672
	ds_read_b128 v[218:221], v66 offset:4704
	s_waitcnt vmcnt(13)
	ds_write_b128 v100, v[138:141] offset:18432
	ds_write_b128 v100, v[130:133] offset:23040
	ds_write_b128 v100, v[134:137] offset:27648
	s_waitcnt vmcnt(11)
	ds_write_b128 v100, v[146:149] offset:32256
	ds_write_b128 v100, v[142:145] offset:55296
	s_waitcnt vmcnt(10)
	ds_write_b128 v100, v[150:153] offset:59904
	s_waitcnt vmcnt(9)
	ds_write_b128 v100, v[154:157] offset:64512
	s_waitcnt vmcnt(8)
	ds_write_b128 v101, v[158:161] offset:32256
	global_load_dwordx4 v[130:133], v[88:89], off offset:640
	global_load_dwordx4 v[134:137], v[90:91], off offset:640
	global_load_dwordx4 v[138:141], v[84:85], off offset:640
	global_load_dwordx4 v[142:145], v[86:87], off offset:640
	global_load_dwordx4 v[146:149], v[92:93], off offset:640
	global_load_dwordx4 v[150:153], v[94:95], off offset:640
	global_load_dwordx4 v[154:157], v[96:97], off offset:640
	global_load_dwordx4 v[158:161], v[98:99], off offset:640
	s_waitcnt lgkmcnt(0)
	s_barrier
	v_mfma_f32_32x32x16_bf16 v[34:49], v[194:197], v[198:201], v[34:49]
	v_mfma_f32_32x32x16_bf16 v[50:65], v[194:197], v[210:213], v[50:65]
	v_mfma_f32_32x32x16_bf16 v[2:17], v[202:205], v[206:209], v[2:17]
	v_mfma_f32_32x32x16_bf16 v[18:33], v[202:205], v[214:217], v[18:33]
	v_mfma_f32_32x32x16_bf16 v[34:49], v[218:221], v[206:209], v[34:49]
	v_mfma_f32_32x32x16_bf16 v[50:65], v[218:221], v[214:217], v[50:65]
	ds_read_b128 v[194:197], v66 offset:18432
	ds_read_b128 v[198:201], v67 offset:55296
	ds_read_b128 v[202:205], v66 offset:18464
	ds_read_b128 v[206:209], v67 offset:55328
	ds_read_b128 v[210:213], v67 offset:59904
	ds_read_b128 v[214:217], v67 offset:59936
	s_waitcnt lgkmcnt(4)
	v_mfma_f32_32x32x16_bf16 v[2:17], v[194:197], v[198:201], v[2:17]
	s_waitcnt lgkmcnt(1)
	v_mfma_f32_32x32x16_bf16 v[18:33], v[194:197], v[210:213], v[18:33]
	ds_read_b128 v[194:197], v66 offset:23040
	ds_read_b128 v[218:221], v66 offset:23072
	s_waitcnt lgkmcnt(1)
	v_mfma_f32_32x32x16_bf16 v[34:49], v[194:197], v[198:201], v[34:49]
	v_mfma_f32_32x32x16_bf16 v[50:65], v[194:197], v[210:213], v[50:65]
	v_mfma_f32_32x32x16_bf16 v[2:17], v[202:205], v[206:209], v[2:17]
	v_mfma_f32_32x32x16_bf16 v[18:33], v[202:205], v[214:217], v[18:33]
	s_waitcnt lgkmcnt(0)
	v_mfma_f32_32x32x16_bf16 v[34:49], v[218:221], v[206:209], v[34:49]
	ds_read_b128 v[194:197], v66 offset:18496
	ds_read_b128 v[198:201], v67 offset:55360
	ds_read_b128 v[202:205], v66 offset:18528
	ds_read_b128 v[206:209], v67 offset:55392
	v_mfma_f32_32x32x16_bf16 v[50:65], v[218:221], v[214:217], v[50:65]
	ds_read_b128 v[210:213], v67 offset:59968
	ds_read_b128 v[214:217], v67 offset:60000
	s_waitcnt lgkmcnt(4)
	v_mfma_f32_32x32x16_bf16 v[2:17], v[194:197], v[198:201], v[2:17]
	s_waitcnt lgkmcnt(1)
	v_mfma_f32_32x32x16_bf16 v[18:33], v[194:197], v[210:213], v[18:33]
	ds_read_b128 v[194:197], v66 offset:23104
	ds_read_b128 v[218:221], v66 offset:23136
	s_waitcnt vmcnt(13)
	ds_write_b128 v100, v[170:173]
	ds_write_b128 v100, v[162:165] offset:4608
	ds_write_b128 v100, v[166:169] offset:9216
	s_waitcnt vmcnt(11)
	ds_write_b128 v100, v[178:181] offset:13824
	ds_write_b128 v100, v[174:177] offset:36864
	s_waitcnt vmcnt(10)
	ds_write_b128 v100, v[182:185] offset:41472
	s_waitcnt vmcnt(9)
	ds_write_b128 v100, v[186:189] offset:46080
	s_waitcnt vmcnt(8)
	ds_write_b128 v100, v[190:193] offset:50688
	global_load_dwordx4 v[162:165], v[88:89], off offset:768
	global_load_dwordx4 v[166:169], v[90:91], off offset:768
	global_load_dwordx4 v[170:173], v[84:85], off offset:768
	global_load_dwordx4 v[174:177], v[86:87], off offset:768
	global_load_dwordx4 v[178:181], v[92:93], off offset:768
	global_load_dwordx4 v[182:185], v[94:95], off offset:768
	global_load_dwordx4 v[186:189], v[96:97], off offset:768
	global_load_dwordx4 v[190:193], v[98:99], off offset:768
	s_waitcnt lgkmcnt(0)
	s_barrier
	v_mfma_f32_32x32x16_bf16 v[34:49], v[194:197], v[198:201], v[34:49]
	v_mfma_f32_32x32x16_bf16 v[50:65], v[194:197], v[210:213], v[50:65]
	v_mfma_f32_32x32x16_bf16 v[2:17], v[202:205], v[206:209], v[2:17]
	v_mfma_f32_32x32x16_bf16 v[18:33], v[202:205], v[214:217], v[18:33]
	v_mfma_f32_32x32x16_bf16 v[34:49], v[218:221], v[206:209], v[34:49]
	v_mfma_f32_32x32x16_bf16 v[50:65], v[218:221], v[214:217], v[50:65]
	ds_read_b128 v[194:197], v66
	ds_read_b128 v[198:201], v67 offset:36864
	ds_read_b128 v[202:205], v66 offset:32
	ds_read_b128 v[206:209], v67 offset:36896
	ds_read_b128 v[210:213], v67 offset:41472
	ds_read_b128 v[214:217], v67 offset:41504
	s_waitcnt lgkmcnt(4)
	v_mfma_f32_32x32x16_bf16 v[2:17], v[194:197], v[198:201], v[2:17]
	s_waitcnt lgkmcnt(1)
	v_mfma_f32_32x32x16_bf16 v[18:33], v[194:197], v[210:213], v[18:33]
	ds_read_b128 v[194:197], v66 offset:4608
	ds_read_b128 v[218:221], v66 offset:4640
	s_waitcnt lgkmcnt(1)
	v_mfma_f32_32x32x16_bf16 v[34:49], v[194:197], v[198:201], v[34:49]
	v_mfma_f32_32x32x16_bf16 v[50:65], v[194:197], v[210:213], v[50:65]
	v_mfma_f32_32x32x16_bf16 v[2:17], v[202:205], v[206:209], v[2:17]
	v_mfma_f32_32x32x16_bf16 v[18:33], v[202:205], v[214:217], v[18:33]
	s_waitcnt lgkmcnt(0)
	v_mfma_f32_32x32x16_bf16 v[34:49], v[218:221], v[206:209], v[34:49]
	ds_read_b128 v[194:197], v66 offset:64
	ds_read_b128 v[198:201], v67 offset:36928
	ds_read_b128 v[202:205], v66 offset:96
	ds_read_b128 v[206:209], v67 offset:36960
	v_mfma_f32_32x32x16_bf16 v[50:65], v[218:221], v[214:217], v[50:65]
	ds_read_b128 v[210:213], v67 offset:41536
	ds_read_b128 v[214:217], v67 offset:41568
	s_waitcnt lgkmcnt(4)
	v_mfma_f32_32x32x16_bf16 v[2:17], v[194:197], v[198:201], v[2:17]
	s_waitcnt lgkmcnt(1)
	v_mfma_f32_32x32x16_bf16 v[18:33], v[194:197], v[210:213], v[18:33]
	ds_read_b128 v[194:197], v66 offset:4672
	ds_read_b128 v[218:221], v66 offset:4704
	s_waitcnt vmcnt(13)
	ds_write_b128 v100, v[138:141] offset:18432
	ds_write_b128 v100, v[130:133] offset:23040
	ds_write_b128 v100, v[134:137] offset:27648
	s_waitcnt vmcnt(11)
	ds_write_b128 v100, v[146:149] offset:32256
	ds_write_b128 v100, v[142:145] offset:55296
	s_waitcnt vmcnt(10)
	ds_write_b128 v100, v[150:153] offset:59904
	s_waitcnt vmcnt(9)
	ds_write_b128 v100, v[154:157] offset:64512
	s_waitcnt vmcnt(8)
	ds_write_b128 v101, v[158:161] offset:32256
	global_load_dwordx4 v[130:133], v[88:89], off offset:896
	global_load_dwordx4 v[134:137], v[90:91], off offset:896
	global_load_dwordx4 v[138:141], v[84:85], off offset:896
	global_load_dwordx4 v[142:145], v[86:87], off offset:896
	global_load_dwordx4 v[146:149], v[92:93], off offset:896
	global_load_dwordx4 v[150:153], v[94:95], off offset:896
	global_load_dwordx4 v[154:157], v[96:97], off offset:896
	global_load_dwordx4 v[158:161], v[98:99], off offset:896
	s_waitcnt lgkmcnt(0)
	s_barrier
	v_mfma_f32_32x32x16_bf16 v[34:49], v[194:197], v[198:201], v[34:49]
	v_mfma_f32_32x32x16_bf16 v[50:65], v[194:197], v[210:213], v[50:65]
	v_mfma_f32_32x32x16_bf16 v[2:17], v[202:205], v[206:209], v[2:17]
	v_mfma_f32_32x32x16_bf16 v[18:33], v[202:205], v[214:217], v[18:33]
	v_mfma_f32_32x32x16_bf16 v[34:49], v[218:221], v[206:209], v[34:49]
	v_mfma_f32_32x32x16_bf16 v[50:65], v[218:221], v[214:217], v[50:65]
	ds_read_b128 v[194:197], v66 offset:18432
	ds_read_b128 v[198:201], v67 offset:55296
	ds_read_b128 v[202:205], v66 offset:18464
	ds_read_b128 v[206:209], v67 offset:55328
	ds_read_b128 v[210:213], v67 offset:59904
	ds_read_b128 v[214:217], v67 offset:59936
	s_waitcnt lgkmcnt(4)
	v_mfma_f32_32x32x16_bf16 v[2:17], v[194:197], v[198:201], v[2:17]
	s_waitcnt lgkmcnt(1)
	v_mfma_f32_32x32x16_bf16 v[18:33], v[194:197], v[210:213], v[18:33]
	ds_read_b128 v[194:197], v66 offset:23040
	ds_read_b128 v[218:221], v66 offset:23072
	s_waitcnt lgkmcnt(1)
	v_mfma_f32_32x32x16_bf16 v[34:49], v[194:197], v[198:201], v[34:49]
	v_mfma_f32_32x32x16_bf16 v[50:65], v[194:197], v[210:213], v[50:65]
	v_mfma_f32_32x32x16_bf16 v[2:17], v[202:205], v[206:209], v[2:17]
	v_mfma_f32_32x32x16_bf16 v[18:33], v[202:205], v[214:217], v[18:33]
	s_waitcnt lgkmcnt(0)
	v_mfma_f32_32x32x16_bf16 v[34:49], v[218:221], v[206:209], v[34:49]
	ds_read_b128 v[194:197], v66 offset:18496
	ds_read_b128 v[198:201], v67 offset:55360
	ds_read_b128 v[202:205], v66 offset:18528
	ds_read_b128 v[206:209], v67 offset:55392
	v_mfma_f32_32x32x16_bf16 v[50:65], v[218:221], v[214:217], v[50:65]
	ds_read_b128 v[210:213], v67 offset:59968
	ds_read_b128 v[214:217], v67 offset:60000
	s_waitcnt lgkmcnt(4)
	v_mfma_f32_32x32x16_bf16 v[2:17], v[194:197], v[198:201], v[2:17]
	s_waitcnt lgkmcnt(1)
	v_mfma_f32_32x32x16_bf16 v[18:33], v[194:197], v[210:213], v[18:33]
	ds_read_b128 v[194:197], v66 offset:23104
	ds_read_b128 v[218:221], v66 offset:23136
	s_waitcnt vmcnt(13)
	ds_write_b128 v100, v[170:173]
	ds_write_b128 v100, v[162:165] offset:4608
	ds_write_b128 v100, v[166:169] offset:9216
	s_waitcnt vmcnt(11)
	ds_write_b128 v100, v[178:181] offset:13824
	ds_write_b128 v100, v[174:177] offset:36864
	s_waitcnt vmcnt(10)
	ds_write_b128 v100, v[182:185] offset:41472
	s_waitcnt vmcnt(9)
	ds_write_b128 v100, v[186:189] offset:46080
	s_waitcnt vmcnt(8)
	ds_write_b128 v100, v[190:193] offset:50688
	global_load_dwordx4 v[162:165], v[88:89], off offset:1024
	global_load_dwordx4 v[166:169], v[90:91], off offset:1024
	global_load_dwordx4 v[170:173], v[84:85], off offset:1024
	global_load_dwordx4 v[174:177], v[86:87], off offset:1024
	global_load_dwordx4 v[178:181], v[92:93], off offset:1024
	global_load_dwordx4 v[182:185], v[94:95], off offset:1024
	global_load_dwordx4 v[186:189], v[96:97], off offset:1024
	global_load_dwordx4 v[190:193], v[98:99], off offset:1024
	s_waitcnt lgkmcnt(0)
	s_barrier
	v_mfma_f32_32x32x16_bf16 v[34:49], v[194:197], v[198:201], v[34:49]
	v_mfma_f32_32x32x16_bf16 v[50:65], v[194:197], v[210:213], v[50:65]
	v_mfma_f32_32x32x16_bf16 v[2:17], v[202:205], v[206:209], v[2:17]
	v_mfma_f32_32x32x16_bf16 v[18:33], v[202:205], v[214:217], v[18:33]
	v_mfma_f32_32x32x16_bf16 v[34:49], v[218:221], v[206:209], v[34:49]
	v_mfma_f32_32x32x16_bf16 v[50:65], v[218:221], v[214:217], v[50:65]
	ds_read_b128 v[194:197], v66
	ds_read_b128 v[198:201], v67 offset:36864
	ds_read_b128 v[202:205], v66 offset:32
	ds_read_b128 v[206:209], v67 offset:36896
	ds_read_b128 v[210:213], v67 offset:41472
	ds_read_b128 v[214:217], v67 offset:41504
	s_waitcnt lgkmcnt(4)
	v_mfma_f32_32x32x16_bf16 v[2:17], v[194:197], v[198:201], v[2:17]
	s_waitcnt lgkmcnt(1)
	v_mfma_f32_32x32x16_bf16 v[18:33], v[194:197], v[210:213], v[18:33]
	ds_read_b128 v[194:197], v66 offset:4608
	ds_read_b128 v[218:221], v66 offset:4640
	s_waitcnt lgkmcnt(1)
	v_mfma_f32_32x32x16_bf16 v[34:49], v[194:197], v[198:201], v[34:49]
	v_mfma_f32_32x32x16_bf16 v[50:65], v[194:197], v[210:213], v[50:65]
	v_mfma_f32_32x32x16_bf16 v[2:17], v[202:205], v[206:209], v[2:17]
	v_mfma_f32_32x32x16_bf16 v[18:33], v[202:205], v[214:217], v[18:33]
	s_waitcnt lgkmcnt(0)
	v_mfma_f32_32x32x16_bf16 v[34:49], v[218:221], v[206:209], v[34:49]
	ds_read_b128 v[194:197], v66 offset:64
	ds_read_b128 v[198:201], v67 offset:36928
	ds_read_b128 v[202:205], v66 offset:96
	ds_read_b128 v[206:209], v67 offset:36960
	v_mfma_f32_32x32x16_bf16 v[50:65], v[218:221], v[214:217], v[50:65]
	ds_read_b128 v[210:213], v67 offset:41536
	ds_read_b128 v[214:217], v67 offset:41568
	s_waitcnt lgkmcnt(4)
	v_mfma_f32_32x32x16_bf16 v[2:17], v[194:197], v[198:201], v[2:17]
	s_waitcnt lgkmcnt(1)
	v_mfma_f32_32x32x16_bf16 v[18:33], v[194:197], v[210:213], v[18:33]
	ds_read_b128 v[194:197], v66 offset:4672
	ds_read_b128 v[218:221], v66 offset:4704
	s_waitcnt vmcnt(13)
	ds_write_b128 v100, v[138:141] offset:18432
	ds_write_b128 v100, v[130:133] offset:23040
	ds_write_b128 v100, v[134:137] offset:27648
	s_waitcnt vmcnt(11)
	ds_write_b128 v100, v[146:149] offset:32256
	ds_write_b128 v100, v[142:145] offset:55296
	s_waitcnt vmcnt(10)
	ds_write_b128 v100, v[150:153] offset:59904
	s_waitcnt vmcnt(9)
	ds_write_b128 v100, v[154:157] offset:64512
	s_waitcnt vmcnt(8)
	ds_write_b128 v101, v[158:161] offset:32256
	global_load_dwordx4 v[130:133], v[88:89], off offset:1152
	global_load_dwordx4 v[134:137], v[90:91], off offset:1152
	global_load_dwordx4 v[138:141], v[84:85], off offset:1152
	global_load_dwordx4 v[142:145], v[86:87], off offset:1152
	global_load_dwordx4 v[146:149], v[92:93], off offset:1152
	global_load_dwordx4 v[150:153], v[94:95], off offset:1152
	global_load_dwordx4 v[154:157], v[96:97], off offset:1152
	global_load_dwordx4 v[158:161], v[98:99], off offset:1152
	s_waitcnt lgkmcnt(0)
	s_barrier
	v_mfma_f32_32x32x16_bf16 v[34:49], v[194:197], v[198:201], v[34:49]
	v_mfma_f32_32x32x16_bf16 v[50:65], v[194:197], v[210:213], v[50:65]
	v_mfma_f32_32x32x16_bf16 v[2:17], v[202:205], v[206:209], v[2:17]
	v_mfma_f32_32x32x16_bf16 v[18:33], v[202:205], v[214:217], v[18:33]
	v_mfma_f32_32x32x16_bf16 v[34:49], v[218:221], v[206:209], v[34:49]
	v_mfma_f32_32x32x16_bf16 v[50:65], v[218:221], v[214:217], v[50:65]
	ds_read_b128 v[194:197], v66 offset:18432
	ds_read_b128 v[198:201], v67 offset:55296
	ds_read_b128 v[202:205], v66 offset:18464
	ds_read_b128 v[206:209], v67 offset:55328
	ds_read_b128 v[210:213], v67 offset:59904
	ds_read_b128 v[214:217], v67 offset:59936
	s_waitcnt lgkmcnt(4)
	v_mfma_f32_32x32x16_bf16 v[2:17], v[194:197], v[198:201], v[2:17]
	s_waitcnt lgkmcnt(1)
	v_mfma_f32_32x32x16_bf16 v[18:33], v[194:197], v[210:213], v[18:33]
	ds_read_b128 v[194:197], v66 offset:23040
	ds_read_b128 v[218:221], v66 offset:23072
	s_waitcnt lgkmcnt(1)
	v_mfma_f32_32x32x16_bf16 v[34:49], v[194:197], v[198:201], v[34:49]
	v_mfma_f32_32x32x16_bf16 v[50:65], v[194:197], v[210:213], v[50:65]
	v_mfma_f32_32x32x16_bf16 v[2:17], v[202:205], v[206:209], v[2:17]
	v_mfma_f32_32x32x16_bf16 v[18:33], v[202:205], v[214:217], v[18:33]
	s_waitcnt lgkmcnt(0)
	v_mfma_f32_32x32x16_bf16 v[34:49], v[218:221], v[206:209], v[34:49]
	ds_read_b128 v[194:197], v66 offset:18496
	ds_read_b128 v[198:201], v67 offset:55360
	ds_read_b128 v[202:205], v66 offset:18528
	ds_read_b128 v[206:209], v67 offset:55392
	v_mfma_f32_32x32x16_bf16 v[50:65], v[218:221], v[214:217], v[50:65]
	ds_read_b128 v[210:213], v67 offset:59968
	ds_read_b128 v[214:217], v67 offset:60000
	s_waitcnt lgkmcnt(4)
	v_mfma_f32_32x32x16_bf16 v[2:17], v[194:197], v[198:201], v[2:17]
	s_waitcnt lgkmcnt(1)
	v_mfma_f32_32x32x16_bf16 v[18:33], v[194:197], v[210:213], v[18:33]
	ds_read_b128 v[194:197], v66 offset:23104
	ds_read_b128 v[218:221], v66 offset:23136
	s_waitcnt vmcnt(13)
	ds_write_b128 v100, v[170:173]
	ds_write_b128 v100, v[162:165] offset:4608
	ds_write_b128 v100, v[166:169] offset:9216
	s_waitcnt vmcnt(11)
	ds_write_b128 v100, v[178:181] offset:13824
	ds_write_b128 v100, v[174:177] offset:36864
	s_waitcnt vmcnt(10)
	ds_write_b128 v100, v[182:185] offset:41472
	s_waitcnt vmcnt(9)
	ds_write_b128 v100, v[186:189] offset:46080
	s_waitcnt vmcnt(8)
	ds_write_b128 v100, v[190:193] offset:50688
	global_load_dwordx4 v[162:165], v[88:89], off offset:1280
	global_load_dwordx4 v[166:169], v[90:91], off offset:1280
	global_load_dwordx4 v[170:173], v[84:85], off offset:1280
	global_load_dwordx4 v[174:177], v[86:87], off offset:1280
	global_load_dwordx4 v[178:181], v[92:93], off offset:1280
	global_load_dwordx4 v[182:185], v[94:95], off offset:1280
	global_load_dwordx4 v[186:189], v[96:97], off offset:1280
	global_load_dwordx4 v[190:193], v[98:99], off offset:1280
	s_waitcnt lgkmcnt(0)
	s_barrier
	v_mfma_f32_32x32x16_bf16 v[34:49], v[194:197], v[198:201], v[34:49]
	v_mfma_f32_32x32x16_bf16 v[50:65], v[194:197], v[210:213], v[50:65]
	v_mfma_f32_32x32x16_bf16 v[2:17], v[202:205], v[206:209], v[2:17]
	v_mfma_f32_32x32x16_bf16 v[18:33], v[202:205], v[214:217], v[18:33]
	v_mfma_f32_32x32x16_bf16 v[34:49], v[218:221], v[206:209], v[34:49]
	v_mfma_f32_32x32x16_bf16 v[50:65], v[218:221], v[214:217], v[50:65]
	ds_read_b128 v[194:197], v66
	ds_read_b128 v[198:201], v67 offset:36864
	ds_read_b128 v[202:205], v66 offset:32
	ds_read_b128 v[206:209], v67 offset:36896
	ds_read_b128 v[210:213], v67 offset:41472
	ds_read_b128 v[214:217], v67 offset:41504
	s_waitcnt lgkmcnt(4)
	v_mfma_f32_32x32x16_bf16 v[2:17], v[194:197], v[198:201], v[2:17]
	s_waitcnt lgkmcnt(1)
	v_mfma_f32_32x32x16_bf16 v[18:33], v[194:197], v[210:213], v[18:33]
	ds_read_b128 v[194:197], v66 offset:4608
	ds_read_b128 v[218:221], v66 offset:4640
	s_waitcnt lgkmcnt(1)
	v_mfma_f32_32x32x16_bf16 v[34:49], v[194:197], v[198:201], v[34:49]
	v_mfma_f32_32x32x16_bf16 v[50:65], v[194:197], v[210:213], v[50:65]
	v_mfma_f32_32x32x16_bf16 v[2:17], v[202:205], v[206:209], v[2:17]
	v_mfma_f32_32x32x16_bf16 v[18:33], v[202:205], v[214:217], v[18:33]
	s_waitcnt lgkmcnt(0)
	v_mfma_f32_32x32x16_bf16 v[34:49], v[218:221], v[206:209], v[34:49]
	ds_read_b128 v[194:197], v66 offset:64
	ds_read_b128 v[198:201], v67 offset:36928
	ds_read_b128 v[202:205], v66 offset:96
	ds_read_b128 v[206:209], v67 offset:36960
	v_mfma_f32_32x32x16_bf16 v[50:65], v[218:221], v[214:217], v[50:65]
	ds_read_b128 v[210:213], v67 offset:41536
	ds_read_b128 v[214:217], v67 offset:41568
	s_waitcnt lgkmcnt(4)
	v_mfma_f32_32x32x16_bf16 v[2:17], v[194:197], v[198:201], v[2:17]
	s_waitcnt lgkmcnt(1)
	v_mfma_f32_32x32x16_bf16 v[18:33], v[194:197], v[210:213], v[18:33]
	ds_read_b128 v[194:197], v66 offset:4672
	ds_read_b128 v[218:221], v66 offset:4704
	s_waitcnt vmcnt(13)
	ds_write_b128 v100, v[138:141] offset:18432
	ds_write_b128 v100, v[130:133] offset:23040
	ds_write_b128 v100, v[134:137] offset:27648
	s_waitcnt vmcnt(11)
	ds_write_b128 v100, v[146:149] offset:32256
	ds_write_b128 v100, v[142:145] offset:55296
	s_waitcnt vmcnt(10)
	ds_write_b128 v100, v[150:153] offset:59904
	s_waitcnt vmcnt(9)
	ds_write_b128 v100, v[154:157] offset:64512
	s_waitcnt vmcnt(8)
	ds_write_b128 v101, v[158:161] offset:32256
	global_load_dwordx4 v[130:133], v[88:89], off offset:1408
	global_load_dwordx4 v[134:137], v[90:91], off offset:1408
	global_load_dwordx4 v[138:141], v[84:85], off offset:1408
	global_load_dwordx4 v[142:145], v[86:87], off offset:1408
	global_load_dwordx4 v[146:149], v[92:93], off offset:1408
	global_load_dwordx4 v[150:153], v[94:95], off offset:1408
	global_load_dwordx4 v[154:157], v[96:97], off offset:1408
	global_load_dwordx4 v[158:161], v[98:99], off offset:1408
	s_waitcnt lgkmcnt(0)
	s_barrier
	v_mfma_f32_32x32x16_bf16 v[34:49], v[194:197], v[198:201], v[34:49]
	v_mfma_f32_32x32x16_bf16 v[50:65], v[194:197], v[210:213], v[50:65]
	v_mfma_f32_32x32x16_bf16 v[2:17], v[202:205], v[206:209], v[2:17]
	v_mfma_f32_32x32x16_bf16 v[18:33], v[202:205], v[214:217], v[18:33]
	v_mfma_f32_32x32x16_bf16 v[34:49], v[218:221], v[206:209], v[34:49]
	v_mfma_f32_32x32x16_bf16 v[50:65], v[218:221], v[214:217], v[50:65]
	ds_read_b128 v[194:197], v66 offset:18432
	ds_read_b128 v[198:201], v67 offset:55296
	ds_read_b128 v[202:205], v66 offset:18464
	ds_read_b128 v[206:209], v67 offset:55328
	ds_read_b128 v[210:213], v67 offset:59904
	ds_read_b128 v[214:217], v67 offset:59936
	s_waitcnt lgkmcnt(4)
	v_mfma_f32_32x32x16_bf16 v[2:17], v[194:197], v[198:201], v[2:17]
	s_waitcnt lgkmcnt(1)
	v_mfma_f32_32x32x16_bf16 v[18:33], v[194:197], v[210:213], v[18:33]
	ds_read_b128 v[194:197], v66 offset:23040
	ds_read_b128 v[218:221], v66 offset:23072
	s_waitcnt lgkmcnt(1)
	v_mfma_f32_32x32x16_bf16 v[34:49], v[194:197], v[198:201], v[34:49]
	v_mfma_f32_32x32x16_bf16 v[50:65], v[194:197], v[210:213], v[50:65]
	v_mfma_f32_32x32x16_bf16 v[2:17], v[202:205], v[206:209], v[2:17]
	v_mfma_f32_32x32x16_bf16 v[18:33], v[202:205], v[214:217], v[18:33]
	s_waitcnt lgkmcnt(0)
	v_mfma_f32_32x32x16_bf16 v[34:49], v[218:221], v[206:209], v[34:49]
	ds_read_b128 v[194:197], v66 offset:18496
	ds_read_b128 v[198:201], v67 offset:55360
	ds_read_b128 v[202:205], v66 offset:18528
	ds_read_b128 v[206:209], v67 offset:55392
	v_mfma_f32_32x32x16_bf16 v[50:65], v[218:221], v[214:217], v[50:65]
	ds_read_b128 v[210:213], v67 offset:59968
	ds_read_b128 v[214:217], v67 offset:60000
	s_waitcnt lgkmcnt(4)
	v_mfma_f32_32x32x16_bf16 v[2:17], v[194:197], v[198:201], v[2:17]
	s_waitcnt lgkmcnt(1)
	v_mfma_f32_32x32x16_bf16 v[18:33], v[194:197], v[210:213], v[18:33]
	ds_read_b128 v[194:197], v66 offset:23104
	ds_read_b128 v[218:221], v66 offset:23136
	s_waitcnt vmcnt(13)
	ds_write_b128 v100, v[170:173]
	ds_write_b128 v100, v[162:165] offset:4608
	ds_write_b128 v100, v[166:169] offset:9216
	s_waitcnt vmcnt(11)
	ds_write_b128 v100, v[178:181] offset:13824
	ds_write_b128 v100, v[174:177] offset:36864
	s_waitcnt vmcnt(10)
	ds_write_b128 v100, v[182:185] offset:41472
	s_waitcnt vmcnt(9)
	ds_write_b128 v100, v[186:189] offset:46080
	s_waitcnt vmcnt(8)
	ds_write_b128 v100, v[190:193] offset:50688
	global_load_dwordx4 v[162:165], v[88:89], off offset:1536
	global_load_dwordx4 v[166:169], v[90:91], off offset:1536
	global_load_dwordx4 v[170:173], v[84:85], off offset:1536
	global_load_dwordx4 v[174:177], v[86:87], off offset:1536
	global_load_dwordx4 v[178:181], v[92:93], off offset:1536
	global_load_dwordx4 v[182:185], v[94:95], off offset:1536
	global_load_dwordx4 v[186:189], v[96:97], off offset:1536
	global_load_dwordx4 v[190:193], v[98:99], off offset:1536
	s_waitcnt lgkmcnt(0)
	s_barrier
	v_mfma_f32_32x32x16_bf16 v[34:49], v[194:197], v[198:201], v[34:49]
	v_mfma_f32_32x32x16_bf16 v[50:65], v[194:197], v[210:213], v[50:65]
	v_mfma_f32_32x32x16_bf16 v[2:17], v[202:205], v[206:209], v[2:17]
	v_mfma_f32_32x32x16_bf16 v[18:33], v[202:205], v[214:217], v[18:33]
	v_mfma_f32_32x32x16_bf16 v[34:49], v[218:221], v[206:209], v[34:49]
	v_mfma_f32_32x32x16_bf16 v[50:65], v[218:221], v[214:217], v[50:65]
	ds_read_b128 v[194:197], v66
	ds_read_b128 v[198:201], v67 offset:36864
	ds_read_b128 v[202:205], v66 offset:32
	ds_read_b128 v[206:209], v67 offset:36896
	ds_read_b128 v[210:213], v67 offset:41472
	ds_read_b128 v[214:217], v67 offset:41504
	s_waitcnt lgkmcnt(4)
	v_mfma_f32_32x32x16_bf16 v[2:17], v[194:197], v[198:201], v[2:17]
	s_waitcnt lgkmcnt(1)
	v_mfma_f32_32x32x16_bf16 v[18:33], v[194:197], v[210:213], v[18:33]
	ds_read_b128 v[194:197], v66 offset:4608
	ds_read_b128 v[218:221], v66 offset:4640
	s_waitcnt lgkmcnt(1)
	v_mfma_f32_32x32x16_bf16 v[34:49], v[194:197], v[198:201], v[34:49]
	v_mfma_f32_32x32x16_bf16 v[50:65], v[194:197], v[210:213], v[50:65]
	v_mfma_f32_32x32x16_bf16 v[2:17], v[202:205], v[206:209], v[2:17]
	v_mfma_f32_32x32x16_bf16 v[18:33], v[202:205], v[214:217], v[18:33]
	s_waitcnt lgkmcnt(0)
	v_mfma_f32_32x32x16_bf16 v[34:49], v[218:221], v[206:209], v[34:49]
	ds_read_b128 v[194:197], v66 offset:64
	ds_read_b128 v[198:201], v67 offset:36928
	ds_read_b128 v[202:205], v66 offset:96
	ds_read_b128 v[206:209], v67 offset:36960
	v_mfma_f32_32x32x16_bf16 v[50:65], v[218:221], v[214:217], v[50:65]
	ds_read_b128 v[210:213], v67 offset:41536
	ds_read_b128 v[214:217], v67 offset:41568
	s_waitcnt lgkmcnt(4)
	v_mfma_f32_32x32x16_bf16 v[2:17], v[194:197], v[198:201], v[2:17]
	s_waitcnt lgkmcnt(1)
	v_mfma_f32_32x32x16_bf16 v[18:33], v[194:197], v[210:213], v[18:33]
	ds_read_b128 v[194:197], v66 offset:4672
	ds_read_b128 v[218:221], v66 offset:4704
	s_waitcnt vmcnt(13)
	ds_write_b128 v100, v[138:141] offset:18432
	ds_write_b128 v100, v[130:133] offset:23040
	ds_write_b128 v100, v[134:137] offset:27648
	s_waitcnt vmcnt(11)
	ds_write_b128 v100, v[146:149] offset:32256
	ds_write_b128 v100, v[142:145] offset:55296
	s_waitcnt vmcnt(10)
	ds_write_b128 v100, v[150:153] offset:59904
	s_waitcnt vmcnt(9)
	ds_write_b128 v100, v[154:157] offset:64512
	s_waitcnt vmcnt(8)
	ds_write_b128 v101, v[158:161] offset:32256
	global_load_dwordx4 v[130:133], v[88:89], off offset:1664
	global_load_dwordx4 v[134:137], v[90:91], off offset:1664
	global_load_dwordx4 v[138:141], v[84:85], off offset:1664
	global_load_dwordx4 v[142:145], v[86:87], off offset:1664
	global_load_dwordx4 v[146:149], v[92:93], off offset:1664
	global_load_dwordx4 v[150:153], v[94:95], off offset:1664
	global_load_dwordx4 v[154:157], v[96:97], off offset:1664
	global_load_dwordx4 v[158:161], v[98:99], off offset:1664
	s_waitcnt lgkmcnt(0)
	s_barrier
	v_mfma_f32_32x32x16_bf16 v[34:49], v[194:197], v[198:201], v[34:49]
	v_mfma_f32_32x32x16_bf16 v[50:65], v[194:197], v[210:213], v[50:65]
	v_mfma_f32_32x32x16_bf16 v[2:17], v[202:205], v[206:209], v[2:17]
	v_mfma_f32_32x32x16_bf16 v[18:33], v[202:205], v[214:217], v[18:33]
	v_mfma_f32_32x32x16_bf16 v[34:49], v[218:221], v[206:209], v[34:49]
	v_mfma_f32_32x32x16_bf16 v[50:65], v[218:221], v[214:217], v[50:65]
	ds_read_b128 v[194:197], v66 offset:18432
	ds_read_b128 v[198:201], v67 offset:55296
	ds_read_b128 v[202:205], v66 offset:18464
	ds_read_b128 v[206:209], v67 offset:55328
	ds_read_b128 v[210:213], v67 offset:59904
	ds_read_b128 v[214:217], v67 offset:59936
	s_waitcnt lgkmcnt(4)
	v_mfma_f32_32x32x16_bf16 v[2:17], v[194:197], v[198:201], v[2:17]
	s_waitcnt lgkmcnt(1)
	v_mfma_f32_32x32x16_bf16 v[18:33], v[194:197], v[210:213], v[18:33]
	ds_read_b128 v[194:197], v66 offset:23040
	ds_read_b128 v[218:221], v66 offset:23072
	s_waitcnt lgkmcnt(1)
	v_mfma_f32_32x32x16_bf16 v[34:49], v[194:197], v[198:201], v[34:49]
	v_mfma_f32_32x32x16_bf16 v[50:65], v[194:197], v[210:213], v[50:65]
	v_mfma_f32_32x32x16_bf16 v[2:17], v[202:205], v[206:209], v[2:17]
	v_mfma_f32_32x32x16_bf16 v[18:33], v[202:205], v[214:217], v[18:33]
	s_waitcnt lgkmcnt(0)
	v_mfma_f32_32x32x16_bf16 v[34:49], v[218:221], v[206:209], v[34:49]
	ds_read_b128 v[194:197], v66 offset:18496
	ds_read_b128 v[198:201], v67 offset:55360
	ds_read_b128 v[202:205], v66 offset:18528
	ds_read_b128 v[206:209], v67 offset:55392
	v_mfma_f32_32x32x16_bf16 v[50:65], v[218:221], v[214:217], v[50:65]
	ds_read_b128 v[210:213], v67 offset:59968
	ds_read_b128 v[214:217], v67 offset:60000
	s_waitcnt lgkmcnt(4)
	v_mfma_f32_32x32x16_bf16 v[2:17], v[194:197], v[198:201], v[2:17]
	s_waitcnt lgkmcnt(1)
	v_mfma_f32_32x32x16_bf16 v[18:33], v[194:197], v[210:213], v[18:33]
	ds_read_b128 v[194:197], v66 offset:23104
	ds_read_b128 v[218:221], v66 offset:23136
	s_waitcnt vmcnt(13)
	ds_write_b128 v100, v[170:173]
	ds_write_b128 v100, v[162:165] offset:4608
	ds_write_b128 v100, v[166:169] offset:9216
	s_waitcnt vmcnt(11)
	ds_write_b128 v100, v[178:181] offset:13824
	ds_write_b128 v100, v[174:177] offset:36864
	s_waitcnt vmcnt(10)
	ds_write_b128 v100, v[182:185] offset:41472
	s_waitcnt vmcnt(9)
	ds_write_b128 v100, v[186:189] offset:46080
	s_waitcnt vmcnt(8)
	ds_write_b128 v100, v[190:193] offset:50688
	global_load_dwordx4 v[162:165], v[88:89], off offset:1792
	global_load_dwordx4 v[166:169], v[90:91], off offset:1792
	global_load_dwordx4 v[170:173], v[84:85], off offset:1792
	global_load_dwordx4 v[174:177], v[86:87], off offset:1792
	global_load_dwordx4 v[178:181], v[92:93], off offset:1792
	global_load_dwordx4 v[182:185], v[94:95], off offset:1792
	global_load_dwordx4 v[186:189], v[96:97], off offset:1792
	global_load_dwordx4 v[190:193], v[98:99], off offset:1792
	s_waitcnt lgkmcnt(0)
	s_barrier
	v_mfma_f32_32x32x16_bf16 v[34:49], v[194:197], v[198:201], v[34:49]
	v_mfma_f32_32x32x16_bf16 v[50:65], v[194:197], v[210:213], v[50:65]
	v_mfma_f32_32x32x16_bf16 v[2:17], v[202:205], v[206:209], v[2:17]
	v_mfma_f32_32x32x16_bf16 v[18:33], v[202:205], v[214:217], v[18:33]
	v_mfma_f32_32x32x16_bf16 v[34:49], v[218:221], v[206:209], v[34:49]
	v_mfma_f32_32x32x16_bf16 v[50:65], v[218:221], v[214:217], v[50:65]
	ds_read_b128 v[194:197], v66
	ds_read_b128 v[198:201], v67 offset:36864
	ds_read_b128 v[202:205], v66 offset:32
	ds_read_b128 v[206:209], v67 offset:36896
	ds_read_b128 v[210:213], v67 offset:41472
	ds_read_b128 v[214:217], v67 offset:41504
	s_waitcnt lgkmcnt(4)
	v_mfma_f32_32x32x16_bf16 v[2:17], v[194:197], v[198:201], v[2:17]
	s_waitcnt lgkmcnt(1)
	v_mfma_f32_32x32x16_bf16 v[18:33], v[194:197], v[210:213], v[18:33]
	ds_read_b128 v[194:197], v66 offset:4608
	ds_read_b128 v[218:221], v66 offset:4640
	s_waitcnt lgkmcnt(1)
	v_mfma_f32_32x32x16_bf16 v[34:49], v[194:197], v[198:201], v[34:49]
	v_mfma_f32_32x32x16_bf16 v[50:65], v[194:197], v[210:213], v[50:65]
	v_mfma_f32_32x32x16_bf16 v[2:17], v[202:205], v[206:209], v[2:17]
	v_mfma_f32_32x32x16_bf16 v[18:33], v[202:205], v[214:217], v[18:33]
	s_waitcnt lgkmcnt(0)
	v_mfma_f32_32x32x16_bf16 v[34:49], v[218:221], v[206:209], v[34:49]
	ds_read_b128 v[194:197], v66 offset:64
	ds_read_b128 v[198:201], v67 offset:36928
	ds_read_b128 v[202:205], v66 offset:96
	ds_read_b128 v[206:209], v67 offset:36960
	v_mfma_f32_32x32x16_bf16 v[50:65], v[218:221], v[214:217], v[50:65]
	ds_read_b128 v[210:213], v67 offset:41536
	ds_read_b128 v[214:217], v67 offset:41568
	s_waitcnt lgkmcnt(4)
	v_mfma_f32_32x32x16_bf16 v[2:17], v[194:197], v[198:201], v[2:17]
	s_waitcnt lgkmcnt(1)
	v_mfma_f32_32x32x16_bf16 v[18:33], v[194:197], v[210:213], v[18:33]
	ds_read_b128 v[194:197], v66 offset:4672
	ds_read_b128 v[218:221], v66 offset:4704
	s_waitcnt vmcnt(13)
	ds_write_b128 v100, v[138:141] offset:18432
	ds_write_b128 v100, v[130:133] offset:23040
	ds_write_b128 v100, v[134:137] offset:27648
	s_waitcnt vmcnt(11)
	ds_write_b128 v100, v[146:149] offset:32256
	ds_write_b128 v100, v[142:145] offset:55296
	s_waitcnt vmcnt(10)
	ds_write_b128 v100, v[150:153] offset:59904
	s_waitcnt vmcnt(9)
	ds_write_b128 v100, v[154:157] offset:64512
	s_waitcnt vmcnt(8)
	ds_write_b128 v101, v[158:161] offset:32256
	s_waitcnt lgkmcnt(0)
	s_barrier
	global_load_dwordx4 v[130:133], v[88:89], off offset:1920
	s_nop 0
	global_load_dwordx4 v[88:91], v[90:91], off offset:1920
	s_nop 0
	global_load_dwordx4 v[134:137], v[84:85], off offset:1920
	s_nop 0
	global_load_dwordx4 v[84:87], v[86:87], off offset:1920
	s_nop 0
	global_load_dwordx4 v[138:141], v[92:93], off offset:1920
	s_nop 0
	global_load_dwordx4 v[92:95], v[94:95], off offset:1920
	s_nop 0
	global_load_dwordx4 v[142:145], v[96:97], off offset:1920
	s_nop 0
	global_load_dwordx4 v[96:99], v[98:99], off offset:1920
	v_mfma_f32_32x32x16_bf16 v[34:49], v[194:197], v[198:201], v[34:49]
	v_mfma_f32_32x32x16_bf16 v[50:65], v[194:197], v[210:213], v[50:65]
	v_mfma_f32_32x32x16_bf16 v[2:17], v[202:205], v[206:209], v[2:17]
	v_mfma_f32_32x32x16_bf16 v[18:33], v[202:205], v[214:217], v[18:33]
	v_mfma_f32_32x32x16_bf16 v[34:49], v[218:221], v[206:209], v[34:49]
	v_mfma_f32_32x32x16_bf16 v[50:65], v[218:221], v[214:217], v[50:65]
	ds_read_b128 v[146:149], v66 offset:18432
	ds_read_b128 v[150:153], v67 offset:55296
	ds_read_b128 v[154:157], v66 offset:18464
	ds_read_b128 v[158:161], v67 offset:55328
	ds_read_b128 v[194:197], v67 offset:59904
	ds_read_b128 v[198:201], v67 offset:59936
	s_waitcnt lgkmcnt(4)
	v_mfma_f32_32x32x16_bf16 v[2:17], v[146:149], v[150:153], v[2:17]
	s_waitcnt lgkmcnt(1)
	v_mfma_f32_32x32x16_bf16 v[18:33], v[146:149], v[194:197], v[18:33]
	ds_read_b128 v[146:149], v66 offset:23040
	ds_read_b128 v[202:205], v66 offset:23072
	s_waitcnt lgkmcnt(1)
	v_mfma_f32_32x32x16_bf16 v[34:49], v[146:149], v[150:153], v[34:49]
	v_mfma_f32_32x32x16_bf16 v[50:65], v[146:149], v[194:197], v[50:65]
	v_mfma_f32_32x32x16_bf16 v[2:17], v[154:157], v[158:161], v[2:17]
	v_mfma_f32_32x32x16_bf16 v[18:33], v[154:157], v[198:201], v[18:33]
	s_waitcnt lgkmcnt(0)
	v_mfma_f32_32x32x16_bf16 v[34:49], v[202:205], v[158:161], v[34:49]
	ds_read_b128 v[146:149], v66 offset:18496
	ds_read_b128 v[150:153], v67 offset:55360
	ds_read_b128 v[154:157], v66 offset:18528
	ds_read_b128 v[158:161], v67 offset:55392
	v_mfma_f32_32x32x16_bf16 v[50:65], v[202:205], v[198:201], v[50:65]
	ds_read_b128 v[194:197], v67 offset:59968
	ds_read_b128 v[198:201], v67 offset:60000
	s_waitcnt lgkmcnt(4)
	v_mfma_f32_32x32x16_bf16 v[2:17], v[146:149], v[150:153], v[2:17]
	s_waitcnt lgkmcnt(1)
	v_mfma_f32_32x32x16_bf16 v[18:33], v[146:149], v[194:197], v[18:33]
	ds_read_b128 v[146:149], v66 offset:23104
	ds_read_b128 v[202:205], v66 offset:23136
	s_waitcnt vmcnt(13)
	ds_write_b128 v100, v[170:173]
	ds_write_b128 v100, v[162:165] offset:4608
	ds_write_b128 v100, v[166:169] offset:9216
	s_waitcnt vmcnt(11)
	ds_write_b128 v100, v[178:181] offset:13824
	ds_write_b128 v100, v[174:177] offset:36864
	s_waitcnt vmcnt(10)
	ds_write_b128 v100, v[182:185] offset:41472
	s_waitcnt vmcnt(9)
	ds_write_b128 v100, v[186:189] offset:46080
	s_waitcnt vmcnt(8)
	ds_write_b128 v100, v[190:193] offset:50688
	s_waitcnt lgkmcnt(0)
	s_barrier
	v_mfma_f32_32x32x16_bf16 v[34:49], v[146:149], v[150:153], v[34:49]
	v_mfma_f32_32x32x16_bf16 v[50:65], v[146:149], v[194:197], v[50:65]
	v_mfma_f32_32x32x16_bf16 v[2:17], v[154:157], v[158:161], v[2:17]
	v_mfma_f32_32x32x16_bf16 v[18:33], v[154:157], v[198:201], v[18:33]
	v_mfma_f32_32x32x16_bf16 v[34:49], v[202:205], v[158:161], v[34:49]
	v_mfma_f32_32x32x16_bf16 v[50:65], v[202:205], v[198:201], v[50:65]
	ds_read_b128 v[146:149], v66
	ds_read_b128 v[150:153], v67 offset:36864
	ds_read_b128 v[154:157], v66 offset:32
	ds_read_b128 v[158:161], v67 offset:36896
	ds_read_b128 v[162:165], v67 offset:41472
	ds_read_b128 v[166:169], v67 offset:41504
	s_waitcnt lgkmcnt(4)
	v_mfma_f32_32x32x16_bf16 v[2:17], v[146:149], v[150:153], v[2:17]
	s_waitcnt lgkmcnt(1)
	v_mfma_f32_32x32x16_bf16 v[18:33], v[146:149], v[162:165], v[18:33]
	ds_read_b128 v[146:149], v66 offset:4608
	ds_read_b128 v[170:173], v66 offset:4640
	s_waitcnt lgkmcnt(1)
	v_mfma_f32_32x32x16_bf16 v[34:49], v[146:149], v[150:153], v[34:49]
	v_mfma_f32_32x32x16_bf16 v[50:65], v[146:149], v[162:165], v[50:65]
	v_mfma_f32_32x32x16_bf16 v[2:17], v[154:157], v[158:161], v[2:17]
	v_mfma_f32_32x32x16_bf16 v[18:33], v[154:157], v[166:169], v[18:33]
	s_waitcnt lgkmcnt(0)
	v_mfma_f32_32x32x16_bf16 v[34:49], v[170:173], v[158:161], v[34:49]
	ds_read_b128 v[146:149], v66 offset:64
	ds_read_b128 v[150:153], v67 offset:36928
	ds_read_b128 v[154:157], v66 offset:96
	ds_read_b128 v[158:161], v67 offset:36960
	v_mfma_f32_32x32x16_bf16 v[50:65], v[170:173], v[166:169], v[50:65]
	ds_read_b128 v[162:165], v67 offset:41536
	ds_read_b128 v[166:169], v67 offset:41568
	s_waitcnt lgkmcnt(4)
	v_mfma_f32_32x32x16_bf16 v[2:17], v[146:149], v[150:153], v[2:17]
	s_waitcnt lgkmcnt(1)
	v_mfma_f32_32x32x16_bf16 v[18:33], v[146:149], v[162:165], v[18:33]
	ds_read_b128 v[146:149], v66 offset:4672
	ds_read_b128 v[170:173], v66 offset:4704
	s_waitcnt vmcnt(5)
	ds_write_b128 v100, v[134:137] offset:18432
	ds_write_b128 v100, v[130:133] offset:23040
	ds_write_b128 v100, v[88:91] offset:27648
	s_waitcnt vmcnt(3)
	ds_write_b128 v100, v[138:141] offset:32256
	ds_write_b128 v100, v[84:87] offset:55296
	s_waitcnt vmcnt(2)
	ds_write_b128 v100, v[92:95] offset:59904
	s_waitcnt vmcnt(1)
	ds_write_b128 v100, v[142:145] offset:64512
	s_waitcnt vmcnt(0)
	ds_write_b128 v101, v[96:99] offset:32256
	s_waitcnt lgkmcnt(0)
	s_barrier
	v_mfma_f32_32x32x16_bf16 v[34:49], v[146:149], v[150:153], v[34:49]
	v_mfma_f32_32x32x16_bf16 v[50:65], v[146:149], v[162:165], v[50:65]
	v_mfma_f32_32x32x16_bf16 v[2:17], v[154:157], v[158:161], v[2:17]
	v_mfma_f32_32x32x16_bf16 v[18:33], v[154:157], v[166:169], v[18:33]
	v_mfma_f32_32x32x16_bf16 v[34:49], v[170:173], v[158:161], v[34:49]
	v_mfma_f32_32x32x16_bf16 v[50:65], v[170:173], v[166:169], v[50:65]
	ds_read_b128 v[84:87], v66 offset:18432
	ds_read_b128 v[88:91], v67 offset:55296
	ds_read_b128 v[92:95], v66 offset:18464
	ds_read_b128 v[96:99], v67 offset:55328
	ds_read_b128 v[130:133], v67 offset:59904
	ds_read_b128 v[134:137], v67 offset:59936
	s_cmp_lt_u32 s53, 4
	s_waitcnt lgkmcnt(4)
	v_mfma_f32_32x32x16_bf16 v[2:17], v[84:87], v[88:91], v[2:17]
	s_cselect_b64 s[8:9], -1, 0
	s_mov_b64 s[30:31], 0x200
	s_and_b64 vcc, exec, s[8:9]
	s_waitcnt lgkmcnt(1)
	v_mfma_f32_32x32x16_bf16 v[18:33], v[84:87], v[130:133], v[18:33]
	ds_read_b128 v[84:87], v66 offset:23040
	ds_read_b128 v[138:141], v66 offset:23072
	s_waitcnt lgkmcnt(1)
	v_mfma_f32_32x32x16_bf16 v[34:49], v[84:87], v[88:91], v[34:49]
	v_mfma_f32_32x32x16_bf16 v[50:65], v[84:87], v[130:133], v[50:65]
	v_mfma_f32_32x32x16_bf16 v[2:17], v[92:95], v[96:99], v[2:17]
	v_mfma_f32_32x32x16_bf16 v[18:33], v[92:95], v[134:137], v[18:33]
	s_waitcnt lgkmcnt(0)
	v_mfma_f32_32x32x16_bf16 v[34:49], v[138:141], v[96:99], v[34:49]
	ds_read_b128 v[84:87], v66 offset:18496
	ds_read_b128 v[88:91], v67 offset:55360
	ds_read_b128 v[92:95], v66 offset:18528
	ds_read_b128 v[96:99], v67 offset:55392
	v_mfma_f32_32x32x16_bf16 v[50:65], v[138:141], v[134:137], v[50:65]
	ds_read_b128 v[130:133], v67 offset:59968
	ds_read_b128 v[134:137], v67 offset:60000
	s_waitcnt lgkmcnt(4)
	v_mfma_f32_32x32x16_bf16 v[2:17], v[84:87], v[88:91], v[2:17]
	s_waitcnt lgkmcnt(1)
	v_mfma_f32_32x32x16_bf16 v[18:33], v[84:87], v[130:133], v[18:33]
	ds_read_b128 v[84:87], v66 offset:23104
	ds_read_b128 v[138:141], v66 offset:23136
	s_waitcnt lgkmcnt(0)
	s_barrier
	v_mfma_f32_32x32x16_bf16 v[34:49], v[84:87], v[88:91], v[34:49]
	v_mfma_f32_32x32x16_bf16 v[50:65], v[84:87], v[130:133], v[50:65]
	v_mfma_f32_32x32x16_bf16 v[2:17], v[92:95], v[96:99], v[2:17]
	v_mfma_f32_32x32x16_bf16 v[18:33], v[92:95], v[134:137], v[18:33]
	v_mfma_f32_32x32x16_bf16 v[34:49], v[138:141], v[96:99], v[34:49]
	s_nop 10
	ds_write2_b32 v102, v2, v18 offset1:32
	v_mfma_f32_32x32x16_bf16 v[50:65], v[138:141], v[134:137], v[50:65]
	s_nop 11
	ds_write2_b32 v112, v34, v50 offset0:32 offset1:64
	ds_write2_b32 v102, v3, v19 offset0:129 offset1:161
	ds_write2_b32 v112, v35, v51 offset0:161 offset1:193
	ds_write2_b32 v113, v4, v20 offset0:2 offset1:34
	ds_write2_b32 v114, v36, v52 offset0:34 offset1:66
	ds_write2_b32 v113, v5, v21 offset0:131 offset1:163
	ds_write2_b32 v114, v37, v53 offset0:163 offset1:195
	ds_write2_b32 v115, v6, v22 offset0:8 offset1:40
	ds_write2_b32 v116, v38, v54 offset0:40 offset1:72
	ds_write2_b32 v115, v7, v23 offset0:137 offset1:169
	ds_write2_b32 v116, v39, v55 offset0:169 offset1:201
	ds_write2_b32 v117, v8, v24 offset0:10 offset1:42
	ds_write2_b32 v118, v40, v56 offset0:42 offset1:74
	ds_write2_b32 v117, v9, v25 offset0:139 offset1:171
	ds_write2_b32 v118, v41, v57 offset0:171 offset1:203
	ds_write2_b32 v119, v10, v26 offset0:16 offset1:48
	ds_write2_b32 v120, v42, v58 offset0:48 offset1:80
	ds_write2_b32 v119, v11, v27 offset0:145 offset1:177
	ds_write2_b32 v120, v43, v59 offset0:177 offset1:209
	ds_write2_b32 v121, v12, v28 offset0:18 offset1:50
	ds_write2_b32 v122, v44, v60 offset0:50 offset1:82
	ds_write2_b32 v121, v13, v29 offset0:147 offset1:179
	ds_write2_b32 v122, v45, v61 offset0:179 offset1:211
	ds_write2_b32 v123, v14, v30 offset0:24 offset1:56
	ds_write2_b32 v124, v46, v62 offset0:56 offset1:88
	ds_write2_b32 v123, v15, v31 offset0:153 offset1:185
	ds_write2_b32 v124, v47, v63 offset0:185 offset1:217
	ds_write2_b32 v125, v16, v32 offset0:26 offset1:58
	ds_write2_b32 v126, v48, v64 offset0:58 offset1:90
	ds_write2_b32 v125, v17, v33 offset0:155 offset1:187
	ds_write2_b32 v126, v49, v65 offset0:187 offset1:219
	s_waitcnt lgkmcnt(0)
	s_barrier
	s_cbranch_vccnz .LBB0_397
	s_cmp_lt_u32 s53, 8
	s_cbranch_scc1 .LBB0_398
	s_cmp_lg_u32 s53, 13
	s_mov_b64 s[28:29], 0
	s_cbranch_scc1 .LBB0_399
	s_movk_i32 s61, 0x680
	s_mov_b64 s[4:5], 0x100
	s_mov_b64 s[36:37], -1
	s_mov_b64 s[26:27], s[12:13]
	s_branch .LBB0_400

.LBB0_563:
	s_and_b32 s4, s15, 0x1ffffc0
	s_lshl_b32 s5, s15, 3
	s_and_b32 s5, s5, 56
	s_or_b32 s4, s4, s3
	s_or_b32 s4, s4, s5
	s_lshl_b32 s12, s4, 7
	s_lshl_b32 s4, s15, 4
	s_and_b32 s23, s4, 0x380
	s_lshl_b64 s[4:5], s[12:13], 11
	v_lshl_add_u64 v[74:75], v[70:71], 0, s[4:5]
	v_add_co_u32_e64 v78, s[4:5], s19, v74
	s_lshl_b32 s12, s23, 11
	s_nop 0
	v_addc_co_u32_e64 v79, s[4:5], 0, v75, s[4:5]
	v_add_co_u32_e64 v80, s[4:5], s20, v74
	v_lshl_add_u64 v[76:77], v[72:73], 0, s[12:13]
	s_nop 0
	v_addc_co_u32_e64 v81, s[4:5], 0, v75, s[4:5]
	v_add_co_u32_e64 v82, s[4:5], s21, v74
	global_load_dwordx4 v[2:5], v[74:75], off
	global_load_dwordx4 v[6:9], v[78:79], off
	v_addc_co_u32_e64 v83, s[4:5], 0, v75, s[4:5]
	global_load_dwordx4 v[10:13], v[80:81], off
	global_load_dwordx4 v[14:17], v[82:83], off
	global_load_dwordx4 v[18:21], v[76:77], off
	v_add_co_u32_e64 v84, s[4:5], s19, v76
	s_nop 1
	v_addc_co_u32_e64 v85, s[4:5], 0, v77, s[4:5]
	v_add_co_u32_e64 v86, s[4:5], s20, v76
	global_load_dwordx4 v[22:25], v[84:85], off
	s_nop 0
	v_addc_co_u32_e64 v87, s[4:5], 0, v77, s[4:5]
	global_load_dwordx4 v[26:29], v[86:87], off
	v_add_co_u32_e64 v88, s[4:5], s21, v76
	s_nop 1
	v_addc_co_u32_e64 v89, s[4:5], 0, v77, s[4:5]
	global_load_dwordx4 v[30:33], v[88:89], off
	global_load_dwordx4 v[118:121], v[74:75], off offset:128
	global_load_dwordx4 v[122:125], v[76:77], off offset:128
	global_load_dwordx4 v[126:129], v[78:79], off offset:128
	global_load_dwordx4 v[130:133], v[80:81], off offset:128
	global_load_dwordx4 v[134:137], v[82:83], off offset:128
	global_load_dwordx4 v[138:141], v[84:85], off offset:128
	global_load_dwordx4 v[142:145], v[86:87], off offset:128
	global_load_dwordx4 v[146:149], v[88:89], off offset:128
	s_lshl_b32 s4, s15, 7
	s_and_b32 s4, s4, 0xffffe000
	s_lshl_b32 s5, s16, 7
	s_or_b32 s4, s4, s18
	s_and_b32 s5, s5, 0x1c00
	s_or_b32 s4, s5, s4
	v_add_u32_e32 v116, s4, v1
	s_waitcnt vmcnt(15)
	ds_write_b128 v90, v[2:5]
	s_waitcnt vmcnt(11)
	ds_write_b128 v90, v[18:21] offset:36864
	ds_write_b128 v90, v[6:9] offset:4608
	ds_write_b128 v90, v[10:13] offset:9216
	ds_write_b128 v90, v[14:17] offset:13824
	s_waitcnt vmcnt(10)
	ds_write_b128 v90, v[22:25] offset:41472
	s_waitcnt vmcnt(9)
	ds_write_b128 v90, v[26:29] offset:46080
	s_waitcnt vmcnt(8)
	ds_write_b128 v90, v[30:33] offset:50688
	s_waitcnt lgkmcnt(0)
	s_barrier
	global_load_dwordx4 v[150:153], v[78:79], off offset:256
	global_load_dwordx4 v[154:157], v[80:81], off offset:256
	global_load_dwordx4 v[158:161], v[74:75], off offset:256
	global_load_dwordx4 v[162:165], v[76:77], off offset:256
	global_load_dwordx4 v[166:169], v[82:83], off offset:256
	global_load_dwordx4 v[170:173], v[84:85], off offset:256
	global_load_dwordx4 v[174:177], v[86:87], off offset:256
	global_load_dwordx4 v[178:181], v[88:89], off offset:256
	ds_read_b128 v[18:21], v66
	ds_read_b128 v[34:37], v67 offset:36864
	ds_read_b128 v[182:185], v66 offset:32
	ds_read_b128 v[186:189], v67 offset:36896
	ds_read_b128 v[50:53], v67 offset:41472
	ds_read_b128 v[190:193], v67 offset:41504
	ds_read_b128 v[54:57], v66 offset:4608
	ds_read_b128 v[194:197], v66 offset:4640
	s_waitcnt lgkmcnt(6)
	v_mfma_f32_32x32x16_bf16 v[2:17], v[18:21], v[34:37], 0
	s_waitcnt lgkmcnt(3)
	v_mfma_f32_32x32x16_bf16 v[18:33], v[18:21], v[50:53], 0
	s_waitcnt lgkmcnt(1)
	v_mfma_f32_32x32x16_bf16 v[34:49], v[54:57], v[34:37], 0
	v_mfma_f32_32x32x16_bf16 v[50:65], v[54:57], v[50:53], 0
	v_mfma_f32_32x32x16_bf16 v[2:17], v[182:185], v[186:189], v[2:17]
	v_mfma_f32_32x32x16_bf16 v[18:33], v[182:185], v[190:193], v[18:33]
	s_waitcnt lgkmcnt(0)
	v_mfma_f32_32x32x16_bf16 v[34:49], v[194:197], v[186:189], v[34:49]
	v_mfma_f32_32x32x16_bf16 v[50:65], v[194:197], v[190:193], v[50:65]
	ds_read_b128 v[182:185], v66 offset:64
	ds_read_b128 v[186:189], v67 offset:36928
	ds_read_b128 v[190:193], v66 offset:96
	ds_read_b128 v[194:197], v67 offset:36960
	ds_read_b128 v[198:201], v67 offset:41536
	ds_read_b128 v[202:205], v67 offset:41568
	s_waitcnt lgkmcnt(4)
	v_mfma_f32_32x32x16_bf16 v[2:17], v[182:185], v[186:189], v[2:17]
	s_waitcnt lgkmcnt(1)
	v_mfma_f32_32x32x16_bf16 v[18:33], v[182:185], v[198:201], v[18:33]
	ds_read_b128 v[182:185], v66 offset:4672
	ds_read_b128 v[206:209], v66 offset:4704
	s_waitcnt vmcnt(15)
	ds_write_b128 v90, v[118:121] offset:18432
	s_waitcnt vmcnt(13)
	ds_write_b128 v90, v[126:129] offset:23040
	s_waitcnt vmcnt(12)
	ds_write_b128 v90, v[130:133] offset:27648
	s_waitcnt vmcnt(11)
	ds_write_b128 v90, v[134:137] offset:32256
	ds_write_b128 v90, v[122:125] offset:55296
	s_waitcnt vmcnt(10)
	ds_write_b128 v90, v[138:141] offset:59904
	s_waitcnt vmcnt(9)
	ds_write_b128 v90, v[142:145] offset:64512
	s_waitcnt vmcnt(8)
	ds_write_b128 v91, v[146:149] offset:32256
	global_load_dwordx4 v[118:121], v[78:79], off offset:384
	global_load_dwordx4 v[122:125], v[80:81], off offset:384
	global_load_dwordx4 v[126:129], v[74:75], off offset:384
	global_load_dwordx4 v[130:133], v[76:77], off offset:384
	global_load_dwordx4 v[134:137], v[82:83], off offset:384
	global_load_dwordx4 v[138:141], v[84:85], off offset:384
	global_load_dwordx4 v[142:145], v[86:87], off offset:384
	global_load_dwordx4 v[146:149], v[88:89], off offset:384
	s_waitcnt lgkmcnt(0)
	s_barrier
	v_mfma_f32_32x32x16_bf16 v[34:49], v[182:185], v[186:189], v[34:49]
	v_mfma_f32_32x32x16_bf16 v[50:65], v[182:185], v[198:201], v[50:65]
	v_mfma_f32_32x32x16_bf16 v[2:17], v[190:193], v[194:197], v[2:17]
	v_mfma_f32_32x32x16_bf16 v[18:33], v[190:193], v[202:205], v[18:33]
	v_mfma_f32_32x32x16_bf16 v[34:49], v[206:209], v[194:197], v[34:49]
	v_mfma_f32_32x32x16_bf16 v[50:65], v[206:209], v[202:205], v[50:65]
	ds_read_b128 v[182:185], v66 offset:18432
	ds_read_b128 v[186:189], v67 offset:55296
	ds_read_b128 v[190:193], v66 offset:18464
	ds_read_b128 v[194:197], v67 offset:55328
	ds_read_b128 v[198:201], v67 offset:59904
	ds_read_b128 v[202:205], v67 offset:59936
	s_waitcnt lgkmcnt(4)
	v_mfma_f32_32x32x16_bf16 v[2:17], v[182:185], v[186:189], v[2:17]
	s_waitcnt lgkmcnt(1)
	v_mfma_f32_32x32x16_bf16 v[18:33], v[182:185], v[198:201], v[18:33]
	ds_read_b128 v[182:185], v66 offset:23040
	ds_read_b128 v[206:209], v66 offset:23072
	s_waitcnt lgkmcnt(1)
	v_mfma_f32_32x32x16_bf16 v[34:49], v[182:185], v[186:189], v[34:49]
	v_mfma_f32_32x32x16_bf16 v[50:65], v[182:185], v[198:201], v[50:65]
	v_mfma_f32_32x32x16_bf16 v[2:17], v[190:193], v[194:197], v[2:17]
	v_mfma_f32_32x32x16_bf16 v[18:33], v[190:193], v[202:205], v[18:33]
	s_waitcnt lgkmcnt(0)
	v_mfma_f32_32x32x16_bf16 v[34:49], v[206:209], v[194:197], v[34:49]
	ds_read_b128 v[182:185], v66 offset:18496
	ds_read_b128 v[186:189], v67 offset:55360
	ds_read_b128 v[190:193], v66 offset:18528
	ds_read_b128 v[194:197], v67 offset:55392
	v_mfma_f32_32x32x16_bf16 v[50:65], v[206:209], v[202:205], v[50:65]
	ds_read_b128 v[198:201], v67 offset:59968
	ds_read_b128 v[202:205], v67 offset:60000
	s_waitcnt lgkmcnt(4)
	v_mfma_f32_32x32x16_bf16 v[2:17], v[182:185], v[186:189], v[2:17]
	s_waitcnt lgkmcnt(1)
	v_mfma_f32_32x32x16_bf16 v[18:33], v[182:185], v[198:201], v[18:33]
	ds_read_b128 v[182:185], v66 offset:23104
	ds_read_b128 v[206:209], v66 offset:23136
	s_waitcnt vmcnt(13)
	ds_write_b128 v90, v[158:161]
	ds_write_b128 v90, v[150:153] offset:4608
	ds_write_b128 v90, v[154:157] offset:9216
	s_waitcnt vmcnt(11)
	ds_write_b128 v90, v[166:169] offset:13824
	ds_write_b128 v90, v[162:165] offset:36864
	s_waitcnt vmcnt(10)
	ds_write_b128 v90, v[170:173] offset:41472
	s_waitcnt vmcnt(9)
	ds_write_b128 v90, v[174:177] offset:46080
	s_waitcnt vmcnt(8)
	ds_write_b128 v90, v[178:181] offset:50688
	global_load_dwordx4 v[150:153], v[78:79], off offset:512
	global_load_dwordx4 v[154:157], v[80:81], off offset:512
	global_load_dwordx4 v[158:161], v[74:75], off offset:512
	global_load_dwordx4 v[162:165], v[76:77], off offset:512
	global_load_dwordx4 v[166:169], v[82:83], off offset:512
	global_load_dwordx4 v[170:173], v[84:85], off offset:512
	global_load_dwordx4 v[174:177], v[86:87], off offset:512
	global_load_dwordx4 v[178:181], v[88:89], off offset:512
	s_waitcnt lgkmcnt(0)
	s_barrier
	v_mfma_f32_32x32x16_bf16 v[34:49], v[182:185], v[186:189], v[34:49]
	v_mfma_f32_32x32x16_bf16 v[50:65], v[182:185], v[198:201], v[50:65]
	v_mfma_f32_32x32x16_bf16 v[2:17], v[190:193], v[194:197], v[2:17]
	v_mfma_f32_32x32x16_bf16 v[18:33], v[190:193], v[202:205], v[18:33]
	v_mfma_f32_32x32x16_bf16 v[34:49], v[206:209], v[194:197], v[34:49]
	v_mfma_f32_32x32x16_bf16 v[50:65], v[206:209], v[202:205], v[50:65]
	ds_read_b128 v[182:185], v66
	ds_read_b128 v[186:189], v67 offset:36864
	ds_read_b128 v[190:193], v66 offset:32
	ds_read_b128 v[194:197], v67 offset:36896
	ds_read_b128 v[198:201], v67 offset:41472
	ds_read_b128 v[202:205], v67 offset:41504
	s_waitcnt lgkmcnt(4)
	v_mfma_f32_32x32x16_bf16 v[2:17], v[182:185], v[186:189], v[2:17]
	s_waitcnt lgkmcnt(1)
	v_mfma_f32_32x32x16_bf16 v[18:33], v[182:185], v[198:201], v[18:33]
	ds_read_b128 v[182:185], v66 offset:4608
	ds_read_b128 v[206:209], v66 offset:4640
	s_waitcnt lgkmcnt(1)
	v_mfma_f32_32x32x16_bf16 v[34:49], v[182:185], v[186:189], v[34:49]
	v_mfma_f32_32x32x16_bf16 v[50:65], v[182:185], v[198:201], v[50:65]
	v_mfma_f32_32x32x16_bf16 v[2:17], v[190:193], v[194:197], v[2:17]
	v_mfma_f32_32x32x16_bf16 v[18:33], v[190:193], v[202:205], v[18:33]
	s_waitcnt lgkmcnt(0)
	v_mfma_f32_32x32x16_bf16 v[34:49], v[206:209], v[194:197], v[34:49]
	ds_read_b128 v[182:185], v66 offset:64
	ds_read_b128 v[186:189], v67 offset:36928
	ds_read_b128 v[190:193], v66 offset:96
	ds_read_b128 v[194:197], v67 offset:36960
	v_mfma_f32_32x32x16_bf16 v[50:65], v[206:209], v[202:205], v[50:65]
	ds_read_b128 v[198:201], v67 offset:41536
	ds_read_b128 v[202:205], v67 offset:41568
	s_waitcnt lgkmcnt(4)
	v_mfma_f32_32x32x16_bf16 v[2:17], v[182:185], v[186:189], v[2:17]
	s_waitcnt lgkmcnt(1)
	v_mfma_f32_32x32x16_bf16 v[18:33], v[182:185], v[198:201], v[18:33]
	ds_read_b128 v[182:185], v66 offset:4672
	ds_read_b128 v[206:209], v66 offset:4704
	s_waitcnt vmcnt(13)
	ds_write_b128 v90, v[126:129] offset:18432
	ds_write_b128 v90, v[118:121] offset:23040
	ds_write_b128 v90, v[122:125] offset:27648
	s_waitcnt vmcnt(11)
	ds_write_b128 v90, v[134:137] offset:32256
	ds_write_b128 v90, v[130:133] offset:55296
	s_waitcnt vmcnt(10)
	ds_write_b128 v90, v[138:141] offset:59904
	s_waitcnt vmcnt(9)
	ds_write_b128 v90, v[142:145] offset:64512
	s_waitcnt vmcnt(8)
	ds_write_b128 v91, v[146:149] offset:32256
	global_load_dwordx4 v[118:121], v[78:79], off offset:640
	global_load_dwordx4 v[122:125], v[80:81], off offset:640
	global_load_dwordx4 v[126:129], v[74:75], off offset:640
	global_load_dwordx4 v[130:133], v[76:77], off offset:640
	global_load_dwordx4 v[134:137], v[82:83], off offset:640
	global_load_dwordx4 v[138:141], v[84:85], off offset:640
	global_load_dwordx4 v[142:145], v[86:87], off offset:640
	global_load_dwordx4 v[146:149], v[88:89], off offset:640
	s_waitcnt lgkmcnt(0)
	s_barrier
	v_mfma_f32_32x32x16_bf16 v[34:49], v[182:185], v[186:189], v[34:49]
	v_mfma_f32_32x32x16_bf16 v[50:65], v[182:185], v[198:201], v[50:65]
	v_mfma_f32_32x32x16_bf16 v[2:17], v[190:193], v[194:197], v[2:17]
	v_mfma_f32_32x32x16_bf16 v[18:33], v[190:193], v[202:205], v[18:33]
	v_mfma_f32_32x32x16_bf16 v[34:49], v[206:209], v[194:197], v[34:49]
	v_mfma_f32_32x32x16_bf16 v[50:65], v[206:209], v[202:205], v[50:65]
	ds_read_b128 v[182:185], v66 offset:18432
	ds_read_b128 v[186:189], v67 offset:55296
	ds_read_b128 v[190:193], v66 offset:18464
	ds_read_b128 v[194:197], v67 offset:55328
	ds_read_b128 v[198:201], v67 offset:59904
	ds_read_b128 v[202:205], v67 offset:59936
	s_waitcnt lgkmcnt(4)
	v_mfma_f32_32x32x16_bf16 v[2:17], v[182:185], v[186:189], v[2:17]
	s_waitcnt lgkmcnt(1)
	v_mfma_f32_32x32x16_bf16 v[18:33], v[182:185], v[198:201], v[18:33]
	ds_read_b128 v[182:185], v66 offset:23040
	ds_read_b128 v[206:209], v66 offset:23072
	s_waitcnt lgkmcnt(1)
	v_mfma_f32_32x32x16_bf16 v[34:49], v[182:185], v[186:189], v[34:49]
	v_mfma_f32_32x32x16_bf16 v[50:65], v[182:185], v[198:201], v[50:65]
	v_mfma_f32_32x32x16_bf16 v[2:17], v[190:193], v[194:197], v[2:17]
	v_mfma_f32_32x32x16_bf16 v[18:33], v[190:193], v[202:205], v[18:33]
	s_waitcnt lgkmcnt(0)
	v_mfma_f32_32x32x16_bf16 v[34:49], v[206:209], v[194:197], v[34:49]
	ds_read_b128 v[182:185], v66 offset:18496
	ds_read_b128 v[186:189], v67 offset:55360
	ds_read_b128 v[190:193], v66 offset:18528
	ds_read_b128 v[194:197], v67 offset:55392
	v_mfma_f32_32x32x16_bf16 v[50:65], v[206:209], v[202:205], v[50:65]
	ds_read_b128 v[198:201], v67 offset:59968
	ds_read_b128 v[202:205], v67 offset:60000
	s_waitcnt lgkmcnt(4)
	v_mfma_f32_32x32x16_bf16 v[2:17], v[182:185], v[186:189], v[2:17]
	s_waitcnt lgkmcnt(1)
	v_mfma_f32_32x32x16_bf16 v[18:33], v[182:185], v[198:201], v[18:33]
	ds_read_b128 v[182:185], v66 offset:23104
	ds_read_b128 v[206:209], v66 offset:23136
	s_waitcnt vmcnt(13)
	ds_write_b128 v90, v[158:161]
	ds_write_b128 v90, v[150:153] offset:4608
	ds_write_b128 v90, v[154:157] offset:9216
	s_waitcnt vmcnt(11)
	ds_write_b128 v90, v[166:169] offset:13824
	ds_write_b128 v90, v[162:165] offset:36864
	s_waitcnt vmcnt(10)
	ds_write_b128 v90, v[170:173] offset:41472
	s_waitcnt vmcnt(9)
	ds_write_b128 v90, v[174:177] offset:46080
	s_waitcnt vmcnt(8)
	ds_write_b128 v90, v[178:181] offset:50688
	global_load_dwordx4 v[150:153], v[78:79], off offset:768
	global_load_dwordx4 v[154:157], v[80:81], off offset:768
	global_load_dwordx4 v[158:161], v[74:75], off offset:768
	global_load_dwordx4 v[162:165], v[76:77], off offset:768
	global_load_dwordx4 v[166:169], v[82:83], off offset:768
	global_load_dwordx4 v[170:173], v[84:85], off offset:768
	global_load_dwordx4 v[174:177], v[86:87], off offset:768
	global_load_dwordx4 v[178:181], v[88:89], off offset:768
	s_waitcnt lgkmcnt(0)
	s_barrier
	v_mfma_f32_32x32x16_bf16 v[34:49], v[182:185], v[186:189], v[34:49]
	v_mfma_f32_32x32x16_bf16 v[50:65], v[182:185], v[198:201], v[50:65]
	v_mfma_f32_32x32x16_bf16 v[2:17], v[190:193], v[194:197], v[2:17]
	v_mfma_f32_32x32x16_bf16 v[18:33], v[190:193], v[202:205], v[18:33]
	v_mfma_f32_32x32x16_bf16 v[34:49], v[206:209], v[194:197], v[34:49]
	v_mfma_f32_32x32x16_bf16 v[50:65], v[206:209], v[202:205], v[50:65]
	ds_read_b128 v[182:185], v66
	ds_read_b128 v[186:189], v67 offset:36864
	ds_read_b128 v[190:193], v66 offset:32
	ds_read_b128 v[194:197], v67 offset:36896
	ds_read_b128 v[198:201], v67 offset:41472
	ds_read_b128 v[202:205], v67 offset:41504
	s_waitcnt lgkmcnt(4)
	v_mfma_f32_32x32x16_bf16 v[2:17], v[182:185], v[186:189], v[2:17]
	s_waitcnt lgkmcnt(1)
	v_mfma_f32_32x32x16_bf16 v[18:33], v[182:185], v[198:201], v[18:33]
	ds_read_b128 v[182:185], v66 offset:4608
	ds_read_b128 v[206:209], v66 offset:4640
	s_waitcnt lgkmcnt(1)
	v_mfma_f32_32x32x16_bf16 v[34:49], v[182:185], v[186:189], v[34:49]
	v_mfma_f32_32x32x16_bf16 v[50:65], v[182:185], v[198:201], v[50:65]
	v_mfma_f32_32x32x16_bf16 v[2:17], v[190:193], v[194:197], v[2:17]
	v_mfma_f32_32x32x16_bf16 v[18:33], v[190:193], v[202:205], v[18:33]
	s_waitcnt lgkmcnt(0)
	v_mfma_f32_32x32x16_bf16 v[34:49], v[206:209], v[194:197], v[34:49]
	ds_read_b128 v[182:185], v66 offset:64
	ds_read_b128 v[186:189], v67 offset:36928
	ds_read_b128 v[190:193], v66 offset:96
	ds_read_b128 v[194:197], v67 offset:36960
	v_mfma_f32_32x32x16_bf16 v[50:65], v[206:209], v[202:205], v[50:65]
	ds_read_b128 v[198:201], v67 offset:41536
	ds_read_b128 v[202:205], v67 offset:41568
	s_waitcnt lgkmcnt(4)
	v_mfma_f32_32x32x16_bf16 v[2:17], v[182:185], v[186:189], v[2:17]
	s_waitcnt lgkmcnt(1)
	v_mfma_f32_32x32x16_bf16 v[18:33], v[182:185], v[198:201], v[18:33]
	ds_read_b128 v[182:185], v66 offset:4672
	ds_read_b128 v[206:209], v66 offset:4704
	s_waitcnt vmcnt(13)
	ds_write_b128 v90, v[126:129] offset:18432
	ds_write_b128 v90, v[118:121] offset:23040
	ds_write_b128 v90, v[122:125] offset:27648
	s_waitcnt vmcnt(11)
	ds_write_b128 v90, v[134:137] offset:32256
	ds_write_b128 v90, v[130:133] offset:55296
	s_waitcnt vmcnt(10)
	ds_write_b128 v90, v[138:141] offset:59904
	s_waitcnt vmcnt(9)
	ds_write_b128 v90, v[142:145] offset:64512
	s_waitcnt vmcnt(8)
	ds_write_b128 v91, v[146:149] offset:32256
	global_load_dwordx4 v[118:121], v[78:79], off offset:896
	global_load_dwordx4 v[122:125], v[80:81], off offset:896
	global_load_dwordx4 v[126:129], v[74:75], off offset:896
	global_load_dwordx4 v[130:133], v[76:77], off offset:896
	global_load_dwordx4 v[134:137], v[82:83], off offset:896
	global_load_dwordx4 v[138:141], v[84:85], off offset:896
	global_load_dwordx4 v[142:145], v[86:87], off offset:896
	global_load_dwordx4 v[146:149], v[88:89], off offset:896
	s_waitcnt lgkmcnt(0)
	s_barrier
	v_mfma_f32_32x32x16_bf16 v[34:49], v[182:185], v[186:189], v[34:49]
	v_mfma_f32_32x32x16_bf16 v[50:65], v[182:185], v[198:201], v[50:65]
	v_mfma_f32_32x32x16_bf16 v[2:17], v[190:193], v[194:197], v[2:17]
	v_mfma_f32_32x32x16_bf16 v[18:33], v[190:193], v[202:205], v[18:33]
	v_mfma_f32_32x32x16_bf16 v[34:49], v[206:209], v[194:197], v[34:49]
	v_mfma_f32_32x32x16_bf16 v[50:65], v[206:209], v[202:205], v[50:65]
	ds_read_b128 v[182:185], v66 offset:18432
	ds_read_b128 v[186:189], v67 offset:55296
	ds_read_b128 v[190:193], v66 offset:18464
	ds_read_b128 v[194:197], v67 offset:55328
	ds_read_b128 v[198:201], v67 offset:59904
	ds_read_b128 v[202:205], v67 offset:59936
	s_waitcnt lgkmcnt(4)
	v_mfma_f32_32x32x16_bf16 v[2:17], v[182:185], v[186:189], v[2:17]
	s_waitcnt lgkmcnt(1)
	v_mfma_f32_32x32x16_bf16 v[18:33], v[182:185], v[198:201], v[18:33]
	ds_read_b128 v[182:185], v66 offset:23040
	ds_read_b128 v[206:209], v66 offset:23072
	s_waitcnt lgkmcnt(1)
	v_mfma_f32_32x32x16_bf16 v[34:49], v[182:185], v[186:189], v[34:49]
	v_mfma_f32_32x32x16_bf16 v[50:65], v[182:185], v[198:201], v[50:65]
	v_mfma_f32_32x32x16_bf16 v[2:17], v[190:193], v[194:197], v[2:17]
	v_mfma_f32_32x32x16_bf16 v[18:33], v[190:193], v[202:205], v[18:33]
	s_waitcnt lgkmcnt(0)
	v_mfma_f32_32x32x16_bf16 v[34:49], v[206:209], v[194:197], v[34:49]
	ds_read_b128 v[182:185], v66 offset:18496
	ds_read_b128 v[186:189], v67 offset:55360
	ds_read_b128 v[190:193], v66 offset:18528
	ds_read_b128 v[194:197], v67 offset:55392
	v_mfma_f32_32x32x16_bf16 v[50:65], v[206:209], v[202:205], v[50:65]
	ds_read_b128 v[198:201], v67 offset:59968
	ds_read_b128 v[202:205], v67 offset:60000
	s_waitcnt lgkmcnt(4)
	v_mfma_f32_32x32x16_bf16 v[2:17], v[182:185], v[186:189], v[2:17]
	s_waitcnt lgkmcnt(1)
	v_mfma_f32_32x32x16_bf16 v[18:33], v[182:185], v[198:201], v[18:33]
	ds_read_b128 v[182:185], v66 offset:23104
	ds_read_b128 v[206:209], v66 offset:23136
	s_waitcnt vmcnt(13)
	ds_write_b128 v90, v[158:161]
	ds_write_b128 v90, v[150:153] offset:4608
	ds_write_b128 v90, v[154:157] offset:9216
	s_waitcnt vmcnt(11)
	ds_write_b128 v90, v[166:169] offset:13824
	ds_write_b128 v90, v[162:165] offset:36864
	s_waitcnt vmcnt(10)
	ds_write_b128 v90, v[170:173] offset:41472
	s_waitcnt vmcnt(9)
	ds_write_b128 v90, v[174:177] offset:46080
	s_waitcnt vmcnt(8)
	ds_write_b128 v90, v[178:181] offset:50688
	global_load_dwordx4 v[150:153], v[78:79], off offset:1024
	global_load_dwordx4 v[154:157], v[80:81], off offset:1024
	global_load_dwordx4 v[158:161], v[74:75], off offset:1024
	global_load_dwordx4 v[162:165], v[76:77], off offset:1024
	global_load_dwordx4 v[166:169], v[82:83], off offset:1024
	global_load_dwordx4 v[170:173], v[84:85], off offset:1024
	global_load_dwordx4 v[174:177], v[86:87], off offset:1024
	global_load_dwordx4 v[178:181], v[88:89], off offset:1024
	s_waitcnt lgkmcnt(0)
	s_barrier
	v_mfma_f32_32x32x16_bf16 v[34:49], v[182:185], v[186:189], v[34:49]
	v_mfma_f32_32x32x16_bf16 v[50:65], v[182:185], v[198:201], v[50:65]
	v_mfma_f32_32x32x16_bf16 v[2:17], v[190:193], v[194:197], v[2:17]
	v_mfma_f32_32x32x16_bf16 v[18:33], v[190:193], v[202:205], v[18:33]
	v_mfma_f32_32x32x16_bf16 v[34:49], v[206:209], v[194:197], v[34:49]
	v_mfma_f32_32x32x16_bf16 v[50:65], v[206:209], v[202:205], v[50:65]
	ds_read_b128 v[182:185], v66
	ds_read_b128 v[186:189], v67 offset:36864
	ds_read_b128 v[190:193], v66 offset:32
	ds_read_b128 v[194:197], v67 offset:36896
	ds_read_b128 v[198:201], v67 offset:41472
	ds_read_b128 v[202:205], v67 offset:41504
	s_waitcnt lgkmcnt(4)
	v_mfma_f32_32x32x16_bf16 v[2:17], v[182:185], v[186:189], v[2:17]
	s_waitcnt lgkmcnt(1)
	v_mfma_f32_32x32x16_bf16 v[18:33], v[182:185], v[198:201], v[18:33]
	ds_read_b128 v[182:185], v66 offset:4608
	ds_read_b128 v[206:209], v66 offset:4640
	s_waitcnt lgkmcnt(1)
	v_mfma_f32_32x32x16_bf16 v[34:49], v[182:185], v[186:189], v[34:49]
	v_mfma_f32_32x32x16_bf16 v[50:65], v[182:185], v[198:201], v[50:65]
	v_mfma_f32_32x32x16_bf16 v[2:17], v[190:193], v[194:197], v[2:17]
	v_mfma_f32_32x32x16_bf16 v[18:33], v[190:193], v[202:205], v[18:33]
	s_waitcnt lgkmcnt(0)
	v_mfma_f32_32x32x16_bf16 v[34:49], v[206:209], v[194:197], v[34:49]
	ds_read_b128 v[182:185], v66 offset:64
	ds_read_b128 v[186:189], v67 offset:36928
	ds_read_b128 v[190:193], v66 offset:96
	ds_read_b128 v[194:197], v67 offset:36960
	v_mfma_f32_32x32x16_bf16 v[50:65], v[206:209], v[202:205], v[50:65]
	ds_read_b128 v[198:201], v67 offset:41536
	ds_read_b128 v[202:205], v67 offset:41568
	s_waitcnt lgkmcnt(4)
	v_mfma_f32_32x32x16_bf16 v[2:17], v[182:185], v[186:189], v[2:17]
	s_waitcnt lgkmcnt(1)
	v_mfma_f32_32x32x16_bf16 v[18:33], v[182:185], v[198:201], v[18:33]
	ds_read_b128 v[182:185], v66 offset:4672
	ds_read_b128 v[206:209], v66 offset:4704
	s_waitcnt vmcnt(13)
	ds_write_b128 v90, v[126:129] offset:18432
	ds_write_b128 v90, v[118:121] offset:23040
	ds_write_b128 v90, v[122:125] offset:27648
	s_waitcnt vmcnt(11)
	ds_write_b128 v90, v[134:137] offset:32256
	ds_write_b128 v90, v[130:133] offset:55296
	s_waitcnt vmcnt(10)
	ds_write_b128 v90, v[138:141] offset:59904
	s_waitcnt vmcnt(9)
	ds_write_b128 v90, v[142:145] offset:64512
	s_waitcnt vmcnt(8)
	ds_write_b128 v91, v[146:149] offset:32256
	global_load_dwordx4 v[118:121], v[78:79], off offset:1152
	global_load_dwordx4 v[122:125], v[80:81], off offset:1152
	global_load_dwordx4 v[126:129], v[74:75], off offset:1152
	global_load_dwordx4 v[130:133], v[76:77], off offset:1152
	global_load_dwordx4 v[134:137], v[82:83], off offset:1152
	global_load_dwordx4 v[138:141], v[84:85], off offset:1152
	global_load_dwordx4 v[142:145], v[86:87], off offset:1152
	global_load_dwordx4 v[146:149], v[88:89], off offset:1152
	s_waitcnt lgkmcnt(0)
	s_barrier
	v_mfma_f32_32x32x16_bf16 v[34:49], v[182:185], v[186:189], v[34:49]
	v_mfma_f32_32x32x16_bf16 v[50:65], v[182:185], v[198:201], v[50:65]
	v_mfma_f32_32x32x16_bf16 v[2:17], v[190:193], v[194:197], v[2:17]
	v_mfma_f32_32x32x16_bf16 v[18:33], v[190:193], v[202:205], v[18:33]
	v_mfma_f32_32x32x16_bf16 v[34:49], v[206:209], v[194:197], v[34:49]
	v_mfma_f32_32x32x16_bf16 v[50:65], v[206:209], v[202:205], v[50:65]
	ds_read_b128 v[182:185], v66 offset:18432
	ds_read_b128 v[186:189], v67 offset:55296
	ds_read_b128 v[190:193], v66 offset:18464
	ds_read_b128 v[194:197], v67 offset:55328
	ds_read_b128 v[198:201], v67 offset:59904
	ds_read_b128 v[202:205], v67 offset:59936
	s_waitcnt lgkmcnt(4)
	v_mfma_f32_32x32x16_bf16 v[2:17], v[182:185], v[186:189], v[2:17]
	s_waitcnt lgkmcnt(1)
	v_mfma_f32_32x32x16_bf16 v[18:33], v[182:185], v[198:201], v[18:33]
	ds_read_b128 v[182:185], v66 offset:23040
	ds_read_b128 v[206:209], v66 offset:23072
	s_waitcnt lgkmcnt(1)
	v_mfma_f32_32x32x16_bf16 v[34:49], v[182:185], v[186:189], v[34:49]
	v_mfma_f32_32x32x16_bf16 v[50:65], v[182:185], v[198:201], v[50:65]
	v_mfma_f32_32x32x16_bf16 v[2:17], v[190:193], v[194:197], v[2:17]
	v_mfma_f32_32x32x16_bf16 v[18:33], v[190:193], v[202:205], v[18:33]
	s_waitcnt lgkmcnt(0)
	v_mfma_f32_32x32x16_bf16 v[34:49], v[206:209], v[194:197], v[34:49]
	ds_read_b128 v[182:185], v66 offset:18496
	ds_read_b128 v[186:189], v67 offset:55360
	ds_read_b128 v[190:193], v66 offset:18528
	ds_read_b128 v[194:197], v67 offset:55392
	v_mfma_f32_32x32x16_bf16 v[50:65], v[206:209], v[202:205], v[50:65]
	ds_read_b128 v[198:201], v67 offset:59968
	ds_read_b128 v[202:205], v67 offset:60000
	s_waitcnt lgkmcnt(4)
	v_mfma_f32_32x32x16_bf16 v[2:17], v[182:185], v[186:189], v[2:17]
	s_waitcnt lgkmcnt(1)
	v_mfma_f32_32x32x16_bf16 v[18:33], v[182:185], v[198:201], v[18:33]
	ds_read_b128 v[182:185], v66 offset:23104
	ds_read_b128 v[206:209], v66 offset:23136
	s_waitcnt vmcnt(13)
	ds_write_b128 v90, v[158:161]
	ds_write_b128 v90, v[150:153] offset:4608
	ds_write_b128 v90, v[154:157] offset:9216
	s_waitcnt vmcnt(11)
	ds_write_b128 v90, v[166:169] offset:13824
	ds_write_b128 v90, v[162:165] offset:36864
	s_waitcnt vmcnt(10)
	ds_write_b128 v90, v[170:173] offset:41472
	s_waitcnt vmcnt(9)
	ds_write_b128 v90, v[174:177] offset:46080
	s_waitcnt vmcnt(8)
	ds_write_b128 v90, v[178:181] offset:50688
	global_load_dwordx4 v[150:153], v[78:79], off offset:1280
	global_load_dwordx4 v[154:157], v[80:81], off offset:1280
	global_load_dwordx4 v[158:161], v[74:75], off offset:1280
	global_load_dwordx4 v[162:165], v[76:77], off offset:1280
	global_load_dwordx4 v[166:169], v[82:83], off offset:1280
	global_load_dwordx4 v[170:173], v[84:85], off offset:1280
	global_load_dwordx4 v[174:177], v[86:87], off offset:1280
	global_load_dwordx4 v[178:181], v[88:89], off offset:1280
	s_waitcnt lgkmcnt(0)
	s_barrier
	v_mfma_f32_32x32x16_bf16 v[34:49], v[182:185], v[186:189], v[34:49]
	v_mfma_f32_32x32x16_bf16 v[50:65], v[182:185], v[198:201], v[50:65]
	v_mfma_f32_32x32x16_bf16 v[2:17], v[190:193], v[194:197], v[2:17]
	v_mfma_f32_32x32x16_bf16 v[18:33], v[190:193], v[202:205], v[18:33]
	v_mfma_f32_32x32x16_bf16 v[34:49], v[206:209], v[194:197], v[34:49]
	v_mfma_f32_32x32x16_bf16 v[50:65], v[206:209], v[202:205], v[50:65]
	ds_read_b128 v[182:185], v66
	ds_read_b128 v[186:189], v67 offset:36864
	ds_read_b128 v[190:193], v66 offset:32
	ds_read_b128 v[194:197], v67 offset:36896
	ds_read_b128 v[198:201], v67 offset:41472
	ds_read_b128 v[202:205], v67 offset:41504
	s_waitcnt lgkmcnt(4)
	v_mfma_f32_32x32x16_bf16 v[2:17], v[182:185], v[186:189], v[2:17]
	s_waitcnt lgkmcnt(1)
	v_mfma_f32_32x32x16_bf16 v[18:33], v[182:185], v[198:201], v[18:33]
	ds_read_b128 v[182:185], v66 offset:4608
	ds_read_b128 v[206:209], v66 offset:4640
	s_waitcnt lgkmcnt(1)
	v_mfma_f32_32x32x16_bf16 v[34:49], v[182:185], v[186:189], v[34:49]
	v_mfma_f32_32x32x16_bf16 v[50:65], v[182:185], v[198:201], v[50:65]
	v_mfma_f32_32x32x16_bf16 v[2:17], v[190:193], v[194:197], v[2:17]
	v_mfma_f32_32x32x16_bf16 v[18:33], v[190:193], v[202:205], v[18:33]
	s_waitcnt lgkmcnt(0)
	v_mfma_f32_32x32x16_bf16 v[34:49], v[206:209], v[194:197], v[34:49]
	ds_read_b128 v[182:185], v66 offset:64
	ds_read_b128 v[186:189], v67 offset:36928
	ds_read_b128 v[190:193], v66 offset:96
	ds_read_b128 v[194:197], v67 offset:36960
	v_mfma_f32_32x32x16_bf16 v[50:65], v[206:209], v[202:205], v[50:65]
	ds_read_b128 v[198:201], v67 offset:41536
	ds_read_b128 v[202:205], v67 offset:41568
	s_waitcnt lgkmcnt(4)
	v_mfma_f32_32x32x16_bf16 v[2:17], v[182:185], v[186:189], v[2:17]
	s_waitcnt lgkmcnt(1)
	v_mfma_f32_32x32x16_bf16 v[18:33], v[182:185], v[198:201], v[18:33]
	ds_read_b128 v[182:185], v66 offset:4672
	ds_read_b128 v[206:209], v66 offset:4704
	s_waitcnt vmcnt(13)
	ds_write_b128 v90, v[126:129] offset:18432
	ds_write_b128 v90, v[118:121] offset:23040
	ds_write_b128 v90, v[122:125] offset:27648
	s_waitcnt vmcnt(11)
	ds_write_b128 v90, v[134:137] offset:32256
	ds_write_b128 v90, v[130:133] offset:55296
	s_waitcnt vmcnt(10)
	ds_write_b128 v90, v[138:141] offset:59904
	s_waitcnt vmcnt(9)
	ds_write_b128 v90, v[142:145] offset:64512
	s_waitcnt vmcnt(8)
	ds_write_b128 v91, v[146:149] offset:32256
	global_load_dwordx4 v[118:121], v[78:79], off offset:1408
	global_load_dwordx4 v[122:125], v[80:81], off offset:1408
	global_load_dwordx4 v[126:129], v[74:75], off offset:1408
	global_load_dwordx4 v[130:133], v[76:77], off offset:1408
	global_load_dwordx4 v[134:137], v[82:83], off offset:1408
	global_load_dwordx4 v[138:141], v[84:85], off offset:1408
	global_load_dwordx4 v[142:145], v[86:87], off offset:1408
	global_load_dwordx4 v[146:149], v[88:89], off offset:1408
	s_waitcnt lgkmcnt(0)
	s_barrier
	v_mfma_f32_32x32x16_bf16 v[34:49], v[182:185], v[186:189], v[34:49]
	v_mfma_f32_32x32x16_bf16 v[50:65], v[182:185], v[198:201], v[50:65]
	v_mfma_f32_32x32x16_bf16 v[2:17], v[190:193], v[194:197], v[2:17]
	v_mfma_f32_32x32x16_bf16 v[18:33], v[190:193], v[202:205], v[18:33]
	v_mfma_f32_32x32x16_bf16 v[34:49], v[206:209], v[194:197], v[34:49]
	v_mfma_f32_32x32x16_bf16 v[50:65], v[206:209], v[202:205], v[50:65]
	ds_read_b128 v[182:185], v66 offset:18432
	ds_read_b128 v[186:189], v67 offset:55296
	ds_read_b128 v[190:193], v66 offset:18464
	ds_read_b128 v[194:197], v67 offset:55328
	ds_read_b128 v[198:201], v67 offset:59904
	ds_read_b128 v[202:205], v67 offset:59936
	s_waitcnt lgkmcnt(4)
	v_mfma_f32_32x32x16_bf16 v[2:17], v[182:185], v[186:189], v[2:17]
	s_waitcnt lgkmcnt(1)
	v_mfma_f32_32x32x16_bf16 v[18:33], v[182:185], v[198:201], v[18:33]
	ds_read_b128 v[182:185], v66 offset:23040
	ds_read_b128 v[206:209], v66 offset:23072
	s_waitcnt lgkmcnt(1)
	v_mfma_f32_32x32x16_bf16 v[34:49], v[182:185], v[186:189], v[34:49]
	v_mfma_f32_32x32x16_bf16 v[50:65], v[182:185], v[198:201], v[50:65]
	v_mfma_f32_32x32x16_bf16 v[2:17], v[190:193], v[194:197], v[2:17]
	v_mfma_f32_32x32x16_bf16 v[18:33], v[190:193], v[202:205], v[18:33]
	s_waitcnt lgkmcnt(0)
	v_mfma_f32_32x32x16_bf16 v[34:49], v[206:209], v[194:197], v[34:49]
	ds_read_b128 v[182:185], v66 offset:18496
	ds_read_b128 v[186:189], v67 offset:55360
	ds_read_b128 v[190:193], v66 offset:18528
	ds_read_b128 v[194:197], v67 offset:55392
	v_mfma_f32_32x32x16_bf16 v[50:65], v[206:209], v[202:205], v[50:65]
	ds_read_b128 v[198:201], v67 offset:59968
	ds_read_b128 v[202:205], v67 offset:60000
	s_waitcnt lgkmcnt(4)
	v_mfma_f32_32x32x16_bf16 v[2:17], v[182:185], v[186:189], v[2:17]
	s_waitcnt lgkmcnt(1)
	v_mfma_f32_32x32x16_bf16 v[18:33], v[182:185], v[198:201], v[18:33]
	ds_read_b128 v[182:185], v66 offset:23104
	ds_read_b128 v[206:209], v66 offset:23136
	s_waitcnt vmcnt(13)
	ds_write_b128 v90, v[158:161]
	ds_write_b128 v90, v[150:153] offset:4608
	ds_write_b128 v90, v[154:157] offset:9216
	s_waitcnt vmcnt(11)
	ds_write_b128 v90, v[166:169] offset:13824
	ds_write_b128 v90, v[162:165] offset:36864
	s_waitcnt vmcnt(10)
	ds_write_b128 v90, v[170:173] offset:41472
	s_waitcnt vmcnt(9)
	ds_write_b128 v90, v[174:177] offset:46080
	s_waitcnt vmcnt(8)
	ds_write_b128 v90, v[178:181] offset:50688
	global_load_dwordx4 v[150:153], v[78:79], off offset:1536
	global_load_dwordx4 v[154:157], v[80:81], off offset:1536
	global_load_dwordx4 v[158:161], v[74:75], off offset:1536
	global_load_dwordx4 v[162:165], v[76:77], off offset:1536
	global_load_dwordx4 v[166:169], v[82:83], off offset:1536
	global_load_dwordx4 v[170:173], v[84:85], off offset:1536
	global_load_dwordx4 v[174:177], v[86:87], off offset:1536
	global_load_dwordx4 v[178:181], v[88:89], off offset:1536
	s_waitcnt lgkmcnt(0)
	s_barrier
	v_mfma_f32_32x32x16_bf16 v[34:49], v[182:185], v[186:189], v[34:49]
	v_mfma_f32_32x32x16_bf16 v[50:65], v[182:185], v[198:201], v[50:65]
	v_mfma_f32_32x32x16_bf16 v[2:17], v[190:193], v[194:197], v[2:17]
	v_mfma_f32_32x32x16_bf16 v[18:33], v[190:193], v[202:205], v[18:33]
	v_mfma_f32_32x32x16_bf16 v[34:49], v[206:209], v[194:197], v[34:49]
	v_mfma_f32_32x32x16_bf16 v[50:65], v[206:209], v[202:205], v[50:65]
	ds_read_b128 v[182:185], v66
	ds_read_b128 v[186:189], v67 offset:36864
	ds_read_b128 v[190:193], v66 offset:32
	ds_read_b128 v[194:197], v67 offset:36896
	ds_read_b128 v[198:201], v67 offset:41472
	ds_read_b128 v[202:205], v67 offset:41504
	s_waitcnt lgkmcnt(4)
	v_mfma_f32_32x32x16_bf16 v[2:17], v[182:185], v[186:189], v[2:17]
	s_waitcnt lgkmcnt(1)
	v_mfma_f32_32x32x16_bf16 v[18:33], v[182:185], v[198:201], v[18:33]
	ds_read_b128 v[182:185], v66 offset:4608
	ds_read_b128 v[206:209], v66 offset:4640
	s_waitcnt lgkmcnt(1)
	v_mfma_f32_32x32x16_bf16 v[34:49], v[182:185], v[186:189], v[34:49]
	v_mfma_f32_32x32x16_bf16 v[50:65], v[182:185], v[198:201], v[50:65]
	v_mfma_f32_32x32x16_bf16 v[2:17], v[190:193], v[194:197], v[2:17]
	v_mfma_f32_32x32x16_bf16 v[18:33], v[190:193], v[202:205], v[18:33]
	s_waitcnt lgkmcnt(0)
	v_mfma_f32_32x32x16_bf16 v[34:49], v[206:209], v[194:197], v[34:49]
	ds_read_b128 v[182:185], v66 offset:64
	ds_read_b128 v[186:189], v67 offset:36928
	ds_read_b128 v[190:193], v66 offset:96
	ds_read_b128 v[194:197], v67 offset:36960
	v_mfma_f32_32x32x16_bf16 v[50:65], v[206:209], v[202:205], v[50:65]
	ds_read_b128 v[198:201], v67 offset:41536
	ds_read_b128 v[202:205], v67 offset:41568
	s_waitcnt lgkmcnt(4)
	v_mfma_f32_32x32x16_bf16 v[2:17], v[182:185], v[186:189], v[2:17]
	s_waitcnt lgkmcnt(1)
	v_mfma_f32_32x32x16_bf16 v[18:33], v[182:185], v[198:201], v[18:33]
	ds_read_b128 v[182:185], v66 offset:4672
	ds_read_b128 v[206:209], v66 offset:4704
	s_waitcnt vmcnt(13)
	ds_write_b128 v90, v[126:129] offset:18432
	ds_write_b128 v90, v[118:121] offset:23040
	ds_write_b128 v90, v[122:125] offset:27648
	s_waitcnt vmcnt(11)
	ds_write_b128 v90, v[134:137] offset:32256
	ds_write_b128 v90, v[130:133] offset:55296
	s_waitcnt vmcnt(10)
	ds_write_b128 v90, v[138:141] offset:59904
	s_waitcnt vmcnt(9)
	ds_write_b128 v90, v[142:145] offset:64512
	s_waitcnt vmcnt(8)
	ds_write_b128 v91, v[146:149] offset:32256
	global_load_dwordx4 v[118:121], v[78:79], off offset:1664
	global_load_dwordx4 v[122:125], v[80:81], off offset:1664
	global_load_dwordx4 v[126:129], v[74:75], off offset:1664
	global_load_dwordx4 v[130:133], v[76:77], off offset:1664
	global_load_dwordx4 v[134:137], v[82:83], off offset:1664
	global_load_dwordx4 v[138:141], v[84:85], off offset:1664
	global_load_dwordx4 v[142:145], v[86:87], off offset:1664
	global_load_dwordx4 v[146:149], v[88:89], off offset:1664
	s_waitcnt lgkmcnt(0)
	s_barrier
	v_mfma_f32_32x32x16_bf16 v[34:49], v[182:185], v[186:189], v[34:49]
	v_mfma_f32_32x32x16_bf16 v[50:65], v[182:185], v[198:201], v[50:65]
	v_mfma_f32_32x32x16_bf16 v[2:17], v[190:193], v[194:197], v[2:17]
	v_mfma_f32_32x32x16_bf16 v[18:33], v[190:193], v[202:205], v[18:33]
	v_mfma_f32_32x32x16_bf16 v[34:49], v[206:209], v[194:197], v[34:49]
	v_mfma_f32_32x32x16_bf16 v[50:65], v[206:209], v[202:205], v[50:65]
	ds_read_b128 v[182:185], v66 offset:18432
	ds_read_b128 v[186:189], v67 offset:55296
	ds_read_b128 v[190:193], v66 offset:18464
	ds_read_b128 v[194:197], v67 offset:55328
	ds_read_b128 v[198:201], v67 offset:59904
	ds_read_b128 v[202:205], v67 offset:59936
	s_waitcnt lgkmcnt(4)
	v_mfma_f32_32x32x16_bf16 v[2:17], v[182:185], v[186:189], v[2:17]
	s_waitcnt lgkmcnt(1)
	v_mfma_f32_32x32x16_bf16 v[18:33], v[182:185], v[198:201], v[18:33]
	ds_read_b128 v[182:185], v66 offset:23040
	ds_read_b128 v[206:209], v66 offset:23072
	s_waitcnt lgkmcnt(1)
	v_mfma_f32_32x32x16_bf16 v[34:49], v[182:185], v[186:189], v[34:49]
	v_mfma_f32_32x32x16_bf16 v[50:65], v[182:185], v[198:201], v[50:65]
	v_mfma_f32_32x32x16_bf16 v[2:17], v[190:193], v[194:197], v[2:17]
	v_mfma_f32_32x32x16_bf16 v[18:33], v[190:193], v[202:205], v[18:33]
	s_waitcnt lgkmcnt(0)
	v_mfma_f32_32x32x16_bf16 v[34:49], v[206:209], v[194:197], v[34:49]
	ds_read_b128 v[182:185], v66 offset:18496
	ds_read_b128 v[186:189], v67 offset:55360
	ds_read_b128 v[190:193], v66 offset:18528
	ds_read_b128 v[194:197], v67 offset:55392
	v_mfma_f32_32x32x16_bf16 v[50:65], v[206:209], v[202:205], v[50:65]
	ds_read_b128 v[198:201], v67 offset:59968
	ds_read_b128 v[202:205], v67 offset:60000
	s_waitcnt lgkmcnt(4)
	v_mfma_f32_32x32x16_bf16 v[2:17], v[182:185], v[186:189], v[2:17]
	s_waitcnt lgkmcnt(1)
	v_mfma_f32_32x32x16_bf16 v[18:33], v[182:185], v[198:201], v[18:33]
	ds_read_b128 v[182:185], v66 offset:23104
	ds_read_b128 v[206:209], v66 offset:23136
	s_waitcnt vmcnt(13)
	ds_write_b128 v90, v[158:161]
	ds_write_b128 v90, v[150:153] offset:4608
	ds_write_b128 v90, v[154:157] offset:9216
	s_waitcnt vmcnt(11)
	ds_write_b128 v90, v[166:169] offset:13824
	ds_write_b128 v90, v[162:165] offset:36864
	s_waitcnt vmcnt(10)
	ds_write_b128 v90, v[170:173] offset:41472
	s_waitcnt vmcnt(9)
	ds_write_b128 v90, v[174:177] offset:46080
	s_waitcnt vmcnt(8)
	ds_write_b128 v90, v[178:181] offset:50688
	global_load_dwordx4 v[150:153], v[78:79], off offset:1792
	global_load_dwordx4 v[154:157], v[80:81], off offset:1792
	global_load_dwordx4 v[158:161], v[74:75], off offset:1792
	global_load_dwordx4 v[162:165], v[76:77], off offset:1792
	global_load_dwordx4 v[166:169], v[82:83], off offset:1792
	global_load_dwordx4 v[170:173], v[84:85], off offset:1792
	global_load_dwordx4 v[174:177], v[86:87], off offset:1792
	global_load_dwordx4 v[178:181], v[88:89], off offset:1792
	s_waitcnt lgkmcnt(0)
	s_barrier
	v_mfma_f32_32x32x16_bf16 v[34:49], v[182:185], v[186:189], v[34:49]
	v_mfma_f32_32x32x16_bf16 v[50:65], v[182:185], v[198:201], v[50:65]
	v_mfma_f32_32x32x16_bf16 v[2:17], v[190:193], v[194:197], v[2:17]
	v_mfma_f32_32x32x16_bf16 v[18:33], v[190:193], v[202:205], v[18:33]
	v_mfma_f32_32x32x16_bf16 v[34:49], v[206:209], v[194:197], v[34:49]
	v_mfma_f32_32x32x16_bf16 v[50:65], v[206:209], v[202:205], v[50:65]
	ds_read_b128 v[182:185], v66
	ds_read_b128 v[186:189], v67 offset:36864
	ds_read_b128 v[190:193], v66 offset:32
	ds_read_b128 v[194:197], v67 offset:36896
	ds_read_b128 v[198:201], v67 offset:41472
	ds_read_b128 v[202:205], v67 offset:41504
	s_waitcnt lgkmcnt(4)
	v_mfma_f32_32x32x16_bf16 v[2:17], v[182:185], v[186:189], v[2:17]
	s_waitcnt lgkmcnt(1)
	v_mfma_f32_32x32x16_bf16 v[18:33], v[182:185], v[198:201], v[18:33]
	ds_read_b128 v[182:185], v66 offset:4608
	ds_read_b128 v[206:209], v66 offset:4640
	s_waitcnt lgkmcnt(1)
	v_mfma_f32_32x32x16_bf16 v[34:49], v[182:185], v[186:189], v[34:49]
	v_mfma_f32_32x32x16_bf16 v[50:65], v[182:185], v[198:201], v[50:65]
	v_mfma_f32_32x32x16_bf16 v[2:17], v[190:193], v[194:197], v[2:17]
	v_mfma_f32_32x32x16_bf16 v[18:33], v[190:193], v[202:205], v[18:33]
	s_waitcnt lgkmcnt(0)
	v_mfma_f32_32x32x16_bf16 v[34:49], v[206:209], v[194:197], v[34:49]
	ds_read_b128 v[182:185], v66 offset:64
	ds_read_b128 v[186:189], v67 offset:36928
	ds_read_b128 v[190:193], v66 offset:96
	ds_read_b128 v[194:197], v67 offset:36960
	v_mfma_f32_32x32x16_bf16 v[50:65], v[206:209], v[202:205], v[50:65]
	ds_read_b128 v[198:201], v67 offset:41536
	ds_read_b128 v[202:205], v67 offset:41568
	s_waitcnt lgkmcnt(4)
	v_mfma_f32_32x32x16_bf16 v[2:17], v[182:185], v[186:189], v[2:17]
	s_waitcnt lgkmcnt(1)
	v_mfma_f32_32x32x16_bf16 v[18:33], v[182:185], v[198:201], v[18:33]
	ds_read_b128 v[182:185], v66 offset:4672
	ds_read_b128 v[206:209], v66 offset:4704
	s_waitcnt vmcnt(13)
	ds_write_b128 v90, v[126:129] offset:18432
	ds_write_b128 v90, v[118:121] offset:23040
	ds_write_b128 v90, v[122:125] offset:27648
	s_waitcnt vmcnt(11)
	ds_write_b128 v90, v[134:137] offset:32256
	ds_write_b128 v90, v[130:133] offset:55296
	s_waitcnt vmcnt(10)
	ds_write_b128 v90, v[138:141] offset:59904
	s_waitcnt vmcnt(9)
	ds_write_b128 v90, v[142:145] offset:64512
	s_waitcnt vmcnt(8)
	ds_write_b128 v91, v[146:149] offset:32256
	s_waitcnt lgkmcnt(0)
	s_barrier
	global_load_dwordx4 v[118:121], v[78:79], off offset:1920
	s_nop 0
	global_load_dwordx4 v[78:81], v[80:81], off offset:1920
	s_nop 0
	global_load_dwordx4 v[122:125], v[74:75], off offset:1920
	s_nop 0
	global_load_dwordx4 v[74:77], v[76:77], off offset:1920
	s_nop 0
	global_load_dwordx4 v[126:129], v[82:83], off offset:1920
	s_nop 0
	global_load_dwordx4 v[82:85], v[84:85], off offset:1920
	s_nop 0
	global_load_dwordx4 v[130:133], v[86:87], off offset:1920
	s_nop 0
	global_load_dwordx4 v[86:89], v[88:89], off offset:1920
	v_mfma_f32_32x32x16_bf16 v[34:49], v[182:185], v[186:189], v[34:49]
	v_mfma_f32_32x32x16_bf16 v[50:65], v[182:185], v[198:201], v[50:65]
	v_mfma_f32_32x32x16_bf16 v[2:17], v[190:193], v[194:197], v[2:17]
	v_mfma_f32_32x32x16_bf16 v[18:33], v[190:193], v[202:205], v[18:33]
	v_mfma_f32_32x32x16_bf16 v[34:49], v[206:209], v[194:197], v[34:49]
	v_mfma_f32_32x32x16_bf16 v[50:65], v[206:209], v[202:205], v[50:65]
	ds_read_b128 v[134:137], v66 offset:18432
	ds_read_b128 v[138:141], v67 offset:55296
	ds_read_b128 v[142:145], v66 offset:18464
	ds_read_b128 v[146:149], v67 offset:55328
	ds_read_b128 v[182:185], v67 offset:59904
	ds_read_b128 v[186:189], v67 offset:59936
	s_waitcnt lgkmcnt(4)
	v_mfma_f32_32x32x16_bf16 v[2:17], v[134:137], v[138:141], v[2:17]
	s_waitcnt lgkmcnt(1)
	v_mfma_f32_32x32x16_bf16 v[18:33], v[134:137], v[182:185], v[18:33]
	ds_read_b128 v[134:137], v66 offset:23040
	ds_read_b128 v[190:193], v66 offset:23072
	s_waitcnt lgkmcnt(1)
	v_mfma_f32_32x32x16_bf16 v[34:49], v[134:137], v[138:141], v[34:49]
	v_mfma_f32_32x32x16_bf16 v[50:65], v[134:137], v[182:185], v[50:65]
	v_mfma_f32_32x32x16_bf16 v[2:17], v[142:145], v[146:149], v[2:17]
	v_mfma_f32_32x32x16_bf16 v[18:33], v[142:145], v[186:189], v[18:33]
	s_waitcnt lgkmcnt(0)
	v_mfma_f32_32x32x16_bf16 v[34:49], v[190:193], v[146:149], v[34:49]
	ds_read_b128 v[134:137], v66 offset:18496
	ds_read_b128 v[138:141], v67 offset:55360
	ds_read_b128 v[142:145], v66 offset:18528
	ds_read_b128 v[146:149], v67 offset:55392
	v_mfma_f32_32x32x16_bf16 v[50:65], v[190:193], v[186:189], v[50:65]
	ds_read_b128 v[182:185], v67 offset:59968
	ds_read_b128 v[186:189], v67 offset:60000
	s_waitcnt lgkmcnt(4)
	v_mfma_f32_32x32x16_bf16 v[2:17], v[134:137], v[138:141], v[2:17]
	s_waitcnt lgkmcnt(1)
	v_mfma_f32_32x32x16_bf16 v[18:33], v[134:137], v[182:185], v[18:33]
	ds_read_b128 v[134:137], v66 offset:23104
	ds_read_b128 v[190:193], v66 offset:23136
	s_waitcnt vmcnt(13)
	ds_write_b128 v90, v[158:161]
	ds_write_b128 v90, v[150:153] offset:4608
	ds_write_b128 v90, v[154:157] offset:9216
	s_waitcnt vmcnt(11)
	ds_write_b128 v90, v[166:169] offset:13824
	ds_write_b128 v90, v[162:165] offset:36864
	s_waitcnt vmcnt(10)
	ds_write_b128 v90, v[170:173] offset:41472
	s_waitcnt vmcnt(9)
	ds_write_b128 v90, v[174:177] offset:46080
	s_waitcnt vmcnt(8)
	ds_write_b128 v90, v[178:181] offset:50688
	s_waitcnt lgkmcnt(0)
	s_barrier
	v_mfma_f32_32x32x16_bf16 v[34:49], v[134:137], v[138:141], v[34:49]
	v_mfma_f32_32x32x16_bf16 v[50:65], v[134:137], v[182:185], v[50:65]
	v_mfma_f32_32x32x16_bf16 v[2:17], v[142:145], v[146:149], v[2:17]
	v_mfma_f32_32x32x16_bf16 v[18:33], v[142:145], v[186:189], v[18:33]
	v_mfma_f32_32x32x16_bf16 v[34:49], v[190:193], v[146:149], v[34:49]
	v_mfma_f32_32x32x16_bf16 v[50:65], v[190:193], v[186:189], v[50:65]
	ds_read_b128 v[134:137], v66
	ds_read_b128 v[138:141], v67 offset:36864
	ds_read_b128 v[142:145], v66 offset:32
	ds_read_b128 v[146:149], v67 offset:36896
	ds_read_b128 v[150:153], v67 offset:41472
	ds_read_b128 v[154:157], v67 offset:41504
	s_waitcnt lgkmcnt(4)
	v_mfma_f32_32x32x16_bf16 v[2:17], v[134:137], v[138:141], v[2:17]
	s_waitcnt lgkmcnt(1)
	v_mfma_f32_32x32x16_bf16 v[18:33], v[134:137], v[150:153], v[18:33]
	ds_read_b128 v[134:137], v66 offset:4608
	ds_read_b128 v[158:161], v66 offset:4640
	s_waitcnt lgkmcnt(1)
	v_mfma_f32_32x32x16_bf16 v[34:49], v[134:137], v[138:141], v[34:49]
	v_mfma_f32_32x32x16_bf16 v[50:65], v[134:137], v[150:153], v[50:65]
	v_mfma_f32_32x32x16_bf16 v[2:17], v[142:145], v[146:149], v[2:17]
	v_mfma_f32_32x32x16_bf16 v[18:33], v[142:145], v[154:157], v[18:33]
	s_waitcnt lgkmcnt(0)
	v_mfma_f32_32x32x16_bf16 v[34:49], v[158:161], v[146:149], v[34:49]
	ds_read_b128 v[134:137], v66 offset:64
	ds_read_b128 v[138:141], v67 offset:36928
	ds_read_b128 v[142:145], v66 offset:96
	ds_read_b128 v[146:149], v67 offset:36960
	v_mfma_f32_32x32x16_bf16 v[50:65], v[158:161], v[154:157], v[50:65]
	ds_read_b128 v[150:153], v67 offset:41536
	ds_read_b128 v[154:157], v67 offset:41568
	s_waitcnt lgkmcnt(4)
	v_mfma_f32_32x32x16_bf16 v[2:17], v[134:137], v[138:141], v[2:17]
	s_waitcnt lgkmcnt(1)
	v_mfma_f32_32x32x16_bf16 v[18:33], v[134:137], v[150:153], v[18:33]
	ds_read_b128 v[134:137], v66 offset:4672
	ds_read_b128 v[158:161], v66 offset:4704
	s_waitcnt vmcnt(5)
	ds_write_b128 v90, v[122:125] offset:18432
	ds_write_b128 v90, v[118:121] offset:23040
	ds_write_b128 v90, v[78:81] offset:27648
	s_waitcnt vmcnt(3)
	ds_write_b128 v90, v[126:129] offset:32256
	ds_write_b128 v90, v[74:77] offset:55296
	s_waitcnt vmcnt(2)
	ds_write_b128 v90, v[82:85] offset:59904
	s_waitcnt vmcnt(1)
	ds_write_b128 v90, v[130:133] offset:64512
	s_waitcnt vmcnt(0)
	ds_write_b128 v91, v[86:89] offset:32256
	s_waitcnt lgkmcnt(0)
	s_barrier
	v_mfma_f32_32x32x16_bf16 v[34:49], v[134:137], v[138:141], v[34:49]
	v_mfma_f32_32x32x16_bf16 v[50:65], v[134:137], v[150:153], v[50:65]
	v_mfma_f32_32x32x16_bf16 v[2:17], v[142:145], v[146:149], v[2:17]
	v_mfma_f32_32x32x16_bf16 v[18:33], v[142:145], v[154:157], v[18:33]
	v_mfma_f32_32x32x16_bf16 v[34:49], v[158:161], v[146:149], v[34:49]
	v_mfma_f32_32x32x16_bf16 v[50:65], v[158:161], v[154:157], v[50:65]
	ds_read_b128 v[74:77], v66 offset:18432
	ds_read_b128 v[78:81], v67 offset:55296
	ds_read_b128 v[82:85], v66 offset:18464
	ds_read_b128 v[86:89], v67 offset:55328
	ds_read_b128 v[118:121], v67 offset:59904
	ds_read_b128 v[122:125], v67 offset:59936
	s_mov_b32 s12, 0
	s_waitcnt lgkmcnt(4)
	v_mfma_f32_32x32x16_bf16 v[2:17], v[74:77], v[78:81], v[2:17]
	s_waitcnt lgkmcnt(1)
	v_mfma_f32_32x32x16_bf16 v[18:33], v[74:77], v[118:121], v[18:33]
	ds_read_b128 v[74:77], v66 offset:23040
	ds_read_b128 v[126:129], v66 offset:23072
	s_waitcnt lgkmcnt(1)
	v_mfma_f32_32x32x16_bf16 v[34:49], v[74:77], v[78:81], v[34:49]
	v_mfma_f32_32x32x16_bf16 v[50:65], v[74:77], v[118:121], v[50:65]
	v_mfma_f32_32x32x16_bf16 v[2:17], v[82:85], v[86:89], v[2:17]
	v_mfma_f32_32x32x16_bf16 v[18:33], v[82:85], v[122:125], v[18:33]
	s_waitcnt lgkmcnt(0)
	v_mfma_f32_32x32x16_bf16 v[34:49], v[126:129], v[86:89], v[34:49]
	ds_read_b128 v[74:77], v66 offset:18496
	ds_read_b128 v[78:81], v67 offset:55360
	ds_read_b128 v[82:85], v66 offset:18528
	ds_read_b128 v[86:89], v67 offset:55392
	v_mfma_f32_32x32x16_bf16 v[50:65], v[126:129], v[122:125], v[50:65]
	ds_read_b128 v[118:121], v67 offset:59968
	ds_read_b128 v[122:125], v67 offset:60000
	s_waitcnt lgkmcnt(4)
	v_mfma_f32_32x32x16_bf16 v[2:17], v[74:77], v[78:81], v[2:17]
	s_waitcnt lgkmcnt(1)
	v_mfma_f32_32x32x16_bf16 v[18:33], v[74:77], v[118:121], v[18:33]
	ds_read_b128 v[74:77], v66 offset:23104
	ds_read_b128 v[126:129], v66 offset:23136
	s_waitcnt lgkmcnt(0)
	s_barrier
	v_mfma_f32_32x32x16_bf16 v[34:49], v[74:77], v[78:81], v[34:49]
	v_mfma_f32_32x32x16_bf16 v[50:65], v[74:77], v[118:121], v[50:65]
	v_mfma_f32_32x32x16_bf16 v[2:17], v[82:85], v[86:89], v[2:17]
	v_mfma_f32_32x32x16_bf16 v[18:33], v[82:85], v[122:125], v[18:33]
	v_mfma_f32_32x32x16_bf16 v[34:49], v[126:129], v[86:89], v[34:49]
	s_nop 10
	ds_write2_b32 v93, v2, v18 offset1:32
	v_mfma_f32_32x32x16_bf16 v[50:65], v[126:129], v[122:125], v[50:65]
	s_nop 11
	ds_write2_b32 v100, v34, v50 offset0:32 offset1:64
	ds_write2_b32 v93, v3, v19 offset0:129 offset1:161
	ds_write2_b32 v100, v35, v51 offset0:161 offset1:193
	ds_write2_b32 v101, v4, v20 offset0:2 offset1:34
	ds_write2_b32 v102, v36, v52 offset0:34 offset1:66
	ds_write2_b32 v101, v5, v21 offset0:131 offset1:163
	ds_write2_b32 v102, v37, v53 offset0:163 offset1:195
	ds_write2_b32 v103, v6, v22 offset0:8 offset1:40
	ds_write2_b32 v104, v38, v54 offset0:40 offset1:72
	ds_write2_b32 v103, v7, v23 offset0:137 offset1:169
	ds_write2_b32 v104, v39, v55 offset0:169 offset1:201
	ds_write2_b32 v105, v8, v24 offset0:10 offset1:42
	ds_write2_b32 v106, v40, v56 offset0:42 offset1:74
	ds_write2_b32 v105, v9, v25 offset0:139 offset1:171
	ds_write2_b32 v106, v41, v57 offset0:171 offset1:203
	ds_write2_b32 v107, v10, v26 offset0:16 offset1:48
	ds_write2_b32 v108, v42, v58 offset0:48 offset1:80
	ds_write2_b32 v107, v11, v27 offset0:145 offset1:177
	ds_write2_b32 v108, v43, v59 offset0:177 offset1:209
	ds_write2_b32 v109, v12, v28 offset0:18 offset1:50
	ds_write2_b32 v110, v44, v60 offset0:50 offset1:82
	ds_write2_b32 v109, v13, v29 offset0:147 offset1:179
	ds_write2_b32 v110, v45, v61 offset0:179 offset1:211
	ds_write2_b32 v111, v14, v30 offset0:24 offset1:56
	ds_write2_b32 v112, v46, v62 offset0:56 offset1:88
	ds_write2_b32 v111, v15, v31 offset0:153 offset1:185
	ds_write2_b32 v112, v47, v63 offset0:185 offset1:217
	ds_write2_b32 v113, v16, v32 offset0:26 offset1:58
	ds_write2_b32 v114, v48, v64 offset0:58 offset1:90
	ds_write2_b32 v113, v17, v33 offset0:155 offset1:187
	ds_write2_b32 v114, v49, v65 offset0:187 offset1:219
	v_or_b32_e32 v8, s23, v92
	v_lshlrev_b32_e32 v68, 2, v8
	s_waitcnt lgkmcnt(0)
	s_barrier
	v_mov_b32_e32 v2, v8
	v_mov_b32_e32 v3, v116
	v_lshlrev_b32_e32 v64, 12, v3
	v_lshl_add_u32 v64, v2, 2, v64
	v_lshlrev_b32_e32 v74, 2, v2
	global_load_dwordx4 v[128:131], v74, s[8:9]
	global_load_dwordx4 v[4:7], v64, s[80:81]
	v_add_u32_e32 v74, 0x8000, v64
	global_load_dwordx4 v[8:11], v74, s[80:81]
	v_add_u32_e32 v65, 0x10000, v64
	global_load_dwordx4 v[12:15], v65, s[80:81]
	v_add_u32_e32 v74, 0x18000, v64
	global_load_dwordx4 v[16:19], v74, s[80:81]
	v_add_u32_e32 v65, 0x20000, v64
	global_load_dwordx4 v[20:23], v65, s[80:81]
	v_add_u32_e32 v74, 0x28000, v64
	global_load_dwordx4 v[24:27], v74, s[80:81]
	v_add_u32_e32 v65, 0x30000, v64
	global_load_dwordx4 v[28:31], v65, s[80:81]
	v_add_u32_e32 v74, 0x38000, v64
	global_load_dwordx4 v[32:35], v74, s[80:81]
	v_add_u32_e32 v65, 0x40000, v64
	global_load_dwordx4 v[36:39], v65, s[80:81]
	v_add_u32_e32 v74, 0x48000, v64
	global_load_dwordx4 v[40:43], v74, s[80:81]
	v_add_u32_e32 v65, 0x50000, v64
	global_load_dwordx4 v[44:47], v65, s[80:81]
	v_add_u32_e32 v74, 0x58000, v64
	global_load_dwordx4 v[48:51], v74, s[80:81]
	v_add_u32_e32 v65, 0x60000, v64
	global_load_dwordx4 v[52:55], v65, s[80:81]
	v_add_u32_e32 v74, 0x68000, v64
	global_load_dwordx4 v[56:59], v74, s[80:81]
	v_add_u32_e32 v65, 0x70000, v64
	global_load_dwordx4 v[60:63], v65, s[80:81]
	v_add_u32_e32 v74, 0x78000, v64
	global_load_dwordx4 v[76:79], v74, s[80:81]
	v_and_b32_e32 v75, 7, v3
	v_mul_u32_u24_e32 v75, 0x204, v75
	v_and_b32_e32 v88, 0x7f, v2
	v_lshl_add_u32 v75, v88, 2, v75
	v_lshlrev_b32_e32 v162, 2, v3
	s_movk_i32 s12, 0x7fff
	v_mov_b32_e32 v163, 1
	ds_read2_b32 v[80:81], v75 offset1:1
	ds_read2_b32 v[82:83], v75 offset0:2 offset1:3
	v_add_u32_e32 v89, 0x1020, v75
	ds_read2_b32 v[84:85], v89 offset1:1
	ds_read2_b32 v[86:87], v89 offset0:2 offset1:3
	v_add_u32_e32 v88, 0x2040, v75
	ds_read2_b32 v[118:119], v88 offset1:1
	ds_read2_b32 v[120:121], v88 offset0:2 offset1:3
	v_add_u32_e32 v89, 0x3060, v75
	ds_read2_b32 v[122:123], v89 offset1:1
	ds_read2_b32 v[124:125], v89 offset0:2 offset1:3
	s_waitcnt vmcnt(15) lgkmcnt(6)
	v_pk_add_f32 v[4:5], v[4:5], v[80:81]
	v_pk_add_f32 v[6:7], v[6:7], v[82:83]
	s_waitcnt vmcnt(14) lgkmcnt(4)
	v_pk_add_f32 v[8:9], v[8:9], v[84:85]
	v_pk_add_f32 v[10:11], v[10:11], v[86:87]
	s_waitcnt vmcnt(13) lgkmcnt(2)
	v_pk_add_f32 v[12:13], v[12:13], v[118:119]
	v_pk_add_f32 v[14:15], v[14:15], v[120:121]
	s_waitcnt vmcnt(12) lgkmcnt(0)
	v_pk_add_f32 v[16:17], v[16:17], v[122:123]
	v_pk_add_f32 v[18:19], v[18:19], v[124:125]
	v_add_u32_e32 v88, 0x4080, v75
	ds_read2_b32 v[80:81], v88 offset1:1
	ds_read2_b32 v[82:83], v88 offset0:2 offset1:3
	v_add_u32_e32 v89, 0x50a0, v75
	ds_read2_b32 v[84:85], v89 offset1:1
	ds_read2_b32 v[86:87], v89 offset0:2 offset1:3
	v_add_u32_e32 v88, 0x60c0, v75
	ds_read2_b32 v[118:119], v88 offset1:1
	ds_read2_b32 v[120:121], v88 offset0:2 offset1:3
	v_add_u32_e32 v89, 0x70e0, v75
	ds_read2_b32 v[122:123], v89 offset1:1
	ds_read2_b32 v[124:125], v89 offset0:2 offset1:3
	global_store_dwordx4 v64, v[4:7], s[80:81]
	v_pk_mul_f32 v[146:147], v[4:5], v[4:5]
	v_pk_mul_f32 v[148:149], v[6:7], v[6:7]
	v_pk_mul_f32 v[150:151], v[4:5], v[128:129]
	v_pk_mul_f32 v[152:153], v[6:7], v[130:131]
	v_lshrrev_b32_e32 v164, 1, v64
	v_add_f32_e32 v126, v146, v147
	v_and_b32_sdwa v154, v150, v163 dst_sel:DWORD dst_unused:UNUSED_PAD src0_sel:WORD_1 src1_sel:DWORD
	v_and_b32_sdwa v155, v151, v163 dst_sel:DWORD dst_unused:UNUSED_PAD src0_sel:WORD_1 src1_sel:DWORD
	v_and_b32_sdwa v156, v152, v163 dst_sel:DWORD dst_unused:UNUSED_PAD src0_sel:WORD_1 src1_sel:DWORD
	v_and_b32_sdwa v157, v153, v163 dst_sel:DWORD dst_unused:UNUSED_PAD src0_sel:WORD_1 src1_sel:DWORD
	v_add_f32_e32 v126, v126, v148
	v_add3_u32 v150, v150, v154, s12
	v_add3_u32 v151, v151, v155, s12
	v_add3_u32 v152, v152, v156, s12
	v_add3_u32 v153, v153, v157, s12
	v_add_f32_e32 v126, v126, v149
	v_and_b32_e32 v151, 0xffff0000, v151
	v_and_b32_e32 v153, 0xffff0000, v153
	s_nop 0
	v_or_b32_sdwa v158, v151, v150 dst_sel:DWORD dst_unused:UNUSED_PAD src0_sel:DWORD src1_sel:WORD_1
	v_or_b32_sdwa v159, v153, v152 dst_sel:DWORD dst_unused:UNUSED_PAD src0_sel:DWORD src1_sel:WORD_1
	global_store_dwordx2 v164, v[158:159], s[92:93]
	v_add_u32_e32 v74, 0x8000, v64
	global_store_dwordx4 v74, v[8:11], s[80:81]
	v_pk_mul_f32 v[146:147], v[8:9], v[8:9]
	v_pk_mul_f32 v[148:149], v[10:11], v[10:11]
	v_pk_mul_f32 v[150:151], v[8:9], v[128:129]
	v_pk_mul_f32 v[152:153], v[10:11], v[130:131]
	v_lshrrev_b32_e32 v165, 1, v74
	v_add_f32_e32 v127, v146, v147
	v_and_b32_sdwa v154, v150, v163 dst_sel:DWORD dst_unused:UNUSED_PAD src0_sel:WORD_1 src1_sel:DWORD
	v_and_b32_sdwa v155, v151, v163 dst_sel:DWORD dst_unused:UNUSED_PAD src0_sel:WORD_1 src1_sel:DWORD
	v_and_b32_sdwa v156, v152, v163 dst_sel:DWORD dst_unused:UNUSED_PAD src0_sel:WORD_1 src1_sel:DWORD
	v_and_b32_sdwa v157, v153, v163 dst_sel:DWORD dst_unused:UNUSED_PAD src0_sel:WORD_1 src1_sel:DWORD
	v_add_f32_e32 v127, v127, v148
	v_add3_u32 v150, v150, v154, s12
	v_add3_u32 v151, v151, v155, s12
	v_add3_u32 v152, v152, v156, s12
	v_add3_u32 v153, v153, v157, s12
	v_add_f32_e32 v127, v127, v149
	v_and_b32_e32 v151, 0xffff0000, v151
	v_and_b32_e32 v153, 0xffff0000, v153
	s_nop 0
	v_or_b32_sdwa v160, v151, v150 dst_sel:DWORD dst_unused:UNUSED_PAD src0_sel:DWORD src1_sel:WORD_1
	v_or_b32_sdwa v161, v153, v152 dst_sel:DWORD dst_unused:UNUSED_PAD src0_sel:DWORD src1_sel:WORD_1
	global_store_dwordx2 v165, v[160:161], s[92:93]
	v_add_u32_e32 v65, 0x10000, v64
	global_store_dwordx4 v65, v[12:15], s[80:81]
	v_pk_mul_f32 v[146:147], v[12:13], v[12:13]
	v_pk_mul_f32 v[148:149], v[14:15], v[14:15]
	v_pk_mul_f32 v[150:151], v[12:13], v[128:129]
	v_pk_mul_f32 v[152:153], v[14:15], v[130:131]
	v_lshrrev_b32_e32 v164, 1, v65
	v_add_f32_e32 v132, v146, v147
	v_and_b32_sdwa v154, v150, v163 dst_sel:DWORD dst_unused:UNUSED_PAD src0_sel:WORD_1 src1_sel:DWORD
	v_and_b32_sdwa v155, v151, v163 dst_sel:DWORD dst_unused:UNUSED_PAD src0_sel:WORD_1 src1_sel:DWORD
	v_and_b32_sdwa v156, v152, v163 dst_sel:DWORD dst_unused:UNUSED_PAD src0_sel:WORD_1 src1_sel:DWORD
	v_and_b32_sdwa v157, v153, v163 dst_sel:DWORD dst_unused:UNUSED_PAD src0_sel:WORD_1 src1_sel:DWORD
	v_add_f32_e32 v132, v132, v148
	v_add3_u32 v150, v150, v154, s12
	v_add3_u32 v151, v151, v155, s12
	v_add3_u32 v152, v152, v156, s12
	v_add3_u32 v153, v153, v157, s12
	v_add_f32_e32 v132, v132, v149
	v_and_b32_e32 v151, 0xffff0000, v151
	v_and_b32_e32 v153, 0xffff0000, v153
	s_nop 0
	v_or_b32_sdwa v158, v151, v150 dst_sel:DWORD dst_unused:UNUSED_PAD src0_sel:DWORD src1_sel:WORD_1
	v_or_b32_sdwa v159, v153, v152 dst_sel:DWORD dst_unused:UNUSED_PAD src0_sel:DWORD src1_sel:WORD_1
	global_store_dwordx2 v164, v[158:159], s[92:93]
	v_add_u32_e32 v74, 0x18000, v64
	global_store_dwordx4 v74, v[16:19], s[80:81]
	v_pk_mul_f32 v[146:147], v[16:17], v[16:17]
	v_pk_mul_f32 v[148:149], v[18:19], v[18:19]
	v_pk_mul_f32 v[150:151], v[16:17], v[128:129]
	v_pk_mul_f32 v[152:153], v[18:19], v[130:131]
	v_lshrrev_b32_e32 v165, 1, v74
	v_add_f32_e32 v133, v146, v147
	v_and_b32_sdwa v154, v150, v163 dst_sel:DWORD dst_unused:UNUSED_PAD src0_sel:WORD_1 src1_sel:DWORD
	v_and_b32_sdwa v155, v151, v163 dst_sel:DWORD dst_unused:UNUSED_PAD src0_sel:WORD_1 src1_sel:DWORD
	v_and_b32_sdwa v156, v152, v163 dst_sel:DWORD dst_unused:UNUSED_PAD src0_sel:WORD_1 src1_sel:DWORD
	v_and_b32_sdwa v157, v153, v163 dst_sel:DWORD dst_unused:UNUSED_PAD src0_sel:WORD_1 src1_sel:DWORD
	v_add_f32_e32 v133, v133, v148
	v_add3_u32 v150, v150, v154, s12
	v_add3_u32 v151, v151, v155, s12
	v_add3_u32 v152, v152, v156, s12
	v_add3_u32 v153, v153, v157, s12
	v_add_f32_e32 v133, v133, v149
	v_and_b32_e32 v151, 0xffff0000, v151
	v_and_b32_e32 v153, 0xffff0000, v153
	s_nop 0
	v_or_b32_sdwa v160, v151, v150 dst_sel:DWORD dst_unused:UNUSED_PAD src0_sel:DWORD src1_sel:WORD_1
	v_or_b32_sdwa v161, v153, v152 dst_sel:DWORD dst_unused:UNUSED_PAD src0_sel:DWORD src1_sel:WORD_1
	global_store_dwordx2 v165, v[160:161], s[92:93]
	s_nop 1
	v_add_f32_dpp v126, v126, v126 quad_perm:[1,0,3,2] row_mask:0xf bank_mask:0xf
	v_add_f32_dpp v127, v127, v127 quad_perm:[1,0,3,2] row_mask:0xf bank_mask:0xf
	v_add_f32_dpp v132, v132, v132 quad_perm:[1,0,3,2] row_mask:0xf bank_mask:0xf
	v_add_f32_dpp v133, v133, v133 quad_perm:[1,0,3,2] row_mask:0xf bank_mask:0xf
	v_add_f32_dpp v126, v126, v126 quad_perm:[2,3,0,1] row_mask:0xf bank_mask:0xf
	v_add_f32_dpp v127, v127, v127 quad_perm:[2,3,0,1] row_mask:0xf bank_mask:0xf
	v_add_f32_dpp v132, v132, v132 quad_perm:[2,3,0,1] row_mask:0xf bank_mask:0xf
	v_add_f32_dpp v133, v133, v133 quad_perm:[2,3,0,1] row_mask:0xf bank_mask:0xf
	v_add_f32_dpp v126, v126, v126 row_half_mirror row_mask:0xf bank_mask:0xf
	v_add_f32_dpp v127, v127, v127 row_half_mirror row_mask:0xf bank_mask:0xf
	v_add_f32_dpp v132, v132, v132 row_half_mirror row_mask:0xf bank_mask:0xf
	v_add_f32_dpp v133, v133, v133 row_half_mirror row_mask:0xf bank_mask:0xf
	v_add_f32_dpp v126, v126, v126 row_mirror row_mask:0xf bank_mask:0xf
	v_add_f32_dpp v127, v127, v127 row_mirror row_mask:0xf bank_mask:0xf
	v_add_f32_dpp v132, v132, v132 row_mirror row_mask:0xf bank_mask:0xf
	v_add_f32_dpp v133, v133, v133 row_mirror row_mask:0xf bank_mask:0xf
	v_add_f32_dpp v126, v126, v126 row_bcast:15 row_mask:0xa bank_mask:0xf
	v_add_f32_dpp v127, v127, v127 row_bcast:15 row_mask:0xa bank_mask:0xf
	v_add_f32_dpp v132, v132, v132 row_bcast:15 row_mask:0xa bank_mask:0xf
	v_add_f32_dpp v133, v133, v133 row_bcast:15 row_mask:0xa bank_mask:0xf
	s_waitcnt vmcnt(19) lgkmcnt(6)
	v_pk_add_f32 v[20:21], v[20:21], v[80:81]
	v_pk_add_f32 v[22:23], v[22:23], v[82:83]
	s_waitcnt vmcnt(18) lgkmcnt(4)
	v_pk_add_f32 v[24:25], v[24:25], v[84:85]
	v_pk_add_f32 v[26:27], v[26:27], v[86:87]
	s_waitcnt vmcnt(17) lgkmcnt(2)
	v_pk_add_f32 v[28:29], v[28:29], v[118:119]
	v_pk_add_f32 v[30:31], v[30:31], v[120:121]
	s_waitcnt vmcnt(16) lgkmcnt(0)
	v_pk_add_f32 v[32:33], v[32:33], v[122:123]
	v_pk_add_f32 v[34:35], v[34:35], v[124:125]
	v_add_u32_e32 v88, 0x8100, v75
	ds_read2_b32 v[80:81], v88 offset1:1
	ds_read2_b32 v[82:83], v88 offset0:2 offset1:3
	v_add_u32_e32 v89, 0x9120, v75
	ds_read2_b32 v[84:85], v89 offset1:1
	ds_read2_b32 v[86:87], v89 offset0:2 offset1:3
	v_add_u32_e32 v88, 0xa140, v75
	ds_read2_b32 v[118:119], v88 offset1:1
	ds_read2_b32 v[120:121], v88 offset0:2 offset1:3
	v_add_u32_e32 v89, 0xb160, v75
	ds_read2_b32 v[122:123], v89 offset1:1
	ds_read2_b32 v[124:125], v89 offset0:2 offset1:3
	v_add_u32_e32 v65, 0x20000, v64
	global_store_dwordx4 v65, v[20:23], s[80:81]
	v_pk_mul_f32 v[146:147], v[20:21], v[20:21]
	v_pk_mul_f32 v[148:149], v[22:23], v[22:23]
	v_pk_mul_f32 v[150:151], v[20:21], v[128:129]
	v_pk_mul_f32 v[152:153], v[22:23], v[130:131]
	v_lshrrev_b32_e32 v164, 1, v65
	v_add_f32_e32 v134, v146, v147
	v_and_b32_sdwa v154, v150, v163 dst_sel:DWORD dst_unused:UNUSED_PAD src0_sel:WORD_1 src1_sel:DWORD
	v_and_b32_sdwa v155, v151, v163 dst_sel:DWORD dst_unused:UNUSED_PAD src0_sel:WORD_1 src1_sel:DWORD
	v_and_b32_sdwa v156, v152, v163 dst_sel:DWORD dst_unused:UNUSED_PAD src0_sel:WORD_1 src1_sel:DWORD
	v_and_b32_sdwa v157, v153, v163 dst_sel:DWORD dst_unused:UNUSED_PAD src0_sel:WORD_1 src1_sel:DWORD
	v_add_f32_e32 v134, v134, v148
	v_add3_u32 v150, v150, v154, s12
	v_add3_u32 v151, v151, v155, s12
	v_add3_u32 v152, v152, v156, s12
	v_add3_u32 v153, v153, v157, s12
	v_add_f32_e32 v134, v134, v149
	v_and_b32_e32 v151, 0xffff0000, v151
	v_and_b32_e32 v153, 0xffff0000, v153
	s_nop 0
	v_or_b32_sdwa v158, v151, v150 dst_sel:DWORD dst_unused:UNUSED_PAD src0_sel:DWORD src1_sel:WORD_1
	v_or_b32_sdwa v159, v153, v152 dst_sel:DWORD dst_unused:UNUSED_PAD src0_sel:DWORD src1_sel:WORD_1
	global_store_dwordx2 v164, v[158:159], s[92:93]
	v_add_u32_e32 v74, 0x28000, v64
	global_store_dwordx4 v74, v[24:27], s[80:81]
	v_pk_mul_f32 v[146:147], v[24:25], v[24:25]
	v_pk_mul_f32 v[148:149], v[26:27], v[26:27]
	v_pk_mul_f32 v[150:151], v[24:25], v[128:129]
	v_pk_mul_f32 v[152:153], v[26:27], v[130:131]
	v_lshrrev_b32_e32 v165, 1, v74
	v_add_f32_e32 v135, v146, v147
	v_and_b32_sdwa v154, v150, v163 dst_sel:DWORD dst_unused:UNUSED_PAD src0_sel:WORD_1 src1_sel:DWORD
	v_and_b32_sdwa v155, v151, v163 dst_sel:DWORD dst_unused:UNUSED_PAD src0_sel:WORD_1 src1_sel:DWORD
	v_and_b32_sdwa v156, v152, v163 dst_sel:DWORD dst_unused:UNUSED_PAD src0_sel:WORD_1 src1_sel:DWORD
	v_and_b32_sdwa v157, v153, v163 dst_sel:DWORD dst_unused:UNUSED_PAD src0_sel:WORD_1 src1_sel:DWORD
	v_add_f32_e32 v135, v135, v148
	v_add3_u32 v150, v150, v154, s12
	v_add3_u32 v151, v151, v155, s12
	v_add3_u32 v152, v152, v156, s12
	v_add3_u32 v153, v153, v157, s12
	v_add_f32_e32 v135, v135, v149
	v_and_b32_e32 v151, 0xffff0000, v151
	v_and_b32_e32 v153, 0xffff0000, v153
	s_nop 0
	v_or_b32_sdwa v160, v151, v150 dst_sel:DWORD dst_unused:UNUSED_PAD src0_sel:DWORD src1_sel:WORD_1
	v_or_b32_sdwa v161, v153, v152 dst_sel:DWORD dst_unused:UNUSED_PAD src0_sel:DWORD src1_sel:WORD_1
	global_store_dwordx2 v165, v[160:161], s[92:93]
	v_add_u32_e32 v65, 0x30000, v64
	global_store_dwordx4 v65, v[28:31], s[80:81]
	v_pk_mul_f32 v[146:147], v[28:29], v[28:29]
	v_pk_mul_f32 v[148:149], v[30:31], v[30:31]
	v_pk_mul_f32 v[150:151], v[28:29], v[128:129]
	v_pk_mul_f32 v[152:153], v[30:31], v[130:131]
	v_lshrrev_b32_e32 v164, 1, v65
	v_add_f32_e32 v136, v146, v147
	v_and_b32_sdwa v154, v150, v163 dst_sel:DWORD dst_unused:UNUSED_PAD src0_sel:WORD_1 src1_sel:DWORD
	v_and_b32_sdwa v155, v151, v163 dst_sel:DWORD dst_unused:UNUSED_PAD src0_sel:WORD_1 src1_sel:DWORD
	v_and_b32_sdwa v156, v152, v163 dst_sel:DWORD dst_unused:UNUSED_PAD src0_sel:WORD_1 src1_sel:DWORD
	v_and_b32_sdwa v157, v153, v163 dst_sel:DWORD dst_unused:UNUSED_PAD src0_sel:WORD_1 src1_sel:DWORD
	v_add_f32_e32 v136, v136, v148
	v_add3_u32 v150, v150, v154, s12
	v_add3_u32 v151, v151, v155, s12
	v_add3_u32 v152, v152, v156, s12
	v_add3_u32 v153, v153, v157, s12
	v_add_f32_e32 v136, v136, v149
	v_and_b32_e32 v151, 0xffff0000, v151
	v_and_b32_e32 v153, 0xffff0000, v153
	s_nop 0
	v_or_b32_sdwa v158, v151, v150 dst_sel:DWORD dst_unused:UNUSED_PAD src0_sel:DWORD src1_sel:WORD_1
	v_or_b32_sdwa v159, v153, v152 dst_sel:DWORD dst_unused:UNUSED_PAD src0_sel:DWORD src1_sel:WORD_1
	global_store_dwordx2 v164, v[158:159], s[92:93]
	v_add_u32_e32 v74, 0x38000, v64
	global_store_dwordx4 v74, v[32:35], s[80:81]
	v_pk_mul_f32 v[146:147], v[32:33], v[32:33]
	v_pk_mul_f32 v[148:149], v[34:35], v[34:35]
	v_pk_mul_f32 v[150:151], v[32:33], v[128:129]
	v_pk_mul_f32 v[152:153], v[34:35], v[130:131]
	v_lshrrev_b32_e32 v165, 1, v74
	v_add_f32_e32 v137, v146, v147
	v_and_b32_sdwa v154, v150, v163 dst_sel:DWORD dst_unused:UNUSED_PAD src0_sel:WORD_1 src1_sel:DWORD
	v_and_b32_sdwa v155, v151, v163 dst_sel:DWORD dst_unused:UNUSED_PAD src0_sel:WORD_1 src1_sel:DWORD
	v_and_b32_sdwa v156, v152, v163 dst_sel:DWORD dst_unused:UNUSED_PAD src0_sel:WORD_1 src1_sel:DWORD
	v_and_b32_sdwa v157, v153, v163 dst_sel:DWORD dst_unused:UNUSED_PAD src0_sel:WORD_1 src1_sel:DWORD
	v_add_f32_e32 v137, v137, v148
	v_add3_u32 v150, v150, v154, s12
	v_add3_u32 v151, v151, v155, s12
	v_add3_u32 v152, v152, v156, s12
	v_add3_u32 v153, v153, v157, s12
	v_add_f32_e32 v137, v137, v149
	v_and_b32_e32 v151, 0xffff0000, v151
	v_and_b32_e32 v153, 0xffff0000, v153
	s_nop 0
	v_or_b32_sdwa v160, v151, v150 dst_sel:DWORD dst_unused:UNUSED_PAD src0_sel:DWORD src1_sel:WORD_1
	v_or_b32_sdwa v161, v153, v152 dst_sel:DWORD dst_unused:UNUSED_PAD src0_sel:DWORD src1_sel:WORD_1
	global_store_dwordx2 v165, v[160:161], s[92:93]
	s_nop 1
	v_add_f32_dpp v134, v134, v134 quad_perm:[1,0,3,2] row_mask:0xf bank_mask:0xf
	v_add_f32_dpp v135, v135, v135 quad_perm:[1,0,3,2] row_mask:0xf bank_mask:0xf
	v_add_f32_dpp v136, v136, v136 quad_perm:[1,0,3,2] row_mask:0xf bank_mask:0xf
	v_add_f32_dpp v137, v137, v137 quad_perm:[1,0,3,2] row_mask:0xf bank_mask:0xf
	v_add_f32_dpp v134, v134, v134 quad_perm:[2,3,0,1] row_mask:0xf bank_mask:0xf
	v_add_f32_dpp v135, v135, v135 quad_perm:[2,3,0,1] row_mask:0xf bank_mask:0xf
	v_add_f32_dpp v136, v136, v136 quad_perm:[2,3,0,1] row_mask:0xf bank_mask:0xf
	v_add_f32_dpp v137, v137, v137 quad_perm:[2,3,0,1] row_mask:0xf bank_mask:0xf
	v_add_f32_dpp v134, v134, v134 row_half_mirror row_mask:0xf bank_mask:0xf
	v_add_f32_dpp v135, v135, v135 row_half_mirror row_mask:0xf bank_mask:0xf
	v_add_f32_dpp v136, v136, v136 row_half_mirror row_mask:0xf bank_mask:0xf
	v_add_f32_dpp v137, v137, v137 row_half_mirror row_mask:0xf bank_mask:0xf
	v_add_f32_dpp v134, v134, v134 row_mirror row_mask:0xf bank_mask:0xf
	v_add_f32_dpp v135, v135, v135 row_mirror row_mask:0xf bank_mask:0xf
	v_add_f32_dpp v136, v136, v136 row_mirror row_mask:0xf bank_mask:0xf
	v_add_f32_dpp v137, v137, v137 row_mirror row_mask:0xf bank_mask:0xf
	v_add_f32_dpp v134, v134, v134 row_bcast:15 row_mask:0xa bank_mask:0xf
	v_add_f32_dpp v135, v135, v135 row_bcast:15 row_mask:0xa bank_mask:0xf
	v_add_f32_dpp v136, v136, v136 row_bcast:15 row_mask:0xa bank_mask:0xf
	v_add_f32_dpp v137, v137, v137 row_bcast:15 row_mask:0xa bank_mask:0xf
	s_waitcnt vmcnt(23) lgkmcnt(6)
	v_pk_add_f32 v[36:37], v[36:37], v[80:81]
	v_pk_add_f32 v[38:39], v[38:39], v[82:83]
	s_waitcnt vmcnt(22) lgkmcnt(4)
	v_pk_add_f32 v[40:41], v[40:41], v[84:85]
	v_pk_add_f32 v[42:43], v[42:43], v[86:87]
	s_waitcnt vmcnt(21) lgkmcnt(2)
	v_pk_add_f32 v[44:45], v[44:45], v[118:119]
	v_pk_add_f32 v[46:47], v[46:47], v[120:121]
	s_waitcnt vmcnt(20) lgkmcnt(0)
	v_pk_add_f32 v[48:49], v[48:49], v[122:123]
	v_pk_add_f32 v[50:51], v[50:51], v[124:125]
	v_add_u32_e32 v88, 0xc180, v75
	ds_read2_b32 v[80:81], v88 offset1:1
	ds_read2_b32 v[82:83], v88 offset0:2 offset1:3
	v_add_u32_e32 v89, 0xd1a0, v75
	ds_read2_b32 v[84:85], v89 offset1:1
	ds_read2_b32 v[86:87], v89 offset0:2 offset1:3
	v_add_u32_e32 v88, 0xe1c0, v75
	ds_read2_b32 v[118:119], v88 offset1:1
	ds_read2_b32 v[120:121], v88 offset0:2 offset1:3
	v_add_u32_e32 v89, 0xf1e0, v75
	ds_read2_b32 v[122:123], v89 offset1:1
	ds_read2_b32 v[124:125], v89 offset0:2 offset1:3
	v_add_u32_e32 v65, 0x40000, v64
	global_store_dwordx4 v65, v[36:39], s[80:81]
	v_pk_mul_f32 v[146:147], v[36:37], v[36:37]
	v_pk_mul_f32 v[148:149], v[38:39], v[38:39]
	v_pk_mul_f32 v[150:151], v[36:37], v[128:129]
	v_pk_mul_f32 v[152:153], v[38:39], v[130:131]
	v_lshrrev_b32_e32 v164, 1, v65
	v_add_f32_e32 v138, v146, v147
	v_and_b32_sdwa v154, v150, v163 dst_sel:DWORD dst_unused:UNUSED_PAD src0_sel:WORD_1 src1_sel:DWORD
	v_and_b32_sdwa v155, v151, v163 dst_sel:DWORD dst_unused:UNUSED_PAD src0_sel:WORD_1 src1_sel:DWORD
	v_and_b32_sdwa v156, v152, v163 dst_sel:DWORD dst_unused:UNUSED_PAD src0_sel:WORD_1 src1_sel:DWORD
	v_and_b32_sdwa v157, v153, v163 dst_sel:DWORD dst_unused:UNUSED_PAD src0_sel:WORD_1 src1_sel:DWORD
	v_add_f32_e32 v138, v138, v148
	v_add3_u32 v150, v150, v154, s12
	v_add3_u32 v151, v151, v155, s12
	v_add3_u32 v152, v152, v156, s12
	v_add3_u32 v153, v153, v157, s12
	v_add_f32_e32 v138, v138, v149
	v_and_b32_e32 v151, 0xffff0000, v151
	v_and_b32_e32 v153, 0xffff0000, v153
	s_nop 0
	v_or_b32_sdwa v158, v151, v150 dst_sel:DWORD dst_unused:UNUSED_PAD src0_sel:DWORD src1_sel:WORD_1
	v_or_b32_sdwa v159, v153, v152 dst_sel:DWORD dst_unused:UNUSED_PAD src0_sel:DWORD src1_sel:WORD_1
	global_store_dwordx2 v164, v[158:159], s[92:93]
	v_add_u32_e32 v74, 0x48000, v64
	global_store_dwordx4 v74, v[40:43], s[80:81]
	v_pk_mul_f32 v[146:147], v[40:41], v[40:41]
	v_pk_mul_f32 v[148:149], v[42:43], v[42:43]
	v_pk_mul_f32 v[150:151], v[40:41], v[128:129]
	v_pk_mul_f32 v[152:153], v[42:43], v[130:131]
	v_lshrrev_b32_e32 v165, 1, v74
	v_add_f32_e32 v139, v146, v147
	v_and_b32_sdwa v154, v150, v163 dst_sel:DWORD dst_unused:UNUSED_PAD src0_sel:WORD_1 src1_sel:DWORD
	v_and_b32_sdwa v155, v151, v163 dst_sel:DWORD dst_unused:UNUSED_PAD src0_sel:WORD_1 src1_sel:DWORD
	v_and_b32_sdwa v156, v152, v163 dst_sel:DWORD dst_unused:UNUSED_PAD src0_sel:WORD_1 src1_sel:DWORD
	v_and_b32_sdwa v157, v153, v163 dst_sel:DWORD dst_unused:UNUSED_PAD src0_sel:WORD_1 src1_sel:DWORD
	v_add_f32_e32 v139, v139, v148
	v_add3_u32 v150, v150, v154, s12
	v_add3_u32 v151, v151, v155, s12
	v_add3_u32 v152, v152, v156, s12
	v_add3_u32 v153, v153, v157, s12
	v_add_f32_e32 v139, v139, v149
	v_and_b32_e32 v151, 0xffff0000, v151
	v_and_b32_e32 v153, 0xffff0000, v153
	s_nop 0
	v_or_b32_sdwa v160, v151, v150 dst_sel:DWORD dst_unused:UNUSED_PAD src0_sel:DWORD src1_sel:WORD_1
	v_or_b32_sdwa v161, v153, v152 dst_sel:DWORD dst_unused:UNUSED_PAD src0_sel:DWORD src1_sel:WORD_1
	global_store_dwordx2 v165, v[160:161], s[92:93]
	v_add_u32_e32 v65, 0x50000, v64
	global_store_dwordx4 v65, v[44:47], s[80:81]
	v_pk_mul_f32 v[146:147], v[44:45], v[44:45]
	v_pk_mul_f32 v[148:149], v[46:47], v[46:47]
	v_pk_mul_f32 v[150:151], v[44:45], v[128:129]
	v_pk_mul_f32 v[152:153], v[46:47], v[130:131]
	v_lshrrev_b32_e32 v164, 1, v65
	v_add_f32_e32 v140, v146, v147
	v_and_b32_sdwa v154, v150, v163 dst_sel:DWORD dst_unused:UNUSED_PAD src0_sel:WORD_1 src1_sel:DWORD
	v_and_b32_sdwa v155, v151, v163 dst_sel:DWORD dst_unused:UNUSED_PAD src0_sel:WORD_1 src1_sel:DWORD
	v_and_b32_sdwa v156, v152, v163 dst_sel:DWORD dst_unused:UNUSED_PAD src0_sel:WORD_1 src1_sel:DWORD
	v_and_b32_sdwa v157, v153, v163 dst_sel:DWORD dst_unused:UNUSED_PAD src0_sel:WORD_1 src1_sel:DWORD
	v_add_f32_e32 v140, v140, v148
	v_add3_u32 v150, v150, v154, s12
	v_add3_u32 v151, v151, v155, s12
	v_add3_u32 v152, v152, v156, s12
	v_add3_u32 v153, v153, v157, s12
	v_add_f32_e32 v140, v140, v149
	v_and_b32_e32 v151, 0xffff0000, v151
	v_and_b32_e32 v153, 0xffff0000, v153
	s_nop 0
	v_or_b32_sdwa v158, v151, v150 dst_sel:DWORD dst_unused:UNUSED_PAD src0_sel:DWORD src1_sel:WORD_1
	v_or_b32_sdwa v159, v153, v152 dst_sel:DWORD dst_unused:UNUSED_PAD src0_sel:DWORD src1_sel:WORD_1
	global_store_dwordx2 v164, v[158:159], s[92:93]
	v_add_u32_e32 v74, 0x58000, v64
	global_store_dwordx4 v74, v[48:51], s[80:81]
	v_pk_mul_f32 v[146:147], v[48:49], v[48:49]
	v_pk_mul_f32 v[148:149], v[50:51], v[50:51]
	v_pk_mul_f32 v[150:151], v[48:49], v[128:129]
	v_pk_mul_f32 v[152:153], v[50:51], v[130:131]
	v_lshrrev_b32_e32 v165, 1, v74
	v_add_f32_e32 v141, v146, v147
	v_and_b32_sdwa v154, v150, v163 dst_sel:DWORD dst_unused:UNUSED_PAD src0_sel:WORD_1 src1_sel:DWORD
	v_and_b32_sdwa v155, v151, v163 dst_sel:DWORD dst_unused:UNUSED_PAD src0_sel:WORD_1 src1_sel:DWORD
	v_and_b32_sdwa v156, v152, v163 dst_sel:DWORD dst_unused:UNUSED_PAD src0_sel:WORD_1 src1_sel:DWORD
	v_and_b32_sdwa v157, v153, v163 dst_sel:DWORD dst_unused:UNUSED_PAD src0_sel:WORD_1 src1_sel:DWORD
	v_add_f32_e32 v141, v141, v148
	v_add3_u32 v150, v150, v154, s12
	v_add3_u32 v151, v151, v155, s12
	v_add3_u32 v152, v152, v156, s12
	v_add3_u32 v153, v153, v157, s12
	v_add_f32_e32 v141, v141, v149
	v_and_b32_e32 v151, 0xffff0000, v151
	v_and_b32_e32 v153, 0xffff0000, v153
	s_nop 0
	v_or_b32_sdwa v160, v151, v150 dst_sel:DWORD dst_unused:UNUSED_PAD src0_sel:DWORD src1_sel:WORD_1
	v_or_b32_sdwa v161, v153, v152 dst_sel:DWORD dst_unused:UNUSED_PAD src0_sel:DWORD src1_sel:WORD_1
	global_store_dwordx2 v165, v[160:161], s[92:93]
	s_nop 1
	v_add_f32_dpp v138, v138, v138 quad_perm:[1,0,3,2] row_mask:0xf bank_mask:0xf
	v_add_f32_dpp v139, v139, v139 quad_perm:[1,0,3,2] row_mask:0xf bank_mask:0xf
	v_add_f32_dpp v140, v140, v140 quad_perm:[1,0,3,2] row_mask:0xf bank_mask:0xf
	v_add_f32_dpp v141, v141, v141 quad_perm:[1,0,3,2] row_mask:0xf bank_mask:0xf
	v_add_f32_dpp v138, v138, v138 quad_perm:[2,3,0,1] row_mask:0xf bank_mask:0xf
	v_add_f32_dpp v139, v139, v139 quad_perm:[2,3,0,1] row_mask:0xf bank_mask:0xf
	v_add_f32_dpp v140, v140, v140 quad_perm:[2,3,0,1] row_mask:0xf bank_mask:0xf
	v_add_f32_dpp v141, v141, v141 quad_perm:[2,3,0,1] row_mask:0xf bank_mask:0xf
	v_add_f32_dpp v138, v138, v138 row_half_mirror row_mask:0xf bank_mask:0xf
	v_add_f32_dpp v139, v139, v139 row_half_mirror row_mask:0xf bank_mask:0xf
	v_add_f32_dpp v140, v140, v140 row_half_mirror row_mask:0xf bank_mask:0xf
	v_add_f32_dpp v141, v141, v141 row_half_mirror row_mask:0xf bank_mask:0xf
	v_add_f32_dpp v138, v138, v138 row_mirror row_mask:0xf bank_mask:0xf
	v_add_f32_dpp v139, v139, v139 row_mirror row_mask:0xf bank_mask:0xf
	v_add_f32_dpp v140, v140, v140 row_mirror row_mask:0xf bank_mask:0xf
	v_add_f32_dpp v141, v141, v141 row_mirror row_mask:0xf bank_mask:0xf
	v_add_f32_dpp v138, v138, v138 row_bcast:15 row_mask:0xa bank_mask:0xf
	v_add_f32_dpp v139, v139, v139 row_bcast:15 row_mask:0xa bank_mask:0xf
	v_add_f32_dpp v140, v140, v140 row_bcast:15 row_mask:0xa bank_mask:0xf
	v_add_f32_dpp v141, v141, v141 row_bcast:15 row_mask:0xa bank_mask:0xf
	s_waitcnt vmcnt(27) lgkmcnt(6)
	v_pk_add_f32 v[52:53], v[52:53], v[80:81]
	v_pk_add_f32 v[54:55], v[54:55], v[82:83]
	s_waitcnt vmcnt(26) lgkmcnt(4)
	v_pk_add_f32 v[56:57], v[56:57], v[84:85]
	v_pk_add_f32 v[58:59], v[58:59], v[86:87]
	s_waitcnt vmcnt(25) lgkmcnt(2)
	v_pk_add_f32 v[60:61], v[60:61], v[118:119]
	v_pk_add_f32 v[62:63], v[62:63], v[120:121]
	s_waitcnt vmcnt(24) lgkmcnt(0)
	v_pk_add_f32 v[76:77], v[76:77], v[122:123]
	v_pk_add_f32 v[78:79], v[78:79], v[124:125]
	v_add_u32_e32 v65, 0x60000, v64
	global_store_dwordx4 v65, v[52:55], s[80:81]
	v_pk_mul_f32 v[146:147], v[52:53], v[52:53]
	v_pk_mul_f32 v[148:149], v[54:55], v[54:55]
	v_pk_mul_f32 v[150:151], v[52:53], v[128:129]
	v_pk_mul_f32 v[152:153], v[54:55], v[130:131]
	v_lshrrev_b32_e32 v164, 1, v65
	v_add_f32_e32 v142, v146, v147
	v_and_b32_sdwa v154, v150, v163 dst_sel:DWORD dst_unused:UNUSED_PAD src0_sel:WORD_1 src1_sel:DWORD
	v_and_b32_sdwa v155, v151, v163 dst_sel:DWORD dst_unused:UNUSED_PAD src0_sel:WORD_1 src1_sel:DWORD
	v_and_b32_sdwa v156, v152, v163 dst_sel:DWORD dst_unused:UNUSED_PAD src0_sel:WORD_1 src1_sel:DWORD
	v_and_b32_sdwa v157, v153, v163 dst_sel:DWORD dst_unused:UNUSED_PAD src0_sel:WORD_1 src1_sel:DWORD
	v_add_f32_e32 v142, v142, v148
	v_add3_u32 v150, v150, v154, s12
	v_add3_u32 v151, v151, v155, s12
	v_add3_u32 v152, v152, v156, s12
	v_add3_u32 v153, v153, v157, s12
	v_add_f32_e32 v142, v142, v149
	v_and_b32_e32 v151, 0xffff0000, v151
	v_and_b32_e32 v153, 0xffff0000, v153
	s_nop 0
	v_or_b32_sdwa v158, v151, v150 dst_sel:DWORD dst_unused:UNUSED_PAD src0_sel:DWORD src1_sel:WORD_1
	v_or_b32_sdwa v159, v153, v152 dst_sel:DWORD dst_unused:UNUSED_PAD src0_sel:DWORD src1_sel:WORD_1
	global_store_dwordx2 v164, v[158:159], s[92:93]
	v_add_u32_e32 v74, 0x68000, v64
	global_store_dwordx4 v74, v[56:59], s[80:81]
	v_pk_mul_f32 v[146:147], v[56:57], v[56:57]
	v_pk_mul_f32 v[148:149], v[58:59], v[58:59]
	v_pk_mul_f32 v[150:151], v[56:57], v[128:129]
	v_pk_mul_f32 v[152:153], v[58:59], v[130:131]
	v_lshrrev_b32_e32 v165, 1, v74
	v_add_f32_e32 v143, v146, v147
	v_and_b32_sdwa v154, v150, v163 dst_sel:DWORD dst_unused:UNUSED_PAD src0_sel:WORD_1 src1_sel:DWORD
	v_and_b32_sdwa v155, v151, v163 dst_sel:DWORD dst_unused:UNUSED_PAD src0_sel:WORD_1 src1_sel:DWORD
	v_and_b32_sdwa v156, v152, v163 dst_sel:DWORD dst_unused:UNUSED_PAD src0_sel:WORD_1 src1_sel:DWORD
	v_and_b32_sdwa v157, v153, v163 dst_sel:DWORD dst_unused:UNUSED_PAD src0_sel:WORD_1 src1_sel:DWORD
	v_add_f32_e32 v143, v143, v148
	v_add3_u32 v150, v150, v154, s12
	v_add3_u32 v151, v151, v155, s12
	v_add3_u32 v152, v152, v156, s12
	v_add3_u32 v153, v153, v157, s12
	v_add_f32_e32 v143, v143, v149
	v_and_b32_e32 v151, 0xffff0000, v151
	v_and_b32_e32 v153, 0xffff0000, v153
	s_nop 0
	v_or_b32_sdwa v160, v151, v150 dst_sel:DWORD dst_unused:UNUSED_PAD src0_sel:DWORD src1_sel:WORD_1
	v_or_b32_sdwa v161, v153, v152 dst_sel:DWORD dst_unused:UNUSED_PAD src0_sel:DWORD src1_sel:WORD_1
	global_store_dwordx2 v165, v[160:161], s[92:93]
	v_add_u32_e32 v65, 0x70000, v64
	global_store_dwordx4 v65, v[60:63], s[80:81]
	v_pk_mul_f32 v[146:147], v[60:61], v[60:61]
	v_pk_mul_f32 v[148:149], v[62:63], v[62:63]
	v_pk_mul_f32 v[150:151], v[60:61], v[128:129]
	v_pk_mul_f32 v[152:153], v[62:63], v[130:131]
	v_lshrrev_b32_e32 v164, 1, v65
	v_add_f32_e32 v144, v146, v147
	v_and_b32_sdwa v154, v150, v163 dst_sel:DWORD dst_unused:UNUSED_PAD src0_sel:WORD_1 src1_sel:DWORD
	v_and_b32_sdwa v155, v151, v163 dst_sel:DWORD dst_unused:UNUSED_PAD src0_sel:WORD_1 src1_sel:DWORD
	v_and_b32_sdwa v156, v152, v163 dst_sel:DWORD dst_unused:UNUSED_PAD src0_sel:WORD_1 src1_sel:DWORD
	v_and_b32_sdwa v157, v153, v163 dst_sel:DWORD dst_unused:UNUSED_PAD src0_sel:WORD_1 src1_sel:DWORD
	v_add_f32_e32 v144, v144, v148
	v_add3_u32 v150, v150, v154, s12
	v_add3_u32 v151, v151, v155, s12
	v_add3_u32 v152, v152, v156, s12
	v_add3_u32 v153, v153, v157, s12
	v_add_f32_e32 v144, v144, v149
	v_and_b32_e32 v151, 0xffff0000, v151
	v_and_b32_e32 v153, 0xffff0000, v153
	s_nop 0
	v_or_b32_sdwa v158, v151, v150 dst_sel:DWORD dst_unused:UNUSED_PAD src0_sel:DWORD src1_sel:WORD_1
	v_or_b32_sdwa v159, v153, v152 dst_sel:DWORD dst_unused:UNUSED_PAD src0_sel:DWORD src1_sel:WORD_1
	global_store_dwordx2 v164, v[158:159], s[92:93]
	v_add_u32_e32 v74, 0x78000, v64
	global_store_dwordx4 v74, v[76:79], s[80:81]
	v_pk_mul_f32 v[146:147], v[76:77], v[76:77]
	v_pk_mul_f32 v[148:149], v[78:79], v[78:79]
	v_pk_mul_f32 v[150:151], v[76:77], v[128:129]
	v_pk_mul_f32 v[152:153], v[78:79], v[130:131]
	v_lshrrev_b32_e32 v165, 1, v74
	v_add_f32_e32 v145, v146, v147
	v_and_b32_sdwa v154, v150, v163 dst_sel:DWORD dst_unused:UNUSED_PAD src0_sel:WORD_1 src1_sel:DWORD
	v_and_b32_sdwa v155, v151, v163 dst_sel:DWORD dst_unused:UNUSED_PAD src0_sel:WORD_1 src1_sel:DWORD
	v_and_b32_sdwa v156, v152, v163 dst_sel:DWORD dst_unused:UNUSED_PAD src0_sel:WORD_1 src1_sel:DWORD
	v_and_b32_sdwa v157, v153, v163 dst_sel:DWORD dst_unused:UNUSED_PAD src0_sel:WORD_1 src1_sel:DWORD
	v_add_f32_e32 v145, v145, v148
	v_add3_u32 v150, v150, v154, s12
	v_add3_u32 v151, v151, v155, s12
	v_add3_u32 v152, v152, v156, s12
	v_add3_u32 v153, v153, v157, s12
	v_add_f32_e32 v145, v145, v149
	v_and_b32_e32 v151, 0xffff0000, v151
	v_and_b32_e32 v153, 0xffff0000, v153
	s_nop 0
	v_or_b32_sdwa v160, v151, v150 dst_sel:DWORD dst_unused:UNUSED_PAD src0_sel:DWORD src1_sel:WORD_1
	v_or_b32_sdwa v161, v153, v152 dst_sel:DWORD dst_unused:UNUSED_PAD src0_sel:DWORD src1_sel:WORD_1
	global_store_dwordx2 v165, v[160:161], s[92:93]
	s_nop 1
	v_add_f32_dpp v142, v142, v142 quad_perm:[1,0,3,2] row_mask:0xf bank_mask:0xf
	v_add_f32_dpp v143, v143, v143 quad_perm:[1,0,3,2] row_mask:0xf bank_mask:0xf
	v_add_f32_dpp v144, v144, v144 quad_perm:[1,0,3,2] row_mask:0xf bank_mask:0xf
	v_add_f32_dpp v145, v145, v145 quad_perm:[1,0,3,2] row_mask:0xf bank_mask:0xf
	v_add_f32_dpp v142, v142, v142 quad_perm:[2,3,0,1] row_mask:0xf bank_mask:0xf
	v_add_f32_dpp v143, v143, v143 quad_perm:[2,3,0,1] row_mask:0xf bank_mask:0xf
	v_add_f32_dpp v144, v144, v144 quad_perm:[2,3,0,1] row_mask:0xf bank_mask:0xf
	v_add_f32_dpp v145, v145, v145 quad_perm:[2,3,0,1] row_mask:0xf bank_mask:0xf
	v_add_f32_dpp v142, v142, v142 row_half_mirror row_mask:0xf bank_mask:0xf
	v_add_f32_dpp v143, v143, v143 row_half_mirror row_mask:0xf bank_mask:0xf
	v_add_f32_dpp v144, v144, v144 row_half_mirror row_mask:0xf bank_mask:0xf
	v_add_f32_dpp v145, v145, v145 row_half_mirror row_mask:0xf bank_mask:0xf
	v_add_f32_dpp v142, v142, v142 row_mirror row_mask:0xf bank_mask:0xf
	v_add_f32_dpp v143, v143, v143 row_mirror row_mask:0xf bank_mask:0xf
	v_add_f32_dpp v144, v144, v144 row_mirror row_mask:0xf bank_mask:0xf
	v_add_f32_dpp v145, v145, v145 row_mirror row_mask:0xf bank_mask:0xf
	v_add_f32_dpp v142, v142, v142 row_bcast:15 row_mask:0xa bank_mask:0xf
	v_add_f32_dpp v143, v143, v143 row_bcast:15 row_mask:0xa bank_mask:0xf
	v_add_f32_dpp v144, v144, v144 row_bcast:15 row_mask:0xa bank_mask:0xf
	v_add_f32_dpp v145, v145, v145 row_bcast:15 row_mask:0xa bank_mask:0xf
	s_nop 1
	s_mov_b32 exec_lo, 0x80000000
	s_mov_b32 exec_hi, 0x80000000
	global_atomic_add_f32 v162, v126, s[10:11]
	global_atomic_add_f32 v162, v127, s[10:11] offset:32
	global_atomic_add_f32 v162, v132, s[10:11] offset:64
	global_atomic_add_f32 v162, v133, s[10:11] offset:96
	global_atomic_add_f32 v162, v134, s[10:11] offset:128
	global_atomic_add_f32 v162, v135, s[10:11] offset:160
	global_atomic_add_f32 v162, v136, s[10:11] offset:192
	global_atomic_add_f32 v162, v137, s[10:11] offset:224
	global_atomic_add_f32 v162, v138, s[10:11] offset:256
	global_atomic_add_f32 v162, v139, s[10:11] offset:288
	global_atomic_add_f32 v162, v140, s[10:11] offset:320
	global_atomic_add_f32 v162, v141, s[10:11] offset:352
	global_atomic_add_f32 v162, v142, s[10:11] offset:384
	global_atomic_add_f32 v162, v143, s[10:11] offset:416
	global_atomic_add_f32 v162, v144, s[10:11] offset:448
	global_atomic_add_f32 v162, v145, s[10:11] offset:480
	s_mov_b64 exec, -1
	s_branch .LBB0_562

.LBB0_590:
	s_lshr_b32 s8, s12, 2
	s_and_b32 s10, s16, 56
	s_and_b32 s8, s8, 0x1ffffc0
	s_or_b32 s10, s10, s3
	s_or_b32 s8, s10, s8
	s_lshl_b32 s8, s8, 7
	s_lshl_b64 s[24:25], s[8:9], 11
	v_lshl_add_u64 v[78:79], v[70:71], 0, s[24:25]
	v_add_co_u32_e32 v80, vcc, s18, v78
	s_and_b32 s10, s14, 0xf80
	s_nop 0
	v_addc_co_u32_e32 v81, vcc, 0, v79, vcc
	s_lshl_b32 s26, s10, 11
	s_mov_b32 s27, s9
	v_add_co_u32_e32 v82, vcc, s19, v78
	v_lshl_add_u64 v[76:77], v[72:73], 0, s[26:27]
	s_nop 0
	v_addc_co_u32_e32 v83, vcc, 0, v79, vcc
	v_add_co_u32_e32 v84, vcc, s18, v76
	global_load_dwordx4 v[2:5], v[78:79], off
	global_load_dwordx4 v[6:9], v[80:81], off
	v_addc_co_u32_e32 v85, vcc, 0, v77, vcc
	v_add_co_u32_e32 v86, vcc, s19, v76
	global_load_dwordx4 v[10:13], v[82:83], off
	global_load_dwordx4 v[14:17], v[76:77], off
	v_addc_co_u32_e32 v87, vcc, 0, v77, vcc
	global_load_dwordx4 v[18:21], v[84:85], off
	global_load_dwordx4 v[22:25], v[86:87], off
	v_add_co_u32_e32 v88, vcc, s20, v76
	s_nop 1
	v_addc_co_u32_e32 v89, vcc, 0, v77, vcc
	global_load_dwordx4 v[26:29], v[88:89], off
	v_add_co_u32_e32 v90, vcc, s20, v78
	s_nop 1
	v_addc_co_u32_e32 v91, vcc, 0, v79, vcc
	global_load_dwordx4 v[30:33], v[90:91], off
	global_load_dwordx4 v[148:151], v[76:77], off offset:128
	global_load_dwordx4 v[152:155], v[84:85], off offset:128
	global_load_dwordx4 v[156:159], v[86:87], off offset:128
	global_load_dwordx4 v[160:163], v[88:89], off offset:128
	global_load_dwordx4 v[164:167], v[78:79], off offset:128
	global_load_dwordx4 v[168:171], v[80:81], off offset:128
	global_load_dwordx4 v[172:175], v[82:83], off offset:128
	global_load_dwordx4 v[176:179], v[90:91], off offset:128
	s_waitcnt vmcnt(12)
	ds_write_b128 v1, v[14:17] offset:36864
	s_waitcnt vmcnt(11)
	ds_write_b128 v1, v[18:21] offset:41472
	s_waitcnt vmcnt(10)
	ds_write_b128 v1, v[22:25] offset:46080
	s_waitcnt vmcnt(9)
	ds_write_b128 v1, v[26:29] offset:50688
	ds_write_b128 v1, v[2:5]
	ds_write_b128 v1, v[6:9] offset:4608
	ds_write_b128 v1, v[10:13] offset:9216
	s_waitcnt vmcnt(8)
	ds_write_b128 v1, v[30:33] offset:13824
	s_waitcnt lgkmcnt(0)
	s_barrier
	global_load_dwordx4 v[180:183], v[80:81], off offset:256
	global_load_dwordx4 v[184:187], v[82:83], off offset:256
	global_load_dwordx4 v[188:191], v[78:79], off offset:256
	global_load_dwordx4 v[192:195], v[76:77], off offset:256
	global_load_dwordx4 v[196:199], v[90:91], off offset:256
	global_load_dwordx4 v[200:203], v[84:85], off offset:256
	global_load_dwordx4 v[204:207], v[86:87], off offset:256
	global_load_dwordx4 v[208:211], v[88:89], off offset:256
	ds_read_b128 v[18:21], v66
	ds_read_b128 v[34:37], v67 offset:36864
	ds_read_b128 v[212:215], v66 offset:32
	ds_read_b128 v[216:219], v67 offset:36896
	ds_read_b128 v[50:53], v67 offset:41472
	ds_read_b128 v[220:223], v67 offset:41504
	ds_read_b128 v[54:57], v66 offset:4608
	ds_read_b128 v[224:227], v66 offset:4640
	s_waitcnt lgkmcnt(6)
	v_mfma_f32_32x32x16_bf16 v[2:17], v[18:21], v[34:37], 0
	s_waitcnt lgkmcnt(3)
	v_mfma_f32_32x32x16_bf16 v[18:33], v[18:21], v[50:53], 0
	s_waitcnt lgkmcnt(1)
	v_mfma_f32_32x32x16_bf16 v[34:49], v[54:57], v[34:37], 0
	v_mfma_f32_32x32x16_bf16 v[50:65], v[54:57], v[50:53], 0
	v_mfma_f32_32x32x16_bf16 v[2:17], v[212:215], v[216:219], v[2:17]
	v_mfma_f32_32x32x16_bf16 v[18:33], v[212:215], v[220:223], v[18:33]
	s_waitcnt lgkmcnt(0)
	v_mfma_f32_32x32x16_bf16 v[34:49], v[224:227], v[216:219], v[34:49]
	v_mfma_f32_32x32x16_bf16 v[50:65], v[224:227], v[220:223], v[50:65]
	ds_read_b128 v[212:215], v66 offset:64
	ds_read_b128 v[216:219], v67 offset:36928
	ds_read_b128 v[220:223], v66 offset:96
	ds_read_b128 v[224:227], v67 offset:36960
	ds_read_b128 v[228:231], v67 offset:41536
	ds_read_b128 v[232:235], v67 offset:41568
	s_waitcnt lgkmcnt(4)
	v_mfma_f32_32x32x16_bf16 v[2:17], v[212:215], v[216:219], v[2:17]
	s_waitcnt lgkmcnt(1)
	v_mfma_f32_32x32x16_bf16 v[18:33], v[212:215], v[228:231], v[18:33]
	ds_read_b128 v[212:215], v66 offset:4672
	ds_read_b128 v[236:239], v66 offset:4704
	s_waitcnt vmcnt(11)
	ds_write_b128 v1, v[164:167] offset:18432
	s_waitcnt vmcnt(10)
	ds_write_b128 v1, v[168:171] offset:23040
	s_waitcnt vmcnt(9)
	ds_write_b128 v1, v[172:175] offset:27648
	s_waitcnt vmcnt(8)
	ds_write_b128 v1, v[176:179] offset:32256
	ds_write_b128 v1, v[148:151] offset:55296
	ds_write_b128 v1, v[152:155] offset:59904
	ds_write_b128 v1, v[156:159] offset:64512
	ds_write_b128 v92, v[160:163] offset:32256
	global_load_dwordx4 v[148:151], v[80:81], off offset:384
	global_load_dwordx4 v[152:155], v[82:83], off offset:384
	global_load_dwordx4 v[156:159], v[78:79], off offset:384
	global_load_dwordx4 v[160:163], v[76:77], off offset:384
	global_load_dwordx4 v[164:167], v[90:91], off offset:384
	global_load_dwordx4 v[168:171], v[84:85], off offset:384
	global_load_dwordx4 v[172:175], v[86:87], off offset:384
	global_load_dwordx4 v[176:179], v[88:89], off offset:384
	s_waitcnt lgkmcnt(0)
	s_barrier
	v_mfma_f32_32x32x16_bf16 v[34:49], v[212:215], v[216:219], v[34:49]
	v_mfma_f32_32x32x16_bf16 v[50:65], v[212:215], v[228:231], v[50:65]
	v_mfma_f32_32x32x16_bf16 v[2:17], v[220:223], v[224:227], v[2:17]
	v_mfma_f32_32x32x16_bf16 v[18:33], v[220:223], v[232:235], v[18:33]
	v_mfma_f32_32x32x16_bf16 v[34:49], v[236:239], v[224:227], v[34:49]
	v_mfma_f32_32x32x16_bf16 v[50:65], v[236:239], v[232:235], v[50:65]
	ds_read_b128 v[212:215], v66 offset:18432
	ds_read_b128 v[216:219], v67 offset:55296
	ds_read_b128 v[220:223], v66 offset:18464
	ds_read_b128 v[224:227], v67 offset:55328
	ds_read_b128 v[228:231], v67 offset:59904
	ds_read_b128 v[232:235], v67 offset:59936
	s_waitcnt lgkmcnt(4)
	v_mfma_f32_32x32x16_bf16 v[2:17], v[212:215], v[216:219], v[2:17]
	s_waitcnt lgkmcnt(1)
	v_mfma_f32_32x32x16_bf16 v[18:33], v[212:215], v[228:231], v[18:33]
	ds_read_b128 v[212:215], v66 offset:23040
	ds_read_b128 v[236:239], v66 offset:23072
	s_waitcnt lgkmcnt(1)
	v_mfma_f32_32x32x16_bf16 v[34:49], v[212:215], v[216:219], v[34:49]
	v_mfma_f32_32x32x16_bf16 v[50:65], v[212:215], v[228:231], v[50:65]
	v_mfma_f32_32x32x16_bf16 v[2:17], v[220:223], v[224:227], v[2:17]
	v_mfma_f32_32x32x16_bf16 v[18:33], v[220:223], v[232:235], v[18:33]
	s_waitcnt lgkmcnt(0)
	v_mfma_f32_32x32x16_bf16 v[34:49], v[236:239], v[224:227], v[34:49]
	ds_read_b128 v[212:215], v66 offset:18496
	ds_read_b128 v[216:219], v67 offset:55360
	ds_read_b128 v[220:223], v66 offset:18528
	ds_read_b128 v[224:227], v67 offset:55392
	v_mfma_f32_32x32x16_bf16 v[50:65], v[236:239], v[232:235], v[50:65]
	ds_read_b128 v[228:231], v67 offset:59968
	ds_read_b128 v[232:235], v67 offset:60000
	s_waitcnt lgkmcnt(4)
	v_mfma_f32_32x32x16_bf16 v[2:17], v[212:215], v[216:219], v[2:17]
	s_waitcnt lgkmcnt(1)
	v_mfma_f32_32x32x16_bf16 v[18:33], v[212:215], v[228:231], v[18:33]
	ds_read_b128 v[212:215], v66 offset:23104
	ds_read_b128 v[236:239], v66 offset:23136
	s_waitcnt vmcnt(13)
	ds_write_b128 v1, v[188:191]
	ds_write_b128 v1, v[180:183] offset:4608
	ds_write_b128 v1, v[184:187] offset:9216
	s_waitcnt vmcnt(11)
	ds_write_b128 v1, v[196:199] offset:13824
	ds_write_b128 v1, v[192:195] offset:36864
	s_waitcnt vmcnt(10)
	ds_write_b128 v1, v[200:203] offset:41472
	s_waitcnt vmcnt(9)
	ds_write_b128 v1, v[204:207] offset:46080
	s_waitcnt vmcnt(8)
	ds_write_b128 v1, v[208:211] offset:50688
	global_load_dwordx4 v[180:183], v[80:81], off offset:512
	global_load_dwordx4 v[184:187], v[82:83], off offset:512
	global_load_dwordx4 v[188:191], v[78:79], off offset:512
	global_load_dwordx4 v[192:195], v[76:77], off offset:512
	global_load_dwordx4 v[196:199], v[90:91], off offset:512
	global_load_dwordx4 v[200:203], v[84:85], off offset:512
	global_load_dwordx4 v[204:207], v[86:87], off offset:512
	global_load_dwordx4 v[208:211], v[88:89], off offset:512
	s_waitcnt lgkmcnt(0)
	s_barrier
	v_mfma_f32_32x32x16_bf16 v[34:49], v[212:215], v[216:219], v[34:49]
	v_mfma_f32_32x32x16_bf16 v[50:65], v[212:215], v[228:231], v[50:65]
	v_mfma_f32_32x32x16_bf16 v[2:17], v[220:223], v[224:227], v[2:17]
	v_mfma_f32_32x32x16_bf16 v[18:33], v[220:223], v[232:235], v[18:33]
	v_mfma_f32_32x32x16_bf16 v[34:49], v[236:239], v[224:227], v[34:49]
	v_mfma_f32_32x32x16_bf16 v[50:65], v[236:239], v[232:235], v[50:65]
	ds_read_b128 v[212:215], v66
	ds_read_b128 v[216:219], v67 offset:36864
	ds_read_b128 v[220:223], v66 offset:32
	ds_read_b128 v[224:227], v67 offset:36896
	ds_read_b128 v[228:231], v67 offset:41472
	ds_read_b128 v[232:235], v67 offset:41504
	s_waitcnt lgkmcnt(4)
	v_mfma_f32_32x32x16_bf16 v[2:17], v[212:215], v[216:219], v[2:17]
	s_waitcnt lgkmcnt(1)
	v_mfma_f32_32x32x16_bf16 v[18:33], v[212:215], v[228:231], v[18:33]
	ds_read_b128 v[212:215], v66 offset:4608
	ds_read_b128 v[236:239], v66 offset:4640
	s_waitcnt lgkmcnt(1)
	v_mfma_f32_32x32x16_bf16 v[34:49], v[212:215], v[216:219], v[34:49]
	v_mfma_f32_32x32x16_bf16 v[50:65], v[212:215], v[228:231], v[50:65]
	v_mfma_f32_32x32x16_bf16 v[2:17], v[220:223], v[224:227], v[2:17]
	v_mfma_f32_32x32x16_bf16 v[18:33], v[220:223], v[232:235], v[18:33]
	s_waitcnt lgkmcnt(0)
	v_mfma_f32_32x32x16_bf16 v[34:49], v[236:239], v[224:227], v[34:49]
	ds_read_b128 v[212:215], v66 offset:64
	ds_read_b128 v[216:219], v67 offset:36928
	ds_read_b128 v[220:223], v66 offset:96
	ds_read_b128 v[224:227], v67 offset:36960
	v_mfma_f32_32x32x16_bf16 v[50:65], v[236:239], v[232:235], v[50:65]
	ds_read_b128 v[228:231], v67 offset:41536
	ds_read_b128 v[232:235], v67 offset:41568
	s_waitcnt lgkmcnt(4)
	v_mfma_f32_32x32x16_bf16 v[2:17], v[212:215], v[216:219], v[2:17]
	s_waitcnt lgkmcnt(1)
	v_mfma_f32_32x32x16_bf16 v[18:33], v[212:215], v[228:231], v[18:33]
	ds_read_b128 v[212:215], v66 offset:4672
	ds_read_b128 v[236:239], v66 offset:4704
	s_waitcnt vmcnt(13)
	ds_write_b128 v1, v[156:159] offset:18432
	ds_write_b128 v1, v[148:151] offset:23040
	ds_write_b128 v1, v[152:155] offset:27648
	s_waitcnt vmcnt(11)
	ds_write_b128 v1, v[164:167] offset:32256
	ds_write_b128 v1, v[160:163] offset:55296
	s_waitcnt vmcnt(10)
	ds_write_b128 v1, v[168:171] offset:59904
	s_waitcnt vmcnt(9)
	ds_write_b128 v1, v[172:175] offset:64512
	s_waitcnt vmcnt(8)
	ds_write_b128 v92, v[176:179] offset:32256
	global_load_dwordx4 v[148:151], v[80:81], off offset:640
	global_load_dwordx4 v[152:155], v[82:83], off offset:640
	global_load_dwordx4 v[156:159], v[78:79], off offset:640
	global_load_dwordx4 v[160:163], v[76:77], off offset:640
	global_load_dwordx4 v[164:167], v[90:91], off offset:640
	global_load_dwordx4 v[168:171], v[84:85], off offset:640
	global_load_dwordx4 v[172:175], v[86:87], off offset:640
	global_load_dwordx4 v[176:179], v[88:89], off offset:640
	s_waitcnt lgkmcnt(0)
	s_barrier
	v_mfma_f32_32x32x16_bf16 v[34:49], v[212:215], v[216:219], v[34:49]
	v_mfma_f32_32x32x16_bf16 v[50:65], v[212:215], v[228:231], v[50:65]
	v_mfma_f32_32x32x16_bf16 v[2:17], v[220:223], v[224:227], v[2:17]
	v_mfma_f32_32x32x16_bf16 v[18:33], v[220:223], v[232:235], v[18:33]
	v_mfma_f32_32x32x16_bf16 v[34:49], v[236:239], v[224:227], v[34:49]
	v_mfma_f32_32x32x16_bf16 v[50:65], v[236:239], v[232:235], v[50:65]
	ds_read_b128 v[212:215], v66 offset:18432
	ds_read_b128 v[216:219], v67 offset:55296
	ds_read_b128 v[220:223], v66 offset:18464
	ds_read_b128 v[224:227], v67 offset:55328
	ds_read_b128 v[228:231], v67 offset:59904
	ds_read_b128 v[232:235], v67 offset:59936
	s_waitcnt lgkmcnt(4)
	v_mfma_f32_32x32x16_bf16 v[2:17], v[212:215], v[216:219], v[2:17]
	s_waitcnt lgkmcnt(1)
	v_mfma_f32_32x32x16_bf16 v[18:33], v[212:215], v[228:231], v[18:33]
	ds_read_b128 v[212:215], v66 offset:23040
	ds_read_b128 v[236:239], v66 offset:23072
	s_waitcnt lgkmcnt(1)
	v_mfma_f32_32x32x16_bf16 v[34:49], v[212:215], v[216:219], v[34:49]
	v_mfma_f32_32x32x16_bf16 v[50:65], v[212:215], v[228:231], v[50:65]
	v_mfma_f32_32x32x16_bf16 v[2:17], v[220:223], v[224:227], v[2:17]
	v_mfma_f32_32x32x16_bf16 v[18:33], v[220:223], v[232:235], v[18:33]
	s_waitcnt lgkmcnt(0)
	v_mfma_f32_32x32x16_bf16 v[34:49], v[236:239], v[224:227], v[34:49]
	ds_read_b128 v[212:215], v66 offset:18496
	ds_read_b128 v[216:219], v67 offset:55360
	ds_read_b128 v[220:223], v66 offset:18528
	ds_read_b128 v[224:227], v67 offset:55392
	v_mfma_f32_32x32x16_bf16 v[50:65], v[236:239], v[232:235], v[50:65]
	ds_read_b128 v[228:231], v67 offset:59968
	ds_read_b128 v[232:235], v67 offset:60000
	s_waitcnt lgkmcnt(4)
	v_mfma_f32_32x32x16_bf16 v[2:17], v[212:215], v[216:219], v[2:17]
	s_waitcnt lgkmcnt(1)
	v_mfma_f32_32x32x16_bf16 v[18:33], v[212:215], v[228:231], v[18:33]
	ds_read_b128 v[212:215], v66 offset:23104
	ds_read_b128 v[236:239], v66 offset:23136
	s_waitcnt vmcnt(13)
	ds_write_b128 v1, v[188:191]
	ds_write_b128 v1, v[180:183] offset:4608
	ds_write_b128 v1, v[184:187] offset:9216
	s_waitcnt vmcnt(11)
	ds_write_b128 v1, v[196:199] offset:13824
	ds_write_b128 v1, v[192:195] offset:36864
	s_waitcnt vmcnt(10)
	ds_write_b128 v1, v[200:203] offset:41472
	s_waitcnt vmcnt(9)
	ds_write_b128 v1, v[204:207] offset:46080
	s_waitcnt vmcnt(8)
	ds_write_b128 v1, v[208:211] offset:50688
	global_load_dwordx4 v[180:183], v[80:81], off offset:768
	global_load_dwordx4 v[184:187], v[82:83], off offset:768
	global_load_dwordx4 v[188:191], v[78:79], off offset:768
	global_load_dwordx4 v[192:195], v[76:77], off offset:768
	global_load_dwordx4 v[196:199], v[90:91], off offset:768
	global_load_dwordx4 v[200:203], v[84:85], off offset:768
	global_load_dwordx4 v[204:207], v[86:87], off offset:768
	global_load_dwordx4 v[208:211], v[88:89], off offset:768
	s_waitcnt lgkmcnt(0)
	s_barrier
	v_mfma_f32_32x32x16_bf16 v[34:49], v[212:215], v[216:219], v[34:49]
	v_mfma_f32_32x32x16_bf16 v[50:65], v[212:215], v[228:231], v[50:65]
	v_mfma_f32_32x32x16_bf16 v[2:17], v[220:223], v[224:227], v[2:17]
	v_mfma_f32_32x32x16_bf16 v[18:33], v[220:223], v[232:235], v[18:33]
	v_mfma_f32_32x32x16_bf16 v[34:49], v[236:239], v[224:227], v[34:49]
	v_mfma_f32_32x32x16_bf16 v[50:65], v[236:239], v[232:235], v[50:65]
	ds_read_b128 v[212:215], v66
	ds_read_b128 v[216:219], v67 offset:36864
	ds_read_b128 v[220:223], v66 offset:32
	ds_read_b128 v[224:227], v67 offset:36896
	ds_read_b128 v[228:231], v67 offset:41472
	ds_read_b128 v[232:235], v67 offset:41504
	s_waitcnt lgkmcnt(4)
	v_mfma_f32_32x32x16_bf16 v[2:17], v[212:215], v[216:219], v[2:17]
	s_waitcnt lgkmcnt(1)
	v_mfma_f32_32x32x16_bf16 v[18:33], v[212:215], v[228:231], v[18:33]
	ds_read_b128 v[212:215], v66 offset:4608
	ds_read_b128 v[236:239], v66 offset:4640
	s_waitcnt lgkmcnt(1)
	v_mfma_f32_32x32x16_bf16 v[34:49], v[212:215], v[216:219], v[34:49]
	v_mfma_f32_32x32x16_bf16 v[50:65], v[212:215], v[228:231], v[50:65]
	v_mfma_f32_32x32x16_bf16 v[2:17], v[220:223], v[224:227], v[2:17]
	v_mfma_f32_32x32x16_bf16 v[18:33], v[220:223], v[232:235], v[18:33]
	s_waitcnt lgkmcnt(0)
	v_mfma_f32_32x32x16_bf16 v[34:49], v[236:239], v[224:227], v[34:49]
	ds_read_b128 v[212:215], v66 offset:64
	ds_read_b128 v[216:219], v67 offset:36928
	ds_read_b128 v[220:223], v66 offset:96
	ds_read_b128 v[224:227], v67 offset:36960
	v_mfma_f32_32x32x16_bf16 v[50:65], v[236:239], v[232:235], v[50:65]
	ds_read_b128 v[228:231], v67 offset:41536
	ds_read_b128 v[232:235], v67 offset:41568
	s_waitcnt lgkmcnt(4)
	v_mfma_f32_32x32x16_bf16 v[2:17], v[212:215], v[216:219], v[2:17]
	s_waitcnt lgkmcnt(1)
	v_mfma_f32_32x32x16_bf16 v[18:33], v[212:215], v[228:231], v[18:33]
	ds_read_b128 v[212:215], v66 offset:4672
	ds_read_b128 v[236:239], v66 offset:4704
	s_waitcnt vmcnt(13)
	ds_write_b128 v1, v[156:159] offset:18432
	ds_write_b128 v1, v[148:151] offset:23040
	ds_write_b128 v1, v[152:155] offset:27648
	s_waitcnt vmcnt(11)
	ds_write_b128 v1, v[164:167] offset:32256
	ds_write_b128 v1, v[160:163] offset:55296
	s_waitcnt vmcnt(10)
	ds_write_b128 v1, v[168:171] offset:59904
	s_waitcnt vmcnt(9)
	ds_write_b128 v1, v[172:175] offset:64512
	s_waitcnt vmcnt(8)
	ds_write_b128 v92, v[176:179] offset:32256
	global_load_dwordx4 v[148:151], v[80:81], off offset:896
	global_load_dwordx4 v[152:155], v[82:83], off offset:896
	global_load_dwordx4 v[156:159], v[78:79], off offset:896
	global_load_dwordx4 v[160:163], v[76:77], off offset:896
	global_load_dwordx4 v[164:167], v[90:91], off offset:896
	global_load_dwordx4 v[168:171], v[84:85], off offset:896
	global_load_dwordx4 v[172:175], v[86:87], off offset:896
	global_load_dwordx4 v[176:179], v[88:89], off offset:896
	s_waitcnt lgkmcnt(0)
	s_barrier
	v_mfma_f32_32x32x16_bf16 v[34:49], v[212:215], v[216:219], v[34:49]
	v_mfma_f32_32x32x16_bf16 v[50:65], v[212:215], v[228:231], v[50:65]
	v_mfma_f32_32x32x16_bf16 v[2:17], v[220:223], v[224:227], v[2:17]
	v_mfma_f32_32x32x16_bf16 v[18:33], v[220:223], v[232:235], v[18:33]
	v_mfma_f32_32x32x16_bf16 v[34:49], v[236:239], v[224:227], v[34:49]
	v_mfma_f32_32x32x16_bf16 v[50:65], v[236:239], v[232:235], v[50:65]
	ds_read_b128 v[212:215], v66 offset:18432
	ds_read_b128 v[216:219], v67 offset:55296
	ds_read_b128 v[220:223], v66 offset:18464
	ds_read_b128 v[224:227], v67 offset:55328
	ds_read_b128 v[228:231], v67 offset:59904
	ds_read_b128 v[232:235], v67 offset:59936
	s_waitcnt lgkmcnt(4)
	v_mfma_f32_32x32x16_bf16 v[2:17], v[212:215], v[216:219], v[2:17]
	s_waitcnt lgkmcnt(1)
	v_mfma_f32_32x32x16_bf16 v[18:33], v[212:215], v[228:231], v[18:33]
	ds_read_b128 v[212:215], v66 offset:23040
	ds_read_b128 v[236:239], v66 offset:23072
	s_waitcnt lgkmcnt(1)
	v_mfma_f32_32x32x16_bf16 v[34:49], v[212:215], v[216:219], v[34:49]
	v_mfma_f32_32x32x16_bf16 v[50:65], v[212:215], v[228:231], v[50:65]
	v_mfma_f32_32x32x16_bf16 v[2:17], v[220:223], v[224:227], v[2:17]
	v_mfma_f32_32x32x16_bf16 v[18:33], v[220:223], v[232:235], v[18:33]
	s_waitcnt lgkmcnt(0)
	v_mfma_f32_32x32x16_bf16 v[34:49], v[236:239], v[224:227], v[34:49]
	ds_read_b128 v[212:215], v66 offset:18496
	ds_read_b128 v[216:219], v67 offset:55360
	ds_read_b128 v[220:223], v66 offset:18528
	ds_read_b128 v[224:227], v67 offset:55392
	v_mfma_f32_32x32x16_bf16 v[50:65], v[236:239], v[232:235], v[50:65]
	ds_read_b128 v[228:231], v67 offset:59968
	ds_read_b128 v[232:235], v67 offset:60000
	s_waitcnt lgkmcnt(4)
	v_mfma_f32_32x32x16_bf16 v[2:17], v[212:215], v[216:219], v[2:17]
	s_waitcnt lgkmcnt(1)
	v_mfma_f32_32x32x16_bf16 v[18:33], v[212:215], v[228:231], v[18:33]
	ds_read_b128 v[212:215], v66 offset:23104
	ds_read_b128 v[236:239], v66 offset:23136
	s_waitcnt vmcnt(13)
	ds_write_b128 v1, v[188:191]
	ds_write_b128 v1, v[180:183] offset:4608
	ds_write_b128 v1, v[184:187] offset:9216
	s_waitcnt vmcnt(11)
	ds_write_b128 v1, v[196:199] offset:13824
	ds_write_b128 v1, v[192:195] offset:36864
	s_waitcnt vmcnt(10)
	ds_write_b128 v1, v[200:203] offset:41472
	s_waitcnt vmcnt(9)
	ds_write_b128 v1, v[204:207] offset:46080
	s_waitcnt vmcnt(8)
	ds_write_b128 v1, v[208:211] offset:50688
	global_load_dwordx4 v[180:183], v[80:81], off offset:1024
	global_load_dwordx4 v[184:187], v[82:83], off offset:1024
	global_load_dwordx4 v[188:191], v[78:79], off offset:1024
	global_load_dwordx4 v[192:195], v[76:77], off offset:1024
	global_load_dwordx4 v[196:199], v[90:91], off offset:1024
	global_load_dwordx4 v[200:203], v[84:85], off offset:1024
	global_load_dwordx4 v[204:207], v[86:87], off offset:1024
	global_load_dwordx4 v[208:211], v[88:89], off offset:1024
	s_waitcnt lgkmcnt(0)
	s_barrier
	v_mfma_f32_32x32x16_bf16 v[34:49], v[212:215], v[216:219], v[34:49]
	v_mfma_f32_32x32x16_bf16 v[50:65], v[212:215], v[228:231], v[50:65]
	v_mfma_f32_32x32x16_bf16 v[2:17], v[220:223], v[224:227], v[2:17]
	v_mfma_f32_32x32x16_bf16 v[18:33], v[220:223], v[232:235], v[18:33]
	v_mfma_f32_32x32x16_bf16 v[34:49], v[236:239], v[224:227], v[34:49]
	v_mfma_f32_32x32x16_bf16 v[50:65], v[236:239], v[232:235], v[50:65]
	ds_read_b128 v[212:215], v66
	ds_read_b128 v[216:219], v67 offset:36864
	ds_read_b128 v[220:223], v66 offset:32
	ds_read_b128 v[224:227], v67 offset:36896
	ds_read_b128 v[228:231], v67 offset:41472
	ds_read_b128 v[232:235], v67 offset:41504
	s_waitcnt lgkmcnt(4)
	v_mfma_f32_32x32x16_bf16 v[2:17], v[212:215], v[216:219], v[2:17]
	s_waitcnt lgkmcnt(1)
	v_mfma_f32_32x32x16_bf16 v[18:33], v[212:215], v[228:231], v[18:33]
	ds_read_b128 v[212:215], v66 offset:4608
	ds_read_b128 v[236:239], v66 offset:4640
	s_waitcnt lgkmcnt(1)
	v_mfma_f32_32x32x16_bf16 v[34:49], v[212:215], v[216:219], v[34:49]
	v_mfma_f32_32x32x16_bf16 v[50:65], v[212:215], v[228:231], v[50:65]
	v_mfma_f32_32x32x16_bf16 v[2:17], v[220:223], v[224:227], v[2:17]
	v_mfma_f32_32x32x16_bf16 v[18:33], v[220:223], v[232:235], v[18:33]
	s_waitcnt lgkmcnt(0)
	v_mfma_f32_32x32x16_bf16 v[34:49], v[236:239], v[224:227], v[34:49]
	ds_read_b128 v[212:215], v66 offset:64
	ds_read_b128 v[216:219], v67 offset:36928
	ds_read_b128 v[220:223], v66 offset:96
	ds_read_b128 v[224:227], v67 offset:36960
	v_mfma_f32_32x32x16_bf16 v[50:65], v[236:239], v[232:235], v[50:65]
	ds_read_b128 v[228:231], v67 offset:41536
	ds_read_b128 v[232:235], v67 offset:41568
	s_waitcnt lgkmcnt(4)
	v_mfma_f32_32x32x16_bf16 v[2:17], v[212:215], v[216:219], v[2:17]
	s_waitcnt lgkmcnt(1)
	v_mfma_f32_32x32x16_bf16 v[18:33], v[212:215], v[228:231], v[18:33]
	ds_read_b128 v[212:215], v66 offset:4672
	ds_read_b128 v[236:239], v66 offset:4704
	s_waitcnt vmcnt(13)
	ds_write_b128 v1, v[156:159] offset:18432
	ds_write_b128 v1, v[148:151] offset:23040
	ds_write_b128 v1, v[152:155] offset:27648
	s_waitcnt vmcnt(11)
	ds_write_b128 v1, v[164:167] offset:32256
	ds_write_b128 v1, v[160:163] offset:55296
	s_waitcnt vmcnt(10)
	ds_write_b128 v1, v[168:171] offset:59904
	s_waitcnt vmcnt(9)
	ds_write_b128 v1, v[172:175] offset:64512
	s_waitcnt vmcnt(8)
	ds_write_b128 v92, v[176:179] offset:32256
	global_load_dwordx4 v[148:151], v[80:81], off offset:1152
	global_load_dwordx4 v[152:155], v[82:83], off offset:1152
	global_load_dwordx4 v[156:159], v[78:79], off offset:1152
	global_load_dwordx4 v[160:163], v[76:77], off offset:1152
	global_load_dwordx4 v[164:167], v[90:91], off offset:1152
	global_load_dwordx4 v[168:171], v[84:85], off offset:1152
	global_load_dwordx4 v[172:175], v[86:87], off offset:1152
	global_load_dwordx4 v[176:179], v[88:89], off offset:1152
	s_waitcnt lgkmcnt(0)
	s_barrier
	v_mfma_f32_32x32x16_bf16 v[34:49], v[212:215], v[216:219], v[34:49]
	v_mfma_f32_32x32x16_bf16 v[50:65], v[212:215], v[228:231], v[50:65]
	v_mfma_f32_32x32x16_bf16 v[2:17], v[220:223], v[224:227], v[2:17]
	v_mfma_f32_32x32x16_bf16 v[18:33], v[220:223], v[232:235], v[18:33]
	v_mfma_f32_32x32x16_bf16 v[34:49], v[236:239], v[224:227], v[34:49]
	v_mfma_f32_32x32x16_bf16 v[50:65], v[236:239], v[232:235], v[50:65]
	ds_read_b128 v[212:215], v66 offset:18432
	ds_read_b128 v[216:219], v67 offset:55296
	ds_read_b128 v[220:223], v66 offset:18464
	ds_read_b128 v[224:227], v67 offset:55328
	ds_read_b128 v[228:231], v67 offset:59904
	ds_read_b128 v[232:235], v67 offset:59936
	s_waitcnt lgkmcnt(4)
	v_mfma_f32_32x32x16_bf16 v[2:17], v[212:215], v[216:219], v[2:17]
	s_waitcnt lgkmcnt(1)
	v_mfma_f32_32x32x16_bf16 v[18:33], v[212:215], v[228:231], v[18:33]
	ds_read_b128 v[212:215], v66 offset:23040
	ds_read_b128 v[236:239], v66 offset:23072
	s_waitcnt lgkmcnt(1)
	v_mfma_f32_32x32x16_bf16 v[34:49], v[212:215], v[216:219], v[34:49]
	v_mfma_f32_32x32x16_bf16 v[50:65], v[212:215], v[228:231], v[50:65]
	v_mfma_f32_32x32x16_bf16 v[2:17], v[220:223], v[224:227], v[2:17]
	v_mfma_f32_32x32x16_bf16 v[18:33], v[220:223], v[232:235], v[18:33]
	s_waitcnt lgkmcnt(0)
	v_mfma_f32_32x32x16_bf16 v[34:49], v[236:239], v[224:227], v[34:49]
	ds_read_b128 v[212:215], v66 offset:18496
	ds_read_b128 v[216:219], v67 offset:55360
	ds_read_b128 v[220:223], v66 offset:18528
	ds_read_b128 v[224:227], v67 offset:55392
	v_mfma_f32_32x32x16_bf16 v[50:65], v[236:239], v[232:235], v[50:65]
	ds_read_b128 v[228:231], v67 offset:59968
	ds_read_b128 v[232:235], v67 offset:60000
	s_waitcnt lgkmcnt(4)
	v_mfma_f32_32x32x16_bf16 v[2:17], v[212:215], v[216:219], v[2:17]
	s_waitcnt lgkmcnt(1)
	v_mfma_f32_32x32x16_bf16 v[18:33], v[212:215], v[228:231], v[18:33]
	ds_read_b128 v[212:215], v66 offset:23104
	ds_read_b128 v[236:239], v66 offset:23136
	s_waitcnt vmcnt(13)
	ds_write_b128 v1, v[188:191]
	ds_write_b128 v1, v[180:183] offset:4608
	ds_write_b128 v1, v[184:187] offset:9216
	s_waitcnt vmcnt(11)
	ds_write_b128 v1, v[196:199] offset:13824
	ds_write_b128 v1, v[192:195] offset:36864
	s_waitcnt vmcnt(10)
	ds_write_b128 v1, v[200:203] offset:41472
	s_waitcnt vmcnt(9)
	ds_write_b128 v1, v[204:207] offset:46080
	s_waitcnt vmcnt(8)
	ds_write_b128 v1, v[208:211] offset:50688
	global_load_dwordx4 v[180:183], v[80:81], off offset:1280
	global_load_dwordx4 v[184:187], v[82:83], off offset:1280
	global_load_dwordx4 v[188:191], v[78:79], off offset:1280
	global_load_dwordx4 v[192:195], v[76:77], off offset:1280
	global_load_dwordx4 v[196:199], v[90:91], off offset:1280
	global_load_dwordx4 v[200:203], v[84:85], off offset:1280
	global_load_dwordx4 v[204:207], v[86:87], off offset:1280
	global_load_dwordx4 v[208:211], v[88:89], off offset:1280
	s_waitcnt lgkmcnt(0)
	s_barrier
	v_mfma_f32_32x32x16_bf16 v[34:49], v[212:215], v[216:219], v[34:49]
	v_mfma_f32_32x32x16_bf16 v[50:65], v[212:215], v[228:231], v[50:65]
	v_mfma_f32_32x32x16_bf16 v[2:17], v[220:223], v[224:227], v[2:17]
	v_mfma_f32_32x32x16_bf16 v[18:33], v[220:223], v[232:235], v[18:33]
	v_mfma_f32_32x32x16_bf16 v[34:49], v[236:239], v[224:227], v[34:49]
	v_mfma_f32_32x32x16_bf16 v[50:65], v[236:239], v[232:235], v[50:65]
	ds_read_b128 v[212:215], v66
	ds_read_b128 v[216:219], v67 offset:36864
	ds_read_b128 v[220:223], v66 offset:32
	ds_read_b128 v[224:227], v67 offset:36896
	ds_read_b128 v[228:231], v67 offset:41472
	ds_read_b128 v[232:235], v67 offset:41504
	s_waitcnt lgkmcnt(4)
	v_mfma_f32_32x32x16_bf16 v[2:17], v[212:215], v[216:219], v[2:17]
	s_waitcnt lgkmcnt(1)
	v_mfma_f32_32x32x16_bf16 v[18:33], v[212:215], v[228:231], v[18:33]
	ds_read_b128 v[212:215], v66 offset:4608
	ds_read_b128 v[236:239], v66 offset:4640
	s_waitcnt lgkmcnt(1)
	v_mfma_f32_32x32x16_bf16 v[34:49], v[212:215], v[216:219], v[34:49]
	v_mfma_f32_32x32x16_bf16 v[50:65], v[212:215], v[228:231], v[50:65]
	v_mfma_f32_32x32x16_bf16 v[2:17], v[220:223], v[224:227], v[2:17]
	v_mfma_f32_32x32x16_bf16 v[18:33], v[220:223], v[232:235], v[18:33]
	s_waitcnt lgkmcnt(0)
	v_mfma_f32_32x32x16_bf16 v[34:49], v[236:239], v[224:227], v[34:49]
	ds_read_b128 v[212:215], v66 offset:64
	ds_read_b128 v[216:219], v67 offset:36928
	ds_read_b128 v[220:223], v66 offset:96
	ds_read_b128 v[224:227], v67 offset:36960
	v_mfma_f32_32x32x16_bf16 v[50:65], v[236:239], v[232:235], v[50:65]
	ds_read_b128 v[228:231], v67 offset:41536
	ds_read_b128 v[232:235], v67 offset:41568
	s_waitcnt lgkmcnt(4)
	v_mfma_f32_32x32x16_bf16 v[2:17], v[212:215], v[216:219], v[2:17]
	s_waitcnt lgkmcnt(1)
	v_mfma_f32_32x32x16_bf16 v[18:33], v[212:215], v[228:231], v[18:33]
	ds_read_b128 v[212:215], v66 offset:4672
	ds_read_b128 v[236:239], v66 offset:4704
	s_waitcnt vmcnt(13)
	ds_write_b128 v1, v[156:159] offset:18432
	ds_write_b128 v1, v[148:151] offset:23040
	ds_write_b128 v1, v[152:155] offset:27648
	s_waitcnt vmcnt(11)
	ds_write_b128 v1, v[164:167] offset:32256
	ds_write_b128 v1, v[160:163] offset:55296
	s_waitcnt vmcnt(10)
	ds_write_b128 v1, v[168:171] offset:59904
	s_waitcnt vmcnt(9)
	ds_write_b128 v1, v[172:175] offset:64512
	s_waitcnt vmcnt(8)
	ds_write_b128 v92, v[176:179] offset:32256
	global_load_dwordx4 v[148:151], v[80:81], off offset:1408
	global_load_dwordx4 v[152:155], v[82:83], off offset:1408
	global_load_dwordx4 v[156:159], v[78:79], off offset:1408
	global_load_dwordx4 v[160:163], v[76:77], off offset:1408
	global_load_dwordx4 v[164:167], v[90:91], off offset:1408
	global_load_dwordx4 v[168:171], v[84:85], off offset:1408
	global_load_dwordx4 v[172:175], v[86:87], off offset:1408
	global_load_dwordx4 v[176:179], v[88:89], off offset:1408
	s_waitcnt lgkmcnt(0)
	s_barrier
	v_mfma_f32_32x32x16_bf16 v[34:49], v[212:215], v[216:219], v[34:49]
	v_mfma_f32_32x32x16_bf16 v[50:65], v[212:215], v[228:231], v[50:65]
	v_mfma_f32_32x32x16_bf16 v[2:17], v[220:223], v[224:227], v[2:17]
	v_mfma_f32_32x32x16_bf16 v[18:33], v[220:223], v[232:235], v[18:33]
	v_mfma_f32_32x32x16_bf16 v[34:49], v[236:239], v[224:227], v[34:49]
	v_mfma_f32_32x32x16_bf16 v[50:65], v[236:239], v[232:235], v[50:65]
	ds_read_b128 v[212:215], v66 offset:18432
	ds_read_b128 v[216:219], v67 offset:55296
	ds_read_b128 v[220:223], v66 offset:18464
	ds_read_b128 v[224:227], v67 offset:55328
	ds_read_b128 v[228:231], v67 offset:59904
	ds_read_b128 v[232:235], v67 offset:59936
	s_waitcnt lgkmcnt(4)
	v_mfma_f32_32x32x16_bf16 v[2:17], v[212:215], v[216:219], v[2:17]
	s_waitcnt lgkmcnt(1)
	v_mfma_f32_32x32x16_bf16 v[18:33], v[212:215], v[228:231], v[18:33]
	ds_read_b128 v[212:215], v66 offset:23040
	ds_read_b128 v[236:239], v66 offset:23072
	s_waitcnt lgkmcnt(1)
	v_mfma_f32_32x32x16_bf16 v[34:49], v[212:215], v[216:219], v[34:49]
	v_mfma_f32_32x32x16_bf16 v[50:65], v[212:215], v[228:231], v[50:65]
	v_mfma_f32_32x32x16_bf16 v[2:17], v[220:223], v[224:227], v[2:17]
	v_mfma_f32_32x32x16_bf16 v[18:33], v[220:223], v[232:235], v[18:33]
	s_waitcnt lgkmcnt(0)
	v_mfma_f32_32x32x16_bf16 v[34:49], v[236:239], v[224:227], v[34:49]
	ds_read_b128 v[212:215], v66 offset:18496
	ds_read_b128 v[216:219], v67 offset:55360
	ds_read_b128 v[220:223], v66 offset:18528
	ds_read_b128 v[224:227], v67 offset:55392
	v_mfma_f32_32x32x16_bf16 v[50:65], v[236:239], v[232:235], v[50:65]
	ds_read_b128 v[228:231], v67 offset:59968
	ds_read_b128 v[232:235], v67 offset:60000
	s_waitcnt lgkmcnt(4)
	v_mfma_f32_32x32x16_bf16 v[2:17], v[212:215], v[216:219], v[2:17]
	s_waitcnt lgkmcnt(1)
	v_mfma_f32_32x32x16_bf16 v[18:33], v[212:215], v[228:231], v[18:33]
	ds_read_b128 v[212:215], v66 offset:23104
	ds_read_b128 v[236:239], v66 offset:23136
	s_waitcnt vmcnt(13)
	ds_write_b128 v1, v[188:191]
	ds_write_b128 v1, v[180:183] offset:4608
	ds_write_b128 v1, v[184:187] offset:9216
	s_waitcnt vmcnt(11)
	ds_write_b128 v1, v[196:199] offset:13824
	ds_write_b128 v1, v[192:195] offset:36864
	s_waitcnt vmcnt(10)
	ds_write_b128 v1, v[200:203] offset:41472
	s_waitcnt vmcnt(9)
	ds_write_b128 v1, v[204:207] offset:46080
	s_waitcnt vmcnt(8)
	ds_write_b128 v1, v[208:211] offset:50688
	global_load_dwordx4 v[180:183], v[80:81], off offset:1536
	global_load_dwordx4 v[184:187], v[82:83], off offset:1536
	global_load_dwordx4 v[188:191], v[78:79], off offset:1536
	global_load_dwordx4 v[192:195], v[76:77], off offset:1536
	global_load_dwordx4 v[196:199], v[90:91], off offset:1536
	global_load_dwordx4 v[200:203], v[84:85], off offset:1536
	global_load_dwordx4 v[204:207], v[86:87], off offset:1536
	global_load_dwordx4 v[208:211], v[88:89], off offset:1536
	s_waitcnt lgkmcnt(0)
	s_barrier
	v_mfma_f32_32x32x16_bf16 v[34:49], v[212:215], v[216:219], v[34:49]
	v_mfma_f32_32x32x16_bf16 v[50:65], v[212:215], v[228:231], v[50:65]
	v_mfma_f32_32x32x16_bf16 v[2:17], v[220:223], v[224:227], v[2:17]
	v_mfma_f32_32x32x16_bf16 v[18:33], v[220:223], v[232:235], v[18:33]
	v_mfma_f32_32x32x16_bf16 v[34:49], v[236:239], v[224:227], v[34:49]
	v_mfma_f32_32x32x16_bf16 v[50:65], v[236:239], v[232:235], v[50:65]
	ds_read_b128 v[212:215], v66
	ds_read_b128 v[216:219], v67 offset:36864
	ds_read_b128 v[220:223], v66 offset:32
	ds_read_b128 v[224:227], v67 offset:36896
	ds_read_b128 v[228:231], v67 offset:41472
	ds_read_b128 v[232:235], v67 offset:41504
	s_waitcnt lgkmcnt(4)
	v_mfma_f32_32x32x16_bf16 v[2:17], v[212:215], v[216:219], v[2:17]
	s_waitcnt lgkmcnt(1)
	v_mfma_f32_32x32x16_bf16 v[18:33], v[212:215], v[228:231], v[18:33]
	ds_read_b128 v[212:215], v66 offset:4608
	ds_read_b128 v[236:239], v66 offset:4640
	s_waitcnt lgkmcnt(1)
	v_mfma_f32_32x32x16_bf16 v[34:49], v[212:215], v[216:219], v[34:49]
	v_mfma_f32_32x32x16_bf16 v[50:65], v[212:215], v[228:231], v[50:65]
	v_mfma_f32_32x32x16_bf16 v[2:17], v[220:223], v[224:227], v[2:17]
	v_mfma_f32_32x32x16_bf16 v[18:33], v[220:223], v[232:235], v[18:33]
	s_waitcnt lgkmcnt(0)
	v_mfma_f32_32x32x16_bf16 v[34:49], v[236:239], v[224:227], v[34:49]
	ds_read_b128 v[212:215], v66 offset:64
	ds_read_b128 v[216:219], v67 offset:36928
	ds_read_b128 v[220:223], v66 offset:96
	ds_read_b128 v[224:227], v67 offset:36960
	v_mfma_f32_32x32x16_bf16 v[50:65], v[236:239], v[232:235], v[50:65]
	ds_read_b128 v[228:231], v67 offset:41536
	ds_read_b128 v[232:235], v67 offset:41568
	s_waitcnt lgkmcnt(4)
	v_mfma_f32_32x32x16_bf16 v[2:17], v[212:215], v[216:219], v[2:17]
	s_waitcnt lgkmcnt(1)
	v_mfma_f32_32x32x16_bf16 v[18:33], v[212:215], v[228:231], v[18:33]
	ds_read_b128 v[212:215], v66 offset:4672
	ds_read_b128 v[236:239], v66 offset:4704
	s_waitcnt vmcnt(13)
	ds_write_b128 v1, v[156:159] offset:18432
	ds_write_b128 v1, v[148:151] offset:23040
	ds_write_b128 v1, v[152:155] offset:27648
	s_waitcnt vmcnt(11)
	ds_write_b128 v1, v[164:167] offset:32256
	ds_write_b128 v1, v[160:163] offset:55296
	s_waitcnt vmcnt(10)
	ds_write_b128 v1, v[168:171] offset:59904
	s_waitcnt vmcnt(9)
	ds_write_b128 v1, v[172:175] offset:64512
	s_waitcnt vmcnt(8)
	ds_write_b128 v92, v[176:179] offset:32256
	global_load_dwordx4 v[148:151], v[80:81], off offset:1664
	global_load_dwordx4 v[152:155], v[82:83], off offset:1664
	global_load_dwordx4 v[156:159], v[78:79], off offset:1664
	global_load_dwordx4 v[160:163], v[76:77], off offset:1664
	global_load_dwordx4 v[164:167], v[90:91], off offset:1664
	global_load_dwordx4 v[168:171], v[84:85], off offset:1664
	global_load_dwordx4 v[172:175], v[86:87], off offset:1664
	global_load_dwordx4 v[176:179], v[88:89], off offset:1664
	s_waitcnt lgkmcnt(0)
	s_barrier
	v_mfma_f32_32x32x16_bf16 v[34:49], v[212:215], v[216:219], v[34:49]
	v_mfma_f32_32x32x16_bf16 v[50:65], v[212:215], v[228:231], v[50:65]
	v_mfma_f32_32x32x16_bf16 v[2:17], v[220:223], v[224:227], v[2:17]
	v_mfma_f32_32x32x16_bf16 v[18:33], v[220:223], v[232:235], v[18:33]
	v_mfma_f32_32x32x16_bf16 v[34:49], v[236:239], v[224:227], v[34:49]
	v_mfma_f32_32x32x16_bf16 v[50:65], v[236:239], v[232:235], v[50:65]
	ds_read_b128 v[212:215], v66 offset:18432
	ds_read_b128 v[216:219], v67 offset:55296
	ds_read_b128 v[220:223], v66 offset:18464
	ds_read_b128 v[224:227], v67 offset:55328
	ds_read_b128 v[228:231], v67 offset:59904
	ds_read_b128 v[232:235], v67 offset:59936
	s_waitcnt lgkmcnt(4)
	v_mfma_f32_32x32x16_bf16 v[2:17], v[212:215], v[216:219], v[2:17]
	s_waitcnt lgkmcnt(1)
	v_mfma_f32_32x32x16_bf16 v[18:33], v[212:215], v[228:231], v[18:33]
	ds_read_b128 v[212:215], v66 offset:23040
	ds_read_b128 v[236:239], v66 offset:23072
	s_waitcnt lgkmcnt(1)
	v_mfma_f32_32x32x16_bf16 v[34:49], v[212:215], v[216:219], v[34:49]
	v_mfma_f32_32x32x16_bf16 v[50:65], v[212:215], v[228:231], v[50:65]
	v_mfma_f32_32x32x16_bf16 v[2:17], v[220:223], v[224:227], v[2:17]
	v_mfma_f32_32x32x16_bf16 v[18:33], v[220:223], v[232:235], v[18:33]
	s_waitcnt lgkmcnt(0)
	v_mfma_f32_32x32x16_bf16 v[34:49], v[236:239], v[224:227], v[34:49]
	ds_read_b128 v[212:215], v66 offset:18496
	ds_read_b128 v[216:219], v67 offset:55360
	ds_read_b128 v[220:223], v66 offset:18528
	ds_read_b128 v[224:227], v67 offset:55392
	v_mfma_f32_32x32x16_bf16 v[50:65], v[236:239], v[232:235], v[50:65]
	ds_read_b128 v[228:231], v67 offset:59968
	ds_read_b128 v[232:235], v67 offset:60000
	s_waitcnt lgkmcnt(4)
	v_mfma_f32_32x32x16_bf16 v[2:17], v[212:215], v[216:219], v[2:17]
	s_waitcnt lgkmcnt(1)
	v_mfma_f32_32x32x16_bf16 v[18:33], v[212:215], v[228:231], v[18:33]
	ds_read_b128 v[212:215], v66 offset:23104
	ds_read_b128 v[236:239], v66 offset:23136
	s_waitcnt vmcnt(13)
	ds_write_b128 v1, v[188:191]
	ds_write_b128 v1, v[180:183] offset:4608
	ds_write_b128 v1, v[184:187] offset:9216
	s_waitcnt vmcnt(11)
	ds_write_b128 v1, v[196:199] offset:13824
	ds_write_b128 v1, v[192:195] offset:36864
	s_waitcnt vmcnt(10)
	ds_write_b128 v1, v[200:203] offset:41472
	s_waitcnt vmcnt(9)
	ds_write_b128 v1, v[204:207] offset:46080
	s_waitcnt vmcnt(8)
	ds_write_b128 v1, v[208:211] offset:50688
	global_load_dwordx4 v[180:183], v[80:81], off offset:1792
	global_load_dwordx4 v[184:187], v[82:83], off offset:1792
	global_load_dwordx4 v[188:191], v[78:79], off offset:1792
	global_load_dwordx4 v[192:195], v[76:77], off offset:1792
	global_load_dwordx4 v[196:199], v[90:91], off offset:1792
	global_load_dwordx4 v[200:203], v[84:85], off offset:1792
	global_load_dwordx4 v[204:207], v[86:87], off offset:1792
	global_load_dwordx4 v[208:211], v[88:89], off offset:1792
	s_waitcnt lgkmcnt(0)
	s_barrier
	v_mfma_f32_32x32x16_bf16 v[34:49], v[212:215], v[216:219], v[34:49]
	v_mfma_f32_32x32x16_bf16 v[50:65], v[212:215], v[228:231], v[50:65]
	v_mfma_f32_32x32x16_bf16 v[2:17], v[220:223], v[224:227], v[2:17]
	v_mfma_f32_32x32x16_bf16 v[18:33], v[220:223], v[232:235], v[18:33]
	v_mfma_f32_32x32x16_bf16 v[34:49], v[236:239], v[224:227], v[34:49]
	v_mfma_f32_32x32x16_bf16 v[50:65], v[236:239], v[232:235], v[50:65]
	ds_read_b128 v[212:215], v66
	ds_read_b128 v[216:219], v67 offset:36864
	ds_read_b128 v[220:223], v66 offset:32
	ds_read_b128 v[224:227], v67 offset:36896
	ds_read_b128 v[228:231], v67 offset:41472
	ds_read_b128 v[232:235], v67 offset:41504
	s_waitcnt lgkmcnt(4)
	v_mfma_f32_32x32x16_bf16 v[2:17], v[212:215], v[216:219], v[2:17]
	s_waitcnt lgkmcnt(1)
	v_mfma_f32_32x32x16_bf16 v[18:33], v[212:215], v[228:231], v[18:33]
	ds_read_b128 v[212:215], v66 offset:4608
	ds_read_b128 v[236:239], v66 offset:4640
	s_waitcnt lgkmcnt(1)
	v_mfma_f32_32x32x16_bf16 v[34:49], v[212:215], v[216:219], v[34:49]
	v_mfma_f32_32x32x16_bf16 v[50:65], v[212:215], v[228:231], v[50:65]
	v_mfma_f32_32x32x16_bf16 v[2:17], v[220:223], v[224:227], v[2:17]
	v_mfma_f32_32x32x16_bf16 v[18:33], v[220:223], v[232:235], v[18:33]
	s_waitcnt lgkmcnt(0)
	v_mfma_f32_32x32x16_bf16 v[34:49], v[236:239], v[224:227], v[34:49]
	ds_read_b128 v[212:215], v66 offset:64
	ds_read_b128 v[216:219], v67 offset:36928
	ds_read_b128 v[220:223], v66 offset:96
	ds_read_b128 v[224:227], v67 offset:36960
	v_mfma_f32_32x32x16_bf16 v[50:65], v[236:239], v[232:235], v[50:65]
	ds_read_b128 v[228:231], v67 offset:41536
	ds_read_b128 v[232:235], v67 offset:41568
	s_waitcnt lgkmcnt(4)
	v_mfma_f32_32x32x16_bf16 v[2:17], v[212:215], v[216:219], v[2:17]
	s_waitcnt lgkmcnt(1)
	v_mfma_f32_32x32x16_bf16 v[18:33], v[212:215], v[228:231], v[18:33]
	ds_read_b128 v[212:215], v66 offset:4672
	ds_read_b128 v[236:239], v66 offset:4704
	s_waitcnt vmcnt(13)
	ds_write_b128 v1, v[156:159] offset:18432
	ds_write_b128 v1, v[148:151] offset:23040
	ds_write_b128 v1, v[152:155] offset:27648
	s_waitcnt vmcnt(11)
	ds_write_b128 v1, v[164:167] offset:32256
	ds_write_b128 v1, v[160:163] offset:55296
	s_waitcnt vmcnt(10)
	ds_write_b128 v1, v[168:171] offset:59904
	s_waitcnt vmcnt(9)
	ds_write_b128 v1, v[172:175] offset:64512
	s_waitcnt vmcnt(8)
	ds_write_b128 v92, v[176:179] offset:32256
	s_waitcnt lgkmcnt(0)
	s_barrier
	global_load_dwordx4 v[148:151], v[80:81], off offset:1920
	s_nop 0
	global_load_dwordx4 v[80:83], v[82:83], off offset:1920
	s_nop 0
	global_load_dwordx4 v[152:155], v[78:79], off offset:1920
	s_nop 0
	global_load_dwordx4 v[76:79], v[76:77], off offset:1920
	s_nop 0
	global_load_dwordx4 v[156:159], v[90:91], off offset:1920
	global_load_dwordx4 v[160:163], v[84:85], off offset:1920
	s_nop 0
	global_load_dwordx4 v[84:87], v[86:87], off offset:1920
	s_nop 0
	global_load_dwordx4 v[88:91], v[88:89], off offset:1920
	v_mfma_f32_32x32x16_bf16 v[34:49], v[212:215], v[216:219], v[34:49]
	v_mfma_f32_32x32x16_bf16 v[50:65], v[212:215], v[228:231], v[50:65]
	v_mfma_f32_32x32x16_bf16 v[2:17], v[220:223], v[224:227], v[2:17]
	v_mfma_f32_32x32x16_bf16 v[18:33], v[220:223], v[232:235], v[18:33]
	v_mfma_f32_32x32x16_bf16 v[34:49], v[236:239], v[224:227], v[34:49]
	v_mfma_f32_32x32x16_bf16 v[50:65], v[236:239], v[232:235], v[50:65]
	ds_read_b128 v[164:167], v66 offset:18432
	ds_read_b128 v[168:171], v67 offset:55296
	ds_read_b128 v[172:175], v66 offset:18464
	ds_read_b128 v[176:179], v67 offset:55328
	ds_read_b128 v[212:215], v67 offset:59904
	ds_read_b128 v[216:219], v67 offset:59936
	s_waitcnt lgkmcnt(4)
	v_mfma_f32_32x32x16_bf16 v[2:17], v[164:167], v[168:171], v[2:17]
	s_waitcnt lgkmcnt(1)
	v_mfma_f32_32x32x16_bf16 v[18:33], v[164:167], v[212:215], v[18:33]
	ds_read_b128 v[164:167], v66 offset:23040
	ds_read_b128 v[220:223], v66 offset:23072
	s_waitcnt lgkmcnt(1)
	v_mfma_f32_32x32x16_bf16 v[34:49], v[164:167], v[168:171], v[34:49]
	v_mfma_f32_32x32x16_bf16 v[50:65], v[164:167], v[212:215], v[50:65]
	v_mfma_f32_32x32x16_bf16 v[2:17], v[172:175], v[176:179], v[2:17]
	v_mfma_f32_32x32x16_bf16 v[18:33], v[172:175], v[216:219], v[18:33]
	s_waitcnt lgkmcnt(0)
	v_mfma_f32_32x32x16_bf16 v[34:49], v[220:223], v[176:179], v[34:49]
	ds_read_b128 v[164:167], v66 offset:18496
	ds_read_b128 v[168:171], v67 offset:55360
	ds_read_b128 v[172:175], v66 offset:18528
	ds_read_b128 v[176:179], v67 offset:55392
	v_mfma_f32_32x32x16_bf16 v[50:65], v[220:223], v[216:219], v[50:65]
	ds_read_b128 v[212:215], v67 offset:59968
	ds_read_b128 v[216:219], v67 offset:60000
	s_waitcnt lgkmcnt(4)
	v_mfma_f32_32x32x16_bf16 v[2:17], v[164:167], v[168:171], v[2:17]
	s_waitcnt lgkmcnt(1)
	v_mfma_f32_32x32x16_bf16 v[18:33], v[164:167], v[212:215], v[18:33]
	ds_read_b128 v[164:167], v66 offset:23104
	ds_read_b128 v[220:223], v66 offset:23136
	s_waitcnt vmcnt(13)
	ds_write_b128 v1, v[188:191]
	ds_write_b128 v1, v[180:183] offset:4608
	ds_write_b128 v1, v[184:187] offset:9216
	s_waitcnt vmcnt(11)
	ds_write_b128 v1, v[196:199] offset:13824
	ds_write_b128 v1, v[192:195] offset:36864
	s_waitcnt vmcnt(10)
	ds_write_b128 v1, v[200:203] offset:41472
	s_waitcnt vmcnt(9)
	ds_write_b128 v1, v[204:207] offset:46080
	s_waitcnt vmcnt(8)
	ds_write_b128 v1, v[208:211] offset:50688
	s_waitcnt lgkmcnt(0)
	s_barrier
	v_mfma_f32_32x32x16_bf16 v[34:49], v[164:167], v[168:171], v[34:49]
	v_mfma_f32_32x32x16_bf16 v[50:65], v[164:167], v[212:215], v[50:65]
	v_mfma_f32_32x32x16_bf16 v[2:17], v[172:175], v[176:179], v[2:17]
	v_mfma_f32_32x32x16_bf16 v[18:33], v[172:175], v[216:219], v[18:33]
	v_mfma_f32_32x32x16_bf16 v[34:49], v[220:223], v[176:179], v[34:49]
	v_mfma_f32_32x32x16_bf16 v[50:65], v[220:223], v[216:219], v[50:65]
	ds_read_b128 v[164:167], v66
	ds_read_b128 v[168:171], v67 offset:36864
	ds_read_b128 v[172:175], v66 offset:32
	ds_read_b128 v[176:179], v67 offset:36896
	ds_read_b128 v[180:183], v67 offset:41472
	ds_read_b128 v[184:187], v67 offset:41504
	s_waitcnt lgkmcnt(4)
	v_mfma_f32_32x32x16_bf16 v[2:17], v[164:167], v[168:171], v[2:17]
	s_waitcnt lgkmcnt(1)
	v_mfma_f32_32x32x16_bf16 v[18:33], v[164:167], v[180:183], v[18:33]
	ds_read_b128 v[164:167], v66 offset:4608
	ds_read_b128 v[188:191], v66 offset:4640
	s_waitcnt lgkmcnt(1)
	v_mfma_f32_32x32x16_bf16 v[34:49], v[164:167], v[168:171], v[34:49]
	v_mfma_f32_32x32x16_bf16 v[50:65], v[164:167], v[180:183], v[50:65]
	v_mfma_f32_32x32x16_bf16 v[2:17], v[172:175], v[176:179], v[2:17]
	v_mfma_f32_32x32x16_bf16 v[18:33], v[172:175], v[184:187], v[18:33]
	s_waitcnt lgkmcnt(0)
	v_mfma_f32_32x32x16_bf16 v[34:49], v[188:191], v[176:179], v[34:49]
	ds_read_b128 v[164:167], v66 offset:64
	ds_read_b128 v[168:171], v67 offset:36928
	ds_read_b128 v[172:175], v66 offset:96
	ds_read_b128 v[176:179], v67 offset:36960
	v_mfma_f32_32x32x16_bf16 v[50:65], v[188:191], v[184:187], v[50:65]
	ds_read_b128 v[180:183], v67 offset:41536
	ds_read_b128 v[184:187], v67 offset:41568
	s_waitcnt lgkmcnt(4)
	v_mfma_f32_32x32x16_bf16 v[2:17], v[164:167], v[168:171], v[2:17]
	s_waitcnt lgkmcnt(1)
	v_mfma_f32_32x32x16_bf16 v[18:33], v[164:167], v[180:183], v[18:33]
	ds_read_b128 v[164:167], v66 offset:4672
	ds_read_b128 v[188:191], v66 offset:4704
	s_waitcnt vmcnt(5)
	ds_write_b128 v1, v[152:155] offset:18432
	ds_write_b128 v1, v[148:151] offset:23040
	ds_write_b128 v1, v[80:83] offset:27648
	s_waitcnt vmcnt(3)
	ds_write_b128 v1, v[156:159] offset:32256
	ds_write_b128 v1, v[76:79] offset:55296
	s_waitcnt vmcnt(2)
	ds_write_b128 v1, v[160:163] offset:59904
	s_waitcnt vmcnt(1)
	ds_write_b128 v1, v[84:87] offset:64512
	s_waitcnt vmcnt(0)
	ds_write_b128 v92, v[88:91] offset:32256
	s_waitcnt lgkmcnt(0)
	s_barrier
	v_mfma_f32_32x32x16_bf16 v[34:49], v[164:167], v[168:171], v[34:49]
	v_mfma_f32_32x32x16_bf16 v[50:65], v[164:167], v[180:183], v[50:65]
	v_mfma_f32_32x32x16_bf16 v[2:17], v[172:175], v[176:179], v[2:17]
	v_mfma_f32_32x32x16_bf16 v[18:33], v[172:175], v[184:187], v[18:33]
	v_mfma_f32_32x32x16_bf16 v[34:49], v[188:191], v[176:179], v[34:49]
	v_mfma_f32_32x32x16_bf16 v[50:65], v[188:191], v[184:187], v[50:65]
	ds_read_b128 v[76:79], v66 offset:18432
	ds_read_b128 v[80:83], v67 offset:55296
	ds_read_b128 v[84:87], v66 offset:18464
	ds_read_b128 v[88:91], v67 offset:55328
	ds_read_b128 v[148:151], v67 offset:59904
	ds_read_b128 v[152:155], v67 offset:59936
	v_or_b32_e32 v68, s8, v94
	s_waitcnt lgkmcnt(4)
	v_mfma_f32_32x32x16_bf16 v[2:17], v[76:79], v[80:83], v[2:17]
	s_lshl_b32 s10, s10, 1
	s_mov_b32 s11, s9
	s_add_i32 s12, s12, s13
	s_add_i32 s14, s14, s15
	s_add_i32 s16, s16, s17
	s_cmpk_lt_u32 s12, 0x400
	s_waitcnt lgkmcnt(1)
	v_mfma_f32_32x32x16_bf16 v[18:33], v[76:79], v[148:151], v[18:33]
	ds_read_b128 v[76:79], v66 offset:23040
	ds_read_b128 v[156:159], v66 offset:23072
	s_waitcnt lgkmcnt(1)
	v_mfma_f32_32x32x16_bf16 v[34:49], v[76:79], v[80:83], v[34:49]
	v_mfma_f32_32x32x16_bf16 v[50:65], v[76:79], v[148:151], v[50:65]
	v_mfma_f32_32x32x16_bf16 v[2:17], v[84:87], v[88:91], v[2:17]
	v_mfma_f32_32x32x16_bf16 v[18:33], v[84:87], v[152:155], v[18:33]
	s_waitcnt lgkmcnt(0)
	v_mfma_f32_32x32x16_bf16 v[34:49], v[156:159], v[88:91], v[34:49]
	ds_read_b128 v[76:79], v66 offset:18496
	ds_read_b128 v[80:83], v67 offset:55360
	ds_read_b128 v[84:87], v66 offset:18528
	ds_read_b128 v[88:91], v67 offset:55392
	v_mfma_f32_32x32x16_bf16 v[50:65], v[156:159], v[152:155], v[50:65]
	ds_read_b128 v[148:151], v67 offset:59968
	ds_read_b128 v[152:155], v67 offset:60000
	s_waitcnt lgkmcnt(4)
	v_mfma_f32_32x32x16_bf16 v[2:17], v[76:79], v[80:83], v[2:17]
	s_waitcnt lgkmcnt(1)
	v_mfma_f32_32x32x16_bf16 v[18:33], v[76:79], v[148:151], v[18:33]
	ds_read_b128 v[76:79], v66 offset:23104
	ds_read_b128 v[156:159], v66 offset:23136
	s_waitcnt lgkmcnt(0)
	s_barrier
	v_mfma_f32_32x32x16_bf16 v[34:49], v[76:79], v[80:83], v[34:49]
	v_mfma_f32_32x32x16_bf16 v[50:65], v[76:79], v[148:151], v[50:65]
	v_mfma_f32_32x32x16_bf16 v[2:17], v[84:87], v[88:91], v[2:17]
	v_mfma_f32_32x32x16_bf16 v[18:33], v[84:87], v[152:155], v[18:33]
	v_mfma_f32_32x32x16_bf16 v[34:49], v[156:159], v[88:91], v[34:49]
	s_nop 10
	ds_write2_b32 v93, v2, v18 offset1:32
	v_mfma_f32_32x32x16_bf16 v[50:65], v[156:159], v[152:155], v[50:65]
	s_nop 11
	ds_write2_b32 v132, v34, v50 offset0:32 offset1:64
	ds_write2_b32 v93, v3, v19 offset0:129 offset1:161
	ds_write2_b32 v132, v35, v51 offset0:161 offset1:193
	ds_write2_b32 v133, v4, v20 offset0:2 offset1:34
	ds_write2_b32 v134, v36, v52 offset0:34 offset1:66
	ds_write2_b32 v133, v5, v21 offset0:131 offset1:163
	ds_write2_b32 v134, v37, v53 offset0:163 offset1:195
	ds_write2_b32 v135, v6, v22 offset0:8 offset1:40
	ds_write2_b32 v136, v38, v54 offset0:40 offset1:72
	ds_write2_b32 v135, v7, v23 offset0:137 offset1:169
	ds_write2_b32 v136, v39, v55 offset0:169 offset1:201
	ds_write2_b32 v137, v8, v24 offset0:10 offset1:42
	ds_write2_b32 v138, v40, v56 offset0:42 offset1:74
	ds_write2_b32 v137, v9, v25 offset0:139 offset1:171
	ds_write2_b32 v138, v41, v57 offset0:171 offset1:203
	ds_write2_b32 v139, v10, v26 offset0:16 offset1:48
	ds_write2_b32 v140, v42, v58 offset0:48 offset1:80
	ds_write2_b32 v139, v11, v27 offset0:145 offset1:177
	ds_write2_b32 v140, v43, v59 offset0:177 offset1:209
	ds_write2_b32 v141, v12, v28 offset0:18 offset1:50
	ds_write2_b32 v142, v44, v60 offset0:50 offset1:82
	ds_write2_b32 v141, v13, v29 offset0:147 offset1:179
	ds_write2_b32 v142, v45, v61 offset0:179 offset1:211
	ds_write2_b32 v143, v14, v30 offset0:24 offset1:56
	ds_write2_b32 v144, v46, v62 offset0:56 offset1:88
	ds_write2_b32 v143, v15, v31 offset0:153 offset1:185
	ds_write2_b32 v144, v47, v63 offset0:185 offset1:217
	ds_write2_b32 v145, v16, v32 offset0:26 offset1:58
	ds_write2_b32 v146, v48, v64 offset0:58 offset1:90
	ds_write2_b32 v145, v17, v33 offset0:155 offset1:187
	ds_write2_b32 v146, v49, v65 offset0:187 offset1:219
	v_lshl_add_u64 v[2:3], v[68:69], 2, s[6:7]
	s_waitcnt lgkmcnt(0)
	s_barrier
	v_mov_b32_e32 v2, v68
	v_lshlrev_b32_e32 v3, 2, v2
	global_load_dword v5, v3, s[6:7]
	global_load_dword v6, v3, s[6:7] offset:64
	global_load_dword v7, v3, s[6:7] offset:128
	global_load_dword v8, v3, s[6:7] offset:192
	global_load_dword v9, v3, s[6:7] offset:256
	global_load_dword v10, v3, s[6:7] offset:320
	global_load_dword v11, v3, s[6:7] offset:384
	global_load_dword v12, v3, s[6:7] offset:448
	v_lshlrev_b32_e32 v4, 13, v2
	v_add3_u32 v4, v4, v74, s10
	s_movk_i32 s24, 0x7fff
	v_mov_b32_e32 v59, 1
	v_mov_b32_e32 v13, 0x358637bd
	ds_read2_b32 v[14:15], v103 offset0:0 offset1:1
	ds_read2_b32 v[16:17], v103 offset0:2 offset1:3
	ds_read2_b32 v[18:19], v103 offset0:4 offset1:5
	ds_read2_b32 v[20:21], v103 offset0:6 offset1:7
	v_add_u32_e32 v56, 0x2040, v103
	ds_read2_b32 v[22:23], v56 offset0:0 offset1:1
	ds_read2_b32 v[24:25], v56 offset0:2 offset1:3
	ds_read2_b32 v[26:27], v56 offset0:4 offset1:5
	ds_read2_b32 v[28:29], v56 offset0:6 offset1:7
	s_waitcnt vmcnt(7) lgkmcnt(4)
	v_fmamk_f32 v54, v5, 0x3a800000, v13
	v_rsq_f32_e32 v54, v54
	s_nop 0
	v_mul_f32_e32 v14, v14, v54
	v_mul_f32_e32 v15, v15, v54
	v_mul_f32_e32 v16, v16, v54
	v_mul_f32_e32 v17, v17, v54
	v_mul_f32_e32 v18, v18, v54
	v_mul_f32_e32 v19, v19, v54
	v_mul_f32_e32 v20, v20, v54
	v_mul_f32_e32 v21, v21, v54
	v_max_f32_e32 v14, 0, v14
	v_max_f32_e32 v15, 0, v15
	v_max_f32_e32 v16, 0, v16
	v_max_f32_e32 v17, 0, v17
	v_max_f32_e32 v18, 0, v18
	v_max_f32_e32 v19, 0, v19
	v_max_f32_e32 v20, 0, v20
	v_max_f32_e32 v21, 0, v21
	v_pk_mul_f32 v[14:15], v[14:15], v[14:15]
	v_pk_mul_f32 v[16:17], v[16:17], v[16:17]
	v_pk_mul_f32 v[18:19], v[18:19], v[18:19]
	v_pk_mul_f32 v[20:21], v[20:21], v[20:21]
	v_and_b32_sdwa v46, v14, v59 dst_sel:DWORD dst_unused:UNUSED_PAD src0_sel:WORD_1 src1_sel:DWORD
	v_and_b32_sdwa v47, v15, v59 dst_sel:DWORD dst_unused:UNUSED_PAD src0_sel:WORD_1 src1_sel:DWORD
	v_and_b32_sdwa v48, v16, v59 dst_sel:DWORD dst_unused:UNUSED_PAD src0_sel:WORD_1 src1_sel:DWORD
	v_and_b32_sdwa v49, v17, v59 dst_sel:DWORD dst_unused:UNUSED_PAD src0_sel:WORD_1 src1_sel:DWORD
	v_and_b32_sdwa v50, v18, v59 dst_sel:DWORD dst_unused:UNUSED_PAD src0_sel:WORD_1 src1_sel:DWORD
	v_and_b32_sdwa v51, v19, v59 dst_sel:DWORD dst_unused:UNUSED_PAD src0_sel:WORD_1 src1_sel:DWORD
	v_and_b32_sdwa v52, v20, v59 dst_sel:DWORD dst_unused:UNUSED_PAD src0_sel:WORD_1 src1_sel:DWORD
	v_and_b32_sdwa v53, v21, v59 dst_sel:DWORD dst_unused:UNUSED_PAD src0_sel:WORD_1 src1_sel:DWORD
	v_add3_u32 v14, v14, v46, s24
	v_add3_u32 v15, v15, v47, s24
	v_add3_u32 v16, v16, v48, s24
	v_add3_u32 v17, v17, v49, s24
	v_add3_u32 v18, v18, v50, s24
	v_add3_u32 v19, v19, v51, s24
	v_add3_u32 v20, v20, v52, s24
	v_add3_u32 v21, v21, v53, s24
	v_and_b32_e32 v15, 0xffff0000, v15
	v_and_b32_e32 v17, 0xffff0000, v17
	v_and_b32_e32 v19, 0xffff0000, v19
	v_and_b32_e32 v21, 0xffff0000, v21
	v_or_b32_sdwa v60, v15, v14 dst_sel:DWORD dst_unused:UNUSED_PAD src0_sel:DWORD src1_sel:WORD_1
	v_or_b32_sdwa v61, v17, v16 dst_sel:DWORD dst_unused:UNUSED_PAD src0_sel:DWORD src1_sel:WORD_1
	v_or_b32_sdwa v62, v19, v18 dst_sel:DWORD dst_unused:UNUSED_PAD src0_sel:DWORD src1_sel:WORD_1
	v_or_b32_sdwa v63, v21, v20 dst_sel:DWORD dst_unused:UNUSED_PAD src0_sel:DWORD src1_sel:WORD_1
	global_store_dwordx4 v4, v[60:63], s[56:57]
	v_add_u32_e32 v55, 0x4080, v103
	ds_read2_b32 v[30:31], v55 offset0:0 offset1:1
	ds_read2_b32 v[32:33], v55 offset0:2 offset1:3
	ds_read2_b32 v[34:35], v55 offset0:4 offset1:5
	ds_read2_b32 v[36:37], v55 offset0:6 offset1:7
	v_add_u32_e32 v56, 0x60c0, v103
	ds_read2_b32 v[38:39], v56 offset0:0 offset1:1
	ds_read2_b32 v[40:41], v56 offset0:2 offset1:3
	ds_read2_b32 v[42:43], v56 offset0:4 offset1:5
	ds_read2_b32 v[44:45], v56 offset0:6 offset1:7
	s_waitcnt vmcnt(7) lgkmcnt(8)
	v_fmamk_f32 v54, v6, 0x3a800000, v13
	v_rsq_f32_e32 v54, v54
	v_add_u32_e32 v58, 0x20000, v4
	v_mul_f32_e32 v22, v22, v54
	v_mul_f32_e32 v23, v23, v54
	v_mul_f32_e32 v24, v24, v54
	v_mul_f32_e32 v25, v25, v54
	v_mul_f32_e32 v26, v26, v54
	v_mul_f32_e32 v27, v27, v54
	v_mul_f32_e32 v28, v28, v54
	v_mul_f32_e32 v29, v29, v54
	v_max_f32_e32 v22, 0, v22
	v_max_f32_e32 v23, 0, v23
	v_max_f32_e32 v24, 0, v24
	v_max_f32_e32 v25, 0, v25
	v_max_f32_e32 v26, 0, v26
	v_max_f32_e32 v27, 0, v27
	v_max_f32_e32 v28, 0, v28
	v_max_f32_e32 v29, 0, v29
	v_pk_mul_f32 v[22:23], v[22:23], v[22:23]
	v_pk_mul_f32 v[24:25], v[24:25], v[24:25]
	v_pk_mul_f32 v[26:27], v[26:27], v[26:27]
	v_pk_mul_f32 v[28:29], v[28:29], v[28:29]
	v_and_b32_sdwa v46, v22, v59 dst_sel:DWORD dst_unused:UNUSED_PAD src0_sel:WORD_1 src1_sel:DWORD
	v_and_b32_sdwa v47, v23, v59 dst_sel:DWORD dst_unused:UNUSED_PAD src0_sel:WORD_1 src1_sel:DWORD
	v_and_b32_sdwa v48, v24, v59 dst_sel:DWORD dst_unused:UNUSED_PAD src0_sel:WORD_1 src1_sel:DWORD
	v_and_b32_sdwa v49, v25, v59 dst_sel:DWORD dst_unused:UNUSED_PAD src0_sel:WORD_1 src1_sel:DWORD
	v_and_b32_sdwa v50, v26, v59 dst_sel:DWORD dst_unused:UNUSED_PAD src0_sel:WORD_1 src1_sel:DWORD
	v_and_b32_sdwa v51, v27, v59 dst_sel:DWORD dst_unused:UNUSED_PAD src0_sel:WORD_1 src1_sel:DWORD
	v_and_b32_sdwa v52, v28, v59 dst_sel:DWORD dst_unused:UNUSED_PAD src0_sel:WORD_1 src1_sel:DWORD
	v_and_b32_sdwa v53, v29, v59 dst_sel:DWORD dst_unused:UNUSED_PAD src0_sel:WORD_1 src1_sel:DWORD
	v_add3_u32 v22, v22, v46, s24
	v_add3_u32 v23, v23, v47, s24
	v_add3_u32 v24, v24, v48, s24
	v_add3_u32 v25, v25, v49, s24
	v_add3_u32 v26, v26, v50, s24
	v_add3_u32 v27, v27, v51, s24
	v_add3_u32 v28, v28, v52, s24
	v_add3_u32 v29, v29, v53, s24
	v_and_b32_e32 v23, 0xffff0000, v23
	v_and_b32_e32 v25, 0xffff0000, v25
	v_and_b32_e32 v27, 0xffff0000, v27
	v_and_b32_e32 v29, 0xffff0000, v29
	v_or_b32_sdwa v76, v23, v22 dst_sel:DWORD dst_unused:UNUSED_PAD src0_sel:DWORD src1_sel:WORD_1
	v_or_b32_sdwa v77, v25, v24 dst_sel:DWORD dst_unused:UNUSED_PAD src0_sel:DWORD src1_sel:WORD_1
	v_or_b32_sdwa v78, v27, v26 dst_sel:DWORD dst_unused:UNUSED_PAD src0_sel:DWORD src1_sel:WORD_1
	v_or_b32_sdwa v79, v29, v28 dst_sel:DWORD dst_unused:UNUSED_PAD src0_sel:DWORD src1_sel:WORD_1
	global_store_dwordx4 v58, v[76:79], s[56:57]
	s_waitcnt vmcnt(7) lgkmcnt(4)
	v_fmamk_f32 v54, v7, 0x3a800000, v13
	v_rsq_f32_e32 v54, v54
	v_add_u32_e32 v57, 0x40000, v4
	v_mul_f32_e32 v30, v30, v54
	v_mul_f32_e32 v31, v31, v54
	v_mul_f32_e32 v32, v32, v54
	v_mul_f32_e32 v33, v33, v54
	v_mul_f32_e32 v34, v34, v54
	v_mul_f32_e32 v35, v35, v54
	v_mul_f32_e32 v36, v36, v54
	v_mul_f32_e32 v37, v37, v54
	v_max_f32_e32 v30, 0, v30
	v_max_f32_e32 v31, 0, v31
	v_max_f32_e32 v32, 0, v32
	v_max_f32_e32 v33, 0, v33
	v_max_f32_e32 v34, 0, v34
	v_max_f32_e32 v35, 0, v35
	v_max_f32_e32 v36, 0, v36
	v_max_f32_e32 v37, 0, v37
	v_pk_mul_f32 v[30:31], v[30:31], v[30:31]
	v_pk_mul_f32 v[32:33], v[32:33], v[32:33]
	v_pk_mul_f32 v[34:35], v[34:35], v[34:35]
	v_pk_mul_f32 v[36:37], v[36:37], v[36:37]
	v_and_b32_sdwa v46, v30, v59 dst_sel:DWORD dst_unused:UNUSED_PAD src0_sel:WORD_1 src1_sel:DWORD
	v_and_b32_sdwa v47, v31, v59 dst_sel:DWORD dst_unused:UNUSED_PAD src0_sel:WORD_1 src1_sel:DWORD
	v_and_b32_sdwa v48, v32, v59 dst_sel:DWORD dst_unused:UNUSED_PAD src0_sel:WORD_1 src1_sel:DWORD
	v_and_b32_sdwa v49, v33, v59 dst_sel:DWORD dst_unused:UNUSED_PAD src0_sel:WORD_1 src1_sel:DWORD
	v_and_b32_sdwa v50, v34, v59 dst_sel:DWORD dst_unused:UNUSED_PAD src0_sel:WORD_1 src1_sel:DWORD
	v_and_b32_sdwa v51, v35, v59 dst_sel:DWORD dst_unused:UNUSED_PAD src0_sel:WORD_1 src1_sel:DWORD
	v_and_b32_sdwa v52, v36, v59 dst_sel:DWORD dst_unused:UNUSED_PAD src0_sel:WORD_1 src1_sel:DWORD
	v_and_b32_sdwa v53, v37, v59 dst_sel:DWORD dst_unused:UNUSED_PAD src0_sel:WORD_1 src1_sel:DWORD
	v_add3_u32 v30, v30, v46, s24
	v_add3_u32 v31, v31, v47, s24
	v_add3_u32 v32, v32, v48, s24
	v_add3_u32 v33, v33, v49, s24
	v_add3_u32 v34, v34, v50, s24
	v_add3_u32 v35, v35, v51, s24
	v_add3_u32 v36, v36, v52, s24
	v_add3_u32 v37, v37, v53, s24
	v_and_b32_e32 v31, 0xffff0000, v31
	v_and_b32_e32 v33, 0xffff0000, v33
	v_and_b32_e32 v35, 0xffff0000, v35
	v_and_b32_e32 v37, 0xffff0000, v37
	v_or_b32_sdwa v60, v31, v30 dst_sel:DWORD dst_unused:UNUSED_PAD src0_sel:DWORD src1_sel:WORD_1
	v_or_b32_sdwa v61, v33, v32 dst_sel:DWORD dst_unused:UNUSED_PAD src0_sel:DWORD src1_sel:WORD_1
	v_or_b32_sdwa v62, v35, v34 dst_sel:DWORD dst_unused:UNUSED_PAD src0_sel:DWORD src1_sel:WORD_1
	v_or_b32_sdwa v63, v37, v36 dst_sel:DWORD dst_unused:UNUSED_PAD src0_sel:DWORD src1_sel:WORD_1
	global_store_dwordx4 v57, v[60:63], s[56:57]
	v_add_u32_e32 v55, 0x8100, v103
	ds_read2_b32 v[14:15], v55 offset0:0 offset1:1
	ds_read2_b32 v[16:17], v55 offset0:2 offset1:3
	ds_read2_b32 v[18:19], v55 offset0:4 offset1:5
	ds_read2_b32 v[20:21], v55 offset0:6 offset1:7
	v_add_u32_e32 v56, 0xa140, v103
	ds_read2_b32 v[22:23], v56 offset0:0 offset1:1
	ds_read2_b32 v[24:25], v56 offset0:2 offset1:3
	ds_read2_b32 v[26:27], v56 offset0:4 offset1:5
	ds_read2_b32 v[28:29], v56 offset0:6 offset1:7
	s_waitcnt vmcnt(7) lgkmcnt(8)
	v_fmamk_f32 v54, v8, 0x3a800000, v13
	v_rsq_f32_e32 v54, v54
	v_add_u32_e32 v58, 0x60000, v4
	v_mul_f32_e32 v38, v38, v54
	v_mul_f32_e32 v39, v39, v54
	v_mul_f32_e32 v40, v40, v54
	v_mul_f32_e32 v41, v41, v54
	v_mul_f32_e32 v42, v42, v54
	v_mul_f32_e32 v43, v43, v54
	v_mul_f32_e32 v44, v44, v54
	v_mul_f32_e32 v45, v45, v54
	v_max_f32_e32 v38, 0, v38
	v_max_f32_e32 v39, 0, v39
	v_max_f32_e32 v40, 0, v40
	v_max_f32_e32 v41, 0, v41
	v_max_f32_e32 v42, 0, v42
	v_max_f32_e32 v43, 0, v43
	v_max_f32_e32 v44, 0, v44
	v_max_f32_e32 v45, 0, v45
	v_pk_mul_f32 v[38:39], v[38:39], v[38:39]
	v_pk_mul_f32 v[40:41], v[40:41], v[40:41]
	v_pk_mul_f32 v[42:43], v[42:43], v[42:43]
	v_pk_mul_f32 v[44:45], v[44:45], v[44:45]
	v_and_b32_sdwa v46, v38, v59 dst_sel:DWORD dst_unused:UNUSED_PAD src0_sel:WORD_1 src1_sel:DWORD
	v_and_b32_sdwa v47, v39, v59 dst_sel:DWORD dst_unused:UNUSED_PAD src0_sel:WORD_1 src1_sel:DWORD
	v_and_b32_sdwa v48, v40, v59 dst_sel:DWORD dst_unused:UNUSED_PAD src0_sel:WORD_1 src1_sel:DWORD
	v_and_b32_sdwa v49, v41, v59 dst_sel:DWORD dst_unused:UNUSED_PAD src0_sel:WORD_1 src1_sel:DWORD
	v_and_b32_sdwa v50, v42, v59 dst_sel:DWORD dst_unused:UNUSED_PAD src0_sel:WORD_1 src1_sel:DWORD
	v_and_b32_sdwa v51, v43, v59 dst_sel:DWORD dst_unused:UNUSED_PAD src0_sel:WORD_1 src1_sel:DWORD
	v_and_b32_sdwa v52, v44, v59 dst_sel:DWORD dst_unused:UNUSED_PAD src0_sel:WORD_1 src1_sel:DWORD
	v_and_b32_sdwa v53, v45, v59 dst_sel:DWORD dst_unused:UNUSED_PAD src0_sel:WORD_1 src1_sel:DWORD
	v_add3_u32 v38, v38, v46, s24
	v_add3_u32 v39, v39, v47, s24
	v_add3_u32 v40, v40, v48, s24
	v_add3_u32 v41, v41, v49, s24
	v_add3_u32 v42, v42, v50, s24
	v_add3_u32 v43, v43, v51, s24
	v_add3_u32 v44, v44, v52, s24
	v_add3_u32 v45, v45, v53, s24
	v_and_b32_e32 v39, 0xffff0000, v39
	v_and_b32_e32 v41, 0xffff0000, v41
	v_and_b32_e32 v43, 0xffff0000, v43
	v_and_b32_e32 v45, 0xffff0000, v45
	v_or_b32_sdwa v76, v39, v38 dst_sel:DWORD dst_unused:UNUSED_PAD src0_sel:DWORD src1_sel:WORD_1
	v_or_b32_sdwa v77, v41, v40 dst_sel:DWORD dst_unused:UNUSED_PAD src0_sel:DWORD src1_sel:WORD_1
	v_or_b32_sdwa v78, v43, v42 dst_sel:DWORD dst_unused:UNUSED_PAD src0_sel:DWORD src1_sel:WORD_1
	v_or_b32_sdwa v79, v45, v44 dst_sel:DWORD dst_unused:UNUSED_PAD src0_sel:DWORD src1_sel:WORD_1
	global_store_dwordx4 v58, v[76:79], s[56:57]
	s_waitcnt vmcnt(7) lgkmcnt(4)
	v_fmamk_f32 v54, v9, 0x3a800000, v13
	v_rsq_f32_e32 v54, v54
	v_add_u32_e32 v57, 0x80000, v4
	v_mul_f32_e32 v14, v14, v54
	v_mul_f32_e32 v15, v15, v54
	v_mul_f32_e32 v16, v16, v54
	v_mul_f32_e32 v17, v17, v54
	v_mul_f32_e32 v18, v18, v54
	v_mul_f32_e32 v19, v19, v54
	v_mul_f32_e32 v20, v20, v54
	v_mul_f32_e32 v21, v21, v54
	v_max_f32_e32 v14, 0, v14
	v_max_f32_e32 v15, 0, v15
	v_max_f32_e32 v16, 0, v16
	v_max_f32_e32 v17, 0, v17
	v_max_f32_e32 v18, 0, v18
	v_max_f32_e32 v19, 0, v19
	v_max_f32_e32 v20, 0, v20
	v_max_f32_e32 v21, 0, v21
	v_pk_mul_f32 v[14:15], v[14:15], v[14:15]
	v_pk_mul_f32 v[16:17], v[16:17], v[16:17]
	v_pk_mul_f32 v[18:19], v[18:19], v[18:19]
	v_pk_mul_f32 v[20:21], v[20:21], v[20:21]
	v_and_b32_sdwa v46, v14, v59 dst_sel:DWORD dst_unused:UNUSED_PAD src0_sel:WORD_1 src1_sel:DWORD
	v_and_b32_sdwa v47, v15, v59 dst_sel:DWORD dst_unused:UNUSED_PAD src0_sel:WORD_1 src1_sel:DWORD
	v_and_b32_sdwa v48, v16, v59 dst_sel:DWORD dst_unused:UNUSED_PAD src0_sel:WORD_1 src1_sel:DWORD
	v_and_b32_sdwa v49, v17, v59 dst_sel:DWORD dst_unused:UNUSED_PAD src0_sel:WORD_1 src1_sel:DWORD
	v_and_b32_sdwa v50, v18, v59 dst_sel:DWORD dst_unused:UNUSED_PAD src0_sel:WORD_1 src1_sel:DWORD
	v_and_b32_sdwa v51, v19, v59 dst_sel:DWORD dst_unused:UNUSED_PAD src0_sel:WORD_1 src1_sel:DWORD
	v_and_b32_sdwa v52, v20, v59 dst_sel:DWORD dst_unused:UNUSED_PAD src0_sel:WORD_1 src1_sel:DWORD
	v_and_b32_sdwa v53, v21, v59 dst_sel:DWORD dst_unused:UNUSED_PAD src0_sel:WORD_1 src1_sel:DWORD
	v_add3_u32 v14, v14, v46, s24
	v_add3_u32 v15, v15, v47, s24
	v_add3_u32 v16, v16, v48, s24
	v_add3_u32 v17, v17, v49, s24
	v_add3_u32 v18, v18, v50, s24
	v_add3_u32 v19, v19, v51, s24
	v_add3_u32 v20, v20, v52, s24
	v_add3_u32 v21, v21, v53, s24
	v_and_b32_e32 v15, 0xffff0000, v15
	v_and_b32_e32 v17, 0xffff0000, v17
	v_and_b32_e32 v19, 0xffff0000, v19
	v_and_b32_e32 v21, 0xffff0000, v21
	v_or_b32_sdwa v60, v15, v14 dst_sel:DWORD dst_unused:UNUSED_PAD src0_sel:DWORD src1_sel:WORD_1
	v_or_b32_sdwa v61, v17, v16 dst_sel:DWORD dst_unused:UNUSED_PAD src0_sel:DWORD src1_sel:WORD_1
	v_or_b32_sdwa v62, v19, v18 dst_sel:DWORD dst_unused:UNUSED_PAD src0_sel:DWORD src1_sel:WORD_1
	v_or_b32_sdwa v63, v21, v20 dst_sel:DWORD dst_unused:UNUSED_PAD src0_sel:DWORD src1_sel:WORD_1
	global_store_dwordx4 v57, v[60:63], s[56:57]
	v_add_u32_e32 v55, 0xc180, v103
	ds_read2_b32 v[30:31], v55 offset0:0 offset1:1
	ds_read2_b32 v[32:33], v55 offset0:2 offset1:3
	ds_read2_b32 v[34:35], v55 offset0:4 offset1:5
	ds_read2_b32 v[36:37], v55 offset0:6 offset1:7
	v_add_u32_e32 v56, 0xe1c0, v103
	ds_read2_b32 v[38:39], v56 offset0:0 offset1:1
	ds_read2_b32 v[40:41], v56 offset0:2 offset1:3
	ds_read2_b32 v[42:43], v56 offset0:4 offset1:5
	ds_read2_b32 v[44:45], v56 offset0:6 offset1:7
	s_waitcnt vmcnt(7) lgkmcnt(8)
	v_fmamk_f32 v54, v10, 0x3a800000, v13
	v_rsq_f32_e32 v54, v54
	v_add_u32_e32 v58, 0xa0000, v4
	v_mul_f32_e32 v22, v22, v54
	v_mul_f32_e32 v23, v23, v54
	v_mul_f32_e32 v24, v24, v54
	v_mul_f32_e32 v25, v25, v54
	v_mul_f32_e32 v26, v26, v54
	v_mul_f32_e32 v27, v27, v54
	v_mul_f32_e32 v28, v28, v54
	v_mul_f32_e32 v29, v29, v54
	v_max_f32_e32 v22, 0, v22
	v_max_f32_e32 v23, 0, v23
	v_max_f32_e32 v24, 0, v24
	v_max_f32_e32 v25, 0, v25
	v_max_f32_e32 v26, 0, v26
	v_max_f32_e32 v27, 0, v27
	v_max_f32_e32 v28, 0, v28
	v_max_f32_e32 v29, 0, v29
	v_pk_mul_f32 v[22:23], v[22:23], v[22:23]
	v_pk_mul_f32 v[24:25], v[24:25], v[24:25]
	v_pk_mul_f32 v[26:27], v[26:27], v[26:27]
	v_pk_mul_f32 v[28:29], v[28:29], v[28:29]
	v_and_b32_sdwa v46, v22, v59 dst_sel:DWORD dst_unused:UNUSED_PAD src0_sel:WORD_1 src1_sel:DWORD
	v_and_b32_sdwa v47, v23, v59 dst_sel:DWORD dst_unused:UNUSED_PAD src0_sel:WORD_1 src1_sel:DWORD
	v_and_b32_sdwa v48, v24, v59 dst_sel:DWORD dst_unused:UNUSED_PAD src0_sel:WORD_1 src1_sel:DWORD
	v_and_b32_sdwa v49, v25, v59 dst_sel:DWORD dst_unused:UNUSED_PAD src0_sel:WORD_1 src1_sel:DWORD
	v_and_b32_sdwa v50, v26, v59 dst_sel:DWORD dst_unused:UNUSED_PAD src0_sel:WORD_1 src1_sel:DWORD
	v_and_b32_sdwa v51, v27, v59 dst_sel:DWORD dst_unused:UNUSED_PAD src0_sel:WORD_1 src1_sel:DWORD
	v_and_b32_sdwa v52, v28, v59 dst_sel:DWORD dst_unused:UNUSED_PAD src0_sel:WORD_1 src1_sel:DWORD
	v_and_b32_sdwa v53, v29, v59 dst_sel:DWORD dst_unused:UNUSED_PAD src0_sel:WORD_1 src1_sel:DWORD
	v_add3_u32 v22, v22, v46, s24
	v_add3_u32 v23, v23, v47, s24
	v_add3_u32 v24, v24, v48, s24
	v_add3_u32 v25, v25, v49, s24
	v_add3_u32 v26, v26, v50, s24
	v_add3_u32 v27, v27, v51, s24
	v_add3_u32 v28, v28, v52, s24
	v_add3_u32 v29, v29, v53, s24
	v_and_b32_e32 v23, 0xffff0000, v23
	v_and_b32_e32 v25, 0xffff0000, v25
	v_and_b32_e32 v27, 0xffff0000, v27
	v_and_b32_e32 v29, 0xffff0000, v29
	v_or_b32_sdwa v76, v23, v22 dst_sel:DWORD dst_unused:UNUSED_PAD src0_sel:DWORD src1_sel:WORD_1
	v_or_b32_sdwa v77, v25, v24 dst_sel:DWORD dst_unused:UNUSED_PAD src0_sel:DWORD src1_sel:WORD_1
	v_or_b32_sdwa v78, v27, v26 dst_sel:DWORD dst_unused:UNUSED_PAD src0_sel:DWORD src1_sel:WORD_1
	v_or_b32_sdwa v79, v29, v28 dst_sel:DWORD dst_unused:UNUSED_PAD src0_sel:DWORD src1_sel:WORD_1
	global_store_dwordx4 v58, v[76:79], s[56:57]
	s_waitcnt vmcnt(7) lgkmcnt(4)
	v_fmamk_f32 v54, v11, 0x3a800000, v13
	v_rsq_f32_e32 v54, v54
	v_add_u32_e32 v57, 0xc0000, v4
	v_mul_f32_e32 v30, v30, v54
	v_mul_f32_e32 v31, v31, v54
	v_mul_f32_e32 v32, v32, v54
	v_mul_f32_e32 v33, v33, v54
	v_mul_f32_e32 v34, v34, v54
	v_mul_f32_e32 v35, v35, v54
	v_mul_f32_e32 v36, v36, v54
	v_mul_f32_e32 v37, v37, v54
	v_max_f32_e32 v30, 0, v30
	v_max_f32_e32 v31, 0, v31
	v_max_f32_e32 v32, 0, v32
	v_max_f32_e32 v33, 0, v33
	v_max_f32_e32 v34, 0, v34
	v_max_f32_e32 v35, 0, v35
	v_max_f32_e32 v36, 0, v36
	v_max_f32_e32 v37, 0, v37
	v_pk_mul_f32 v[30:31], v[30:31], v[30:31]
	v_pk_mul_f32 v[32:33], v[32:33], v[32:33]
	v_pk_mul_f32 v[34:35], v[34:35], v[34:35]
	v_pk_mul_f32 v[36:37], v[36:37], v[36:37]
	v_and_b32_sdwa v46, v30, v59 dst_sel:DWORD dst_unused:UNUSED_PAD src0_sel:WORD_1 src1_sel:DWORD
	v_and_b32_sdwa v47, v31, v59 dst_sel:DWORD dst_unused:UNUSED_PAD src0_sel:WORD_1 src1_sel:DWORD
	v_and_b32_sdwa v48, v32, v59 dst_sel:DWORD dst_unused:UNUSED_PAD src0_sel:WORD_1 src1_sel:DWORD
	v_and_b32_sdwa v49, v33, v59 dst_sel:DWORD dst_unused:UNUSED_PAD src0_sel:WORD_1 src1_sel:DWORD
	v_and_b32_sdwa v50, v34, v59 dst_sel:DWORD dst_unused:UNUSED_PAD src0_sel:WORD_1 src1_sel:DWORD
	v_and_b32_sdwa v51, v35, v59 dst_sel:DWORD dst_unused:UNUSED_PAD src0_sel:WORD_1 src1_sel:DWORD
	v_and_b32_sdwa v52, v36, v59 dst_sel:DWORD dst_unused:UNUSED_PAD src0_sel:WORD_1 src1_sel:DWORD
	v_and_b32_sdwa v53, v37, v59 dst_sel:DWORD dst_unused:UNUSED_PAD src0_sel:WORD_1 src1_sel:DWORD
	v_add3_u32 v30, v30, v46, s24
	v_add3_u32 v31, v31, v47, s24
	v_add3_u32 v32, v32, v48, s24
	v_add3_u32 v33, v33, v49, s24
	v_add3_u32 v34, v34, v50, s24
	v_add3_u32 v35, v35, v51, s24
	v_add3_u32 v36, v36, v52, s24
	v_add3_u32 v37, v37, v53, s24
	v_and_b32_e32 v31, 0xffff0000, v31
	v_and_b32_e32 v33, 0xffff0000, v33
	v_and_b32_e32 v35, 0xffff0000, v35
	v_and_b32_e32 v37, 0xffff0000, v37
	v_or_b32_sdwa v60, v31, v30 dst_sel:DWORD dst_unused:UNUSED_PAD src0_sel:DWORD src1_sel:WORD_1
	v_or_b32_sdwa v61, v33, v32 dst_sel:DWORD dst_unused:UNUSED_PAD src0_sel:DWORD src1_sel:WORD_1
	v_or_b32_sdwa v62, v35, v34 dst_sel:DWORD dst_unused:UNUSED_PAD src0_sel:DWORD src1_sel:WORD_1
	v_or_b32_sdwa v63, v37, v36 dst_sel:DWORD dst_unused:UNUSED_PAD src0_sel:DWORD src1_sel:WORD_1
	global_store_dwordx4 v57, v[60:63], s[56:57]
	s_waitcnt vmcnt(7) lgkmcnt(0)
	v_fmamk_f32 v54, v12, 0x3a800000, v13
	v_rsq_f32_e32 v54, v54
	v_add_u32_e32 v58, 0xe0000, v4
	v_mul_f32_e32 v38, v38, v54
	v_mul_f32_e32 v39, v39, v54
	v_mul_f32_e32 v40, v40, v54
	v_mul_f32_e32 v41, v41, v54
	v_mul_f32_e32 v42, v42, v54
	v_mul_f32_e32 v43, v43, v54
	v_mul_f32_e32 v44, v44, v54
	v_mul_f32_e32 v45, v45, v54
	v_max_f32_e32 v38, 0, v38
	v_max_f32_e32 v39, 0, v39
	v_max_f32_e32 v40, 0, v40
	v_max_f32_e32 v41, 0, v41
	v_max_f32_e32 v42, 0, v42
	v_max_f32_e32 v43, 0, v43
	v_max_f32_e32 v44, 0, v44
	v_max_f32_e32 v45, 0, v45
	v_pk_mul_f32 v[38:39], v[38:39], v[38:39]
	v_pk_mul_f32 v[40:41], v[40:41], v[40:41]
	v_pk_mul_f32 v[42:43], v[42:43], v[42:43]
	v_pk_mul_f32 v[44:45], v[44:45], v[44:45]
	v_and_b32_sdwa v46, v38, v59 dst_sel:DWORD dst_unused:UNUSED_PAD src0_sel:WORD_1 src1_sel:DWORD
	v_and_b32_sdwa v47, v39, v59 dst_sel:DWORD dst_unused:UNUSED_PAD src0_sel:WORD_1 src1_sel:DWORD
	v_and_b32_sdwa v48, v40, v59 dst_sel:DWORD dst_unused:UNUSED_PAD src0_sel:WORD_1 src1_sel:DWORD
	v_and_b32_sdwa v49, v41, v59 dst_sel:DWORD dst_unused:UNUSED_PAD src0_sel:WORD_1 src1_sel:DWORD
	v_and_b32_sdwa v50, v42, v59 dst_sel:DWORD dst_unused:UNUSED_PAD src0_sel:WORD_1 src1_sel:DWORD
	v_and_b32_sdwa v51, v43, v59 dst_sel:DWORD dst_unused:UNUSED_PAD src0_sel:WORD_1 src1_sel:DWORD
	v_and_b32_sdwa v52, v44, v59 dst_sel:DWORD dst_unused:UNUSED_PAD src0_sel:WORD_1 src1_sel:DWORD
	v_and_b32_sdwa v53, v45, v59 dst_sel:DWORD dst_unused:UNUSED_PAD src0_sel:WORD_1 src1_sel:DWORD
	v_add3_u32 v38, v38, v46, s24
	v_add3_u32 v39, v39, v47, s24
	v_add3_u32 v40, v40, v48, s24
	v_add3_u32 v41, v41, v49, s24
	v_add3_u32 v42, v42, v50, s24
	v_add3_u32 v43, v43, v51, s24
	v_add3_u32 v44, v44, v52, s24
	v_add3_u32 v45, v45, v53, s24
	v_and_b32_e32 v39, 0xffff0000, v39
	v_and_b32_e32 v41, 0xffff0000, v41
	v_and_b32_e32 v43, 0xffff0000, v43
	v_and_b32_e32 v45, 0xffff0000, v45
	v_or_b32_sdwa v76, v39, v38 dst_sel:DWORD dst_unused:UNUSED_PAD src0_sel:DWORD src1_sel:WORD_1
	v_or_b32_sdwa v77, v41, v40 dst_sel:DWORD dst_unused:UNUSED_PAD src0_sel:DWORD src1_sel:WORD_1
	v_or_b32_sdwa v78, v43, v42 dst_sel:DWORD dst_unused:UNUSED_PAD src0_sel:DWORD src1_sel:WORD_1
	v_or_b32_sdwa v79, v45, v44 dst_sel:DWORD dst_unused:UNUSED_PAD src0_sel:DWORD src1_sel:WORD_1
	global_store_dwordx4 v58, v[76:79], s[56:57]
	s_cmpk_lt_u32 s12, 0x400
	s_barrier
	s_cbranch_scc1 .LBB0_590
